# v12 + KIND 0 (HGRN in-proj) GEMM epilogue trace-specialised per activation segment (pn>>2 uniform per unit): scalar dispatch to 4 straight-line copies, per-lane exec-mask branches removed
# speedup vs baseline: 1.0074x; 1.0062x over previous
.LBB0_396:
	s_add_u32 s36, s4, 0x100
	s_addc_u32 s37, s5, 0
	s_add_i32 s68, 0, 0x10000
	v_add_u32_e32 v30, s68, v204
	ds_read_b128 v[14:17], v30
	ds_read_b128 v[22:25], v30 offset:1024
	ds_read_b128 v[26:29], v30 offset:2048
	ds_read_b128 v[30:33], v30 offset:3072
	s_cmp_eq_u32 s57, 12
	s_cselect_b32 s45, s46, s37
	s_cselect_b32 s44, s47, s36
	s_cselect_b32 s43, s51, s56
	s_cselect_b32 s42, s54, s55
	v_lshl_add_u64 v[178:179], s[4:5], 0, v[188:189]
	s_add_i32 m0, s60, 0xc000
	ds_read_b128 v[38:41], v209
	ds_read_b128 v[42:45], v209 offset:1024
	ds_read_b128 v[46:49], v209 offset:2048
	ds_read_b128 v[54:57], v209 offset:3072
	ds_read_b128 v[58:61], v209 offset:4096
	ds_read_b128 v[62:65], v209 offset:5120
	ds_read_b128 v[66:69], v209 offset:6144
	ds_read_b128 v[70:73], v209 offset:7168
	global_load_lds_dwordx4 v[178:179], off
	v_lshl_add_u64 v[178:179], s[4:5], 0, v[186:187]
	s_add_i32 m0, s60, 0xe000
	s_nop 0
	global_load_lds_dwordx4 v[178:179], off
	s_waitcnt lgkmcnt(8)
	s_barrier
	s_waitcnt lgkmcnt(0)
	s_setprio 1
	s_waitcnt lgkmcnt(0)
	v_mfma_f32_16x16x32_bf16 v[174:177], v[14:17], v[38:41], v[174:177]
	v_mfma_f32_16x16x32_bf16 v[170:173], v[26:29], v[38:41], v[170:173]
	v_mfma_f32_16x16x32_bf16 v[158:161], v[14:17], v[46:49], v[158:161]
	v_mfma_f32_16x16x32_bf16 v[154:157], v[26:29], v[46:49], v[154:157]
	v_mfma_f32_16x16x32_bf16 v[142:145], v[14:17], v[58:61], v[142:145]
	v_mfma_f32_16x16x32_bf16 v[138:141], v[26:29], v[58:61], v[138:141]
	v_mfma_f32_16x16x32_bf16 v[126:129], v[14:17], v[66:69], v[126:129]
	v_mfma_f32_16x16x32_bf16 v[122:125], v[26:29], v[66:69], v[122:125]
	v_mfma_f32_16x16x32_bf16 v[174:177], v[22:25], v[42:45], v[174:177]
	v_mfma_f32_16x16x32_bf16 v[170:173], v[30:33], v[42:45], v[170:173]
	v_mfma_f32_16x16x32_bf16 v[158:161], v[22:25], v[54:57], v[158:161]
	v_mfma_f32_16x16x32_bf16 v[154:157], v[30:33], v[54:57], v[154:157]
	v_mfma_f32_16x16x32_bf16 v[142:145], v[22:25], v[62:65], v[142:145]
	v_mfma_f32_16x16x32_bf16 v[138:141], v[30:33], v[62:65], v[138:141]
	v_mfma_f32_16x16x32_bf16 v[126:129], v[22:25], v[70:73], v[126:129]
	v_mfma_f32_16x16x32_bf16 v[122:125], v[30:33], v[70:73], v[122:125]
	s_setprio 0
	s_barrier
	s_add_i32 s69, 0, 0x14000
	v_add_u32_e32 v210, s69, v204
	s_add_i32 s4, s68, s59
	ds_read_b128 v[178:181], v210
	ds_read_b128 v[190:193], v210 offset:1024
	ds_read_b128 v[200:203], v210 offset:2048
	ds_read_b128 v[222:225], v210 offset:3072
	v_lshl_add_u64 v[210:211], s[42:43], 0, v[184:185]
	s_mov_b32 m0, s4
	v_lshl_add_u64 v[214:215], s[42:43], 0, v[182:183]
	global_load_lds_dwordx4 v[210:211], off
	s_add_i32 m0, s4, 0x2000
	s_nop 0
	global_load_lds_dwordx4 v[214:215], off
	s_barrier
	s_waitcnt lgkmcnt(0)
	s_setprio 1
	s_waitcnt lgkmcnt(0)
	v_mfma_f32_16x16x32_bf16 v[166:169], v[178:181], v[38:41], v[166:169]
	v_mfma_f32_16x16x32_bf16 v[38:41], v[200:203], v[38:41], v[162:165]
	v_mfma_f32_16x16x32_bf16 v[166:169], v[190:193], v[42:45], v[166:169]
	v_mfma_f32_16x16x32_bf16 v[38:41], v[222:225], v[42:45], v[38:41]
	v_mfma_f32_16x16x32_bf16 v[42:45], v[178:181], v[46:49], v[150:153]
	v_mfma_f32_16x16x32_bf16 v[46:49], v[200:203], v[46:49], v[146:149]
	v_mfma_f32_16x16x32_bf16 v[42:45], v[190:193], v[54:57], v[42:45]
	v_mfma_f32_16x16x32_bf16 v[46:49], v[222:225], v[54:57], v[46:49]
	v_mfma_f32_16x16x32_bf16 v[54:57], v[178:181], v[58:61], v[134:137]
	v_mfma_f32_16x16x32_bf16 v[58:61], v[200:203], v[58:61], v[130:133]
	v_mfma_f32_16x16x32_bf16 v[54:57], v[190:193], v[62:65], v[54:57]
	v_mfma_f32_16x16x32_bf16 v[58:61], v[222:225], v[62:65], v[58:61]
	v_mfma_f32_16x16x32_bf16 v[62:65], v[178:181], v[66:69], v[118:121]
	v_mfma_f32_16x16x32_bf16 v[66:69], v[200:203], v[66:69], v[114:117]
	v_mfma_f32_16x16x32_bf16 v[62:65], v[190:193], v[70:73], v[62:65]
	v_mfma_f32_16x16x32_bf16 v[66:69], v[222:225], v[70:73], v[66:69]
	s_setprio 0
	s_mov_b32 m0, s60
	v_lshl_add_u64 v[242:243], s[44:45], 0, v[184:185]
	s_barrier
	ds_read_b128 v[70:73], v209 offset:16384
	ds_read_b128 v[114:117], v209 offset:17408
	ds_read_b128 v[118:121], v209 offset:18432
	ds_read_b128 v[130:133], v209 offset:19456
	ds_read_b128 v[134:137], v209 offset:20480
	ds_read_b128 v[146:149], v209 offset:21504
	ds_read_b128 v[150:153], v209 offset:22528
	ds_read_b128 v[162:165], v209 offset:23552
	global_load_lds_dwordx4 v[242:243], off
	v_lshl_add_u64 v[244:245], s[44:45], 0, v[182:183]
	s_mov_b32 m0, s61
	s_nop 0
	global_load_lds_dwordx4 v[244:245], off
	s_barrier
	s_waitcnt lgkmcnt(0)
	s_setprio 1
	s_waitcnt lgkmcnt(0)
	v_mfma_f32_16x16x32_bf16 v[110:113], v[14:17], v[70:73], v[110:113]
	v_mfma_f32_16x16x32_bf16 v[106:109], v[26:29], v[70:73], v[106:109]
	v_mfma_f32_16x16x32_bf16 v[94:97], v[14:17], v[118:121], v[94:97]
	v_mfma_f32_16x16x32_bf16 v[90:93], v[26:29], v[118:121], v[90:93]
	v_mfma_f32_16x16x32_bf16 v[78:81], v[14:17], v[134:137], v[78:81]
	v_mfma_f32_16x16x32_bf16 v[74:77], v[26:29], v[134:137], v[74:77]
	v_mfma_f32_16x16x32_bf16 v[10:13], v[26:29], v[150:153], v[10:13]
	v_mfma_f32_16x16x32_bf16 v[110:113], v[22:25], v[114:117], v[110:113]
	v_mfma_f32_16x16x32_bf16 v[106:109], v[30:33], v[114:117], v[106:109]
	v_mfma_f32_16x16x32_bf16 v[94:97], v[22:25], v[130:133], v[94:97]
	v_mfma_f32_16x16x32_bf16 v[90:93], v[30:33], v[130:133], v[90:93]
	v_mfma_f32_16x16x32_bf16 v[78:81], v[22:25], v[146:149], v[78:81]
	v_mfma_f32_16x16x32_bf16 v[74:77], v[30:33], v[146:149], v[74:77]
	v_mfma_f32_16x16x32_bf16 v[14:17], v[14:17], v[150:153], v[18:21]
	v_mfma_f32_16x16x32_bf16 v[10:13], v[30:33], v[162:165], v[10:13]
	v_mfma_f32_16x16x32_bf16 v[14:17], v[22:25], v[162:165], v[14:17]
	s_setprio 0
	s_barrier
	s_add_u32 s4, s42, 0x40000
	s_addc_u32 s5, s43, 0
	s_add_i32 s68, s69, s59
	v_lshl_add_u64 v[18:19], s[4:5], 0, v[184:185]
	s_mov_b32 m0, s68
	s_nop 0
	global_load_lds_dwordx4 v[18:19], off
	v_lshl_add_u64 v[18:19], s[4:5], 0, v[182:183]
	s_add_i32 m0, s68, 0x2000
	s_nop 0
	global_load_lds_dwordx4 v[18:19], off
	s_waitcnt vmcnt(6)
	s_barrier
	s_setprio 1
	v_mfma_f32_16x16x32_bf16 v[18:21], v[178:181], v[70:73], v[102:105]
	v_mfma_f32_16x16x32_bf16 v[22:25], v[190:193], v[114:117], v[18:21]
	v_mfma_f32_16x16x32_bf16 v[18:21], v[200:203], v[70:73], v[98:101]
	v_mfma_f32_16x16x32_bf16 v[26:29], v[222:225], v[114:117], v[18:21]
	v_mfma_f32_16x16x32_bf16 v[18:21], v[178:181], v[118:121], v[86:89]
	v_mfma_f32_16x16x32_bf16 v[30:33], v[190:193], v[130:133], v[18:21]
	v_mfma_f32_16x16x32_bf16 v[18:21], v[200:203], v[118:121], v[82:85]
	v_mfma_f32_16x16x32_bf16 v[70:73], v[222:225], v[130:133], v[18:21]
	v_mfma_f32_16x16x32_bf16 v[18:21], v[178:181], v[134:137], v[50:53]
	v_mfma_f32_16x16x32_bf16 v[50:53], v[190:193], v[146:149], v[18:21]
	v_mfma_f32_16x16x32_bf16 v[18:21], v[200:203], v[134:137], v[34:37]
	v_mfma_f32_16x16x32_bf16 v[6:9], v[178:181], v[150:153], v[6:9]
	v_mfma_f32_16x16x32_bf16 v[2:5], v[200:203], v[150:153], v[2:5]
	v_mfma_f32_16x16x32_bf16 v[34:37], v[222:225], v[146:149], v[18:21]
	v_mfma_f32_16x16x32_bf16 v[6:9], v[190:193], v[162:165], v[6:9]
	v_mfma_f32_16x16x32_bf16 v[2:5], v[222:225], v[162:165], v[2:5]
	s_setprio 0
	s_add_i32 s68, 0, 0x18000
	v_add_u32_e32 v98, s68, v204
	s_barrier
	ds_read_b128 v[18:21], v98
	ds_read_b128 v[82:85], v98 offset:1024
	ds_read_b128 v[86:89], v98 offset:2048
	ds_read_b128 v[98:101], v98 offset:3072
	s_add_u32 s4, s44, 0x40000
	s_addc_u32 s5, s45, 0
	s_mov_b32 m0, s62
	v_lshl_add_u64 v[134:135], s[4:5], 0, v[184:185]
	ds_read_b128 v[102:105], v209 offset:32768
	ds_read_b128 v[114:117], v209 offset:33792
	ds_read_b128 v[118:121], v209 offset:34816
	ds_read_b128 v[130:133], v209 offset:35840
	ds_read_b128 v[178:181], v209 offset:36864
	ds_read_b128 v[190:193], v209 offset:37888
	ds_read_b128 v[200:203], v209 offset:38912
	ds_read_b128 v[222:225], v209 offset:39936
	global_load_lds_dwordx4 v[134:135], off
	v_lshl_add_u64 v[134:135], s[4:5], 0, v[182:183]
	s_mov_b32 m0, s63
	s_nop 0
	global_load_lds_dwordx4 v[134:135], off
	s_waitcnt lgkmcnt(8)
	s_barrier
	s_waitcnt lgkmcnt(0)
	s_setprio 1
	s_waitcnt lgkmcnt(0)
	v_mfma_f32_16x16x32_bf16 v[134:137], v[18:21], v[102:105], v[174:177]
	v_mfma_f32_16x16x32_bf16 v[174:177], v[82:85], v[114:117], v[134:137]
	v_mfma_f32_16x16x32_bf16 v[134:137], v[86:89], v[102:105], v[170:173]
	v_mfma_f32_16x16x32_bf16 v[170:173], v[98:101], v[114:117], v[134:137]
	v_mfma_f32_16x16x32_bf16 v[134:137], v[18:21], v[118:121], v[158:161]
	v_mfma_f32_16x16x32_bf16 v[158:161], v[82:85], v[130:133], v[134:137]
	v_mfma_f32_16x16x32_bf16 v[134:137], v[86:89], v[118:121], v[154:157]
	v_mfma_f32_16x16x32_bf16 v[154:157], v[98:101], v[130:133], v[134:137]
	v_mfma_f32_16x16x32_bf16 v[134:137], v[18:21], v[178:181], v[142:145]
	v_mfma_f32_16x16x32_bf16 v[142:145], v[82:85], v[190:193], v[134:137]
	v_mfma_f32_16x16x32_bf16 v[134:137], v[86:89], v[178:181], v[138:141]
	v_mfma_f32_16x16x32_bf16 v[126:129], v[18:21], v[200:203], v[126:129]
	v_mfma_f32_16x16x32_bf16 v[122:125], v[86:89], v[200:203], v[122:125]
	v_mfma_f32_16x16x32_bf16 v[138:141], v[98:101], v[190:193], v[134:137]
	v_mfma_f32_16x16x32_bf16 v[126:129], v[82:85], v[222:225], v[126:129]
	v_mfma_f32_16x16x32_bf16 v[122:125], v[98:101], v[222:225], v[122:125]
	s_setprio 0
	s_barrier
	s_add_i32 s44, 0, 0x1c000
	v_add_u32_e32 v134, s44, v204
	s_add_i32 s4, s68, s59
	ds_read_b128 v[226:229], v134
	ds_read_b128 v[230:233], v134 offset:1024
	ds_read_b128 v[234:237], v134 offset:2048
	ds_read_b128 v[238:241], v134 offset:3072
	v_lshl_add_u64 v[134:135], v[210:211], 0, s[22:23]
	s_mov_b32 m0, s4
	s_nop 0
	global_load_lds_dwordx4 v[134:135], off
	v_lshl_add_u64 v[134:135], v[214:215], 0, s[22:23]
	s_add_i32 m0, s4, 0x2000
	s_nop 0
	global_load_lds_dwordx4 v[134:135], off
	s_barrier
	s_waitcnt lgkmcnt(0)
	s_setprio 1
	s_waitcnt lgkmcnt(0)
	v_mfma_f32_16x16x32_bf16 v[38:41], v[234:237], v[102:105], v[38:41]
	v_mfma_f32_16x16x32_bf16 v[162:165], v[238:241], v[114:117], v[38:41]
	v_mfma_f32_16x16x32_bf16 v[38:41], v[226:229], v[118:121], v[42:45]
	v_mfma_f32_16x16x32_bf16 v[150:153], v[230:233], v[130:133], v[38:41]
	v_mfma_f32_16x16x32_bf16 v[38:41], v[234:237], v[118:121], v[46:49]
	v_mfma_f32_16x16x32_bf16 v[134:137], v[226:229], v[102:105], v[166:169]
	v_mfma_f32_16x16x32_bf16 v[146:149], v[238:241], v[130:133], v[38:41]
	v_mfma_f32_16x16x32_bf16 v[38:41], v[226:229], v[178:181], v[54:57]
	v_mfma_f32_16x16x32_bf16 v[166:169], v[230:233], v[114:117], v[134:137]
	v_mfma_f32_16x16x32_bf16 v[134:137], v[230:233], v[190:193], v[38:41]
	v_mfma_f32_16x16x32_bf16 v[38:41], v[234:237], v[178:181], v[58:61]
	v_mfma_f32_16x16x32_bf16 v[130:133], v[238:241], v[190:193], v[38:41]
	v_mfma_f32_16x16x32_bf16 v[38:41], v[226:229], v[200:203], v[62:65]
	v_mfma_f32_16x16x32_bf16 v[118:121], v[230:233], v[222:225], v[38:41]
	v_mfma_f32_16x16x32_bf16 v[38:41], v[234:237], v[200:203], v[66:69]
	v_mfma_f32_16x16x32_bf16 v[114:117], v[238:241], v[222:225], v[38:41]
	s_setprio 0
	s_mov_b32 m0, s64
	v_lshl_add_u64 v[102:103], v[242:243], 0, s[22:23]
	s_barrier
	s_nop 2
	ds_read_b128 v[38:41], v209 offset:49152
	ds_read_b128 v[42:45], v209 offset:50176
	ds_read_b128 v[46:49], v209 offset:51200
	ds_read_b128 v[54:57], v209 offset:52224
	ds_read_b128 v[58:61], v209 offset:53248
	ds_read_b128 v[62:65], v209 offset:54272
	ds_read_b128 v[66:69], v209 offset:55296
	ds_read_b128 v[178:181], v209 offset:56320
	global_load_lds_dwordx4 v[102:103], off
	v_lshl_add_u64 v[102:103], v[244:245], 0, s[22:23]
	s_mov_b32 m0, s65
	s_nop 0
	global_load_lds_dwordx4 v[102:103], off
	s_barrier
	s_waitcnt lgkmcnt(0)
	s_setprio 1
	s_waitcnt lgkmcnt(0)
	v_mfma_f32_16x16x32_bf16 v[102:105], v[18:21], v[38:41], v[110:113]
	v_mfma_f32_16x16x32_bf16 v[110:113], v[82:85], v[42:45], v[102:105]
	v_mfma_f32_16x16x32_bf16 v[102:105], v[86:89], v[38:41], v[106:109]
	v_mfma_f32_16x16x32_bf16 v[94:97], v[18:21], v[46:49], v[94:97]
	v_mfma_f32_16x16x32_bf16 v[90:93], v[86:89], v[46:49], v[90:93]
	v_mfma_f32_16x16x32_bf16 v[78:81], v[18:21], v[58:61], v[78:81]
	v_mfma_f32_16x16x32_bf16 v[74:77], v[86:89], v[58:61], v[74:77]
	v_mfma_f32_16x16x32_bf16 v[14:17], v[18:21], v[66:69], v[14:17]
	v_mfma_f32_16x16x32_bf16 v[10:13], v[86:89], v[66:69], v[10:13]
	v_mfma_f32_16x16x32_bf16 v[106:109], v[98:101], v[42:45], v[102:105]
	v_mfma_f32_16x16x32_bf16 v[94:97], v[82:85], v[54:57], v[94:97]
	v_mfma_f32_16x16x32_bf16 v[90:93], v[98:101], v[54:57], v[90:93]
	v_mfma_f32_16x16x32_bf16 v[78:81], v[82:85], v[62:65], v[78:81]
	v_mfma_f32_16x16x32_bf16 v[74:77], v[98:101], v[62:65], v[74:77]
	v_mfma_f32_16x16x32_bf16 v[18:21], v[82:85], v[178:181], v[14:17]
	v_mfma_f32_16x16x32_bf16 v[10:13], v[98:101], v[178:181], v[10:13]
	s_setprio 0
	s_barrier
	s_add_u32 s4, s42, 0x40080
	s_addc_u32 s5, s43, 0
	s_add_i32 s42, s44, s59
	v_lshl_add_u64 v[14:15], s[4:5], 0, v[184:185]
	s_mov_b32 m0, s42
	s_nop 0
	global_load_lds_dwordx4 v[14:15], off
	v_lshl_add_u64 v[14:15], s[4:5], 0, v[182:183]
	s_add_i32 m0, s42, 0x2000
	s_nop 0
	global_load_lds_dwordx4 v[14:15], off
	s_waitcnt vmcnt(6)
	s_barrier
	s_setprio 1
	v_mfma_f32_16x16x32_bf16 v[14:17], v[226:229], v[38:41], v[22:25]
	v_mfma_f32_16x16x32_bf16 v[102:105], v[230:233], v[42:45], v[14:17]
	v_mfma_f32_16x16x32_bf16 v[14:17], v[234:237], v[38:41], v[26:29]
	v_mfma_f32_16x16x32_bf16 v[98:101], v[238:241], v[42:45], v[14:17]
	v_mfma_f32_16x16x32_bf16 v[14:17], v[226:229], v[46:49], v[30:33]
	v_mfma_f32_16x16x32_bf16 v[86:89], v[230:233], v[54:57], v[14:17]
	v_mfma_f32_16x16x32_bf16 v[14:17], v[234:237], v[46:49], v[70:73]
	v_mfma_f32_16x16x32_bf16 v[82:85], v[238:241], v[54:57], v[14:17]
	v_mfma_f32_16x16x32_bf16 v[14:17], v[226:229], v[58:61], v[50:53]
	v_mfma_f32_16x16x32_bf16 v[50:53], v[230:233], v[62:65], v[14:17]
	v_mfma_f32_16x16x32_bf16 v[14:17], v[234:237], v[58:61], v[34:37]
	v_mfma_f32_16x16x32_bf16 v[6:9], v[226:229], v[66:69], v[6:9]
	v_mfma_f32_16x16x32_bf16 v[2:5], v[234:237], v[66:69], v[2:5]
	v_mfma_f32_16x16x32_bf16 v[34:37], v[238:241], v[62:65], v[14:17]
	v_mfma_f32_16x16x32_bf16 v[6:9], v[230:233], v[178:181], v[6:9]
	v_mfma_f32_16x16x32_bf16 v[2:5], v[238:241], v[178:181], v[2:5]
	s_setprio 0
	s_add_i32 s57, s57, 2
	s_add_u32 s55, s55, 0x100
	s_addc_u32 s56, s56, 0
	s_cmp_gt_u32 s57, 13
	s_mov_b64 s[4:5], s[36:37]
	s_barrier
	s_cbranch_scc0 .LBB0_396
	s_lshr_b32 s32, s27, 2
	s_cmp_eq_u32 s32, 0
	s_cbranch_scc1 .Lepi0_seg0
	s_cmp_eq_u32 s32, 1
	s_cbranch_scc1 .Lepi0_seg1
	s_cmp_eq_u32 s32, 2
	s_cbranch_scc1 .Lepi0_seg2
	s_branch .Lepi0_seg3

.Lepi0_seg0:
	v_lshl_or_b32 v202, s27, 8, v208
	s_and_b32 s4, s27, -4
	v_ashrrev_i32_e32 v203, 31, v202
	v_lshlrev_b64 v[14:15], 2, v[202:203]
	v_lshl_add_u64 v[16:17], s[10:11], 0, v[14:15]
	v_lshl_add_u64 v[22:23], s[12:13], 0, v[14:15]
	flat_load_dwordx4 v[70:73], v[16:17]
	flat_load_dwordx4 v[66:69], v[22:23]
	s_cmp_eq_u32 s4, 4
	s_cselect_b64 s[36:37], -1, 0
	s_cmp_lg_u32 s4, 4
	v_mov_b32_e32 v46, 0
	v_and_b32_e32 v210, 0x3ff, v202
	v_mov_b32_e32 v62, 0
	v_mov_b32_e32 v63, 0
	v_mov_b32_e32 v64, 0
	v_mov_b32_e32 v65, 0
	flat_load_dwordx4 v[58:61], v[16:17] offset:16
	flat_load_dwordx4 v[54:57], v[22:23] offset:16
	v_cndmask_b32_e64 v14, 0, 1, s[36:37]
	v_cmp_ne_u32_e64 s[4:5], 1, v14
	s_andn2_b64 vcc, exec, s[36:37]
	v_mov_b32_e32 v47, 0
	v_mov_b32_e32 v48, 0
	v_mov_b32_e32 v49, 0
	flat_load_dwordx4 v[42:45], v[16:17] offset:512
	flat_load_dwordx4 v[38:41], v[22:23] offset:512
	v_add_u32_e32 v212, 0x80, v202
	v_mov_b32_e32 v14, 0
	s_and_b64 vcc, exec, s[4:5]
	v_and_b32_e32 v203, 0x3ff, v212
	v_mov_b32_e32 v30, 0
	v_mov_b32_e32 v31, 0
	v_mov_b32_e32 v32, 0
	v_mov_b32_e32 v33, 0
	flat_load_dwordx4 v[26:29], v[16:17] offset:528
	s_nop 0
	flat_load_dwordx4 v[22:25], v[22:23] offset:528
	s_and_b64 vcc, exec, s[4:5]
	v_mov_b32_e32 v15, 0
	v_mov_b32_e32 v16, 0
	v_mov_b32_e32 v17, 0
	v_mov_b32_e32 v214, v1
	v_cndmask_b32_e64 v178, 0, 1, s[6:7]
	v_cmp_ne_u32_e64 s[46:47], 1, v178
	s_andn2_b64 vcc, exec, s[6:7]
	v_lshl_add_u32 v211, v214, 3, s33
	s_cbranch_vccnz .LBB0_407_sg0
	s_waitcnt vmcnt(0)
	ds_read_b64 v[200:201], v211
	s_waitcnt lgkmcnt(0)
	v_mov_b32_e32 v192, v201
	s_branch .LBB0_408_sg0

.LBB0_408_sg0:
	s_waitcnt vmcnt(0) lgkmcnt(0)
	v_xor_b32_e32 v191, 0x80000000, v73
	v_xor_b32_e32 v190, 0x80000000, v72
	v_pk_fma_f32 v[72:73], v[190:191], v[200:201], v[176:177] op_sel_hi:[1,0,1]
	v_pk_fma_f32 v[174:175], v[70:71], v[200:201], v[174:175] op_sel_hi:[1,0,1] neg_lo:[1,0,0] neg_hi:[1,0,0]
	s_movk_i32 s4, 0x3ff
	v_pk_fma_f32 v[174:175], v[192:193], v[174:175], v[66:67] op_sel_hi:[0,1,1]
	v_pk_fma_f32 v[176:177], v[192:193], v[72:73], v[68:69] op_sel_hi:[0,1,1]
	v_cmp_lt_u32_e64 s[42:43], s4, v202
	s_and_saveexec_b64 s[4:5], s[42:43]
	s_xor_b64 s[4:5], exec, s[4:5]
	s_andn2_saveexec_b64 s[4:5], s[4:5]
	v_mul_f32_e32 v72, 0xbfb8aa3b, v174
	v_mul_f32_e32 v73, 0xbfb8aa3b, v175
	v_mul_f32_e32 v178, 0xbfb8aa3b, v176
	v_mul_f32_e32 v179, 0xbfb8aa3b, v177
	v_exp_f32_e32 v72, v72
	v_exp_f32_e32 v73, v73
	v_exp_f32_e32 v178, v178
	v_exp_f32_e32 v179, v179
	v_add_f32_e32 v72, 1.0, v72
	v_add_f32_e32 v73, 1.0, v73
	v_add_f32_e32 v178, 1.0, v178
	v_add_f32_e32 v179, 1.0, v179
	v_rcp_f32_e32 v72, v72
	v_rcp_f32_e32 v73, v73
	v_rcp_f32_e32 v178, v178
	v_rcp_f32_e32 v179, v179
	s_mov_b32 s36, 0x3db504f3
	v_pk_mul_f32 v[72:73], v[174:175], v[72:73]
	v_pk_mul_f32 v[174:175], v[176:177], v[178:179]
	s_nop 0
	v_pk_mul_f32 v[180:181], v[174:175], s[36:37] op_sel_hi:[1,0]
	v_pk_mul_f32 v[178:179], v[72:73], s[36:37] op_sel_hi:[1,0]
	s_or_b64 exec, exec, s[4:5]
	v_mov_b32_e32 v201, v200
	v_xor_b32_e32 v61, 0x80000000, v61
	v_xor_b32_e32 v60, 0x80000000, v60
	v_mov_b32_e32 v72, v200
	v_mov_b32_e32 v73, v200
	v_mov_b32_e32 v193, v192
	v_pk_fma_f32 v[72:73], v[60:61], v[72:73], v[172:173]
	v_pk_fma_f32 v[170:171], v[58:59], v[200:201], v[170:171] neg_lo:[1,0,0] neg_hi:[1,0,0]
	v_mov_b32_e32 v172, v192
	v_mov_b32_e32 v173, v192
	v_pk_fma_f32 v[170:171], v[192:193], v[170:171], v[54:55]
	v_pk_fma_f32 v[172:173], v[172:173], v[72:73], v[56:57]
	v_cvt_pk_bf16_f32 v174, v178, v179
	v_cvt_pk_bf16_f32 v175, v180, v181
	s_and_saveexec_b64 s[4:5], s[42:43]
	s_xor_b64 s[4:5], exec, s[4:5]
	s_andn2_saveexec_b64 s[4:5], s[4:5]
	v_mul_f32_e32 v72, 0xbfb8aa3b, v170
	v_mul_f32_e32 v73, 0xbfb8aa3b, v171
	v_mul_f32_e32 v176, 0xbfb8aa3b, v172
	v_mul_f32_e32 v177, 0xbfb8aa3b, v173
	v_exp_f32_e32 v72, v72
	v_exp_f32_e32 v73, v73
	v_exp_f32_e32 v176, v176
	v_exp_f32_e32 v177, v177
	v_add_f32_e32 v72, 1.0, v72
	v_add_f32_e32 v73, 1.0, v73
	v_add_f32_e32 v176, 1.0, v176
	v_add_f32_e32 v177, 1.0, v177
	v_rcp_f32_e32 v72, v72
	v_rcp_f32_e32 v73, v73
	v_rcp_f32_e32 v176, v176
	v_rcp_f32_e32 v177, v177
	s_mov_b32 s36, 0x3db504f3
	v_pk_mul_f32 v[72:73], v[170:171], v[72:73]
	v_mov_b32_e32 v180, 0
	v_pk_mul_f32 v[170:171], v[172:173], v[176:177]
	v_pk_mul_f32 v[176:177], v[72:73], s[36:37] op_sel_hi:[1,0]
	v_pk_mul_f32 v[178:179], v[170:171], s[36:37] op_sel_hi:[1,0]
	s_or_b64 exec, exec, s[4:5]
	s_lshl_b32 s51, s3, 8
	v_add_lshl_u32 v181, v214, s51, 10
	s_mov_b32 s3, 0x1020000
	v_cvt_pk_bf16_f32 v176, v176, v177
	v_cvt_pk_bf16_f32 v177, v178, v179
	v_mul_lo_u32 v178, v180, s3
	v_or_b32_e32 v72, v181, v210
	v_add_lshl_u32 v72, v72, v178, 1
	buffer_store_dwordx4 v[174:177], v72, s[28:31], 0 offen sc1
	v_xor_b32_e32 v45, 0x80000000, v45
	v_xor_b32_e32 v44, 0x80000000, v44
	v_mov_b32_e32 v72, v200
	v_mov_b32_e32 v73, v200
	v_pk_fma_f32 v[72:73], v[44:45], v[72:73], v[168:169]
	v_pk_fma_f32 v[166:167], v[42:43], v[200:201], v[166:167] neg_lo:[1,0,0] neg_hi:[1,0,0]
	v_mov_b32_e32 v168, v192
	v_mov_b32_e32 v169, v192
	s_movk_i32 s3, 0x3ff
	v_pk_fma_f32 v[166:167], v[192:193], v[166:167], v[38:39]
	v_pk_fma_f32 v[168:169], v[168:169], v[72:73], v[40:41]
	v_cmp_lt_u32_e64 s[44:45], s3, v212
	s_and_saveexec_b64 s[4:5], s[44:45]
	s_xor_b64 s[4:5], exec, s[4:5]
	s_andn2_saveexec_b64 s[4:5], s[4:5]
	v_mul_f32_e32 v72, 0xbfb8aa3b, v166
	v_mul_f32_e32 v73, 0xbfb8aa3b, v167
	v_mul_f32_e32 v170, 0xbfb8aa3b, v168
	v_mul_f32_e32 v171, 0xbfb8aa3b, v169
	v_exp_f32_e32 v72, v72
	v_exp_f32_e32 v73, v73
	v_exp_f32_e32 v170, v170
	v_exp_f32_e32 v171, v171
	v_add_f32_e32 v72, 1.0, v72
	v_add_f32_e32 v73, 1.0, v73
	v_add_f32_e32 v170, 1.0, v170
	v_add_f32_e32 v171, 1.0, v171
	v_rcp_f32_e32 v72, v72
	v_rcp_f32_e32 v73, v73
	v_rcp_f32_e32 v170, v170
	v_rcp_f32_e32 v171, v171
	s_mov_b32 s36, 0x3db504f3
	v_pk_mul_f32 v[72:73], v[166:167], v[72:73]
	v_pk_mul_f32 v[166:167], v[168:169], v[170:171]
	s_nop 0
	v_pk_mul_f32 v[172:173], v[166:167], s[36:37] op_sel_hi:[1,0]
	v_pk_mul_f32 v[170:171], v[72:73], s[36:37] op_sel_hi:[1,0]
	s_or_b64 exec, exec, s[4:5]
	v_xor_b32_e32 v29, 0x80000000, v29
	v_xor_b32_e32 v28, 0x80000000, v28
	v_mov_b32_e32 v72, v200
	v_mov_b32_e32 v73, v200
	v_pk_fma_f32 v[162:163], v[26:27], v[200:201], v[162:163] neg_lo:[1,0,0] neg_hi:[1,0,0]
	v_pk_fma_f32 v[72:73], v[28:29], v[72:73], v[164:165]
	v_pk_fma_f32 v[162:163], v[192:193], v[162:163], v[22:23]
	v_mov_b32_e32 v193, v192
	v_pk_fma_f32 v[164:165], v[192:193], v[72:73], v[24:25]
	v_cvt_pk_bf16_f32 v166, v170, v171
	v_cvt_pk_bf16_f32 v167, v172, v173
	s_and_saveexec_b64 s[4:5], s[44:45]
	s_xor_b64 s[4:5], exec, s[4:5]
	s_andn2_saveexec_b64 s[4:5], s[4:5]
	v_mul_f32_e32 v72, 0xbfb8aa3b, v162
	v_mul_f32_e32 v73, 0xbfb8aa3b, v163
	v_mul_f32_e32 v168, 0xbfb8aa3b, v164
	v_mul_f32_e32 v169, 0xbfb8aa3b, v165
	v_exp_f32_e32 v72, v72
	v_exp_f32_e32 v73, v73
	v_exp_f32_e32 v168, v168
	v_exp_f32_e32 v169, v169
	v_add_f32_e32 v72, 1.0, v72
	v_add_f32_e32 v73, 1.0, v73
	v_add_f32_e32 v168, 1.0, v168
	v_add_f32_e32 v169, 1.0, v169
	v_rcp_f32_e32 v72, v72
	v_rcp_f32_e32 v73, v73
	v_rcp_f32_e32 v168, v168
	v_rcp_f32_e32 v169, v169
	s_mov_b32 s36, 0x3db504f3
	v_pk_mul_f32 v[72:73], v[162:163], v[72:73]
	v_mov_b32_e32 v172, 0
	v_pk_mul_f32 v[162:163], v[164:165], v[168:169]
	v_pk_mul_f32 v[168:169], v[72:73], s[36:37] op_sel_hi:[1,0]
	v_pk_mul_f32 v[170:171], v[162:163], s[36:37] op_sel_hi:[1,0]
	s_or_b64 exec, exec, s[4:5]
	s_mov_b32 s3, 0x1020000
	v_cvt_pk_bf16_f32 v168, v168, v169
	v_cvt_pk_bf16_f32 v169, v170, v171
	v_mul_lo_u32 v170, v172, s3
	v_or_b32_e32 v72, v181, v203
	v_add_lshl_u32 v72, v72, v170, 1
	s_and_b64 vcc, exec, s[46:47]
	buffer_store_dwordx4 v[166:169], v72, s[28:31], 0 offen sc1
	s_cbranch_vccnz .LBB0_458_sg0
	ds_read_b64 v[166:167], v211 offset:128
	s_waitcnt lgkmcnt(0)
	v_mov_b32_e32 v72, v167
	s_branch .LBB0_459_sg0

.LBB0_459_sg0:
	v_pk_fma_f32 v[160:161], v[190:191], v[166:167], v[160:161] op_sel_hi:[1,0,1]
	v_pk_fma_f32 v[158:159], v[70:71], v[166:167], v[158:159] op_sel_hi:[1,0,1] neg_lo:[1,0,0] neg_hi:[1,0,0]
	v_pk_fma_f32 v[160:161], v[72:73], v[160:161], v[68:69] op_sel_hi:[0,1,1]
	v_pk_fma_f32 v[158:159], v[72:73], v[158:159], v[66:67] op_sel_hi:[0,1,1]
	s_and_saveexec_b64 s[4:5], s[42:43]
	s_xor_b64 s[4:5], exec, s[4:5]
	s_andn2_saveexec_b64 s[4:5], s[4:5]
	v_mul_f32_e32 v73, 0xbfb8aa3b, v158
	v_exp_f32_e32 v73, v73
	v_mul_f32_e32 v162, 0xbfb8aa3b, v159
	v_exp_f32_e32 v162, v162
	v_mul_f32_e32 v164, 0xbfb8aa3b, v161
	v_add_f32_e32 v73, 1.0, v73
	v_exp_f32_e32 v165, v164
	v_add_f32_e32 v163, 1.0, v162
	v_rcp_f32_e32 v162, v73
	v_mul_f32_e32 v73, 0xbfb8aa3b, v160
	v_exp_f32_e32 v73, v73
	v_rcp_f32_e32 v163, v163
	s_mov_b32 s36, 0x3db504f3
	v_add_f32_e32 v73, 1.0, v73
	v_rcp_f32_e32 v164, v73
	v_add_f32_e32 v73, 1.0, v165
	v_rcp_f32_e32 v165, v73
	v_pk_mul_f32 v[158:159], v[158:159], v[162:163]
	v_pk_mul_f32 v[160:161], v[160:161], v[164:165]
	s_nop 0
	v_pk_mul_f32 v[164:165], v[160:161], s[36:37] op_sel_hi:[1,0]
	v_pk_mul_f32 v[162:163], v[158:159], s[36:37] op_sel_hi:[1,0]
	s_or_b64 exec, exec, s[4:5]
	v_mov_b32_e32 v167, v166
	v_mov_b32_e32 v160, v166
	v_mov_b32_e32 v161, v166
	v_mov_b32_e32 v73, v72
	v_pk_fma_f32 v[156:157], v[60:61], v[160:161], v[156:157]
	v_pk_fma_f32 v[154:155], v[58:59], v[166:167], v[154:155] neg_lo:[1,0,0] neg_hi:[1,0,0]
	v_mov_b32_e32 v160, v72
	v_mov_b32_e32 v161, v72
	v_pk_fma_f32 v[154:155], v[72:73], v[154:155], v[54:55]
	v_pk_fma_f32 v[156:157], v[160:161], v[156:157], v[56:57]
	v_cvt_pk_bf16_f32 v158, v162, v163
	v_cvt_pk_bf16_f32 v159, v164, v165
	s_and_saveexec_b64 s[4:5], s[42:43]
	s_xor_b64 s[4:5], exec, s[4:5]
	s_andn2_saveexec_b64 s[4:5], s[4:5]
	v_mul_f32_e32 v160, 0xbfb8aa3b, v154
	v_mul_f32_e32 v161, 0xbfb8aa3b, v155
	v_mul_f32_e32 v162, 0xbfb8aa3b, v156
	v_mul_f32_e32 v163, 0xbfb8aa3b, v157
	v_exp_f32_e32 v160, v160
	v_exp_f32_e32 v161, v161
	v_exp_f32_e32 v162, v162
	v_exp_f32_e32 v163, v163
	v_add_f32_e32 v160, 1.0, v160
	v_add_f32_e32 v161, 1.0, v161
	v_add_f32_e32 v162, 1.0, v162
	v_add_f32_e32 v163, 1.0, v163
	v_rcp_f32_e32 v160, v160
	v_rcp_f32_e32 v161, v161
	v_rcp_f32_e32 v162, v162
	v_rcp_f32_e32 v163, v163
	s_mov_b32 s36, 0x3db504f3
	v_pk_mul_f32 v[154:155], v[154:155], v[160:161]
	v_pk_mul_f32 v[156:157], v[156:157], v[162:163]
	s_nop 0
	v_pk_mul_f32 v[162:163], v[156:157], s[36:37] op_sel_hi:[1,0]
	v_pk_mul_f32 v[160:161], v[154:155], s[36:37] op_sel_hi:[1,0]
	s_or_b64 exec, exec, s[4:5]
	v_add_u32_e32 v164, 0x4000, v181
	v_or_b32_e32 v154, v164, v210
	v_add_lshl_u32 v154, v154, v178, 1
	v_cvt_pk_bf16_f32 v160, v160, v161
	v_cvt_pk_bf16_f32 v161, v162, v163
	buffer_store_dwordx4 v[158:161], v154, s[28:31], 0 offen sc1
	v_mov_b32_e32 v154, v166
	v_mov_b32_e32 v155, v166
	v_pk_fma_f32 v[152:153], v[44:45], v[154:155], v[152:153]
	v_pk_fma_f32 v[150:151], v[42:43], v[166:167], v[150:151] neg_lo:[1,0,0] neg_hi:[1,0,0]
	v_mov_b32_e32 v154, v72
	v_mov_b32_e32 v155, v72
	v_pk_fma_f32 v[150:151], v[72:73], v[150:151], v[38:39]
	v_pk_fma_f32 v[152:153], v[154:155], v[152:153], v[40:41]
	s_and_saveexec_b64 s[4:5], s[44:45]
	s_xor_b64 s[4:5], exec, s[4:5]
	s_andn2_saveexec_b64 s[4:5], s[4:5]
	v_mul_f32_e32 v154, 0xbfb8aa3b, v150
	v_mul_f32_e32 v155, 0xbfb8aa3b, v151
	v_mul_f32_e32 v156, 0xbfb8aa3b, v152
	v_mul_f32_e32 v157, 0xbfb8aa3b, v153
	v_exp_f32_e32 v154, v154
	v_exp_f32_e32 v155, v155
	v_exp_f32_e32 v156, v156
	v_exp_f32_e32 v157, v157
	v_add_f32_e32 v154, 1.0, v154
	v_add_f32_e32 v155, 1.0, v155
	v_add_f32_e32 v156, 1.0, v156
	v_add_f32_e32 v157, 1.0, v157
	v_rcp_f32_e32 v154, v154
	v_rcp_f32_e32 v155, v155
	v_rcp_f32_e32 v156, v156
	v_rcp_f32_e32 v157, v157
	s_mov_b32 s36, 0x3db504f3
	v_pk_mul_f32 v[150:151], v[150:151], v[154:155]
	v_pk_mul_f32 v[152:153], v[152:153], v[156:157]
	s_nop 0
	v_pk_mul_f32 v[156:157], v[152:153], s[36:37] op_sel_hi:[1,0]
	v_pk_mul_f32 v[154:155], v[150:151], s[36:37] op_sel_hi:[1,0]
	s_or_b64 exec, exec, s[4:5]
	v_mov_b32_e32 v152, v166
	v_mov_b32_e32 v153, v166
	v_pk_fma_f32 v[146:147], v[26:27], v[166:167], v[146:147] neg_lo:[1,0,0] neg_hi:[1,0,0]
	v_pk_fma_f32 v[148:149], v[28:29], v[152:153], v[148:149]
	v_pk_fma_f32 v[146:147], v[72:73], v[146:147], v[22:23]
	v_mov_b32_e32 v73, v72
	v_pk_fma_f32 v[148:149], v[72:73], v[148:149], v[24:25]
	v_cvt_pk_bf16_f32 v150, v154, v155
	v_cvt_pk_bf16_f32 v151, v156, v157
	s_and_saveexec_b64 s[4:5], s[44:45]
	s_xor_b64 s[4:5], exec, s[4:5]
	s_andn2_saveexec_b64 s[4:5], s[4:5]
	v_mul_f32_e32 v72, 0xbfb8aa3b, v146
	v_mul_f32_e32 v73, 0xbfb8aa3b, v147
	v_mul_f32_e32 v152, 0xbfb8aa3b, v148
	v_mul_f32_e32 v153, 0xbfb8aa3b, v149
	v_exp_f32_e32 v72, v72
	v_exp_f32_e32 v73, v73
	v_exp_f32_e32 v152, v152
	v_exp_f32_e32 v153, v153
	v_add_f32_e32 v72, 1.0, v72
	v_add_f32_e32 v73, 1.0, v73
	v_add_f32_e32 v152, 1.0, v152
	v_add_f32_e32 v153, 1.0, v153
	v_rcp_f32_e32 v72, v72
	v_rcp_f32_e32 v73, v73
	v_rcp_f32_e32 v152, v152
	v_rcp_f32_e32 v153, v153
	s_mov_b32 s36, 0x3db504f3
	v_pk_mul_f32 v[72:73], v[146:147], v[72:73]
	v_pk_mul_f32 v[146:147], v[148:149], v[152:153]
	s_nop 0
	v_pk_mul_f32 v[154:155], v[146:147], s[36:37] op_sel_hi:[1,0]
	v_pk_mul_f32 v[152:153], v[72:73], s[36:37] op_sel_hi:[1,0]
	s_or_b64 exec, exec, s[4:5]
	v_or_b32_e32 v72, v164, v203
	v_add_lshl_u32 v72, v72, v170, 1
	v_cvt_pk_bf16_f32 v152, v152, v153
	v_cvt_pk_bf16_f32 v153, v154, v155
	buffer_store_dwordx4 v[150:153], v72, s[28:31], 0 offen sc1
	s_and_b64 vcc, exec, s[46:47]
	s_nop 0
	v_mov_b32_e32 v153, v205
	s_nop 0
	v_lshl_add_u32 v152, v153, 3, s33
	s_cbranch_vccnz .LBB0_509_sg0
	ds_read_b64 v[150:151], v152
	s_waitcnt lgkmcnt(0)
	v_mov_b32_e32 v72, v151
	s_branch .LBB0_510_sg0

.LBB0_510_sg0:
	v_pk_fma_f32 v[144:145], v[190:191], v[150:151], v[144:145] op_sel_hi:[1,0,1]
	v_pk_fma_f32 v[142:143], v[70:71], v[150:151], v[142:143] op_sel_hi:[1,0,1] neg_lo:[1,0,0] neg_hi:[1,0,0]
	v_pk_fma_f32 v[144:145], v[72:73], v[144:145], v[68:69] op_sel_hi:[0,1,1]
	v_pk_fma_f32 v[142:143], v[72:73], v[142:143], v[66:67] op_sel_hi:[0,1,1]
	s_and_saveexec_b64 s[4:5], s[42:43]
	s_xor_b64 s[4:5], exec, s[4:5]
	s_andn2_saveexec_b64 s[4:5], s[4:5]
	v_mul_f32_e32 v73, 0xbfb8aa3b, v142
	v_exp_f32_e32 v73, v73
	v_mul_f32_e32 v146, 0xbfb8aa3b, v143
	v_exp_f32_e32 v146, v146
	v_mul_f32_e32 v148, 0xbfb8aa3b, v145
	v_add_f32_e32 v73, 1.0, v73
	v_exp_f32_e32 v149, v148
	v_add_f32_e32 v147, 1.0, v146
	v_rcp_f32_e32 v146, v73
	v_mul_f32_e32 v73, 0xbfb8aa3b, v144
	v_exp_f32_e32 v73, v73
	v_rcp_f32_e32 v147, v147
	s_mov_b32 s36, 0x3db504f3
	v_add_f32_e32 v73, 1.0, v73
	v_rcp_f32_e32 v148, v73
	v_add_f32_e32 v73, 1.0, v149
	v_rcp_f32_e32 v149, v73
	v_pk_mul_f32 v[142:143], v[142:143], v[146:147]
	v_pk_mul_f32 v[144:145], v[144:145], v[148:149]
	s_nop 0
	v_pk_mul_f32 v[148:149], v[144:145], s[36:37] op_sel_hi:[1,0]
	v_pk_mul_f32 v[146:147], v[142:143], s[36:37] op_sel_hi:[1,0]
	s_or_b64 exec, exec, s[4:5]
	v_mov_b32_e32 v151, v150
	v_mov_b32_e32 v144, v150
	v_mov_b32_e32 v145, v150
	v_mov_b32_e32 v73, v72
	v_pk_fma_f32 v[140:141], v[60:61], v[144:145], v[140:141]
	v_pk_fma_f32 v[138:139], v[58:59], v[150:151], v[138:139] neg_lo:[1,0,0] neg_hi:[1,0,0]
	v_mov_b32_e32 v144, v72
	v_mov_b32_e32 v145, v72
	v_pk_fma_f32 v[138:139], v[72:73], v[138:139], v[54:55]
	v_pk_fma_f32 v[140:141], v[144:145], v[140:141], v[56:57]
	v_cvt_pk_bf16_f32 v142, v146, v147
	v_cvt_pk_bf16_f32 v143, v148, v149
	s_and_saveexec_b64 s[4:5], s[42:43]
	s_xor_b64 s[4:5], exec, s[4:5]
	s_andn2_saveexec_b64 s[4:5], s[4:5]
	v_mul_f32_e32 v144, 0xbfb8aa3b, v138
	v_mul_f32_e32 v145, 0xbfb8aa3b, v139
	v_mul_f32_e32 v146, 0xbfb8aa3b, v140
	v_mul_f32_e32 v147, 0xbfb8aa3b, v141
	v_exp_f32_e32 v144, v144
	v_exp_f32_e32 v145, v145
	v_exp_f32_e32 v146, v146
	v_exp_f32_e32 v147, v147
	v_add_f32_e32 v144, 1.0, v144
	v_add_f32_e32 v145, 1.0, v145
	v_add_f32_e32 v146, 1.0, v146
	v_add_f32_e32 v147, 1.0, v147
	v_rcp_f32_e32 v144, v144
	v_rcp_f32_e32 v145, v145
	v_rcp_f32_e32 v146, v146
	v_rcp_f32_e32 v147, v147
	s_mov_b32 s36, 0x3db504f3
	v_pk_mul_f32 v[138:139], v[138:139], v[144:145]
	v_pk_mul_f32 v[140:141], v[140:141], v[146:147]
	s_nop 0
	v_pk_mul_f32 v[146:147], v[140:141], s[36:37] op_sel_hi:[1,0]
	v_pk_mul_f32 v[144:145], v[138:139], s[36:37] op_sel_hi:[1,0]
	s_or_b64 exec, exec, s[4:5]
	v_add_lshl_u32 v148, v153, s51, 10
	v_cvt_pk_bf16_f32 v144, v144, v145
	v_cvt_pk_bf16_f32 v145, v146, v147
	v_or_b32_e32 v146, v178, v210
	v_add_lshl_u32 v138, v148, v146, 1
	buffer_store_dwordx4 v[142:145], v138, s[28:31], 0 offen sc1
	v_mov_b32_e32 v138, v150
	v_mov_b32_e32 v139, v150
	v_pk_fma_f32 v[136:137], v[44:45], v[138:139], v[136:137]
	v_pk_fma_f32 v[134:135], v[42:43], v[150:151], v[134:135] neg_lo:[1,0,0] neg_hi:[1,0,0]
	v_mov_b32_e32 v138, v72
	v_mov_b32_e32 v139, v72
	v_pk_fma_f32 v[134:135], v[72:73], v[134:135], v[38:39]
	v_pk_fma_f32 v[136:137], v[138:139], v[136:137], v[40:41]
	s_and_saveexec_b64 s[4:5], s[44:45]
	s_xor_b64 s[4:5], exec, s[4:5]
	s_andn2_saveexec_b64 s[4:5], s[4:5]
	v_mul_f32_e32 v138, 0xbfb8aa3b, v134
	v_mul_f32_e32 v139, 0xbfb8aa3b, v135
	v_mul_f32_e32 v140, 0xbfb8aa3b, v136
	v_mul_f32_e32 v141, 0xbfb8aa3b, v137
	v_exp_f32_e32 v138, v138
	v_exp_f32_e32 v139, v139
	v_exp_f32_e32 v140, v140
	v_exp_f32_e32 v141, v141
	v_add_f32_e32 v138, 1.0, v138
	v_add_f32_e32 v139, 1.0, v139
	v_add_f32_e32 v140, 1.0, v140
	v_add_f32_e32 v141, 1.0, v141
	v_rcp_f32_e32 v138, v138
	v_rcp_f32_e32 v139, v139
	v_rcp_f32_e32 v140, v140
	v_rcp_f32_e32 v141, v141
	s_mov_b32 s36, 0x3db504f3
	v_pk_mul_f32 v[134:135], v[134:135], v[138:139]
	v_pk_mul_f32 v[136:137], v[136:137], v[140:141]
	s_nop 0
	v_pk_mul_f32 v[140:141], v[136:137], s[36:37] op_sel_hi:[1,0]
	v_pk_mul_f32 v[138:139], v[134:135], s[36:37] op_sel_hi:[1,0]
	s_or_b64 exec, exec, s[4:5]
	v_mov_b32_e32 v136, v150
	v_mov_b32_e32 v137, v150
	v_pk_fma_f32 v[130:131], v[26:27], v[150:151], v[130:131] neg_lo:[1,0,0] neg_hi:[1,0,0]
	v_pk_fma_f32 v[132:133], v[28:29], v[136:137], v[132:133]
	v_pk_fma_f32 v[130:131], v[72:73], v[130:131], v[22:23]
	v_mov_b32_e32 v73, v72
	v_pk_fma_f32 v[132:133], v[72:73], v[132:133], v[24:25]
	v_cvt_pk_bf16_f32 v134, v138, v139
	v_cvt_pk_bf16_f32 v135, v140, v141
	s_and_saveexec_b64 s[4:5], s[44:45]
	s_xor_b64 s[4:5], exec, s[4:5]
	s_andn2_saveexec_b64 s[4:5], s[4:5]
	v_mul_f32_e32 v72, 0xbfb8aa3b, v130
	v_mul_f32_e32 v73, 0xbfb8aa3b, v131
	v_mul_f32_e32 v136, 0xbfb8aa3b, v132
	v_mul_f32_e32 v137, 0xbfb8aa3b, v133
	v_exp_f32_e32 v72, v72
	v_exp_f32_e32 v73, v73
	v_exp_f32_e32 v136, v136
	v_exp_f32_e32 v137, v137
	v_add_f32_e32 v72, 1.0, v72
	v_add_f32_e32 v73, 1.0, v73
	v_add_f32_e32 v136, 1.0, v136
	v_add_f32_e32 v137, 1.0, v137
	v_rcp_f32_e32 v72, v72
	v_rcp_f32_e32 v73, v73
	v_rcp_f32_e32 v136, v136
	v_rcp_f32_e32 v137, v137
	s_mov_b32 s36, 0x3db504f3
	v_pk_mul_f32 v[72:73], v[130:131], v[72:73]
	v_pk_mul_f32 v[130:131], v[132:133], v[136:137]
	s_nop 0
	v_pk_mul_f32 v[138:139], v[130:131], s[36:37] op_sel_hi:[1,0]
	v_pk_mul_f32 v[136:137], v[72:73], s[36:37] op_sel_hi:[1,0]
	s_or_b64 exec, exec, s[4:5]
	v_cvt_pk_bf16_f32 v136, v136, v137
	v_cvt_pk_bf16_f32 v137, v138, v139
	v_or_b32_e32 v138, v170, v203
	v_add_lshl_u32 v72, v148, v138, 1
	s_and_b64 vcc, exec, s[46:47]
	buffer_store_dwordx4 v[134:137], v72, s[28:31], 0 offen sc1
	s_cbranch_vccnz .LBB0_560_sg0
	ds_read_b64 v[134:135], v152 offset:128
	s_waitcnt lgkmcnt(0)
	v_mov_b32_e32 v72, v135
	s_branch .LBB0_561_sg0

.LBB0_561_sg0:
	v_pk_fma_f32 v[128:129], v[190:191], v[134:135], v[128:129] op_sel_hi:[1,0,1]
	v_pk_fma_f32 v[126:127], v[70:71], v[134:135], v[126:127] op_sel_hi:[1,0,1] neg_lo:[1,0,0] neg_hi:[1,0,0]
	v_pk_fma_f32 v[128:129], v[72:73], v[128:129], v[68:69] op_sel_hi:[0,1,1]
	v_pk_fma_f32 v[126:127], v[72:73], v[126:127], v[66:67] op_sel_hi:[0,1,1]
	s_and_saveexec_b64 s[4:5], s[42:43]
	s_xor_b64 s[4:5], exec, s[4:5]
	s_andn2_saveexec_b64 s[4:5], s[4:5]
	v_mul_f32_e32 v73, 0xbfb8aa3b, v126
	v_exp_f32_e32 v73, v73
	v_mul_f32_e32 v130, 0xbfb8aa3b, v127
	v_exp_f32_e32 v130, v130
	v_mul_f32_e32 v132, 0xbfb8aa3b, v129
	v_add_f32_e32 v73, 1.0, v73
	v_exp_f32_e32 v133, v132
	v_add_f32_e32 v131, 1.0, v130
	v_rcp_f32_e32 v130, v73
	v_mul_f32_e32 v73, 0xbfb8aa3b, v128
	v_exp_f32_e32 v73, v73
	v_rcp_f32_e32 v131, v131
	s_mov_b32 s36, 0x3db504f3
	v_add_f32_e32 v73, 1.0, v73
	v_rcp_f32_e32 v132, v73
	v_add_f32_e32 v73, 1.0, v133
	v_rcp_f32_e32 v133, v73
	v_pk_mul_f32 v[126:127], v[126:127], v[130:131]
	v_pk_mul_f32 v[128:129], v[128:129], v[132:133]
	s_nop 0
	v_pk_mul_f32 v[132:133], v[128:129], s[36:37] op_sel_hi:[1,0]
	v_pk_mul_f32 v[130:131], v[126:127], s[36:37] op_sel_hi:[1,0]
	s_or_b64 exec, exec, s[4:5]
	v_mov_b32_e32 v135, v134
	v_mov_b32_e32 v128, v134
	v_mov_b32_e32 v129, v134
	v_mov_b32_e32 v73, v72
	v_pk_fma_f32 v[124:125], v[60:61], v[128:129], v[124:125]
	v_pk_fma_f32 v[122:123], v[58:59], v[134:135], v[122:123] neg_lo:[1,0,0] neg_hi:[1,0,0]
	v_mov_b32_e32 v128, v72
	v_mov_b32_e32 v129, v72
	v_pk_fma_f32 v[122:123], v[72:73], v[122:123], v[54:55]
	v_pk_fma_f32 v[124:125], v[128:129], v[124:125], v[56:57]
	v_cvt_pk_bf16_f32 v126, v130, v131
	v_cvt_pk_bf16_f32 v127, v132, v133
	s_and_saveexec_b64 s[4:5], s[42:43]
	s_xor_b64 s[4:5], exec, s[4:5]
	s_andn2_saveexec_b64 s[4:5], s[4:5]
	v_mul_f32_e32 v128, 0xbfb8aa3b, v122
	v_mul_f32_e32 v129, 0xbfb8aa3b, v123
	v_mul_f32_e32 v130, 0xbfb8aa3b, v124
	v_mul_f32_e32 v131, 0xbfb8aa3b, v125
	v_exp_f32_e32 v128, v128
	v_exp_f32_e32 v129, v129
	v_exp_f32_e32 v130, v130
	v_exp_f32_e32 v131, v131
	v_add_f32_e32 v128, 1.0, v128
	v_add_f32_e32 v129, 1.0, v129
	v_add_f32_e32 v130, 1.0, v130
	v_add_f32_e32 v131, 1.0, v131
	v_rcp_f32_e32 v128, v128
	v_rcp_f32_e32 v129, v129
	v_rcp_f32_e32 v130, v130
	v_rcp_f32_e32 v131, v131
	s_mov_b32 s36, 0x3db504f3
	v_pk_mul_f32 v[122:123], v[122:123], v[128:129]
	v_pk_mul_f32 v[124:125], v[124:125], v[130:131]
	s_nop 0
	v_pk_mul_f32 v[130:131], v[124:125], s[36:37] op_sel_hi:[1,0]
	v_pk_mul_f32 v[128:129], v[122:123], s[36:37] op_sel_hi:[1,0]
	s_or_b64 exec, exec, s[4:5]
	v_add_u32_e32 v132, 0x4000, v148
	v_add_lshl_u32 v122, v132, v146, 1
	v_cvt_pk_bf16_f32 v128, v128, v129
	v_cvt_pk_bf16_f32 v129, v130, v131
	buffer_store_dwordx4 v[126:129], v122, s[28:31], 0 offen sc1
	v_mov_b32_e32 v122, v134
	v_mov_b32_e32 v123, v134
	v_pk_fma_f32 v[120:121], v[44:45], v[122:123], v[120:121]
	v_pk_fma_f32 v[118:119], v[42:43], v[134:135], v[118:119] neg_lo:[1,0,0] neg_hi:[1,0,0]
	v_mov_b32_e32 v122, v72
	v_mov_b32_e32 v123, v72
	v_pk_fma_f32 v[118:119], v[72:73], v[118:119], v[38:39]
	v_pk_fma_f32 v[120:121], v[122:123], v[120:121], v[40:41]
	s_and_saveexec_b64 s[4:5], s[44:45]
	s_xor_b64 s[4:5], exec, s[4:5]
	s_andn2_saveexec_b64 s[4:5], s[4:5]
	v_mul_f32_e32 v122, 0xbfb8aa3b, v118
	v_mul_f32_e32 v123, 0xbfb8aa3b, v119
	v_mul_f32_e32 v124, 0xbfb8aa3b, v120
	v_mul_f32_e32 v125, 0xbfb8aa3b, v121
	v_exp_f32_e32 v122, v122
	v_exp_f32_e32 v123, v123
	v_exp_f32_e32 v124, v124
	v_exp_f32_e32 v125, v125
	v_add_f32_e32 v122, 1.0, v122
	v_add_f32_e32 v123, 1.0, v123
	v_add_f32_e32 v124, 1.0, v124
	v_add_f32_e32 v125, 1.0, v125
	v_rcp_f32_e32 v122, v122
	v_rcp_f32_e32 v123, v123
	v_rcp_f32_e32 v124, v124
	v_rcp_f32_e32 v125, v125
	s_mov_b32 s36, 0x3db504f3
	v_pk_mul_f32 v[118:119], v[118:119], v[122:123]
	v_pk_mul_f32 v[120:121], v[120:121], v[124:125]
	s_nop 0
	v_pk_mul_f32 v[124:125], v[120:121], s[36:37] op_sel_hi:[1,0]
	v_pk_mul_f32 v[122:123], v[118:119], s[36:37] op_sel_hi:[1,0]
	s_or_b64 exec, exec, s[4:5]
	v_mov_b32_e32 v120, v134
	v_mov_b32_e32 v121, v134
	v_pk_fma_f32 v[114:115], v[26:27], v[134:135], v[114:115] neg_lo:[1,0,0] neg_hi:[1,0,0]
	v_pk_fma_f32 v[116:117], v[28:29], v[120:121], v[116:117]
	v_pk_fma_f32 v[114:115], v[72:73], v[114:115], v[22:23]
	v_mov_b32_e32 v73, v72
	v_pk_fma_f32 v[116:117], v[72:73], v[116:117], v[24:25]
	v_cvt_pk_bf16_f32 v118, v122, v123
	v_cvt_pk_bf16_f32 v119, v124, v125
	s_and_saveexec_b64 s[4:5], s[44:45]
	s_xor_b64 s[4:5], exec, s[4:5]
	s_andn2_saveexec_b64 s[4:5], s[4:5]
	v_mul_f32_e32 v72, 0xbfb8aa3b, v114
	v_mul_f32_e32 v73, 0xbfb8aa3b, v115
	v_mul_f32_e32 v120, 0xbfb8aa3b, v116
	v_mul_f32_e32 v121, 0xbfb8aa3b, v117
	v_exp_f32_e32 v72, v72
	v_exp_f32_e32 v73, v73
	v_exp_f32_e32 v120, v120
	v_exp_f32_e32 v121, v121
	v_add_f32_e32 v72, 1.0, v72
	v_add_f32_e32 v73, 1.0, v73
	v_add_f32_e32 v120, 1.0, v120
	v_add_f32_e32 v121, 1.0, v121
	v_rcp_f32_e32 v72, v72
	v_rcp_f32_e32 v73, v73
	v_rcp_f32_e32 v120, v120
	v_rcp_f32_e32 v121, v121
	s_mov_b32 s36, 0x3db504f3
	v_pk_mul_f32 v[72:73], v[114:115], v[72:73]
	v_pk_mul_f32 v[114:115], v[116:117], v[120:121]
	s_nop 0
	v_pk_mul_f32 v[122:123], v[114:115], s[36:37] op_sel_hi:[1,0]
	v_pk_mul_f32 v[120:121], v[72:73], s[36:37] op_sel_hi:[1,0]
	s_or_b64 exec, exec, s[4:5]
	v_add_lshl_u32 v72, v132, v138, 1
	v_cvt_pk_bf16_f32 v120, v120, v121
	v_cvt_pk_bf16_f32 v121, v122, v123
	buffer_store_dwordx4 v[118:121], v72, s[28:31], 0 offen sc1
	s_and_b64 vcc, exec, s[46:47]
	s_nop 0
	v_mov_b32_e32 v121, v206
	s_nop 0
	v_lshl_add_u32 v120, v121, 3, s33
	s_cbranch_vccnz .LBB0_611_sg0
	ds_read_b64 v[118:119], v120
	s_waitcnt lgkmcnt(0)
	v_mov_b32_e32 v72, v119
	s_branch .LBB0_612_sg0

.LBB0_612_sg0:
	v_pk_fma_f32 v[112:113], v[190:191], v[118:119], v[112:113] op_sel_hi:[1,0,1]
	v_pk_fma_f32 v[110:111], v[70:71], v[118:119], v[110:111] op_sel_hi:[1,0,1] neg_lo:[1,0,0] neg_hi:[1,0,0]
	v_pk_fma_f32 v[112:113], v[72:73], v[112:113], v[68:69] op_sel_hi:[0,1,1]
	v_pk_fma_f32 v[110:111], v[72:73], v[110:111], v[66:67] op_sel_hi:[0,1,1]
	s_and_saveexec_b64 s[4:5], s[42:43]
	s_xor_b64 s[4:5], exec, s[4:5]
	s_andn2_saveexec_b64 s[4:5], s[4:5]
	v_mul_f32_e32 v73, 0xbfb8aa3b, v110
	v_exp_f32_e32 v73, v73
	v_mul_f32_e32 v114, 0xbfb8aa3b, v111
	v_exp_f32_e32 v114, v114
	v_mul_f32_e32 v116, 0xbfb8aa3b, v113
	v_add_f32_e32 v73, 1.0, v73
	v_exp_f32_e32 v117, v116
	v_add_f32_e32 v115, 1.0, v114
	v_rcp_f32_e32 v114, v73
	v_mul_f32_e32 v73, 0xbfb8aa3b, v112
	v_exp_f32_e32 v73, v73
	v_rcp_f32_e32 v115, v115
	s_mov_b32 s36, 0x3db504f3
	v_add_f32_e32 v73, 1.0, v73
	v_rcp_f32_e32 v116, v73
	v_add_f32_e32 v73, 1.0, v117
	v_rcp_f32_e32 v117, v73
	v_pk_mul_f32 v[110:111], v[110:111], v[114:115]
	v_pk_mul_f32 v[112:113], v[112:113], v[116:117]
	s_nop 0
	v_pk_mul_f32 v[116:117], v[112:113], s[36:37] op_sel_hi:[1,0]
	v_pk_mul_f32 v[114:115], v[110:111], s[36:37] op_sel_hi:[1,0]
	s_or_b64 exec, exec, s[4:5]
	v_mov_b32_e32 v119, v118
	v_mov_b32_e32 v112, v118
	v_mov_b32_e32 v113, v118
	v_mov_b32_e32 v73, v72
	v_pk_fma_f32 v[108:109], v[60:61], v[112:113], v[108:109]
	v_pk_fma_f32 v[106:107], v[58:59], v[118:119], v[106:107] neg_lo:[1,0,0] neg_hi:[1,0,0]
	v_mov_b32_e32 v112, v72
	v_mov_b32_e32 v113, v72
	v_pk_fma_f32 v[106:107], v[72:73], v[106:107], v[54:55]
	v_pk_fma_f32 v[108:109], v[112:113], v[108:109], v[56:57]
	v_cvt_pk_bf16_f32 v110, v114, v115
	v_cvt_pk_bf16_f32 v111, v116, v117
	s_and_saveexec_b64 s[4:5], s[42:43]
	s_xor_b64 s[4:5], exec, s[4:5]
	s_andn2_saveexec_b64 s[4:5], s[4:5]
	v_mul_f32_e32 v112, 0xbfb8aa3b, v106
	v_mul_f32_e32 v113, 0xbfb8aa3b, v107
	v_mul_f32_e32 v114, 0xbfb8aa3b, v108
	v_mul_f32_e32 v115, 0xbfb8aa3b, v109
	v_exp_f32_e32 v112, v112
	v_exp_f32_e32 v113, v113
	v_exp_f32_e32 v114, v114
	v_exp_f32_e32 v115, v115
	v_add_f32_e32 v112, 1.0, v112
	v_add_f32_e32 v113, 1.0, v113
	v_add_f32_e32 v114, 1.0, v114
	v_add_f32_e32 v115, 1.0, v115
	v_rcp_f32_e32 v112, v112
	v_rcp_f32_e32 v113, v113
	v_rcp_f32_e32 v114, v114
	v_rcp_f32_e32 v115, v115
	s_mov_b32 s36, 0x3db504f3
	v_pk_mul_f32 v[106:107], v[106:107], v[112:113]
	v_pk_mul_f32 v[108:109], v[108:109], v[114:115]
	s_nop 0
	v_pk_mul_f32 v[114:115], v[108:109], s[36:37] op_sel_hi:[1,0]
	v_pk_mul_f32 v[112:113], v[106:107], s[36:37] op_sel_hi:[1,0]
	s_or_b64 exec, exec, s[4:5]
	v_add_lshl_u32 v116, v121, s51, 10
	v_add_lshl_u32 v106, v116, v146, 1
	v_cvt_pk_bf16_f32 v112, v112, v113
	v_cvt_pk_bf16_f32 v113, v114, v115
	buffer_store_dwordx4 v[110:113], v106, s[28:31], 0 offen sc1
	v_mov_b32_e32 v106, v118
	v_mov_b32_e32 v107, v118
	v_pk_fma_f32 v[104:105], v[44:45], v[106:107], v[104:105]
	v_pk_fma_f32 v[102:103], v[42:43], v[118:119], v[102:103] neg_lo:[1,0,0] neg_hi:[1,0,0]
	v_mov_b32_e32 v106, v72
	v_mov_b32_e32 v107, v72
	v_pk_fma_f32 v[102:103], v[72:73], v[102:103], v[38:39]
	v_pk_fma_f32 v[104:105], v[106:107], v[104:105], v[40:41]
	s_and_saveexec_b64 s[4:5], s[44:45]
	s_xor_b64 s[4:5], exec, s[4:5]
	s_andn2_saveexec_b64 s[4:5], s[4:5]
	v_mul_f32_e32 v106, 0xbfb8aa3b, v102
	v_mul_f32_e32 v107, 0xbfb8aa3b, v103
	v_mul_f32_e32 v108, 0xbfb8aa3b, v104
	v_mul_f32_e32 v109, 0xbfb8aa3b, v105
	v_exp_f32_e32 v106, v106
	v_exp_f32_e32 v107, v107
	v_exp_f32_e32 v108, v108
	v_exp_f32_e32 v109, v109
	v_add_f32_e32 v106, 1.0, v106
	v_add_f32_e32 v107, 1.0, v107
	v_add_f32_e32 v108, 1.0, v108
	v_add_f32_e32 v109, 1.0, v109
	v_rcp_f32_e32 v106, v106
	v_rcp_f32_e32 v107, v107
	v_rcp_f32_e32 v108, v108
	v_rcp_f32_e32 v109, v109
	s_mov_b32 s36, 0x3db504f3
	v_pk_mul_f32 v[102:103], v[102:103], v[106:107]
	v_pk_mul_f32 v[104:105], v[104:105], v[108:109]
	s_nop 0
	v_pk_mul_f32 v[108:109], v[104:105], s[36:37] op_sel_hi:[1,0]
	v_pk_mul_f32 v[106:107], v[102:103], s[36:37] op_sel_hi:[1,0]
	s_or_b64 exec, exec, s[4:5]
	v_mov_b32_e32 v104, v118
	v_mov_b32_e32 v105, v118
	v_pk_fma_f32 v[98:99], v[26:27], v[118:119], v[98:99] neg_lo:[1,0,0] neg_hi:[1,0,0]
	v_pk_fma_f32 v[100:101], v[28:29], v[104:105], v[100:101]
	v_pk_fma_f32 v[98:99], v[72:73], v[98:99], v[22:23]
	v_mov_b32_e32 v73, v72
	v_pk_fma_f32 v[100:101], v[72:73], v[100:101], v[24:25]
	v_cvt_pk_bf16_f32 v102, v106, v107
	v_cvt_pk_bf16_f32 v103, v108, v109
	s_and_saveexec_b64 s[4:5], s[44:45]
	s_xor_b64 s[4:5], exec, s[4:5]
	s_andn2_saveexec_b64 s[4:5], s[4:5]
	v_mul_f32_e32 v72, 0xbfb8aa3b, v98
	v_mul_f32_e32 v73, 0xbfb8aa3b, v99
	v_mul_f32_e32 v104, 0xbfb8aa3b, v100
	v_mul_f32_e32 v105, 0xbfb8aa3b, v101
	v_exp_f32_e32 v72, v72
	v_exp_f32_e32 v73, v73
	v_exp_f32_e32 v104, v104
	v_exp_f32_e32 v105, v105
	v_add_f32_e32 v72, 1.0, v72
	v_add_f32_e32 v73, 1.0, v73
	v_add_f32_e32 v104, 1.0, v104
	v_add_f32_e32 v105, 1.0, v105
	v_rcp_f32_e32 v72, v72
	v_rcp_f32_e32 v73, v73
	v_rcp_f32_e32 v104, v104
	v_rcp_f32_e32 v105, v105
	s_mov_b32 s36, 0x3db504f3
	v_pk_mul_f32 v[72:73], v[98:99], v[72:73]
	v_pk_mul_f32 v[98:99], v[100:101], v[104:105]
	s_nop 0
	v_pk_mul_f32 v[106:107], v[98:99], s[36:37] op_sel_hi:[1,0]
	v_pk_mul_f32 v[104:105], v[72:73], s[36:37] op_sel_hi:[1,0]
	s_or_b64 exec, exec, s[4:5]
	v_add_lshl_u32 v72, v116, v138, 1
	s_and_b64 vcc, exec, s[46:47]
	v_cvt_pk_bf16_f32 v104, v104, v105
	v_cvt_pk_bf16_f32 v105, v106, v107
	buffer_store_dwordx4 v[102:105], v72, s[28:31], 0 offen sc1
	s_cbranch_vccnz .LBB0_662_sg0
	ds_read_b64 v[102:103], v120 offset:128
	s_waitcnt lgkmcnt(0)
	v_mov_b32_e32 v72, v103
	s_branch .LBB0_663_sg0

.LBB0_663_sg0:
	v_pk_fma_f32 v[96:97], v[190:191], v[102:103], v[96:97] op_sel_hi:[1,0,1]
	v_pk_fma_f32 v[94:95], v[70:71], v[102:103], v[94:95] op_sel_hi:[1,0,1] neg_lo:[1,0,0] neg_hi:[1,0,0]
	v_pk_fma_f32 v[96:97], v[72:73], v[96:97], v[68:69] op_sel_hi:[0,1,1]
	v_pk_fma_f32 v[94:95], v[72:73], v[94:95], v[66:67] op_sel_hi:[0,1,1]
	s_and_saveexec_b64 s[4:5], s[42:43]
	s_xor_b64 s[4:5], exec, s[4:5]
	s_andn2_saveexec_b64 s[4:5], s[4:5]
	v_mul_f32_e32 v73, 0xbfb8aa3b, v94
	v_exp_f32_e32 v73, v73
	v_mul_f32_e32 v98, 0xbfb8aa3b, v95
	v_exp_f32_e32 v98, v98
	v_mul_f32_e32 v100, 0xbfb8aa3b, v97
	v_add_f32_e32 v73, 1.0, v73
	v_exp_f32_e32 v101, v100
	v_add_f32_e32 v99, 1.0, v98
	v_rcp_f32_e32 v98, v73
	v_mul_f32_e32 v73, 0xbfb8aa3b, v96
	v_exp_f32_e32 v73, v73
	v_rcp_f32_e32 v99, v99
	s_mov_b32 s36, 0x3db504f3
	v_add_f32_e32 v73, 1.0, v73
	v_rcp_f32_e32 v100, v73
	v_add_f32_e32 v73, 1.0, v101
	v_rcp_f32_e32 v101, v73
	v_pk_mul_f32 v[94:95], v[94:95], v[98:99]
	v_pk_mul_f32 v[96:97], v[96:97], v[100:101]
	s_nop 0
	v_pk_mul_f32 v[100:101], v[96:97], s[36:37] op_sel_hi:[1,0]
	v_pk_mul_f32 v[98:99], v[94:95], s[36:37] op_sel_hi:[1,0]
	s_or_b64 exec, exec, s[4:5]
	v_mov_b32_e32 v103, v102
	v_mov_b32_e32 v96, v102
	v_mov_b32_e32 v97, v102
	v_mov_b32_e32 v73, v72
	v_pk_fma_f32 v[92:93], v[60:61], v[96:97], v[92:93]
	v_pk_fma_f32 v[90:91], v[58:59], v[102:103], v[90:91] neg_lo:[1,0,0] neg_hi:[1,0,0]
	v_mov_b32_e32 v96, v72
	v_mov_b32_e32 v97, v72
	v_pk_fma_f32 v[90:91], v[72:73], v[90:91], v[54:55]
	v_pk_fma_f32 v[92:93], v[96:97], v[92:93], v[56:57]
	v_cvt_pk_bf16_f32 v94, v98, v99
	v_cvt_pk_bf16_f32 v95, v100, v101
	s_and_saveexec_b64 s[4:5], s[42:43]
	s_xor_b64 s[4:5], exec, s[4:5]
	s_andn2_saveexec_b64 s[4:5], s[4:5]
	v_mul_f32_e32 v96, 0xbfb8aa3b, v90
	v_mul_f32_e32 v97, 0xbfb8aa3b, v91
	v_mul_f32_e32 v98, 0xbfb8aa3b, v92
	v_mul_f32_e32 v99, 0xbfb8aa3b, v93
	v_exp_f32_e32 v96, v96
	v_exp_f32_e32 v97, v97
	v_exp_f32_e32 v98, v98
	v_exp_f32_e32 v99, v99
	v_add_f32_e32 v96, 1.0, v96
	v_add_f32_e32 v97, 1.0, v97
	v_add_f32_e32 v98, 1.0, v98
	v_add_f32_e32 v99, 1.0, v99
	v_rcp_f32_e32 v96, v96
	v_rcp_f32_e32 v97, v97
	v_rcp_f32_e32 v98, v98
	v_rcp_f32_e32 v99, v99
	s_mov_b32 s36, 0x3db504f3
	v_pk_mul_f32 v[90:91], v[90:91], v[96:97]
	v_pk_mul_f32 v[92:93], v[92:93], v[98:99]
	s_nop 0
	v_pk_mul_f32 v[98:99], v[92:93], s[36:37] op_sel_hi:[1,0]
	v_pk_mul_f32 v[96:97], v[90:91], s[36:37] op_sel_hi:[1,0]
	s_or_b64 exec, exec, s[4:5]
	v_add_u32_e32 v100, 0x4000, v116
	v_add_lshl_u32 v90, v100, v146, 1
	v_cvt_pk_bf16_f32 v96, v96, v97
	v_cvt_pk_bf16_f32 v97, v98, v99
	buffer_store_dwordx4 v[94:97], v90, s[28:31], 0 offen sc1
	v_mov_b32_e32 v90, v102
	v_mov_b32_e32 v91, v102
	v_pk_fma_f32 v[88:89], v[44:45], v[90:91], v[88:89]
	v_pk_fma_f32 v[86:87], v[42:43], v[102:103], v[86:87] neg_lo:[1,0,0] neg_hi:[1,0,0]
	v_mov_b32_e32 v90, v72
	v_mov_b32_e32 v91, v72
	v_pk_fma_f32 v[86:87], v[72:73], v[86:87], v[38:39]
	v_pk_fma_f32 v[88:89], v[90:91], v[88:89], v[40:41]
	s_and_saveexec_b64 s[4:5], s[44:45]
	s_xor_b64 s[4:5], exec, s[4:5]
	s_andn2_saveexec_b64 s[4:5], s[4:5]
	v_mul_f32_e32 v90, 0xbfb8aa3b, v86
	v_mul_f32_e32 v91, 0xbfb8aa3b, v87
	v_mul_f32_e32 v92, 0xbfb8aa3b, v88
	v_mul_f32_e32 v93, 0xbfb8aa3b, v89
	v_exp_f32_e32 v90, v90
	v_exp_f32_e32 v91, v91
	v_exp_f32_e32 v92, v92
	v_exp_f32_e32 v93, v93
	v_add_f32_e32 v90, 1.0, v90
	v_add_f32_e32 v91, 1.0, v91
	v_add_f32_e32 v92, 1.0, v92
	v_add_f32_e32 v93, 1.0, v93
	v_rcp_f32_e32 v90, v90
	v_rcp_f32_e32 v91, v91
	v_rcp_f32_e32 v92, v92
	v_rcp_f32_e32 v93, v93
	s_mov_b32 s36, 0x3db504f3
	v_pk_mul_f32 v[86:87], v[86:87], v[90:91]
	v_pk_mul_f32 v[88:89], v[88:89], v[92:93]
	s_nop 0
	v_pk_mul_f32 v[92:93], v[88:89], s[36:37] op_sel_hi:[1,0]
	v_pk_mul_f32 v[90:91], v[86:87], s[36:37] op_sel_hi:[1,0]
	s_or_b64 exec, exec, s[4:5]
	v_mov_b32_e32 v88, v102
	v_mov_b32_e32 v89, v102
	v_pk_fma_f32 v[82:83], v[26:27], v[102:103], v[82:83] neg_lo:[1,0,0] neg_hi:[1,0,0]
	v_pk_fma_f32 v[84:85], v[28:29], v[88:89], v[84:85]
	v_pk_fma_f32 v[82:83], v[72:73], v[82:83], v[22:23]
	v_mov_b32_e32 v73, v72
	v_pk_fma_f32 v[84:85], v[72:73], v[84:85], v[24:25]
	v_cvt_pk_bf16_f32 v86, v90, v91
	v_cvt_pk_bf16_f32 v87, v92, v93
	s_and_saveexec_b64 s[4:5], s[44:45]
	s_xor_b64 s[4:5], exec, s[4:5]
	s_andn2_saveexec_b64 s[4:5], s[4:5]
	v_mul_f32_e32 v72, 0xbfb8aa3b, v82
	v_mul_f32_e32 v73, 0xbfb8aa3b, v83
	v_mul_f32_e32 v88, 0xbfb8aa3b, v84
	v_mul_f32_e32 v89, 0xbfb8aa3b, v85
	v_exp_f32_e32 v72, v72
	v_exp_f32_e32 v73, v73
	v_exp_f32_e32 v88, v88
	v_exp_f32_e32 v89, v89
	v_add_f32_e32 v72, 1.0, v72
	v_add_f32_e32 v73, 1.0, v73
	v_add_f32_e32 v88, 1.0, v88
	v_add_f32_e32 v89, 1.0, v89
	v_rcp_f32_e32 v72, v72
	v_rcp_f32_e32 v73, v73
	v_rcp_f32_e32 v88, v88
	v_rcp_f32_e32 v89, v89
	s_mov_b32 s36, 0x3db504f3
	v_pk_mul_f32 v[72:73], v[82:83], v[72:73]
	v_pk_mul_f32 v[82:83], v[84:85], v[88:89]
	s_nop 0
	v_pk_mul_f32 v[90:91], v[82:83], s[36:37] op_sel_hi:[1,0]
	v_pk_mul_f32 v[88:89], v[72:73], s[36:37] op_sel_hi:[1,0]
	s_or_b64 exec, exec, s[4:5]
	v_add_lshl_u32 v72, v100, v138, 1
	v_cvt_pk_bf16_f32 v88, v88, v89
	v_cvt_pk_bf16_f32 v89, v90, v91
	buffer_store_dwordx4 v[86:89], v72, s[28:31], 0 offen sc1
	v_mov_b32_e32 v91, v207
	s_and_b64 vcc, exec, s[46:47]
	v_lshl_add_u32 v90, v91, 3, s33
	s_cbranch_vccnz .LBB0_713_sg0
	ds_read_b64 v[88:89], v90
	s_waitcnt lgkmcnt(0)
	v_mov_b32_e32 v86, v89
	s_branch .LBB0_714_sg0

.LBB0_714_sg0:
	v_pk_fma_f32 v[72:73], v[190:191], v[88:89], v[80:81] op_sel_hi:[1,0,1]
	v_pk_fma_f32 v[78:79], v[70:71], v[88:89], v[78:79] op_sel_hi:[1,0,1] neg_lo:[1,0,0] neg_hi:[1,0,0]
	v_pk_fma_f32 v[80:81], v[86:87], v[72:73], v[68:69] op_sel_hi:[0,1,1]
	v_pk_fma_f32 v[78:79], v[86:87], v[78:79], v[66:67] op_sel_hi:[0,1,1]
	s_and_saveexec_b64 s[4:5], s[42:43]
	s_xor_b64 s[4:5], exec, s[4:5]
	s_andn2_saveexec_b64 s[4:5], s[4:5]
	v_mul_f32_e32 v72, 0xbfb8aa3b, v78
	v_mul_f32_e32 v73, 0xbfb8aa3b, v79
	v_mul_f32_e32 v82, 0xbfb8aa3b, v80
	v_mul_f32_e32 v83, 0xbfb8aa3b, v81
	v_exp_f32_e32 v72, v72
	v_exp_f32_e32 v73, v73
	v_exp_f32_e32 v82, v82
	v_exp_f32_e32 v83, v83
	v_add_f32_e32 v72, 1.0, v72
	v_add_f32_e32 v73, 1.0, v73
	v_add_f32_e32 v82, 1.0, v82
	v_add_f32_e32 v83, 1.0, v83
	v_rcp_f32_e32 v72, v72
	v_rcp_f32_e32 v73, v73
	v_rcp_f32_e32 v82, v82
	v_rcp_f32_e32 v83, v83
	s_mov_b32 s36, 0x3db504f3
	v_pk_mul_f32 v[72:73], v[78:79], v[72:73]
	v_pk_mul_f32 v[78:79], v[80:81], v[82:83]
	s_nop 0
	v_pk_mul_f32 v[84:85], v[78:79], s[36:37] op_sel_hi:[1,0]
	v_pk_mul_f32 v[82:83], v[72:73], s[36:37] op_sel_hi:[1,0]
	s_or_b64 exec, exec, s[4:5]
	v_mov_b32_e32 v89, v88
	v_mov_b32_e32 v78, v88
	v_mov_b32_e32 v79, v88
	v_mov_b32_e32 v87, v86
	v_pk_fma_f32 v[76:77], v[60:61], v[78:79], v[76:77]
	v_pk_fma_f32 v[74:75], v[58:59], v[88:89], v[74:75] neg_lo:[1,0,0] neg_hi:[1,0,0]
	v_mov_b32_e32 v78, v86
	v_mov_b32_e32 v79, v86
	v_pk_fma_f32 v[74:75], v[86:87], v[74:75], v[54:55]
	v_pk_fma_f32 v[76:77], v[78:79], v[76:77], v[56:57]
	v_cvt_pk_bf16_f32 v72, v82, v83
	v_cvt_pk_bf16_f32 v73, v84, v85
	s_and_saveexec_b64 s[4:5], s[42:43]
	s_xor_b64 s[4:5], exec, s[4:5]
	s_andn2_saveexec_b64 s[4:5], s[4:5]
	v_mul_f32_e32 v78, 0xbfb8aa3b, v74
	v_mul_f32_e32 v79, 0xbfb8aa3b, v75
	v_mul_f32_e32 v80, 0xbfb8aa3b, v76
	v_mul_f32_e32 v81, 0xbfb8aa3b, v77
	v_exp_f32_e32 v78, v78
	v_exp_f32_e32 v79, v79
	v_exp_f32_e32 v80, v80
	v_exp_f32_e32 v81, v81
	v_add_f32_e32 v78, 1.0, v78
	v_add_f32_e32 v79, 1.0, v79
	v_add_f32_e32 v80, 1.0, v80
	v_add_f32_e32 v81, 1.0, v81
	v_rcp_f32_e32 v78, v78
	v_rcp_f32_e32 v79, v79
	v_rcp_f32_e32 v80, v80
	v_rcp_f32_e32 v81, v81
	s_mov_b32 s36, 0x3db504f3
	v_pk_mul_f32 v[74:75], v[74:75], v[78:79]
	v_pk_mul_f32 v[76:77], v[76:77], v[80:81]
	s_nop 0
	v_pk_mul_f32 v[80:81], v[76:77], s[36:37] op_sel_hi:[1,0]
	v_pk_mul_f32 v[78:79], v[74:75], s[36:37] op_sel_hi:[1,0]
	s_or_b64 exec, exec, s[4:5]
	v_add_lshl_u32 v76, v91, s51, 10
	v_add_lshl_u32 v77, v76, v146, 1
	v_cvt_pk_bf16_f32 v74, v78, v79
	v_cvt_pk_bf16_f32 v75, v80, v81
	buffer_store_dwordx4 v[72:75], v77, s[28:31], 0 offen sc1
	v_pk_fma_f32 v[50:51], v[42:43], v[88:89], v[50:51] neg_lo:[1,0,0] neg_hi:[1,0,0]
	s_nop 0
	v_mov_b32_e32 v72, v88
	v_mov_b32_e32 v73, v88
	v_pk_fma_f32 v[52:53], v[44:45], v[72:73], v[52:53]
	v_mov_b32_e32 v72, v86
	v_mov_b32_e32 v73, v86
	v_pk_fma_f32 v[50:51], v[86:87], v[50:51], v[38:39]
	v_pk_fma_f32 v[52:53], v[72:73], v[52:53], v[40:41]
	s_and_saveexec_b64 s[4:5], s[44:45]
	s_xor_b64 s[4:5], exec, s[4:5]
	s_andn2_saveexec_b64 s[4:5], s[4:5]
	v_mul_f32_e32 v72, 0xbfb8aa3b, v50
	v_mul_f32_e32 v73, 0xbfb8aa3b, v51
	v_mul_f32_e32 v74, 0xbfb8aa3b, v52
	v_mul_f32_e32 v75, 0xbfb8aa3b, v53
	v_exp_f32_e32 v72, v72
	v_exp_f32_e32 v73, v73
	v_exp_f32_e32 v74, v74
	v_exp_f32_e32 v75, v75
	v_add_f32_e32 v72, 1.0, v72
	v_add_f32_e32 v73, 1.0, v73
	v_add_f32_e32 v74, 1.0, v74
	v_add_f32_e32 v75, 1.0, v75
	v_rcp_f32_e32 v72, v72
	v_rcp_f32_e32 v73, v73
	v_rcp_f32_e32 v74, v74
	v_rcp_f32_e32 v75, v75
	s_mov_b32 s36, 0x3db504f3
	v_pk_mul_f32 v[50:51], v[50:51], v[72:73]
	v_pk_mul_f32 v[52:53], v[52:53], v[74:75]
	s_nop 0
	v_pk_mul_f32 v[74:75], v[52:53], s[36:37] op_sel_hi:[1,0]
	v_pk_mul_f32 v[72:73], v[50:51], s[36:37] op_sel_hi:[1,0]
	s_or_b64 exec, exec, s[4:5]
	v_mov_b32_e32 v52, v88
	v_mov_b32_e32 v53, v88
	v_pk_fma_f32 v[34:35], v[26:27], v[88:89], v[34:35] neg_lo:[1,0,0] neg_hi:[1,0,0]
	v_pk_fma_f32 v[36:37], v[28:29], v[52:53], v[36:37]
	v_pk_fma_f32 v[34:35], v[86:87], v[34:35], v[22:23]
	v_mov_b32_e32 v87, v86
	v_pk_fma_f32 v[36:37], v[86:87], v[36:37], v[24:25]
	v_cvt_pk_bf16_f32 v50, v72, v73
	v_cvt_pk_bf16_f32 v51, v74, v75
	s_and_saveexec_b64 s[4:5], s[44:45]
	s_xor_b64 s[4:5], exec, s[4:5]
	s_andn2_saveexec_b64 s[4:5], s[4:5]
	v_mul_f32_e32 v52, 0xbfb8aa3b, v34
	v_mul_f32_e32 v53, 0xbfb8aa3b, v35
	v_mul_f32_e32 v72, 0xbfb8aa3b, v36
	v_mul_f32_e32 v73, 0xbfb8aa3b, v37
	v_exp_f32_e32 v52, v52
	v_exp_f32_e32 v53, v53
	v_exp_f32_e32 v72, v72
	v_exp_f32_e32 v73, v73
	v_add_f32_e32 v52, 1.0, v52
	v_add_f32_e32 v53, 1.0, v53
	v_add_f32_e32 v72, 1.0, v72
	v_add_f32_e32 v73, 1.0, v73
	v_rcp_f32_e32 v52, v52
	v_rcp_f32_e32 v53, v53
	v_rcp_f32_e32 v72, v72
	v_rcp_f32_e32 v73, v73
	s_mov_b32 s36, 0x3db504f3
	v_pk_mul_f32 v[34:35], v[34:35], v[52:53]
	v_pk_mul_f32 v[36:37], v[36:37], v[72:73]
	s_nop 0
	v_pk_mul_f32 v[74:75], v[36:37], s[36:37] op_sel_hi:[1,0]
	v_pk_mul_f32 v[72:73], v[34:35], s[36:37] op_sel_hi:[1,0]
	s_or_b64 exec, exec, s[4:5]
	v_add_lshl_u32 v34, v76, v138, 1
	s_and_b64 vcc, exec, s[46:47]
	v_cvt_pk_bf16_f32 v52, v72, v73
	v_cvt_pk_bf16_f32 v53, v74, v75
	buffer_store_dwordx4 v[50:53], v34, s[28:31], 0 offen sc1
	s_cbranch_vccnz .LBB0_764_sg0
	ds_read_b64 v[52:53], v90 offset:128
	s_waitcnt lgkmcnt(0)
	v_mov_b32_e32 v50, v53
	s_branch .LBB0_765_sg0

.LBB0_765_sg0:
	v_pk_fma_f32 v[20:21], v[190:191], v[52:53], v[20:21] op_sel_hi:[1,0,1]
	v_pk_fma_f32 v[18:19], v[70:71], v[52:53], v[18:19] op_sel_hi:[1,0,1] neg_lo:[1,0,0] neg_hi:[1,0,0]
	v_pk_fma_f32 v[20:21], v[50:51], v[20:21], v[68:69] op_sel_hi:[0,1,1]
	v_pk_fma_f32 v[18:19], v[50:51], v[18:19], v[66:67] op_sel_hi:[0,1,1]
	s_and_saveexec_b64 s[4:5], s[42:43]
	s_xor_b64 s[4:5], exec, s[4:5]
	s_andn2_saveexec_b64 s[4:5], s[4:5]
	v_mul_f32_e32 v34, 0xbfb8aa3b, v18
	v_mul_f32_e32 v35, 0xbfb8aa3b, v19
	v_mul_f32_e32 v36, 0xbfb8aa3b, v20
	v_mul_f32_e32 v37, 0xbfb8aa3b, v21
	v_exp_f32_e32 v34, v34
	v_exp_f32_e32 v35, v35
	v_exp_f32_e32 v36, v36
	v_exp_f32_e32 v37, v37
	v_add_f32_e32 v34, 1.0, v34
	v_add_f32_e32 v35, 1.0, v35
	v_add_f32_e32 v36, 1.0, v36
	v_add_f32_e32 v37, 1.0, v37
	v_rcp_f32_e32 v34, v34
	v_rcp_f32_e32 v35, v35
	v_rcp_f32_e32 v36, v36
	v_rcp_f32_e32 v37, v37
	s_mov_b32 s36, 0x3db504f3
	v_pk_mul_f32 v[18:19], v[18:19], v[34:35]
	v_pk_mul_f32 v[20:21], v[20:21], v[36:37]
	s_nop 0
	v_pk_mul_f32 v[36:37], v[20:21], s[36:37] op_sel_hi:[1,0]
	v_pk_mul_f32 v[34:35], v[18:19], s[36:37] op_sel_hi:[1,0]
	s_or_b64 exec, exec, s[4:5]
	v_mov_b32_e32 v53, v52
	v_mov_b32_e32 v20, v52
	v_mov_b32_e32 v21, v52
	v_mov_b32_e32 v51, v50
	v_pk_fma_f32 v[12:13], v[60:61], v[20:21], v[12:13]
	v_pk_fma_f32 v[10:11], v[58:59], v[52:53], v[10:11] neg_lo:[1,0,0] neg_hi:[1,0,0]
	v_mov_b32_e32 v20, v50
	v_mov_b32_e32 v21, v50
	v_pk_fma_f32 v[10:11], v[50:51], v[10:11], v[54:55]
	v_pk_fma_f32 v[12:13], v[20:21], v[12:13], v[56:57]
	v_cvt_pk_bf16_f32 v18, v34, v35
	v_cvt_pk_bf16_f32 v19, v36, v37
	s_and_saveexec_b64 s[4:5], s[42:43]
	s_xor_b64 s[4:5], exec, s[4:5]
	s_andn2_saveexec_b64 s[4:5], s[4:5]
	v_mul_f32_e32 v20, 0xbfb8aa3b, v10
	v_mul_f32_e32 v21, 0xbfb8aa3b, v11
	v_mul_f32_e32 v34, 0xbfb8aa3b, v12
	v_mul_f32_e32 v35, 0xbfb8aa3b, v13
	v_exp_f32_e32 v20, v20
	v_exp_f32_e32 v21, v21
	v_exp_f32_e32 v34, v34
	v_exp_f32_e32 v35, v35
	v_add_f32_e32 v20, 1.0, v20
	v_add_f32_e32 v21, 1.0, v21
	v_add_f32_e32 v34, 1.0, v34
	v_add_f32_e32 v35, 1.0, v35
	v_rcp_f32_e32 v20, v20
	v_rcp_f32_e32 v21, v21
	v_rcp_f32_e32 v34, v34
	v_rcp_f32_e32 v35, v35
	s_mov_b32 s36, 0x3db504f3
	v_pk_mul_f32 v[10:11], v[10:11], v[20:21]
	v_pk_mul_f32 v[12:13], v[12:13], v[34:35]
	s_nop 0
	v_pk_mul_f32 v[36:37], v[12:13], s[36:37] op_sel_hi:[1,0]
	v_pk_mul_f32 v[34:35], v[10:11], s[36:37] op_sel_hi:[1,0]
	s_or_b64 exec, exec, s[4:5]
	v_add_u32_e32 v46, 0x4000, v76
	v_add_lshl_u32 v10, v46, v146, 1
	v_cvt_pk_bf16_f32 v20, v34, v35
	v_cvt_pk_bf16_f32 v21, v36, v37
	buffer_store_dwordx4 v[18:21], v10, s[28:31], 0 offen sc1
	v_mov_b32_e32 v10, v52
	v_mov_b32_e32 v11, v52
	v_pk_fma_f32 v[8:9], v[44:45], v[10:11], v[8:9]
	v_pk_fma_f32 v[6:7], v[42:43], v[52:53], v[6:7] neg_lo:[1,0,0] neg_hi:[1,0,0]
	v_mov_b32_e32 v10, v50
	v_mov_b32_e32 v11, v50
	v_pk_fma_f32 v[6:7], v[50:51], v[6:7], v[38:39]
	v_pk_fma_f32 v[8:9], v[10:11], v[8:9], v[40:41]
	s_and_saveexec_b64 s[4:5], s[44:45]
	s_xor_b64 s[4:5], exec, s[4:5]
	s_andn2_saveexec_b64 s[4:5], s[4:5]
	v_mul_f32_e32 v10, 0xbfb8aa3b, v6
	v_mul_f32_e32 v11, 0xbfb8aa3b, v7
	v_mul_f32_e32 v12, 0xbfb8aa3b, v8
	v_mul_f32_e32 v13, 0xbfb8aa3b, v9
	v_exp_f32_e32 v10, v10
	v_exp_f32_e32 v11, v11
	v_exp_f32_e32 v12, v12
	v_exp_f32_e32 v13, v13
	v_add_f32_e32 v10, 1.0, v10
	v_add_f32_e32 v11, 1.0, v11
	v_add_f32_e32 v12, 1.0, v12
	v_add_f32_e32 v13, 1.0, v13
	v_rcp_f32_e32 v10, v10
	v_rcp_f32_e32 v11, v11
	v_rcp_f32_e32 v12, v12
	v_rcp_f32_e32 v13, v13
	s_mov_b32 s36, 0x3db504f3
	v_pk_mul_f32 v[6:7], v[6:7], v[10:11]
	v_pk_mul_f32 v[8:9], v[8:9], v[12:13]
	s_nop 0
	v_pk_mul_f32 v[12:13], v[8:9], s[36:37] op_sel_hi:[1,0]
	v_pk_mul_f32 v[10:11], v[6:7], s[36:37] op_sel_hi:[1,0]
	s_or_b64 exec, exec, s[4:5]
	v_mov_b32_e32 v8, v52
	v_mov_b32_e32 v9, v52
	v_pk_fma_f32 v[2:3], v[26:27], v[52:53], v[2:3] neg_lo:[1,0,0] neg_hi:[1,0,0]
	v_pk_fma_f32 v[4:5], v[28:29], v[8:9], v[4:5]
	v_pk_fma_f32 v[2:3], v[50:51], v[2:3], v[22:23]
	v_mov_b32_e32 v51, v50
	v_pk_fma_f32 v[4:5], v[50:51], v[4:5], v[24:25]
	v_cvt_pk_bf16_f32 v6, v10, v11
	v_cvt_pk_bf16_f32 v7, v12, v13
	s_and_saveexec_b64 s[4:5], s[44:45]
	s_xor_b64 s[4:5], exec, s[4:5]
	s_andn2_saveexec_b64 s[4:5], s[4:5]
	v_mul_f32_e32 v8, 0xbfb8aa3b, v2
	v_mul_f32_e32 v9, 0xbfb8aa3b, v3
	v_mul_f32_e32 v10, 0xbfb8aa3b, v4
	v_mul_f32_e32 v11, 0xbfb8aa3b, v5
	v_exp_f32_e32 v8, v8
	v_exp_f32_e32 v9, v9
	v_exp_f32_e32 v10, v10
	v_exp_f32_e32 v11, v11
	v_add_f32_e32 v8, 1.0, v8
	v_add_f32_e32 v9, 1.0, v9
	v_add_f32_e32 v10, 1.0, v10
	v_add_f32_e32 v11, 1.0, v11
	v_rcp_f32_e32 v8, v8
	v_rcp_f32_e32 v9, v9
	v_rcp_f32_e32 v10, v10
	v_rcp_f32_e32 v11, v11
	s_mov_b32 s36, 0x3db504f3
	v_pk_mul_f32 v[2:3], v[2:3], v[8:9]
	v_pk_mul_f32 v[4:5], v[4:5], v[10:11]
	s_nop 0
	v_pk_mul_f32 v[10:11], v[4:5], s[36:37] op_sel_hi:[1,0]
	v_pk_mul_f32 v[8:9], v[2:3], s[36:37] op_sel_hi:[1,0]
	s_branch .LBB0_394
.Lepi0_seg1:
	v_lshl_or_b32 v202, s27, 8, v208
	s_and_b32 s4, s27, -4
	v_ashrrev_i32_e32 v203, 31, v202
	v_lshlrev_b64 v[14:15], 2, v[202:203]
	v_lshl_add_u64 v[16:17], s[10:11], 0, v[14:15]
	v_lshl_add_u64 v[22:23], s[12:13], 0, v[14:15]
	flat_load_dwordx4 v[70:73], v[16:17]
	flat_load_dwordx4 v[66:69], v[22:23]
	s_cmp_eq_u32 s4, 4
	s_cselect_b64 s[36:37], -1, 0
	s_cmp_lg_u32 s4, 4
	v_mov_b32_e32 v46, 0
	v_and_b32_e32 v210, 0x3ff, v202
	v_mov_b32_e32 v62, 0
	v_mov_b32_e32 v63, 0
	v_mov_b32_e32 v64, 0
	v_mov_b32_e32 v65, 0
	v_lshlrev_b32_e32 v14, 2, v210
	v_mov_b32_e32 v15, v0
	v_lshl_add_u64 v[14:15], s[14:15], 0, v[14:15]
	flat_load_dwordx4 v[62:65], v[14:15]
	flat_load_dwordx4 v[58:61], v[16:17] offset:16
	flat_load_dwordx4 v[54:57], v[22:23] offset:16
	v_cndmask_b32_e64 v14, 0, 1, s[36:37]
	v_cmp_ne_u32_e64 s[4:5], 1, v14
	s_andn2_b64 vcc, exec, s[36:37]
	v_mov_b32_e32 v47, 0
	v_mov_b32_e32 v48, 0
	v_mov_b32_e32 v49, 0
	v_add_u32_e32 v14, 4, v202
	v_and_b32_e32 v14, 0x3ff, v14
	v_lshlrev_b32_e32 v14, 2, v14
	v_mov_b32_e32 v15, v0
	v_lshl_add_u64 v[14:15], s[14:15], 0, v[14:15]
	flat_load_dwordx4 v[46:49], v[14:15]
	flat_load_dwordx4 v[42:45], v[16:17] offset:512
	flat_load_dwordx4 v[38:41], v[22:23] offset:512
	v_add_u32_e32 v212, 0x80, v202
	v_mov_b32_e32 v14, 0
	s_and_b64 vcc, exec, s[4:5]
	v_and_b32_e32 v203, 0x3ff, v212
	v_mov_b32_e32 v30, 0
	v_mov_b32_e32 v31, 0
	v_mov_b32_e32 v32, 0
	v_mov_b32_e32 v33, 0
	v_lshlrev_b32_e32 v24, 2, v203
	v_mov_b32_e32 v25, v0
	v_lshl_add_u64 v[24:25], s[14:15], 0, v[24:25]
	flat_load_dwordx4 v[30:33], v[24:25]
	flat_load_dwordx4 v[26:29], v[16:17] offset:528
	s_nop 0
	flat_load_dwordx4 v[22:25], v[22:23] offset:528
	s_and_b64 vcc, exec, s[4:5]
	v_mov_b32_e32 v15, 0
	v_mov_b32_e32 v16, 0
	v_mov_b32_e32 v17, 0
	v_add_u32_e32 v14, 0x84, v202
	v_and_b32_e32 v14, 0x3ff, v14
	v_lshlrev_b32_e32 v14, 2, v14
	v_mov_b32_e32 v15, v0
	v_lshl_add_u64 v[14:15], s[14:15], 0, v[14:15]
	flat_load_dwordx4 v[14:17], v[14:15]
	v_mov_b32_e32 v214, v1
	v_cndmask_b32_e64 v178, 0, 1, s[6:7]
	v_cmp_ne_u32_e64 s[46:47], 1, v178
	s_andn2_b64 vcc, exec, s[6:7]
	v_lshl_add_u32 v211, v214, 3, s33
	s_cbranch_vccnz .LBB0_407_sg1
	s_waitcnt vmcnt(0)
	ds_read_b64 v[200:201], v211
	s_waitcnt lgkmcnt(0)
	v_mov_b32_e32 v192, v201
	s_branch .LBB0_408_sg1

.LBB0_408_sg1:
	s_waitcnt vmcnt(0) lgkmcnt(0)
	v_xor_b32_e32 v191, 0x80000000, v73
	v_xor_b32_e32 v190, 0x80000000, v72
	v_pk_fma_f32 v[72:73], v[190:191], v[200:201], v[176:177] op_sel_hi:[1,0,1]
	v_pk_fma_f32 v[174:175], v[70:71], v[200:201], v[174:175] op_sel_hi:[1,0,1] neg_lo:[1,0,0] neg_hi:[1,0,0]
	s_movk_i32 s4, 0x3ff
	v_pk_fma_f32 v[174:175], v[192:193], v[174:175], v[66:67] op_sel_hi:[0,1,1]
	v_pk_fma_f32 v[176:177], v[192:193], v[72:73], v[68:69] op_sel_hi:[0,1,1]
	v_cmp_lt_u32_e64 s[42:43], s4, v202
	s_and_saveexec_b64 s[4:5], s[42:43]
	s_xor_b64 s[4:5], exec, s[4:5]
	v_ashrrev_i32_e32 v72, 10, v202
	v_cmp_lt_i32_e32 vcc, 1, v72
	s_mov_b64 s[36:37], 0
	s_mov_b64 s[44:45], 0
	s_and_saveexec_b64 s[54:55], vcc
	s_xor_b64 s[54:55], exec, s[54:55]
	v_cmp_ne_u32_e32 vcc, 2, v72
	s_and_b64 s[44:45], vcc, exec
	s_andn2_saveexec_b64 s[54:55], s[54:55]
	v_cmp_ne_u32_e32 vcc, 1, v72
	s_andn2_b64 s[36:37], s[44:45], exec
	s_and_b64 s[44:45], vcc, exec
	s_or_b64 s[44:45], s[36:37], s[44:45]
	s_mov_b64 s[36:37], exec
	s_or_b64 exec, exec, s[54:55]
	v_mov_b64_e32 v[180:181], v[176:177]
	v_mov_b64_e32 v[178:179], v[174:175]
	s_and_saveexec_b64 s[54:55], s[44:45]
	s_xor_b64 s[44:45], exec, s[54:55]
	s_or_b64 exec, exec, s[44:45]
	s_and_saveexec_b64 s[44:45], s[36:37]
	s_mov_b32 s27, 0xbfb8aa3b
	v_mul_f32_e64 v72, -v174, s27
	v_mul_f32_e64 v175, -v175, s27
	v_mul_f32_e64 v176, -v176, s27
	v_mul_f32_e64 v177, -v177, s27
	v_exp_f32_e32 v174, v72
	v_exp_f32_e32 v175, v175
	v_exp_f32_e32 v176, v176
	v_exp_f32_e32 v177, v177
	v_add_f32_e32 v174, 1.0, v174
	v_add_f32_e32 v175, 1.0, v175
	v_add_f32_e32 v176, 1.0, v176
	v_add_f32_e32 v177, 1.0, v177
	v_rcp_f32_e32 v174, v174
	v_rcp_f32_e32 v176, v176
	v_rcp_f32_e32 v177, v177
	v_rcp_f32_e32 v175, v175
	v_sub_f32_e32 v73, 1.0, v63
	v_sub_f32_e32 v72, 1.0, v62
	v_sub_f32_e32 v179, 1.0, v65
	v_sub_f32_e32 v178, 1.0, v64
	v_pk_mul_f32 v[180:181], v[178:179], v[176:177]
	v_pk_mul_f32 v[178:179], v[72:73], v[174:175]
	s_or_b64 exec, exec, s[44:45]
	s_andn2_saveexec_b64 s[4:5], s[4:5]
	s_or_b64 exec, exec, s[4:5]
	v_mov_b32_e32 v201, v200
	v_xor_b32_e32 v61, 0x80000000, v61
	v_xor_b32_e32 v60, 0x80000000, v60
	v_mov_b32_e32 v72, v200
	v_mov_b32_e32 v73, v200
	v_mov_b32_e32 v193, v192
	v_pk_fma_f32 v[72:73], v[60:61], v[72:73], v[172:173]
	v_pk_fma_f32 v[170:171], v[58:59], v[200:201], v[170:171] neg_lo:[1,0,0] neg_hi:[1,0,0]
	v_mov_b32_e32 v172, v192
	v_mov_b32_e32 v173, v192
	v_pk_fma_f32 v[170:171], v[192:193], v[170:171], v[54:55]
	v_pk_fma_f32 v[172:173], v[172:173], v[72:73], v[56:57]
	v_cvt_pk_bf16_f32 v174, v178, v179
	v_cvt_pk_bf16_f32 v175, v180, v181
	s_and_saveexec_b64 s[4:5], s[42:43]
	s_xor_b64 s[4:5], exec, s[4:5]
	v_ashrrev_i32_e32 v180, 10, v202
	v_cmp_lt_i32_e32 vcc, 1, v180
	s_mov_b64 s[36:37], 0
	s_mov_b64 s[44:45], 0
	s_and_saveexec_b64 s[54:55], vcc
	s_xor_b64 s[54:55], exec, s[54:55]
	v_cmp_ne_u32_e32 vcc, 2, v180
	s_and_b64 s[44:45], vcc, exec
	s_andn2_saveexec_b64 s[54:55], s[54:55]
	v_cmp_ne_u32_e32 vcc, 1, v180
	s_andn2_b64 s[36:37], s[44:45], exec
	s_and_b64 s[44:45], vcc, exec
	s_or_b64 s[44:45], s[36:37], s[44:45]
	s_mov_b64 s[36:37], exec
	s_or_b64 exec, exec, s[54:55]
	v_mov_b64_e32 v[178:179], v[172:173]
	v_mov_b64_e32 v[176:177], v[170:171]
	s_and_saveexec_b64 s[54:55], s[44:45]
	s_xor_b64 s[44:45], exec, s[54:55]
	s_or_b64 exec, exec, s[44:45]
	s_and_saveexec_b64 s[44:45], s[36:37]
	s_mov_b32 s27, 0xbfb8aa3b
	v_mul_f32_e64 v72, -v170, s27
	v_mul_f32_e64 v171, -v171, s27
	v_mul_f32_e64 v172, -v172, s27
	v_mul_f32_e64 v173, -v173, s27
	v_exp_f32_e32 v170, v72
	v_exp_f32_e32 v171, v171
	v_exp_f32_e32 v172, v172
	v_exp_f32_e32 v173, v173
	v_add_f32_e32 v170, 1.0, v170
	v_add_f32_e32 v171, 1.0, v171
	v_add_f32_e32 v172, 1.0, v172
	v_add_f32_e32 v173, 1.0, v173
	v_rcp_f32_e32 v170, v170
	v_rcp_f32_e32 v172, v172
	v_rcp_f32_e32 v173, v173
	v_rcp_f32_e32 v171, v171
	v_sub_f32_e32 v73, 1.0, v47
	v_sub_f32_e32 v72, 1.0, v46
	v_sub_f32_e32 v177, 1.0, v49
	v_sub_f32_e32 v176, 1.0, v48
	v_pk_mul_f32 v[178:179], v[176:177], v[172:173]
	v_pk_mul_f32 v[176:177], v[72:73], v[170:171]
	v_mov_b32_e32 v180, 1
	s_or_b64 exec, exec, s[44:45]
	s_andn2_saveexec_b64 s[4:5], s[4:5]
	s_or_b64 exec, exec, s[4:5]
	s_lshl_b32 s51, s3, 8
	v_add_lshl_u32 v181, v214, s51, 10
	s_mov_b32 s3, 0x1020000
	v_cvt_pk_bf16_f32 v176, v176, v177
	v_cvt_pk_bf16_f32 v177, v178, v179
	v_mul_lo_u32 v178, v180, s3
	v_or_b32_e32 v72, v181, v210
	v_add_lshl_u32 v72, v72, v178, 1
	buffer_store_dwordx4 v[174:177], v72, s[28:31], 0 offen sc1
	v_xor_b32_e32 v45, 0x80000000, v45
	v_xor_b32_e32 v44, 0x80000000, v44
	v_mov_b32_e32 v72, v200
	v_mov_b32_e32 v73, v200
	v_pk_fma_f32 v[72:73], v[44:45], v[72:73], v[168:169]
	v_pk_fma_f32 v[166:167], v[42:43], v[200:201], v[166:167] neg_lo:[1,0,0] neg_hi:[1,0,0]
	v_mov_b32_e32 v168, v192
	v_mov_b32_e32 v169, v192
	s_movk_i32 s3, 0x3ff
	v_pk_fma_f32 v[166:167], v[192:193], v[166:167], v[38:39]
	v_pk_fma_f32 v[168:169], v[168:169], v[72:73], v[40:41]
	v_cmp_lt_u32_e64 s[44:45], s3, v212
	s_and_saveexec_b64 s[4:5], s[44:45]
	s_xor_b64 s[4:5], exec, s[4:5]
	v_ashrrev_i32_e32 v72, 10, v212
	v_cmp_lt_i32_e32 vcc, 1, v72
	s_mov_b64 s[36:37], 0
	s_mov_b64 s[54:55], 0
	s_and_saveexec_b64 s[56:57], vcc
	s_xor_b64 s[56:57], exec, s[56:57]
	v_cmp_ne_u32_e32 vcc, 2, v72
	s_and_b64 s[54:55], vcc, exec
	s_andn2_saveexec_b64 s[56:57], s[56:57]
	v_cmp_ne_u32_e32 vcc, 1, v72
	s_andn2_b64 s[36:37], s[54:55], exec
	s_and_b64 s[54:55], vcc, exec
	s_or_b64 s[54:55], s[36:37], s[54:55]
	s_mov_b64 s[36:37], exec
	s_or_b64 exec, exec, s[56:57]
	v_mov_b64_e32 v[172:173], v[168:169]
	v_mov_b64_e32 v[170:171], v[166:167]
	s_and_saveexec_b64 s[56:57], s[54:55]
	s_xor_b64 s[54:55], exec, s[56:57]
	s_or_b64 exec, exec, s[54:55]
	s_and_saveexec_b64 s[54:55], s[36:37]
	s_mov_b32 s3, 0xbfb8aa3b
	v_mul_f32_e64 v72, -v166, s3
	v_mul_f32_e64 v167, -v167, s3
	v_mul_f32_e64 v168, -v168, s3
	v_mul_f32_e64 v169, -v169, s3
	v_exp_f32_e32 v166, v72
	v_exp_f32_e32 v167, v167
	v_exp_f32_e32 v168, v168
	v_exp_f32_e32 v169, v169
	v_add_f32_e32 v166, 1.0, v166
	v_add_f32_e32 v167, 1.0, v167
	v_add_f32_e32 v168, 1.0, v168
	v_add_f32_e32 v169, 1.0, v169
	v_rcp_f32_e32 v166, v166
	v_rcp_f32_e32 v168, v168
	v_rcp_f32_e32 v169, v169
	v_rcp_f32_e32 v167, v167
	v_sub_f32_e32 v73, 1.0, v31
	v_sub_f32_e32 v72, 1.0, v30
	v_sub_f32_e32 v171, 1.0, v33
	v_sub_f32_e32 v170, 1.0, v32
	v_pk_mul_f32 v[172:173], v[170:171], v[168:169]
	v_pk_mul_f32 v[170:171], v[72:73], v[166:167]
	s_or_b64 exec, exec, s[54:55]
	s_andn2_saveexec_b64 s[4:5], s[4:5]
	s_or_b64 exec, exec, s[4:5]
	v_xor_b32_e32 v29, 0x80000000, v29
	v_xor_b32_e32 v28, 0x80000000, v28
	v_mov_b32_e32 v72, v200
	v_mov_b32_e32 v73, v200
	v_pk_fma_f32 v[162:163], v[26:27], v[200:201], v[162:163] neg_lo:[1,0,0] neg_hi:[1,0,0]
	v_pk_fma_f32 v[72:73], v[28:29], v[72:73], v[164:165]
	v_pk_fma_f32 v[162:163], v[192:193], v[162:163], v[22:23]
	v_mov_b32_e32 v193, v192
	v_pk_fma_f32 v[164:165], v[192:193], v[72:73], v[24:25]
	v_cvt_pk_bf16_f32 v166, v170, v171
	v_cvt_pk_bf16_f32 v167, v172, v173
	s_and_saveexec_b64 s[4:5], s[44:45]
	s_xor_b64 s[4:5], exec, s[4:5]
	v_ashrrev_i32_e32 v172, 10, v212
	v_cmp_lt_i32_e32 vcc, 1, v172
	s_mov_b64 s[36:37], 0
	s_mov_b64 s[54:55], 0
	s_and_saveexec_b64 s[56:57], vcc
	s_xor_b64 s[56:57], exec, s[56:57]
	v_cmp_ne_u32_e32 vcc, 2, v172
	s_and_b64 s[54:55], vcc, exec
	s_andn2_saveexec_b64 s[56:57], s[56:57]
	v_cmp_ne_u32_e32 vcc, 1, v172
	s_andn2_b64 s[36:37], s[54:55], exec
	s_and_b64 s[54:55], vcc, exec
	s_or_b64 s[54:55], s[36:37], s[54:55]
	s_mov_b64 s[36:37], exec
	s_or_b64 exec, exec, s[56:57]
	v_mov_b64_e32 v[170:171], v[164:165]
	v_mov_b64_e32 v[168:169], v[162:163]
	s_and_saveexec_b64 s[56:57], s[54:55]
	s_xor_b64 s[54:55], exec, s[56:57]
	s_or_b64 exec, exec, s[54:55]
	s_and_saveexec_b64 s[54:55], s[36:37]
	s_mov_b32 s3, 0xbfb8aa3b
	v_mul_f32_e64 v72, -v162, s3
	v_mul_f32_e64 v163, -v163, s3
	v_mul_f32_e64 v164, -v164, s3
	v_mul_f32_e64 v165, -v165, s3
	v_exp_f32_e32 v162, v72
	v_exp_f32_e32 v163, v163
	v_exp_f32_e32 v164, v164
	v_exp_f32_e32 v165, v165
	v_add_f32_e32 v162, 1.0, v162
	v_add_f32_e32 v163, 1.0, v163
	v_add_f32_e32 v164, 1.0, v164
	v_add_f32_e32 v165, 1.0, v165
	v_rcp_f32_e32 v162, v162
	v_rcp_f32_e32 v164, v164
	v_rcp_f32_e32 v165, v165
	v_rcp_f32_e32 v163, v163
	v_sub_f32_e32 v73, 1.0, v15
	v_sub_f32_e32 v72, 1.0, v14
	v_sub_f32_e32 v169, 1.0, v17
	v_sub_f32_e32 v168, 1.0, v16
	v_pk_mul_f32 v[170:171], v[168:169], v[164:165]
	v_pk_mul_f32 v[168:169], v[72:73], v[162:163]
	v_mov_b32_e32 v172, 1
	s_or_b64 exec, exec, s[54:55]
	s_andn2_saveexec_b64 s[4:5], s[4:5]
	s_or_b64 exec, exec, s[4:5]
	s_mov_b32 s3, 0x1020000
	v_cvt_pk_bf16_f32 v168, v168, v169
	v_cvt_pk_bf16_f32 v169, v170, v171
	v_mul_lo_u32 v170, v172, s3
	v_or_b32_e32 v72, v181, v203
	v_add_lshl_u32 v72, v72, v170, 1
	s_and_b64 vcc, exec, s[46:47]
	buffer_store_dwordx4 v[166:169], v72, s[28:31], 0 offen sc1
	s_cbranch_vccnz .LBB0_458_sg1
	ds_read_b64 v[166:167], v211 offset:128
	s_waitcnt lgkmcnt(0)
	v_mov_b32_e32 v72, v167
	s_branch .LBB0_459_sg1

.LBB0_459_sg1:
	v_pk_fma_f32 v[160:161], v[190:191], v[166:167], v[160:161] op_sel_hi:[1,0,1]
	v_pk_fma_f32 v[158:159], v[70:71], v[166:167], v[158:159] op_sel_hi:[1,0,1] neg_lo:[1,0,0] neg_hi:[1,0,0]
	v_pk_fma_f32 v[160:161], v[72:73], v[160:161], v[68:69] op_sel_hi:[0,1,1]
	v_pk_fma_f32 v[158:159], v[72:73], v[158:159], v[66:67] op_sel_hi:[0,1,1]
	s_and_saveexec_b64 s[4:5], s[42:43]
	s_xor_b64 s[4:5], exec, s[4:5]
	v_cmp_lt_i32_e32 vcc, 1, v180
	s_mov_b64 s[36:37], 0
	s_mov_b64 s[54:55], 0
	s_and_saveexec_b64 s[56:57], vcc
	s_xor_b64 s[56:57], exec, s[56:57]
	v_cmp_ne_u32_e32 vcc, 2, v180
	s_and_b64 s[54:55], vcc, exec
	s_andn2_saveexec_b64 s[56:57], s[56:57]
	v_cmp_ne_u32_e32 vcc, 1, v180
	s_andn2_b64 s[36:37], s[54:55], exec
	s_and_b64 s[54:55], vcc, exec
	s_or_b64 s[54:55], s[36:37], s[54:55]
	s_mov_b64 s[36:37], exec
	s_or_b64 exec, exec, s[56:57]
	v_mov_b64_e32 v[164:165], v[160:161]
	v_mov_b64_e32 v[162:163], v[158:159]
	s_and_saveexec_b64 s[56:57], s[54:55]
	s_xor_b64 s[54:55], exec, s[56:57]
	s_or_b64 exec, exec, s[54:55]
	s_and_saveexec_b64 s[54:55], s[36:37]
	s_mov_b32 s3, 0xbfb8aa3b
	v_mul_f32_e64 v73, -v158, s3
	v_exp_f32_e32 v73, v73
	v_mul_f32_e64 v159, -v159, s3
	v_sub_f32_e32 v163, 1.0, v63
	v_sub_f32_e32 v162, 1.0, v62
	v_add_f32_e32 v73, 1.0, v73
	v_rcp_f32_e32 v158, v73
	v_exp_f32_e32 v73, v159
	v_mul_f32_e64 v159, -v160, s3
	v_exp_f32_e32 v159, v159
	v_mul_f32_e64 v160, -v161, s3
	v_exp_f32_e32 v161, v160
	v_add_f32_e32 v73, 1.0, v73
	v_add_f32_e32 v159, 1.0, v159
	v_rcp_f32_e32 v160, v159
	v_add_f32_e32 v159, 1.0, v161
	v_rcp_f32_e32 v161, v159
	v_rcp_f32_e32 v159, v73
	v_sub_f32_e32 v165, 1.0, v65
	v_sub_f32_e32 v164, 1.0, v64
	v_pk_mul_f32 v[164:165], v[164:165], v[160:161]
	v_pk_mul_f32 v[162:163], v[162:163], v[158:159]
	s_or_b64 exec, exec, s[54:55]
	s_andn2_saveexec_b64 s[4:5], s[4:5]
	s_or_b64 exec, exec, s[4:5]
	v_mov_b32_e32 v167, v166
	v_mov_b32_e32 v160, v166
	v_mov_b32_e32 v161, v166
	v_mov_b32_e32 v73, v72
	v_pk_fma_f32 v[156:157], v[60:61], v[160:161], v[156:157]
	v_pk_fma_f32 v[154:155], v[58:59], v[166:167], v[154:155] neg_lo:[1,0,0] neg_hi:[1,0,0]
	v_mov_b32_e32 v160, v72
	v_mov_b32_e32 v161, v72
	v_pk_fma_f32 v[154:155], v[72:73], v[154:155], v[54:55]
	v_pk_fma_f32 v[156:157], v[160:161], v[156:157], v[56:57]
	v_cvt_pk_bf16_f32 v158, v162, v163
	v_cvt_pk_bf16_f32 v159, v164, v165
	s_and_saveexec_b64 s[4:5], s[42:43]
	s_xor_b64 s[4:5], exec, s[4:5]
	v_cmp_lt_i32_e32 vcc, 1, v180
	s_mov_b64 s[36:37], 0
	s_mov_b64 s[54:55], 0
	s_and_saveexec_b64 s[56:57], vcc
	s_xor_b64 s[56:57], exec, s[56:57]
	v_cmp_ne_u32_e32 vcc, 2, v180
	s_and_b64 s[54:55], vcc, exec
	s_andn2_saveexec_b64 s[56:57], s[56:57]
	v_cmp_ne_u32_e32 vcc, 1, v180
	s_andn2_b64 s[36:37], s[54:55], exec
	s_and_b64 s[54:55], vcc, exec
	s_or_b64 s[54:55], s[36:37], s[54:55]
	s_mov_b64 s[36:37], exec
	s_or_b64 exec, exec, s[56:57]
	v_mov_b64_e32 v[162:163], v[156:157]
	v_mov_b64_e32 v[160:161], v[154:155]
	s_and_saveexec_b64 s[56:57], s[54:55]
	s_xor_b64 s[54:55], exec, s[56:57]
	s_or_b64 exec, exec, s[54:55]
	s_and_saveexec_b64 s[54:55], s[36:37]
	s_mov_b32 s3, 0xbfb8aa3b
	v_mul_f32_e64 v154, -v154, s3
	v_mul_f32_e64 v155, -v155, s3
	v_mul_f32_e64 v156, -v156, s3
	v_mul_f32_e64 v157, -v157, s3
	v_exp_f32_e32 v154, v154
	v_exp_f32_e32 v155, v155
	v_exp_f32_e32 v156, v156
	v_exp_f32_e32 v157, v157
	v_add_f32_e32 v154, 1.0, v154
	v_add_f32_e32 v155, 1.0, v155
	v_add_f32_e32 v156, 1.0, v156
	v_add_f32_e32 v157, 1.0, v157
	v_rcp_f32_e32 v154, v154
	v_rcp_f32_e32 v156, v156
	v_rcp_f32_e32 v157, v157
	v_rcp_f32_e32 v155, v155
	v_sub_f32_e32 v161, 1.0, v47
	v_sub_f32_e32 v160, 1.0, v46
	v_sub_f32_e32 v163, 1.0, v49
	v_sub_f32_e32 v162, 1.0, v48
	v_pk_mul_f32 v[162:163], v[162:163], v[156:157]
	v_pk_mul_f32 v[160:161], v[160:161], v[154:155]
	s_or_b64 exec, exec, s[54:55]
	s_andn2_saveexec_b64 s[4:5], s[4:5]
	s_or_b64 exec, exec, s[4:5]
	v_add_u32_e32 v164, 0x4000, v181
	v_or_b32_e32 v154, v164, v210
	v_add_lshl_u32 v154, v154, v178, 1
	v_cvt_pk_bf16_f32 v160, v160, v161
	v_cvt_pk_bf16_f32 v161, v162, v163
	buffer_store_dwordx4 v[158:161], v154, s[28:31], 0 offen sc1
	v_mov_b32_e32 v154, v166
	v_mov_b32_e32 v155, v166
	v_pk_fma_f32 v[152:153], v[44:45], v[154:155], v[152:153]
	v_pk_fma_f32 v[150:151], v[42:43], v[166:167], v[150:151] neg_lo:[1,0,0] neg_hi:[1,0,0]
	v_mov_b32_e32 v154, v72
	v_mov_b32_e32 v155, v72
	v_pk_fma_f32 v[150:151], v[72:73], v[150:151], v[38:39]
	v_pk_fma_f32 v[152:153], v[154:155], v[152:153], v[40:41]
	s_and_saveexec_b64 s[4:5], s[44:45]
	s_xor_b64 s[4:5], exec, s[4:5]
	v_cmp_lt_i32_e32 vcc, 1, v172
	s_mov_b64 s[36:37], 0
	s_mov_b64 s[54:55], 0
	s_and_saveexec_b64 s[56:57], vcc
	s_xor_b64 s[56:57], exec, s[56:57]
	v_cmp_ne_u32_e32 vcc, 2, v172
	s_and_b64 s[54:55], vcc, exec
	s_andn2_saveexec_b64 s[56:57], s[56:57]
	v_cmp_ne_u32_e32 vcc, 1, v172
	s_andn2_b64 s[36:37], s[54:55], exec
	s_and_b64 s[54:55], vcc, exec
	s_or_b64 s[54:55], s[36:37], s[54:55]
	s_mov_b64 s[36:37], exec
	s_or_b64 exec, exec, s[56:57]
	v_mov_b64_e32 v[156:157], v[152:153]
	v_mov_b64_e32 v[154:155], v[150:151]
	s_and_saveexec_b64 s[56:57], s[54:55]
	s_xor_b64 s[54:55], exec, s[56:57]
	s_or_b64 exec, exec, s[54:55]
	s_and_saveexec_b64 s[54:55], s[36:37]
	s_mov_b32 s3, 0xbfb8aa3b
	v_mul_f32_e64 v150, -v150, s3
	v_mul_f32_e64 v151, -v151, s3
	v_mul_f32_e64 v152, -v152, s3
	v_mul_f32_e64 v153, -v153, s3
	v_exp_f32_e32 v150, v150
	v_exp_f32_e32 v151, v151
	v_exp_f32_e32 v152, v152
	v_exp_f32_e32 v153, v153
	v_add_f32_e32 v150, 1.0, v150
	v_add_f32_e32 v151, 1.0, v151
	v_add_f32_e32 v152, 1.0, v152
	v_add_f32_e32 v153, 1.0, v153
	v_rcp_f32_e32 v150, v150
	v_rcp_f32_e32 v152, v152
	v_rcp_f32_e32 v153, v153
	v_rcp_f32_e32 v151, v151
	v_sub_f32_e32 v155, 1.0, v31
	v_sub_f32_e32 v154, 1.0, v30
	v_sub_f32_e32 v157, 1.0, v33
	v_sub_f32_e32 v156, 1.0, v32
	v_pk_mul_f32 v[156:157], v[156:157], v[152:153]
	v_pk_mul_f32 v[154:155], v[154:155], v[150:151]
	s_or_b64 exec, exec, s[54:55]
	s_andn2_saveexec_b64 s[4:5], s[4:5]
	s_or_b64 exec, exec, s[4:5]
	v_mov_b32_e32 v152, v166
	v_mov_b32_e32 v153, v166
	v_pk_fma_f32 v[146:147], v[26:27], v[166:167], v[146:147] neg_lo:[1,0,0] neg_hi:[1,0,0]
	v_pk_fma_f32 v[148:149], v[28:29], v[152:153], v[148:149]
	v_pk_fma_f32 v[146:147], v[72:73], v[146:147], v[22:23]
	v_mov_b32_e32 v73, v72
	v_pk_fma_f32 v[148:149], v[72:73], v[148:149], v[24:25]
	v_cvt_pk_bf16_f32 v150, v154, v155
	v_cvt_pk_bf16_f32 v151, v156, v157
	s_and_saveexec_b64 s[4:5], s[44:45]
	s_xor_b64 s[4:5], exec, s[4:5]
	v_cmp_lt_i32_e32 vcc, 1, v172
	s_mov_b64 s[36:37], 0
	s_mov_b64 s[54:55], 0
	s_and_saveexec_b64 s[56:57], vcc
	s_xor_b64 s[56:57], exec, s[56:57]
	v_cmp_ne_u32_e32 vcc, 2, v172
	s_and_b64 s[54:55], vcc, exec
	s_andn2_saveexec_b64 s[56:57], s[56:57]
	v_cmp_ne_u32_e32 vcc, 1, v172
	s_andn2_b64 s[36:37], s[54:55], exec
	s_and_b64 s[54:55], vcc, exec
	s_or_b64 s[54:55], s[36:37], s[54:55]
	s_mov_b64 s[36:37], exec
	s_or_b64 exec, exec, s[56:57]
	v_mov_b64_e32 v[154:155], v[148:149]
	v_mov_b64_e32 v[152:153], v[146:147]
	s_and_saveexec_b64 s[56:57], s[54:55]
	s_xor_b64 s[54:55], exec, s[56:57]
	s_or_b64 exec, exec, s[54:55]
	s_and_saveexec_b64 s[54:55], s[36:37]
	s_mov_b32 s3, 0xbfb8aa3b
	v_mul_f32_e64 v72, -v146, s3
	v_mul_f32_e64 v147, -v147, s3
	v_mul_f32_e64 v148, -v148, s3
	v_mul_f32_e64 v149, -v149, s3
	v_exp_f32_e32 v146, v72
	v_exp_f32_e32 v147, v147
	v_exp_f32_e32 v148, v148
	v_exp_f32_e32 v149, v149
	v_add_f32_e32 v146, 1.0, v146
	v_add_f32_e32 v147, 1.0, v147
	v_add_f32_e32 v148, 1.0, v148
	v_add_f32_e32 v149, 1.0, v149
	v_rcp_f32_e32 v146, v146
	v_rcp_f32_e32 v148, v148
	v_rcp_f32_e32 v149, v149
	v_rcp_f32_e32 v147, v147
	v_sub_f32_e32 v73, 1.0, v15
	v_sub_f32_e32 v72, 1.0, v14
	v_sub_f32_e32 v153, 1.0, v17
	v_sub_f32_e32 v152, 1.0, v16
	v_pk_mul_f32 v[154:155], v[152:153], v[148:149]
	v_pk_mul_f32 v[152:153], v[72:73], v[146:147]
	s_or_b64 exec, exec, s[54:55]
	s_andn2_saveexec_b64 s[4:5], s[4:5]
	s_or_b64 exec, exec, s[4:5]
	v_or_b32_e32 v72, v164, v203
	v_add_lshl_u32 v72, v72, v170, 1
	v_cvt_pk_bf16_f32 v152, v152, v153
	v_cvt_pk_bf16_f32 v153, v154, v155
	buffer_store_dwordx4 v[150:153], v72, s[28:31], 0 offen sc1
	s_and_b64 vcc, exec, s[46:47]
	s_nop 0
	v_mov_b32_e32 v153, v205
	s_nop 0
	v_lshl_add_u32 v152, v153, 3, s33
	s_cbranch_vccnz .LBB0_509_sg1
	ds_read_b64 v[150:151], v152
	s_waitcnt lgkmcnt(0)
	v_mov_b32_e32 v72, v151
	s_branch .LBB0_510_sg1

.LBB0_510_sg1:
	v_pk_fma_f32 v[144:145], v[190:191], v[150:151], v[144:145] op_sel_hi:[1,0,1]
	v_pk_fma_f32 v[142:143], v[70:71], v[150:151], v[142:143] op_sel_hi:[1,0,1] neg_lo:[1,0,0] neg_hi:[1,0,0]
	v_pk_fma_f32 v[144:145], v[72:73], v[144:145], v[68:69] op_sel_hi:[0,1,1]
	v_pk_fma_f32 v[142:143], v[72:73], v[142:143], v[66:67] op_sel_hi:[0,1,1]
	s_and_saveexec_b64 s[4:5], s[42:43]
	s_xor_b64 s[4:5], exec, s[4:5]
	v_cmp_lt_i32_e32 vcc, 1, v180
	s_mov_b64 s[36:37], 0
	s_mov_b64 s[54:55], 0
	s_and_saveexec_b64 s[56:57], vcc
	s_xor_b64 s[56:57], exec, s[56:57]
	v_cmp_ne_u32_e32 vcc, 2, v180
	s_and_b64 s[54:55], vcc, exec
	s_andn2_saveexec_b64 s[56:57], s[56:57]
	v_cmp_ne_u32_e32 vcc, 1, v180
	s_andn2_b64 s[36:37], s[54:55], exec
	s_and_b64 s[54:55], vcc, exec
	s_or_b64 s[54:55], s[36:37], s[54:55]
	s_mov_b64 s[36:37], exec
	s_or_b64 exec, exec, s[56:57]
	v_mov_b64_e32 v[148:149], v[144:145]
	v_mov_b64_e32 v[146:147], v[142:143]
	s_and_saveexec_b64 s[56:57], s[54:55]
	s_xor_b64 s[54:55], exec, s[56:57]
	s_or_b64 exec, exec, s[54:55]
	s_and_saveexec_b64 s[54:55], s[36:37]
	s_mov_b32 s3, 0xbfb8aa3b
	v_mul_f32_e64 v73, -v142, s3
	v_exp_f32_e32 v73, v73
	v_mul_f32_e64 v143, -v143, s3
	v_sub_f32_e32 v147, 1.0, v63
	v_sub_f32_e32 v146, 1.0, v62
	v_add_f32_e32 v73, 1.0, v73
	v_rcp_f32_e32 v142, v73
	v_exp_f32_e32 v73, v143
	v_mul_f32_e64 v143, -v144, s3
	v_exp_f32_e32 v143, v143
	v_mul_f32_e64 v144, -v145, s3
	v_exp_f32_e32 v145, v144
	v_add_f32_e32 v73, 1.0, v73
	v_add_f32_e32 v143, 1.0, v143
	v_rcp_f32_e32 v144, v143
	v_add_f32_e32 v143, 1.0, v145
	v_rcp_f32_e32 v145, v143
	v_rcp_f32_e32 v143, v73
	v_sub_f32_e32 v149, 1.0, v65
	v_sub_f32_e32 v148, 1.0, v64
	v_pk_mul_f32 v[148:149], v[148:149], v[144:145]
	v_pk_mul_f32 v[146:147], v[146:147], v[142:143]
	s_or_b64 exec, exec, s[54:55]
	s_andn2_saveexec_b64 s[4:5], s[4:5]
	s_or_b64 exec, exec, s[4:5]
	v_mov_b32_e32 v151, v150
	v_mov_b32_e32 v144, v150
	v_mov_b32_e32 v145, v150
	v_mov_b32_e32 v73, v72
	v_pk_fma_f32 v[140:141], v[60:61], v[144:145], v[140:141]
	v_pk_fma_f32 v[138:139], v[58:59], v[150:151], v[138:139] neg_lo:[1,0,0] neg_hi:[1,0,0]
	v_mov_b32_e32 v144, v72
	v_mov_b32_e32 v145, v72
	v_pk_fma_f32 v[138:139], v[72:73], v[138:139], v[54:55]
	v_pk_fma_f32 v[140:141], v[144:145], v[140:141], v[56:57]
	v_cvt_pk_bf16_f32 v142, v146, v147
	v_cvt_pk_bf16_f32 v143, v148, v149
	s_and_saveexec_b64 s[4:5], s[42:43]
	s_xor_b64 s[4:5], exec, s[4:5]
	v_cmp_lt_i32_e32 vcc, 1, v180
	s_mov_b64 s[36:37], 0
	s_mov_b64 s[54:55], 0
	s_and_saveexec_b64 s[56:57], vcc
	s_xor_b64 s[56:57], exec, s[56:57]
	v_cmp_ne_u32_e32 vcc, 2, v180
	s_and_b64 s[54:55], vcc, exec
	s_andn2_saveexec_b64 s[56:57], s[56:57]
	v_cmp_ne_u32_e32 vcc, 1, v180
	s_andn2_b64 s[36:37], s[54:55], exec
	s_and_b64 s[54:55], vcc, exec
	s_or_b64 s[54:55], s[36:37], s[54:55]
	s_mov_b64 s[36:37], exec
	s_or_b64 exec, exec, s[56:57]
	v_mov_b64_e32 v[146:147], v[140:141]
	v_mov_b64_e32 v[144:145], v[138:139]
	s_and_saveexec_b64 s[56:57], s[54:55]
	s_xor_b64 s[54:55], exec, s[56:57]
	s_or_b64 exec, exec, s[54:55]
	s_and_saveexec_b64 s[54:55], s[36:37]
	s_mov_b32 s3, 0xbfb8aa3b
	v_mul_f32_e64 v138, -v138, s3
	v_mul_f32_e64 v139, -v139, s3
	v_mul_f32_e64 v140, -v140, s3
	v_mul_f32_e64 v141, -v141, s3
	v_exp_f32_e32 v138, v138
	v_exp_f32_e32 v139, v139
	v_exp_f32_e32 v140, v140
	v_exp_f32_e32 v141, v141
	v_add_f32_e32 v138, 1.0, v138
	v_add_f32_e32 v139, 1.0, v139
	v_add_f32_e32 v140, 1.0, v140
	v_add_f32_e32 v141, 1.0, v141
	v_rcp_f32_e32 v138, v138
	v_rcp_f32_e32 v140, v140
	v_rcp_f32_e32 v141, v141
	v_rcp_f32_e32 v139, v139
	v_sub_f32_e32 v145, 1.0, v47
	v_sub_f32_e32 v144, 1.0, v46
	v_sub_f32_e32 v147, 1.0, v49
	v_sub_f32_e32 v146, 1.0, v48
	v_pk_mul_f32 v[146:147], v[146:147], v[140:141]
	v_pk_mul_f32 v[144:145], v[144:145], v[138:139]
	s_or_b64 exec, exec, s[54:55]
	s_andn2_saveexec_b64 s[4:5], s[4:5]
	s_or_b64 exec, exec, s[4:5]
	v_add_lshl_u32 v148, v153, s51, 10
	v_cvt_pk_bf16_f32 v144, v144, v145
	v_cvt_pk_bf16_f32 v145, v146, v147
	v_or_b32_e32 v146, v178, v210
	v_add_lshl_u32 v138, v148, v146, 1
	buffer_store_dwordx4 v[142:145], v138, s[28:31], 0 offen sc1
	v_mov_b32_e32 v138, v150
	v_mov_b32_e32 v139, v150
	v_pk_fma_f32 v[136:137], v[44:45], v[138:139], v[136:137]
	v_pk_fma_f32 v[134:135], v[42:43], v[150:151], v[134:135] neg_lo:[1,0,0] neg_hi:[1,0,0]
	v_mov_b32_e32 v138, v72
	v_mov_b32_e32 v139, v72
	v_pk_fma_f32 v[134:135], v[72:73], v[134:135], v[38:39]
	v_pk_fma_f32 v[136:137], v[138:139], v[136:137], v[40:41]
	s_and_saveexec_b64 s[4:5], s[44:45]
	s_xor_b64 s[4:5], exec, s[4:5]
	v_cmp_lt_i32_e32 vcc, 1, v172
	s_mov_b64 s[36:37], 0
	s_mov_b64 s[54:55], 0
	s_and_saveexec_b64 s[56:57], vcc
	s_xor_b64 s[56:57], exec, s[56:57]
	v_cmp_ne_u32_e32 vcc, 2, v172
	s_and_b64 s[54:55], vcc, exec
	s_andn2_saveexec_b64 s[56:57], s[56:57]
	v_cmp_ne_u32_e32 vcc, 1, v172
	s_andn2_b64 s[36:37], s[54:55], exec
	s_and_b64 s[54:55], vcc, exec
	s_or_b64 s[54:55], s[36:37], s[54:55]
	s_mov_b64 s[36:37], exec
	s_or_b64 exec, exec, s[56:57]
	v_mov_b64_e32 v[140:141], v[136:137]
	v_mov_b64_e32 v[138:139], v[134:135]
	s_and_saveexec_b64 s[56:57], s[54:55]
	s_xor_b64 s[54:55], exec, s[56:57]
	s_or_b64 exec, exec, s[54:55]
	s_and_saveexec_b64 s[54:55], s[36:37]
	s_mov_b32 s3, 0xbfb8aa3b
	v_mul_f32_e64 v134, -v134, s3
	v_mul_f32_e64 v135, -v135, s3
	v_mul_f32_e64 v136, -v136, s3
	v_mul_f32_e64 v137, -v137, s3
	v_exp_f32_e32 v134, v134
	v_exp_f32_e32 v135, v135
	v_exp_f32_e32 v136, v136
	v_exp_f32_e32 v137, v137
	v_add_f32_e32 v134, 1.0, v134
	v_add_f32_e32 v135, 1.0, v135
	v_add_f32_e32 v136, 1.0, v136
	v_add_f32_e32 v137, 1.0, v137
	v_rcp_f32_e32 v134, v134
	v_rcp_f32_e32 v136, v136
	v_rcp_f32_e32 v137, v137
	v_rcp_f32_e32 v135, v135
	v_sub_f32_e32 v139, 1.0, v31
	v_sub_f32_e32 v138, 1.0, v30
	v_sub_f32_e32 v141, 1.0, v33
	v_sub_f32_e32 v140, 1.0, v32
	v_pk_mul_f32 v[140:141], v[140:141], v[136:137]
	v_pk_mul_f32 v[138:139], v[138:139], v[134:135]
	s_or_b64 exec, exec, s[54:55]
	s_andn2_saveexec_b64 s[4:5], s[4:5]
	s_or_b64 exec, exec, s[4:5]
	v_mov_b32_e32 v136, v150
	v_mov_b32_e32 v137, v150
	v_pk_fma_f32 v[130:131], v[26:27], v[150:151], v[130:131] neg_lo:[1,0,0] neg_hi:[1,0,0]
	v_pk_fma_f32 v[132:133], v[28:29], v[136:137], v[132:133]
	v_pk_fma_f32 v[130:131], v[72:73], v[130:131], v[22:23]
	v_mov_b32_e32 v73, v72
	v_pk_fma_f32 v[132:133], v[72:73], v[132:133], v[24:25]
	v_cvt_pk_bf16_f32 v134, v138, v139
	v_cvt_pk_bf16_f32 v135, v140, v141
	s_and_saveexec_b64 s[4:5], s[44:45]
	s_xor_b64 s[4:5], exec, s[4:5]
	v_cmp_lt_i32_e32 vcc, 1, v172
	s_mov_b64 s[36:37], 0
	s_mov_b64 s[54:55], 0
	s_and_saveexec_b64 s[56:57], vcc
	s_xor_b64 s[56:57], exec, s[56:57]
	v_cmp_ne_u32_e32 vcc, 2, v172
	s_and_b64 s[54:55], vcc, exec
	s_andn2_saveexec_b64 s[56:57], s[56:57]
	v_cmp_ne_u32_e32 vcc, 1, v172
	s_andn2_b64 s[36:37], s[54:55], exec
	s_and_b64 s[54:55], vcc, exec
	s_or_b64 s[54:55], s[36:37], s[54:55]
	s_mov_b64 s[36:37], exec
	s_or_b64 exec, exec, s[56:57]
	v_mov_b64_e32 v[138:139], v[132:133]
	v_mov_b64_e32 v[136:137], v[130:131]
	s_and_saveexec_b64 s[56:57], s[54:55]
	s_xor_b64 s[54:55], exec, s[56:57]
	s_or_b64 exec, exec, s[54:55]
	s_and_saveexec_b64 s[54:55], s[36:37]
	s_mov_b32 s3, 0xbfb8aa3b
	v_mul_f32_e64 v72, -v130, s3
	v_mul_f32_e64 v131, -v131, s3
	v_mul_f32_e64 v132, -v132, s3
	v_mul_f32_e64 v133, -v133, s3
	v_exp_f32_e32 v130, v72
	v_exp_f32_e32 v131, v131
	v_exp_f32_e32 v132, v132
	v_exp_f32_e32 v133, v133
	v_add_f32_e32 v130, 1.0, v130
	v_add_f32_e32 v131, 1.0, v131
	v_add_f32_e32 v132, 1.0, v132
	v_add_f32_e32 v133, 1.0, v133
	v_rcp_f32_e32 v130, v130
	v_rcp_f32_e32 v132, v132
	v_rcp_f32_e32 v133, v133
	v_rcp_f32_e32 v131, v131
	v_sub_f32_e32 v73, 1.0, v15
	v_sub_f32_e32 v72, 1.0, v14
	v_sub_f32_e32 v137, 1.0, v17
	v_sub_f32_e32 v136, 1.0, v16
	v_pk_mul_f32 v[138:139], v[136:137], v[132:133]
	v_pk_mul_f32 v[136:137], v[72:73], v[130:131]
	s_or_b64 exec, exec, s[54:55]
	s_andn2_saveexec_b64 s[4:5], s[4:5]
	s_or_b64 exec, exec, s[4:5]
	v_cvt_pk_bf16_f32 v136, v136, v137
	v_cvt_pk_bf16_f32 v137, v138, v139
	v_or_b32_e32 v138, v170, v203
	v_add_lshl_u32 v72, v148, v138, 1
	s_and_b64 vcc, exec, s[46:47]
	buffer_store_dwordx4 v[134:137], v72, s[28:31], 0 offen sc1
	s_cbranch_vccnz .LBB0_560_sg1
	ds_read_b64 v[134:135], v152 offset:128
	s_waitcnt lgkmcnt(0)
	v_mov_b32_e32 v72, v135
	s_branch .LBB0_561_sg1

.LBB0_561_sg1:
	v_pk_fma_f32 v[128:129], v[190:191], v[134:135], v[128:129] op_sel_hi:[1,0,1]
	v_pk_fma_f32 v[126:127], v[70:71], v[134:135], v[126:127] op_sel_hi:[1,0,1] neg_lo:[1,0,0] neg_hi:[1,0,0]
	v_pk_fma_f32 v[128:129], v[72:73], v[128:129], v[68:69] op_sel_hi:[0,1,1]
	v_pk_fma_f32 v[126:127], v[72:73], v[126:127], v[66:67] op_sel_hi:[0,1,1]
	s_and_saveexec_b64 s[4:5], s[42:43]
	s_xor_b64 s[4:5], exec, s[4:5]
	v_cmp_lt_i32_e32 vcc, 1, v180
	s_mov_b64 s[36:37], 0
	s_mov_b64 s[54:55], 0
	s_and_saveexec_b64 s[56:57], vcc
	s_xor_b64 s[56:57], exec, s[56:57]
	v_cmp_ne_u32_e32 vcc, 2, v180
	s_and_b64 s[54:55], vcc, exec
	s_andn2_saveexec_b64 s[56:57], s[56:57]
	v_cmp_ne_u32_e32 vcc, 1, v180
	s_andn2_b64 s[36:37], s[54:55], exec
	s_and_b64 s[54:55], vcc, exec
	s_or_b64 s[54:55], s[36:37], s[54:55]
	s_mov_b64 s[36:37], exec
	s_or_b64 exec, exec, s[56:57]
	v_mov_b64_e32 v[132:133], v[128:129]
	v_mov_b64_e32 v[130:131], v[126:127]
	s_and_saveexec_b64 s[56:57], s[54:55]
	s_xor_b64 s[54:55], exec, s[56:57]
	s_or_b64 exec, exec, s[54:55]
	s_and_saveexec_b64 s[54:55], s[36:37]
	s_mov_b32 s3, 0xbfb8aa3b
	v_mul_f32_e64 v73, -v126, s3
	v_exp_f32_e32 v73, v73
	v_mul_f32_e64 v127, -v127, s3
	v_sub_f32_e32 v131, 1.0, v63
	v_sub_f32_e32 v130, 1.0, v62
	v_add_f32_e32 v73, 1.0, v73
	v_rcp_f32_e32 v126, v73
	v_exp_f32_e32 v73, v127
	v_mul_f32_e64 v127, -v128, s3
	v_exp_f32_e32 v127, v127
	v_mul_f32_e64 v128, -v129, s3
	v_exp_f32_e32 v129, v128
	v_add_f32_e32 v73, 1.0, v73
	v_add_f32_e32 v127, 1.0, v127
	v_rcp_f32_e32 v128, v127
	v_add_f32_e32 v127, 1.0, v129
	v_rcp_f32_e32 v129, v127
	v_rcp_f32_e32 v127, v73
	v_sub_f32_e32 v133, 1.0, v65
	v_sub_f32_e32 v132, 1.0, v64
	v_pk_mul_f32 v[132:133], v[132:133], v[128:129]
	v_pk_mul_f32 v[130:131], v[130:131], v[126:127]
	s_or_b64 exec, exec, s[54:55]
	s_andn2_saveexec_b64 s[4:5], s[4:5]
	s_or_b64 exec, exec, s[4:5]
	v_mov_b32_e32 v135, v134
	v_mov_b32_e32 v128, v134
	v_mov_b32_e32 v129, v134
	v_mov_b32_e32 v73, v72
	v_pk_fma_f32 v[124:125], v[60:61], v[128:129], v[124:125]
	v_pk_fma_f32 v[122:123], v[58:59], v[134:135], v[122:123] neg_lo:[1,0,0] neg_hi:[1,0,0]
	v_mov_b32_e32 v128, v72
	v_mov_b32_e32 v129, v72
	v_pk_fma_f32 v[122:123], v[72:73], v[122:123], v[54:55]
	v_pk_fma_f32 v[124:125], v[128:129], v[124:125], v[56:57]
	v_cvt_pk_bf16_f32 v126, v130, v131
	v_cvt_pk_bf16_f32 v127, v132, v133
	s_and_saveexec_b64 s[4:5], s[42:43]
	s_xor_b64 s[4:5], exec, s[4:5]
	v_cmp_lt_i32_e32 vcc, 1, v180
	s_mov_b64 s[36:37], 0
	s_mov_b64 s[54:55], 0
	s_and_saveexec_b64 s[56:57], vcc
	s_xor_b64 s[56:57], exec, s[56:57]
	v_cmp_ne_u32_e32 vcc, 2, v180
	s_and_b64 s[54:55], vcc, exec
	s_andn2_saveexec_b64 s[56:57], s[56:57]
	v_cmp_ne_u32_e32 vcc, 1, v180
	s_andn2_b64 s[36:37], s[54:55], exec
	s_and_b64 s[54:55], vcc, exec
	s_or_b64 s[54:55], s[36:37], s[54:55]
	s_mov_b64 s[36:37], exec
	s_or_b64 exec, exec, s[56:57]
	v_mov_b64_e32 v[130:131], v[124:125]
	v_mov_b64_e32 v[128:129], v[122:123]
	s_and_saveexec_b64 s[56:57], s[54:55]
	s_xor_b64 s[54:55], exec, s[56:57]
	s_or_b64 exec, exec, s[54:55]
	s_and_saveexec_b64 s[54:55], s[36:37]
	s_mov_b32 s3, 0xbfb8aa3b
	v_mul_f32_e64 v122, -v122, s3
	v_mul_f32_e64 v123, -v123, s3
	v_mul_f32_e64 v124, -v124, s3
	v_mul_f32_e64 v125, -v125, s3
	v_exp_f32_e32 v122, v122
	v_exp_f32_e32 v123, v123
	v_exp_f32_e32 v124, v124
	v_exp_f32_e32 v125, v125
	v_add_f32_e32 v122, 1.0, v122
	v_add_f32_e32 v123, 1.0, v123
	v_add_f32_e32 v124, 1.0, v124
	v_add_f32_e32 v125, 1.0, v125
	v_rcp_f32_e32 v122, v122
	v_rcp_f32_e32 v124, v124
	v_rcp_f32_e32 v125, v125
	v_rcp_f32_e32 v123, v123
	v_sub_f32_e32 v129, 1.0, v47
	v_sub_f32_e32 v128, 1.0, v46
	v_sub_f32_e32 v131, 1.0, v49
	v_sub_f32_e32 v130, 1.0, v48
	v_pk_mul_f32 v[130:131], v[130:131], v[124:125]
	v_pk_mul_f32 v[128:129], v[128:129], v[122:123]
	s_or_b64 exec, exec, s[54:55]
	s_andn2_saveexec_b64 s[4:5], s[4:5]
	s_or_b64 exec, exec, s[4:5]
	v_add_u32_e32 v132, 0x4000, v148
	v_add_lshl_u32 v122, v132, v146, 1
	v_cvt_pk_bf16_f32 v128, v128, v129
	v_cvt_pk_bf16_f32 v129, v130, v131
	buffer_store_dwordx4 v[126:129], v122, s[28:31], 0 offen sc1
	v_mov_b32_e32 v122, v134
	v_mov_b32_e32 v123, v134
	v_pk_fma_f32 v[120:121], v[44:45], v[122:123], v[120:121]
	v_pk_fma_f32 v[118:119], v[42:43], v[134:135], v[118:119] neg_lo:[1,0,0] neg_hi:[1,0,0]
	v_mov_b32_e32 v122, v72
	v_mov_b32_e32 v123, v72
	v_pk_fma_f32 v[118:119], v[72:73], v[118:119], v[38:39]
	v_pk_fma_f32 v[120:121], v[122:123], v[120:121], v[40:41]
	s_and_saveexec_b64 s[4:5], s[44:45]
	s_xor_b64 s[4:5], exec, s[4:5]
	v_cmp_lt_i32_e32 vcc, 1, v172
	s_mov_b64 s[36:37], 0
	s_mov_b64 s[54:55], 0
	s_and_saveexec_b64 s[56:57], vcc
	s_xor_b64 s[56:57], exec, s[56:57]
	v_cmp_ne_u32_e32 vcc, 2, v172
	s_and_b64 s[54:55], vcc, exec
	s_andn2_saveexec_b64 s[56:57], s[56:57]
	v_cmp_ne_u32_e32 vcc, 1, v172
	s_andn2_b64 s[36:37], s[54:55], exec
	s_and_b64 s[54:55], vcc, exec
	s_or_b64 s[54:55], s[36:37], s[54:55]
	s_mov_b64 s[36:37], exec
	s_or_b64 exec, exec, s[56:57]
	v_mov_b64_e32 v[124:125], v[120:121]
	v_mov_b64_e32 v[122:123], v[118:119]
	s_and_saveexec_b64 s[56:57], s[54:55]
	s_xor_b64 s[54:55], exec, s[56:57]
	s_or_b64 exec, exec, s[54:55]
	s_and_saveexec_b64 s[54:55], s[36:37]
	s_mov_b32 s3, 0xbfb8aa3b
	v_mul_f32_e64 v118, -v118, s3
	v_mul_f32_e64 v119, -v119, s3
	v_mul_f32_e64 v120, -v120, s3
	v_mul_f32_e64 v121, -v121, s3
	v_exp_f32_e32 v118, v118
	v_exp_f32_e32 v119, v119
	v_exp_f32_e32 v120, v120
	v_exp_f32_e32 v121, v121
	v_add_f32_e32 v118, 1.0, v118
	v_add_f32_e32 v119, 1.0, v119
	v_add_f32_e32 v120, 1.0, v120
	v_add_f32_e32 v121, 1.0, v121
	v_rcp_f32_e32 v118, v118
	v_rcp_f32_e32 v120, v120
	v_rcp_f32_e32 v121, v121
	v_rcp_f32_e32 v119, v119
	v_sub_f32_e32 v123, 1.0, v31
	v_sub_f32_e32 v122, 1.0, v30
	v_sub_f32_e32 v125, 1.0, v33
	v_sub_f32_e32 v124, 1.0, v32
	v_pk_mul_f32 v[124:125], v[124:125], v[120:121]
	v_pk_mul_f32 v[122:123], v[122:123], v[118:119]
	s_or_b64 exec, exec, s[54:55]
	s_andn2_saveexec_b64 s[4:5], s[4:5]
	s_or_b64 exec, exec, s[4:5]
	v_mov_b32_e32 v120, v134
	v_mov_b32_e32 v121, v134
	v_pk_fma_f32 v[114:115], v[26:27], v[134:135], v[114:115] neg_lo:[1,0,0] neg_hi:[1,0,0]
	v_pk_fma_f32 v[116:117], v[28:29], v[120:121], v[116:117]
	v_pk_fma_f32 v[114:115], v[72:73], v[114:115], v[22:23]
	v_mov_b32_e32 v73, v72
	v_pk_fma_f32 v[116:117], v[72:73], v[116:117], v[24:25]
	v_cvt_pk_bf16_f32 v118, v122, v123
	v_cvt_pk_bf16_f32 v119, v124, v125
	s_and_saveexec_b64 s[4:5], s[44:45]
	s_xor_b64 s[4:5], exec, s[4:5]
	v_cmp_lt_i32_e32 vcc, 1, v172
	s_mov_b64 s[36:37], 0
	s_mov_b64 s[54:55], 0
	s_and_saveexec_b64 s[56:57], vcc
	s_xor_b64 s[56:57], exec, s[56:57]
	v_cmp_ne_u32_e32 vcc, 2, v172
	s_and_b64 s[54:55], vcc, exec
	s_andn2_saveexec_b64 s[56:57], s[56:57]
	v_cmp_ne_u32_e32 vcc, 1, v172
	s_andn2_b64 s[36:37], s[54:55], exec
	s_and_b64 s[54:55], vcc, exec
	s_or_b64 s[54:55], s[36:37], s[54:55]
	s_mov_b64 s[36:37], exec
	s_or_b64 exec, exec, s[56:57]
	v_mov_b64_e32 v[122:123], v[116:117]
	v_mov_b64_e32 v[120:121], v[114:115]
	s_and_saveexec_b64 s[56:57], s[54:55]
	s_xor_b64 s[54:55], exec, s[56:57]
	s_or_b64 exec, exec, s[54:55]
	s_and_saveexec_b64 s[54:55], s[36:37]
	s_mov_b32 s3, 0xbfb8aa3b
	v_mul_f32_e64 v72, -v114, s3
	v_mul_f32_e64 v115, -v115, s3
	v_mul_f32_e64 v116, -v116, s3
	v_mul_f32_e64 v117, -v117, s3
	v_exp_f32_e32 v114, v72
	v_exp_f32_e32 v115, v115
	v_exp_f32_e32 v116, v116
	v_exp_f32_e32 v117, v117
	v_add_f32_e32 v114, 1.0, v114
	v_add_f32_e32 v115, 1.0, v115
	v_add_f32_e32 v116, 1.0, v116
	v_add_f32_e32 v117, 1.0, v117
	v_rcp_f32_e32 v114, v114
	v_rcp_f32_e32 v116, v116
	v_rcp_f32_e32 v117, v117
	v_rcp_f32_e32 v115, v115
	v_sub_f32_e32 v73, 1.0, v15
	v_sub_f32_e32 v72, 1.0, v14
	v_sub_f32_e32 v121, 1.0, v17
	v_sub_f32_e32 v120, 1.0, v16
	v_pk_mul_f32 v[122:123], v[120:121], v[116:117]
	v_pk_mul_f32 v[120:121], v[72:73], v[114:115]
	s_or_b64 exec, exec, s[54:55]
	s_andn2_saveexec_b64 s[4:5], s[4:5]
	s_or_b64 exec, exec, s[4:5]
	v_add_lshl_u32 v72, v132, v138, 1
	v_cvt_pk_bf16_f32 v120, v120, v121
	v_cvt_pk_bf16_f32 v121, v122, v123
	buffer_store_dwordx4 v[118:121], v72, s[28:31], 0 offen sc1
	s_and_b64 vcc, exec, s[46:47]
	s_nop 0
	v_mov_b32_e32 v121, v206
	s_nop 0
	v_lshl_add_u32 v120, v121, 3, s33
	s_cbranch_vccnz .LBB0_611_sg1
	ds_read_b64 v[118:119], v120
	s_waitcnt lgkmcnt(0)
	v_mov_b32_e32 v72, v119
	s_branch .LBB0_612_sg1

.LBB0_612_sg1:
	v_pk_fma_f32 v[112:113], v[190:191], v[118:119], v[112:113] op_sel_hi:[1,0,1]
	v_pk_fma_f32 v[110:111], v[70:71], v[118:119], v[110:111] op_sel_hi:[1,0,1] neg_lo:[1,0,0] neg_hi:[1,0,0]
	v_pk_fma_f32 v[112:113], v[72:73], v[112:113], v[68:69] op_sel_hi:[0,1,1]
	v_pk_fma_f32 v[110:111], v[72:73], v[110:111], v[66:67] op_sel_hi:[0,1,1]
	s_and_saveexec_b64 s[4:5], s[42:43]
	s_xor_b64 s[4:5], exec, s[4:5]
	v_cmp_lt_i32_e32 vcc, 1, v180
	s_mov_b64 s[36:37], 0
	s_mov_b64 s[54:55], 0
	s_and_saveexec_b64 s[56:57], vcc
	s_xor_b64 s[56:57], exec, s[56:57]
	v_cmp_ne_u32_e32 vcc, 2, v180
	s_and_b64 s[54:55], vcc, exec
	s_andn2_saveexec_b64 s[56:57], s[56:57]
	v_cmp_ne_u32_e32 vcc, 1, v180
	s_andn2_b64 s[36:37], s[54:55], exec
	s_and_b64 s[54:55], vcc, exec
	s_or_b64 s[54:55], s[36:37], s[54:55]
	s_mov_b64 s[36:37], exec
	s_or_b64 exec, exec, s[56:57]
	v_mov_b64_e32 v[116:117], v[112:113]
	v_mov_b64_e32 v[114:115], v[110:111]
	s_and_saveexec_b64 s[56:57], s[54:55]
	s_xor_b64 s[54:55], exec, s[56:57]
	s_or_b64 exec, exec, s[54:55]
	s_and_saveexec_b64 s[54:55], s[36:37]
	s_mov_b32 s3, 0xbfb8aa3b
	v_mul_f32_e64 v73, -v110, s3
	v_exp_f32_e32 v73, v73
	v_mul_f32_e64 v111, -v111, s3
	v_sub_f32_e32 v115, 1.0, v63
	v_sub_f32_e32 v114, 1.0, v62
	v_add_f32_e32 v73, 1.0, v73
	v_rcp_f32_e32 v110, v73
	v_exp_f32_e32 v73, v111
	v_mul_f32_e64 v111, -v112, s3
	v_exp_f32_e32 v111, v111
	v_mul_f32_e64 v112, -v113, s3
	v_exp_f32_e32 v113, v112
	v_add_f32_e32 v73, 1.0, v73
	v_add_f32_e32 v111, 1.0, v111
	v_rcp_f32_e32 v112, v111
	v_add_f32_e32 v111, 1.0, v113
	v_rcp_f32_e32 v113, v111
	v_rcp_f32_e32 v111, v73
	v_sub_f32_e32 v117, 1.0, v65
	v_sub_f32_e32 v116, 1.0, v64
	v_pk_mul_f32 v[116:117], v[116:117], v[112:113]
	v_pk_mul_f32 v[114:115], v[114:115], v[110:111]
	s_or_b64 exec, exec, s[54:55]
	s_andn2_saveexec_b64 s[4:5], s[4:5]
	s_or_b64 exec, exec, s[4:5]
	v_mov_b32_e32 v119, v118
	v_mov_b32_e32 v112, v118
	v_mov_b32_e32 v113, v118
	v_mov_b32_e32 v73, v72
	v_pk_fma_f32 v[108:109], v[60:61], v[112:113], v[108:109]
	v_pk_fma_f32 v[106:107], v[58:59], v[118:119], v[106:107] neg_lo:[1,0,0] neg_hi:[1,0,0]
	v_mov_b32_e32 v112, v72
	v_mov_b32_e32 v113, v72
	v_pk_fma_f32 v[106:107], v[72:73], v[106:107], v[54:55]
	v_pk_fma_f32 v[108:109], v[112:113], v[108:109], v[56:57]
	v_cvt_pk_bf16_f32 v110, v114, v115
	v_cvt_pk_bf16_f32 v111, v116, v117
	s_and_saveexec_b64 s[4:5], s[42:43]
	s_xor_b64 s[4:5], exec, s[4:5]
	v_cmp_lt_i32_e32 vcc, 1, v180
	s_mov_b64 s[36:37], 0
	s_mov_b64 s[54:55], 0
	s_and_saveexec_b64 s[56:57], vcc
	s_xor_b64 s[56:57], exec, s[56:57]
	v_cmp_ne_u32_e32 vcc, 2, v180
	s_and_b64 s[54:55], vcc, exec
	s_andn2_saveexec_b64 s[56:57], s[56:57]
	v_cmp_ne_u32_e32 vcc, 1, v180
	s_andn2_b64 s[36:37], s[54:55], exec
	s_and_b64 s[54:55], vcc, exec
	s_or_b64 s[54:55], s[36:37], s[54:55]
	s_mov_b64 s[36:37], exec
	s_or_b64 exec, exec, s[56:57]
	v_mov_b64_e32 v[114:115], v[108:109]
	v_mov_b64_e32 v[112:113], v[106:107]
	s_and_saveexec_b64 s[56:57], s[54:55]
	s_xor_b64 s[54:55], exec, s[56:57]
	s_or_b64 exec, exec, s[54:55]
	s_and_saveexec_b64 s[54:55], s[36:37]
	s_mov_b32 s3, 0xbfb8aa3b
	v_mul_f32_e64 v106, -v106, s3
	v_mul_f32_e64 v107, -v107, s3
	v_mul_f32_e64 v108, -v108, s3
	v_mul_f32_e64 v109, -v109, s3
	v_exp_f32_e32 v106, v106
	v_exp_f32_e32 v107, v107
	v_exp_f32_e32 v108, v108
	v_exp_f32_e32 v109, v109
	v_add_f32_e32 v106, 1.0, v106
	v_add_f32_e32 v107, 1.0, v107
	v_add_f32_e32 v108, 1.0, v108
	v_add_f32_e32 v109, 1.0, v109
	v_rcp_f32_e32 v106, v106
	v_rcp_f32_e32 v108, v108
	v_rcp_f32_e32 v109, v109
	v_rcp_f32_e32 v107, v107
	v_sub_f32_e32 v113, 1.0, v47
	v_sub_f32_e32 v112, 1.0, v46
	v_sub_f32_e32 v115, 1.0, v49
	v_sub_f32_e32 v114, 1.0, v48
	v_pk_mul_f32 v[114:115], v[114:115], v[108:109]
	v_pk_mul_f32 v[112:113], v[112:113], v[106:107]
	s_or_b64 exec, exec, s[54:55]
	s_andn2_saveexec_b64 s[4:5], s[4:5]
	s_or_b64 exec, exec, s[4:5]
	v_add_lshl_u32 v116, v121, s51, 10
	v_add_lshl_u32 v106, v116, v146, 1
	v_cvt_pk_bf16_f32 v112, v112, v113
	v_cvt_pk_bf16_f32 v113, v114, v115
	buffer_store_dwordx4 v[110:113], v106, s[28:31], 0 offen sc1
	v_mov_b32_e32 v106, v118
	v_mov_b32_e32 v107, v118
	v_pk_fma_f32 v[104:105], v[44:45], v[106:107], v[104:105]
	v_pk_fma_f32 v[102:103], v[42:43], v[118:119], v[102:103] neg_lo:[1,0,0] neg_hi:[1,0,0]
	v_mov_b32_e32 v106, v72
	v_mov_b32_e32 v107, v72
	v_pk_fma_f32 v[102:103], v[72:73], v[102:103], v[38:39]
	v_pk_fma_f32 v[104:105], v[106:107], v[104:105], v[40:41]
	s_and_saveexec_b64 s[4:5], s[44:45]
	s_xor_b64 s[4:5], exec, s[4:5]
	v_cmp_lt_i32_e32 vcc, 1, v172
	s_mov_b64 s[36:37], 0
	s_mov_b64 s[54:55], 0
	s_and_saveexec_b64 s[56:57], vcc
	s_xor_b64 s[56:57], exec, s[56:57]
	v_cmp_ne_u32_e32 vcc, 2, v172
	s_and_b64 s[54:55], vcc, exec
	s_andn2_saveexec_b64 s[56:57], s[56:57]
	v_cmp_ne_u32_e32 vcc, 1, v172
	s_andn2_b64 s[36:37], s[54:55], exec
	s_and_b64 s[54:55], vcc, exec
	s_or_b64 s[54:55], s[36:37], s[54:55]
	s_mov_b64 s[36:37], exec
	s_or_b64 exec, exec, s[56:57]
	v_mov_b64_e32 v[108:109], v[104:105]
	v_mov_b64_e32 v[106:107], v[102:103]
	s_and_saveexec_b64 s[56:57], s[54:55]
	s_xor_b64 s[54:55], exec, s[56:57]
	s_or_b64 exec, exec, s[54:55]
	s_and_saveexec_b64 s[54:55], s[36:37]
	s_mov_b32 s3, 0xbfb8aa3b
	v_mul_f32_e64 v102, -v102, s3
	v_mul_f32_e64 v103, -v103, s3
	v_mul_f32_e64 v104, -v104, s3
	v_mul_f32_e64 v105, -v105, s3
	v_exp_f32_e32 v102, v102
	v_exp_f32_e32 v103, v103
	v_exp_f32_e32 v104, v104
	v_exp_f32_e32 v105, v105
	v_add_f32_e32 v102, 1.0, v102
	v_add_f32_e32 v103, 1.0, v103
	v_add_f32_e32 v104, 1.0, v104
	v_add_f32_e32 v105, 1.0, v105
	v_rcp_f32_e32 v102, v102
	v_rcp_f32_e32 v104, v104
	v_rcp_f32_e32 v105, v105
	v_rcp_f32_e32 v103, v103
	v_sub_f32_e32 v107, 1.0, v31
	v_sub_f32_e32 v106, 1.0, v30
	v_sub_f32_e32 v109, 1.0, v33
	v_sub_f32_e32 v108, 1.0, v32
	v_pk_mul_f32 v[108:109], v[108:109], v[104:105]
	v_pk_mul_f32 v[106:107], v[106:107], v[102:103]
	s_or_b64 exec, exec, s[54:55]
	s_andn2_saveexec_b64 s[4:5], s[4:5]
	s_or_b64 exec, exec, s[4:5]
	v_mov_b32_e32 v104, v118
	v_mov_b32_e32 v105, v118
	v_pk_fma_f32 v[98:99], v[26:27], v[118:119], v[98:99] neg_lo:[1,0,0] neg_hi:[1,0,0]
	v_pk_fma_f32 v[100:101], v[28:29], v[104:105], v[100:101]
	v_pk_fma_f32 v[98:99], v[72:73], v[98:99], v[22:23]
	v_mov_b32_e32 v73, v72
	v_pk_fma_f32 v[100:101], v[72:73], v[100:101], v[24:25]
	v_cvt_pk_bf16_f32 v102, v106, v107
	v_cvt_pk_bf16_f32 v103, v108, v109
	s_and_saveexec_b64 s[4:5], s[44:45]
	s_xor_b64 s[4:5], exec, s[4:5]
	v_cmp_lt_i32_e32 vcc, 1, v172
	s_mov_b64 s[36:37], 0
	s_mov_b64 s[54:55], 0
	s_and_saveexec_b64 s[56:57], vcc
	s_xor_b64 s[56:57], exec, s[56:57]
	v_cmp_ne_u32_e32 vcc, 2, v172
	s_and_b64 s[54:55], vcc, exec
	s_andn2_saveexec_b64 s[56:57], s[56:57]
	v_cmp_ne_u32_e32 vcc, 1, v172
	s_andn2_b64 s[36:37], s[54:55], exec
	s_and_b64 s[54:55], vcc, exec
	s_or_b64 s[54:55], s[36:37], s[54:55]
	s_mov_b64 s[36:37], exec
	s_or_b64 exec, exec, s[56:57]
	v_mov_b64_e32 v[106:107], v[100:101]
	v_mov_b64_e32 v[104:105], v[98:99]
	s_and_saveexec_b64 s[56:57], s[54:55]
	s_xor_b64 s[54:55], exec, s[56:57]
	s_or_b64 exec, exec, s[54:55]
	s_and_saveexec_b64 s[54:55], s[36:37]
	s_mov_b32 s3, 0xbfb8aa3b
	v_mul_f32_e64 v72, -v98, s3
	v_mul_f32_e64 v99, -v99, s3
	v_mul_f32_e64 v100, -v100, s3
	v_mul_f32_e64 v101, -v101, s3
	v_exp_f32_e32 v98, v72
	v_exp_f32_e32 v99, v99
	v_exp_f32_e32 v100, v100
	v_exp_f32_e32 v101, v101
	v_add_f32_e32 v98, 1.0, v98
	v_add_f32_e32 v99, 1.0, v99
	v_add_f32_e32 v100, 1.0, v100
	v_add_f32_e32 v101, 1.0, v101
	v_rcp_f32_e32 v98, v98
	v_rcp_f32_e32 v100, v100
	v_rcp_f32_e32 v101, v101
	v_rcp_f32_e32 v99, v99
	v_sub_f32_e32 v73, 1.0, v15
	v_sub_f32_e32 v72, 1.0, v14
	v_sub_f32_e32 v105, 1.0, v17
	v_sub_f32_e32 v104, 1.0, v16
	v_pk_mul_f32 v[106:107], v[104:105], v[100:101]
	v_pk_mul_f32 v[104:105], v[72:73], v[98:99]
	s_or_b64 exec, exec, s[54:55]
	s_andn2_saveexec_b64 s[4:5], s[4:5]
	s_or_b64 exec, exec, s[4:5]
	v_add_lshl_u32 v72, v116, v138, 1
	s_and_b64 vcc, exec, s[46:47]
	v_cvt_pk_bf16_f32 v104, v104, v105
	v_cvt_pk_bf16_f32 v105, v106, v107
	buffer_store_dwordx4 v[102:105], v72, s[28:31], 0 offen sc1
	s_cbranch_vccnz .LBB0_662_sg1
	ds_read_b64 v[102:103], v120 offset:128
	s_waitcnt lgkmcnt(0)
	v_mov_b32_e32 v72, v103
	s_branch .LBB0_663_sg1

.LBB0_663_sg1:
	v_pk_fma_f32 v[96:97], v[190:191], v[102:103], v[96:97] op_sel_hi:[1,0,1]
	v_pk_fma_f32 v[94:95], v[70:71], v[102:103], v[94:95] op_sel_hi:[1,0,1] neg_lo:[1,0,0] neg_hi:[1,0,0]
	v_pk_fma_f32 v[96:97], v[72:73], v[96:97], v[68:69] op_sel_hi:[0,1,1]
	v_pk_fma_f32 v[94:95], v[72:73], v[94:95], v[66:67] op_sel_hi:[0,1,1]
	s_and_saveexec_b64 s[4:5], s[42:43]
	s_xor_b64 s[4:5], exec, s[4:5]
	v_cmp_lt_i32_e32 vcc, 1, v180
	s_mov_b64 s[36:37], 0
	s_mov_b64 s[54:55], 0
	s_and_saveexec_b64 s[56:57], vcc
	s_xor_b64 s[56:57], exec, s[56:57]
	v_cmp_ne_u32_e32 vcc, 2, v180
	s_and_b64 s[54:55], vcc, exec
	s_andn2_saveexec_b64 s[56:57], s[56:57]
	v_cmp_ne_u32_e32 vcc, 1, v180
	s_andn2_b64 s[36:37], s[54:55], exec
	s_and_b64 s[54:55], vcc, exec
	s_or_b64 s[54:55], s[36:37], s[54:55]
	s_mov_b64 s[36:37], exec
	s_or_b64 exec, exec, s[56:57]
	v_mov_b64_e32 v[100:101], v[96:97]
	v_mov_b64_e32 v[98:99], v[94:95]
	s_and_saveexec_b64 s[56:57], s[54:55]
	s_xor_b64 s[54:55], exec, s[56:57]
	s_or_b64 exec, exec, s[54:55]
	s_and_saveexec_b64 s[54:55], s[36:37]
	s_mov_b32 s3, 0xbfb8aa3b
	v_mul_f32_e64 v73, -v94, s3
	v_exp_f32_e32 v73, v73
	v_mul_f32_e64 v95, -v95, s3
	v_sub_f32_e32 v99, 1.0, v63
	v_sub_f32_e32 v98, 1.0, v62
	v_add_f32_e32 v73, 1.0, v73
	v_rcp_f32_e32 v94, v73
	v_exp_f32_e32 v73, v95
	v_mul_f32_e64 v95, -v96, s3
	v_exp_f32_e32 v95, v95
	v_mul_f32_e64 v96, -v97, s3
	v_exp_f32_e32 v97, v96
	v_add_f32_e32 v73, 1.0, v73
	v_add_f32_e32 v95, 1.0, v95
	v_rcp_f32_e32 v96, v95
	v_add_f32_e32 v95, 1.0, v97
	v_rcp_f32_e32 v97, v95
	v_rcp_f32_e32 v95, v73
	v_sub_f32_e32 v101, 1.0, v65
	v_sub_f32_e32 v100, 1.0, v64
	v_pk_mul_f32 v[100:101], v[100:101], v[96:97]
	v_pk_mul_f32 v[98:99], v[98:99], v[94:95]
	s_or_b64 exec, exec, s[54:55]
	s_andn2_saveexec_b64 s[4:5], s[4:5]
	s_or_b64 exec, exec, s[4:5]
	v_mov_b32_e32 v103, v102
	v_mov_b32_e32 v96, v102
	v_mov_b32_e32 v97, v102
	v_mov_b32_e32 v73, v72
	v_pk_fma_f32 v[92:93], v[60:61], v[96:97], v[92:93]
	v_pk_fma_f32 v[90:91], v[58:59], v[102:103], v[90:91] neg_lo:[1,0,0] neg_hi:[1,0,0]
	v_mov_b32_e32 v96, v72
	v_mov_b32_e32 v97, v72
	v_pk_fma_f32 v[90:91], v[72:73], v[90:91], v[54:55]
	v_pk_fma_f32 v[92:93], v[96:97], v[92:93], v[56:57]
	v_cvt_pk_bf16_f32 v94, v98, v99
	v_cvt_pk_bf16_f32 v95, v100, v101
	s_and_saveexec_b64 s[4:5], s[42:43]
	s_xor_b64 s[4:5], exec, s[4:5]
	v_cmp_lt_i32_e32 vcc, 1, v180
	s_mov_b64 s[36:37], 0
	s_mov_b64 s[54:55], 0
	s_and_saveexec_b64 s[56:57], vcc
	s_xor_b64 s[56:57], exec, s[56:57]
	v_cmp_ne_u32_e32 vcc, 2, v180
	s_and_b64 s[54:55], vcc, exec
	s_andn2_saveexec_b64 s[56:57], s[56:57]
	v_cmp_ne_u32_e32 vcc, 1, v180
	s_andn2_b64 s[36:37], s[54:55], exec
	s_and_b64 s[54:55], vcc, exec
	s_or_b64 s[54:55], s[36:37], s[54:55]
	s_mov_b64 s[36:37], exec
	s_or_b64 exec, exec, s[56:57]
	v_mov_b64_e32 v[98:99], v[92:93]
	v_mov_b64_e32 v[96:97], v[90:91]
	s_and_saveexec_b64 s[56:57], s[54:55]
	s_xor_b64 s[54:55], exec, s[56:57]
	s_or_b64 exec, exec, s[54:55]
	s_and_saveexec_b64 s[54:55], s[36:37]
	s_mov_b32 s3, 0xbfb8aa3b
	v_mul_f32_e64 v90, -v90, s3
	v_mul_f32_e64 v91, -v91, s3
	v_mul_f32_e64 v92, -v92, s3
	v_mul_f32_e64 v93, -v93, s3
	v_exp_f32_e32 v90, v90
	v_exp_f32_e32 v91, v91
	v_exp_f32_e32 v92, v92
	v_exp_f32_e32 v93, v93
	v_add_f32_e32 v90, 1.0, v90
	v_add_f32_e32 v91, 1.0, v91
	v_add_f32_e32 v92, 1.0, v92
	v_add_f32_e32 v93, 1.0, v93
	v_rcp_f32_e32 v90, v90
	v_rcp_f32_e32 v92, v92
	v_rcp_f32_e32 v93, v93
	v_rcp_f32_e32 v91, v91
	v_sub_f32_e32 v97, 1.0, v47
	v_sub_f32_e32 v96, 1.0, v46
	v_sub_f32_e32 v99, 1.0, v49
	v_sub_f32_e32 v98, 1.0, v48
	v_pk_mul_f32 v[98:99], v[98:99], v[92:93]
	v_pk_mul_f32 v[96:97], v[96:97], v[90:91]
	s_or_b64 exec, exec, s[54:55]
	s_andn2_saveexec_b64 s[4:5], s[4:5]
	s_or_b64 exec, exec, s[4:5]
	v_add_u32_e32 v100, 0x4000, v116
	v_add_lshl_u32 v90, v100, v146, 1
	v_cvt_pk_bf16_f32 v96, v96, v97
	v_cvt_pk_bf16_f32 v97, v98, v99
	buffer_store_dwordx4 v[94:97], v90, s[28:31], 0 offen sc1
	v_mov_b32_e32 v90, v102
	v_mov_b32_e32 v91, v102
	v_pk_fma_f32 v[88:89], v[44:45], v[90:91], v[88:89]
	v_pk_fma_f32 v[86:87], v[42:43], v[102:103], v[86:87] neg_lo:[1,0,0] neg_hi:[1,0,0]
	v_mov_b32_e32 v90, v72
	v_mov_b32_e32 v91, v72
	v_pk_fma_f32 v[86:87], v[72:73], v[86:87], v[38:39]
	v_pk_fma_f32 v[88:89], v[90:91], v[88:89], v[40:41]
	s_and_saveexec_b64 s[4:5], s[44:45]
	s_xor_b64 s[4:5], exec, s[4:5]
	v_cmp_lt_i32_e32 vcc, 1, v172
	s_mov_b64 s[36:37], 0
	s_mov_b64 s[54:55], 0
	s_and_saveexec_b64 s[56:57], vcc
	s_xor_b64 s[56:57], exec, s[56:57]
	v_cmp_ne_u32_e32 vcc, 2, v172
	s_and_b64 s[54:55], vcc, exec
	s_andn2_saveexec_b64 s[56:57], s[56:57]
	v_cmp_ne_u32_e32 vcc, 1, v172
	s_andn2_b64 s[36:37], s[54:55], exec
	s_and_b64 s[54:55], vcc, exec
	s_or_b64 s[54:55], s[36:37], s[54:55]
	s_mov_b64 s[36:37], exec
	s_or_b64 exec, exec, s[56:57]
	v_mov_b64_e32 v[92:93], v[88:89]
	v_mov_b64_e32 v[90:91], v[86:87]
	s_and_saveexec_b64 s[56:57], s[54:55]
	s_xor_b64 s[54:55], exec, s[56:57]
	s_or_b64 exec, exec, s[54:55]
	s_and_saveexec_b64 s[54:55], s[36:37]
	s_mov_b32 s3, 0xbfb8aa3b
	v_mul_f32_e64 v86, -v86, s3
	v_mul_f32_e64 v87, -v87, s3
	v_mul_f32_e64 v88, -v88, s3
	v_mul_f32_e64 v89, -v89, s3
	v_exp_f32_e32 v86, v86
	v_exp_f32_e32 v87, v87
	v_exp_f32_e32 v88, v88
	v_exp_f32_e32 v89, v89
	v_add_f32_e32 v86, 1.0, v86
	v_add_f32_e32 v87, 1.0, v87
	v_add_f32_e32 v88, 1.0, v88
	v_add_f32_e32 v89, 1.0, v89
	v_rcp_f32_e32 v86, v86
	v_rcp_f32_e32 v88, v88
	v_rcp_f32_e32 v89, v89
	v_rcp_f32_e32 v87, v87
	v_sub_f32_e32 v91, 1.0, v31
	v_sub_f32_e32 v90, 1.0, v30
	v_sub_f32_e32 v93, 1.0, v33
	v_sub_f32_e32 v92, 1.0, v32
	v_pk_mul_f32 v[92:93], v[92:93], v[88:89]
	v_pk_mul_f32 v[90:91], v[90:91], v[86:87]
	s_or_b64 exec, exec, s[54:55]
	s_andn2_saveexec_b64 s[4:5], s[4:5]
	s_or_b64 exec, exec, s[4:5]
	v_mov_b32_e32 v88, v102
	v_mov_b32_e32 v89, v102
	v_pk_fma_f32 v[82:83], v[26:27], v[102:103], v[82:83] neg_lo:[1,0,0] neg_hi:[1,0,0]
	v_pk_fma_f32 v[84:85], v[28:29], v[88:89], v[84:85]
	v_pk_fma_f32 v[82:83], v[72:73], v[82:83], v[22:23]
	v_mov_b32_e32 v73, v72
	v_pk_fma_f32 v[84:85], v[72:73], v[84:85], v[24:25]
	v_cvt_pk_bf16_f32 v86, v90, v91
	v_cvt_pk_bf16_f32 v87, v92, v93
	s_and_saveexec_b64 s[4:5], s[44:45]
	s_xor_b64 s[4:5], exec, s[4:5]
	v_cmp_lt_i32_e32 vcc, 1, v172
	s_mov_b64 s[36:37], 0
	s_mov_b64 s[54:55], 0
	s_and_saveexec_b64 s[56:57], vcc
	s_xor_b64 s[56:57], exec, s[56:57]
	v_cmp_ne_u32_e32 vcc, 2, v172
	s_and_b64 s[54:55], vcc, exec
	s_andn2_saveexec_b64 s[56:57], s[56:57]
	v_cmp_ne_u32_e32 vcc, 1, v172
	s_andn2_b64 s[36:37], s[54:55], exec
	s_and_b64 s[54:55], vcc, exec
	s_or_b64 s[54:55], s[36:37], s[54:55]
	s_mov_b64 s[36:37], exec
	s_or_b64 exec, exec, s[56:57]
	v_mov_b64_e32 v[90:91], v[84:85]
	v_mov_b64_e32 v[88:89], v[82:83]
	s_and_saveexec_b64 s[56:57], s[54:55]
	s_xor_b64 s[54:55], exec, s[56:57]
	s_or_b64 exec, exec, s[54:55]
	s_and_saveexec_b64 s[54:55], s[36:37]
	s_mov_b32 s3, 0xbfb8aa3b
	v_mul_f32_e64 v72, -v82, s3
	v_mul_f32_e64 v83, -v83, s3
	v_mul_f32_e64 v84, -v84, s3
	v_mul_f32_e64 v85, -v85, s3
	v_exp_f32_e32 v82, v72
	v_exp_f32_e32 v83, v83
	v_exp_f32_e32 v84, v84
	v_exp_f32_e32 v85, v85
	v_add_f32_e32 v82, 1.0, v82
	v_add_f32_e32 v83, 1.0, v83
	v_add_f32_e32 v84, 1.0, v84
	v_add_f32_e32 v85, 1.0, v85
	v_rcp_f32_e32 v82, v82
	v_rcp_f32_e32 v84, v84
	v_rcp_f32_e32 v85, v85
	v_rcp_f32_e32 v83, v83
	v_sub_f32_e32 v73, 1.0, v15
	v_sub_f32_e32 v72, 1.0, v14
	v_sub_f32_e32 v89, 1.0, v17
	v_sub_f32_e32 v88, 1.0, v16
	v_pk_mul_f32 v[90:91], v[88:89], v[84:85]
	v_pk_mul_f32 v[88:89], v[72:73], v[82:83]
	s_or_b64 exec, exec, s[54:55]
	s_andn2_saveexec_b64 s[4:5], s[4:5]
	s_or_b64 exec, exec, s[4:5]
	v_add_lshl_u32 v72, v100, v138, 1
	v_cvt_pk_bf16_f32 v88, v88, v89
	v_cvt_pk_bf16_f32 v89, v90, v91
	buffer_store_dwordx4 v[86:89], v72, s[28:31], 0 offen sc1
	v_mov_b32_e32 v91, v207
	s_and_b64 vcc, exec, s[46:47]
	v_lshl_add_u32 v90, v91, 3, s33
	s_cbranch_vccnz .LBB0_713_sg1
	ds_read_b64 v[88:89], v90
	s_waitcnt lgkmcnt(0)
	v_mov_b32_e32 v86, v89
	s_branch .LBB0_714_sg1

.LBB0_714_sg1:
	v_pk_fma_f32 v[72:73], v[190:191], v[88:89], v[80:81] op_sel_hi:[1,0,1]
	v_pk_fma_f32 v[78:79], v[70:71], v[88:89], v[78:79] op_sel_hi:[1,0,1] neg_lo:[1,0,0] neg_hi:[1,0,0]
	v_pk_fma_f32 v[80:81], v[86:87], v[72:73], v[68:69] op_sel_hi:[0,1,1]
	v_pk_fma_f32 v[78:79], v[86:87], v[78:79], v[66:67] op_sel_hi:[0,1,1]
	s_and_saveexec_b64 s[4:5], s[42:43]
	s_xor_b64 s[4:5], exec, s[4:5]
	v_cmp_lt_i32_e32 vcc, 1, v180
	s_mov_b64 s[36:37], 0
	s_mov_b64 s[54:55], 0
	s_and_saveexec_b64 s[56:57], vcc
	s_xor_b64 s[56:57], exec, s[56:57]
	v_cmp_ne_u32_e32 vcc, 2, v180
	s_and_b64 s[54:55], vcc, exec
	s_andn2_saveexec_b64 s[56:57], s[56:57]
	v_cmp_ne_u32_e32 vcc, 1, v180
	s_andn2_b64 s[36:37], s[54:55], exec
	s_and_b64 s[54:55], vcc, exec
	s_or_b64 s[54:55], s[36:37], s[54:55]
	s_mov_b64 s[36:37], exec
	s_or_b64 exec, exec, s[56:57]
	v_mov_b64_e32 v[84:85], v[80:81]
	v_mov_b64_e32 v[82:83], v[78:79]
	s_and_saveexec_b64 s[56:57], s[54:55]
	s_xor_b64 s[54:55], exec, s[56:57]
	s_or_b64 exec, exec, s[54:55]
	s_and_saveexec_b64 s[54:55], s[36:37]
	s_mov_b32 s3, 0xbfb8aa3b
	v_mul_f32_e64 v72, -v78, s3
	v_mul_f32_e64 v79, -v79, s3
	v_mul_f32_e64 v80, -v80, s3
	v_mul_f32_e64 v81, -v81, s3
	v_exp_f32_e32 v78, v72
	v_exp_f32_e32 v79, v79
	v_exp_f32_e32 v80, v80
	v_exp_f32_e32 v81, v81
	v_add_f32_e32 v78, 1.0, v78
	v_add_f32_e32 v79, 1.0, v79
	v_add_f32_e32 v80, 1.0, v80
	v_add_f32_e32 v81, 1.0, v81
	v_rcp_f32_e32 v78, v78
	v_rcp_f32_e32 v80, v80
	v_rcp_f32_e32 v81, v81
	v_rcp_f32_e32 v79, v79
	v_sub_f32_e32 v73, 1.0, v63
	v_sub_f32_e32 v72, 1.0, v62
	v_sub_f32_e32 v83, 1.0, v65
	v_sub_f32_e32 v82, 1.0, v64
	v_pk_mul_f32 v[84:85], v[82:83], v[80:81]
	v_pk_mul_f32 v[82:83], v[72:73], v[78:79]
	s_or_b64 exec, exec, s[54:55]
	s_andn2_saveexec_b64 s[4:5], s[4:5]
	s_or_b64 exec, exec, s[4:5]
	v_mov_b32_e32 v89, v88
	v_mov_b32_e32 v78, v88
	v_mov_b32_e32 v79, v88
	v_mov_b32_e32 v87, v86
	v_pk_fma_f32 v[76:77], v[60:61], v[78:79], v[76:77]
	v_pk_fma_f32 v[74:75], v[58:59], v[88:89], v[74:75] neg_lo:[1,0,0] neg_hi:[1,0,0]
	v_mov_b32_e32 v78, v86
	v_mov_b32_e32 v79, v86
	v_pk_fma_f32 v[74:75], v[86:87], v[74:75], v[54:55]
	v_pk_fma_f32 v[76:77], v[78:79], v[76:77], v[56:57]
	v_cvt_pk_bf16_f32 v72, v82, v83
	v_cvt_pk_bf16_f32 v73, v84, v85
	s_and_saveexec_b64 s[4:5], s[42:43]
	s_xor_b64 s[4:5], exec, s[4:5]
	v_cmp_lt_i32_e32 vcc, 1, v180
	s_mov_b64 s[36:37], 0
	s_mov_b64 s[54:55], 0
	s_and_saveexec_b64 s[56:57], vcc
	s_xor_b64 s[56:57], exec, s[56:57]
	v_cmp_ne_u32_e32 vcc, 2, v180
	s_and_b64 s[54:55], vcc, exec
	s_andn2_saveexec_b64 s[56:57], s[56:57]
	v_cmp_ne_u32_e32 vcc, 1, v180
	s_andn2_b64 s[36:37], s[54:55], exec
	s_and_b64 s[54:55], vcc, exec
	s_or_b64 s[54:55], s[36:37], s[54:55]
	s_mov_b64 s[36:37], exec
	s_or_b64 exec, exec, s[56:57]
	v_mov_b64_e32 v[80:81], v[76:77]
	v_mov_b64_e32 v[78:79], v[74:75]
	s_and_saveexec_b64 s[56:57], s[54:55]
	s_xor_b64 s[54:55], exec, s[56:57]
	s_or_b64 exec, exec, s[54:55]
	s_and_saveexec_b64 s[54:55], s[36:37]
	s_mov_b32 s3, 0xbfb8aa3b
	v_mul_f32_e64 v74, -v74, s3
	v_mul_f32_e64 v75, -v75, s3
	v_mul_f32_e64 v76, -v76, s3
	v_mul_f32_e64 v77, -v77, s3
	v_exp_f32_e32 v74, v74
	v_exp_f32_e32 v75, v75
	v_exp_f32_e32 v76, v76
	v_exp_f32_e32 v77, v77
	v_add_f32_e32 v74, 1.0, v74
	v_add_f32_e32 v75, 1.0, v75
	v_add_f32_e32 v76, 1.0, v76
	v_add_f32_e32 v77, 1.0, v77
	v_rcp_f32_e32 v74, v74
	v_rcp_f32_e32 v76, v76
	v_rcp_f32_e32 v77, v77
	v_rcp_f32_e32 v75, v75
	v_sub_f32_e32 v79, 1.0, v47
	v_sub_f32_e32 v78, 1.0, v46
	v_sub_f32_e32 v81, 1.0, v49
	v_sub_f32_e32 v80, 1.0, v48
	v_pk_mul_f32 v[80:81], v[80:81], v[76:77]
	v_pk_mul_f32 v[78:79], v[78:79], v[74:75]
	s_or_b64 exec, exec, s[54:55]
	s_andn2_saveexec_b64 s[4:5], s[4:5]
	s_or_b64 exec, exec, s[4:5]
	v_add_lshl_u32 v76, v91, s51, 10
	v_add_lshl_u32 v77, v76, v146, 1
	v_cvt_pk_bf16_f32 v74, v78, v79
	v_cvt_pk_bf16_f32 v75, v80, v81
	buffer_store_dwordx4 v[72:75], v77, s[28:31], 0 offen sc1
	v_pk_fma_f32 v[50:51], v[42:43], v[88:89], v[50:51] neg_lo:[1,0,0] neg_hi:[1,0,0]
	s_nop 0
	v_mov_b32_e32 v72, v88
	v_mov_b32_e32 v73, v88
	v_pk_fma_f32 v[52:53], v[44:45], v[72:73], v[52:53]
	v_mov_b32_e32 v72, v86
	v_mov_b32_e32 v73, v86
	v_pk_fma_f32 v[50:51], v[86:87], v[50:51], v[38:39]
	v_pk_fma_f32 v[52:53], v[72:73], v[52:53], v[40:41]
	s_and_saveexec_b64 s[4:5], s[44:45]
	s_xor_b64 s[4:5], exec, s[4:5]
	v_cmp_lt_i32_e32 vcc, 1, v172
	s_mov_b64 s[36:37], 0
	s_mov_b64 s[54:55], 0
	s_and_saveexec_b64 s[56:57], vcc
	s_xor_b64 s[56:57], exec, s[56:57]
	v_cmp_ne_u32_e32 vcc, 2, v172
	s_and_b64 s[54:55], vcc, exec
	s_andn2_saveexec_b64 s[56:57], s[56:57]
	v_cmp_ne_u32_e32 vcc, 1, v172
	s_andn2_b64 s[36:37], s[54:55], exec
	s_and_b64 s[54:55], vcc, exec
	s_or_b64 s[54:55], s[36:37], s[54:55]
	s_mov_b64 s[36:37], exec
	s_or_b64 exec, exec, s[56:57]
	v_mov_b64_e32 v[74:75], v[52:53]
	v_mov_b64_e32 v[72:73], v[50:51]
	s_and_saveexec_b64 s[56:57], s[54:55]
	s_xor_b64 s[54:55], exec, s[56:57]
	s_or_b64 exec, exec, s[54:55]
	s_and_saveexec_b64 s[54:55], s[36:37]
	s_mov_b32 s3, 0xbfb8aa3b
	v_mul_f32_e64 v50, -v50, s3
	v_mul_f32_e64 v51, -v51, s3
	v_mul_f32_e64 v52, -v52, s3
	v_mul_f32_e64 v53, -v53, s3
	v_exp_f32_e32 v50, v50
	v_exp_f32_e32 v51, v51
	v_exp_f32_e32 v52, v52
	v_exp_f32_e32 v53, v53
	v_add_f32_e32 v50, 1.0, v50
	v_add_f32_e32 v51, 1.0, v51
	v_add_f32_e32 v52, 1.0, v52
	v_add_f32_e32 v53, 1.0, v53
	v_rcp_f32_e32 v50, v50
	v_rcp_f32_e32 v52, v52
	v_rcp_f32_e32 v53, v53
	v_rcp_f32_e32 v51, v51
	v_sub_f32_e32 v73, 1.0, v31
	v_sub_f32_e32 v72, 1.0, v30
	v_sub_f32_e32 v75, 1.0, v33
	v_sub_f32_e32 v74, 1.0, v32
	v_pk_mul_f32 v[74:75], v[74:75], v[52:53]
	v_pk_mul_f32 v[72:73], v[72:73], v[50:51]
	s_or_b64 exec, exec, s[54:55]
	s_andn2_saveexec_b64 s[4:5], s[4:5]
	s_or_b64 exec, exec, s[4:5]
	v_mov_b32_e32 v52, v88
	v_mov_b32_e32 v53, v88
	v_pk_fma_f32 v[34:35], v[26:27], v[88:89], v[34:35] neg_lo:[1,0,0] neg_hi:[1,0,0]
	v_pk_fma_f32 v[36:37], v[28:29], v[52:53], v[36:37]
	v_pk_fma_f32 v[34:35], v[86:87], v[34:35], v[22:23]
	v_mov_b32_e32 v87, v86
	v_pk_fma_f32 v[36:37], v[86:87], v[36:37], v[24:25]
	v_cvt_pk_bf16_f32 v50, v72, v73
	v_cvt_pk_bf16_f32 v51, v74, v75
	s_and_saveexec_b64 s[4:5], s[44:45]
	s_xor_b64 s[4:5], exec, s[4:5]
	v_cmp_lt_i32_e32 vcc, 1, v172
	s_mov_b64 s[36:37], 0
	s_mov_b64 s[54:55], 0
	s_and_saveexec_b64 s[56:57], vcc
	s_xor_b64 s[56:57], exec, s[56:57]
	v_cmp_ne_u32_e32 vcc, 2, v172
	s_and_b64 s[54:55], vcc, exec
	s_andn2_saveexec_b64 s[56:57], s[56:57]
	v_cmp_ne_u32_e32 vcc, 1, v172
	s_andn2_b64 s[36:37], s[54:55], exec
	s_and_b64 s[54:55], vcc, exec
	s_or_b64 s[54:55], s[36:37], s[54:55]
	s_mov_b64 s[36:37], exec
	s_or_b64 exec, exec, s[56:57]
	v_mov_b64_e32 v[74:75], v[36:37]
	v_mov_b64_e32 v[72:73], v[34:35]
	s_and_saveexec_b64 s[56:57], s[54:55]
	s_xor_b64 s[54:55], exec, s[56:57]
	s_or_b64 exec, exec, s[54:55]
	s_and_saveexec_b64 s[54:55], s[36:37]
	s_mov_b32 s3, 0xbfb8aa3b
	v_mul_f32_e64 v34, -v34, s3
	v_mul_f32_e64 v35, -v35, s3
	v_mul_f32_e64 v36, -v36, s3
	v_mul_f32_e64 v37, -v37, s3
	v_exp_f32_e32 v34, v34
	v_exp_f32_e32 v35, v35
	v_exp_f32_e32 v36, v36
	v_exp_f32_e32 v37, v37
	v_add_f32_e32 v34, 1.0, v34
	v_add_f32_e32 v35, 1.0, v35
	v_add_f32_e32 v36, 1.0, v36
	v_add_f32_e32 v37, 1.0, v37
	v_rcp_f32_e32 v34, v34
	v_rcp_f32_e32 v36, v36
	v_rcp_f32_e32 v37, v37
	v_rcp_f32_e32 v35, v35
	v_sub_f32_e32 v53, 1.0, v15
	v_sub_f32_e32 v52, 1.0, v14
	v_sub_f32_e32 v73, 1.0, v17
	v_sub_f32_e32 v72, 1.0, v16
	v_pk_mul_f32 v[74:75], v[72:73], v[36:37]
	v_pk_mul_f32 v[72:73], v[52:53], v[34:35]
	s_or_b64 exec, exec, s[54:55]
	s_andn2_saveexec_b64 s[4:5], s[4:5]
	s_or_b64 exec, exec, s[4:5]
	v_add_lshl_u32 v34, v76, v138, 1
	s_and_b64 vcc, exec, s[46:47]
	v_cvt_pk_bf16_f32 v52, v72, v73
	v_cvt_pk_bf16_f32 v53, v74, v75
	buffer_store_dwordx4 v[50:53], v34, s[28:31], 0 offen sc1
	s_cbranch_vccnz .LBB0_764_sg1
	ds_read_b64 v[52:53], v90 offset:128
	s_waitcnt lgkmcnt(0)
	v_mov_b32_e32 v50, v53
	s_branch .LBB0_765_sg1

.LBB0_765_sg1:
	v_pk_fma_f32 v[20:21], v[190:191], v[52:53], v[20:21] op_sel_hi:[1,0,1]
	v_pk_fma_f32 v[18:19], v[70:71], v[52:53], v[18:19] op_sel_hi:[1,0,1] neg_lo:[1,0,0] neg_hi:[1,0,0]
	v_pk_fma_f32 v[20:21], v[50:51], v[20:21], v[68:69] op_sel_hi:[0,1,1]
	v_pk_fma_f32 v[18:19], v[50:51], v[18:19], v[66:67] op_sel_hi:[0,1,1]
	s_and_saveexec_b64 s[4:5], s[42:43]
	s_xor_b64 s[4:5], exec, s[4:5]
	v_cmp_lt_i32_e32 vcc, 1, v180
	s_mov_b64 s[36:37], 0
	s_mov_b64 s[46:47], 0
	s_and_saveexec_b64 s[54:55], vcc
	s_xor_b64 s[54:55], exec, s[54:55]
	v_cmp_ne_u32_e32 vcc, 2, v180
	s_and_b64 s[46:47], vcc, exec
	s_andn2_saveexec_b64 s[54:55], s[54:55]
	v_cmp_ne_u32_e32 vcc, 1, v180
	s_andn2_b64 s[36:37], s[46:47], exec
	s_and_b64 s[46:47], vcc, exec
	s_or_b64 s[46:47], s[36:37], s[46:47]
	s_mov_b64 s[36:37], exec
	s_or_b64 exec, exec, s[54:55]
	v_mov_b64_e32 v[36:37], v[20:21]
	v_mov_b64_e32 v[34:35], v[18:19]
	s_and_saveexec_b64 s[54:55], s[46:47]
	s_xor_b64 s[46:47], exec, s[54:55]
	s_or_b64 exec, exec, s[46:47]
	s_and_saveexec_b64 s[46:47], s[36:37]
	s_mov_b32 s3, 0xbfb8aa3b
	v_mul_f32_e64 v18, -v18, s3
	v_mul_f32_e64 v19, -v19, s3
	v_mul_f32_e64 v20, -v20, s3
	v_mul_f32_e64 v21, -v21, s3
	v_exp_f32_e32 v18, v18
	v_exp_f32_e32 v19, v19
	v_exp_f32_e32 v20, v20
	v_exp_f32_e32 v21, v21
	v_add_f32_e32 v18, 1.0, v18
	v_add_f32_e32 v19, 1.0, v19
	v_add_f32_e32 v20, 1.0, v20
	v_add_f32_e32 v21, 1.0, v21
	v_rcp_f32_e32 v18, v18
	v_rcp_f32_e32 v20, v20
	v_rcp_f32_e32 v21, v21
	v_rcp_f32_e32 v19, v19
	v_sub_f32_e32 v35, 1.0, v63
	v_sub_f32_e32 v34, 1.0, v62
	v_sub_f32_e32 v37, 1.0, v65
	v_sub_f32_e32 v36, 1.0, v64
	v_pk_mul_f32 v[36:37], v[36:37], v[20:21]
	v_pk_mul_f32 v[34:35], v[34:35], v[18:19]
	s_or_b64 exec, exec, s[46:47]
	s_andn2_saveexec_b64 s[4:5], s[4:5]
	s_or_b64 exec, exec, s[4:5]
	v_mov_b32_e32 v53, v52
	v_mov_b32_e32 v20, v52
	v_mov_b32_e32 v21, v52
	v_mov_b32_e32 v51, v50
	v_pk_fma_f32 v[12:13], v[60:61], v[20:21], v[12:13]
	v_pk_fma_f32 v[10:11], v[58:59], v[52:53], v[10:11] neg_lo:[1,0,0] neg_hi:[1,0,0]
	v_mov_b32_e32 v20, v50
	v_mov_b32_e32 v21, v50
	v_pk_fma_f32 v[10:11], v[50:51], v[10:11], v[54:55]
	v_pk_fma_f32 v[12:13], v[20:21], v[12:13], v[56:57]
	v_cvt_pk_bf16_f32 v18, v34, v35
	v_cvt_pk_bf16_f32 v19, v36, v37
	s_and_saveexec_b64 s[4:5], s[42:43]
	s_xor_b64 s[4:5], exec, s[4:5]
	v_cmp_lt_i32_e32 vcc, 1, v180
	s_mov_b64 s[36:37], 0
	s_mov_b64 s[42:43], 0
	s_and_saveexec_b64 s[46:47], vcc
	s_xor_b64 s[46:47], exec, s[46:47]
	v_cmp_ne_u32_e32 vcc, 2, v180
	s_and_b64 s[42:43], vcc, exec
	s_andn2_saveexec_b64 s[46:47], s[46:47]
	v_cmp_ne_u32_e32 vcc, 1, v180
	s_andn2_b64 s[36:37], s[42:43], exec
	s_and_b64 s[42:43], vcc, exec
	s_or_b64 s[42:43], s[36:37], s[42:43]
	s_mov_b64 s[36:37], exec
	s_or_b64 exec, exec, s[46:47]
	v_mov_b64_e32 v[36:37], v[12:13]
	v_mov_b64_e32 v[34:35], v[10:11]
	s_and_saveexec_b64 s[46:47], s[42:43]
	s_xor_b64 s[42:43], exec, s[46:47]
	s_or_b64 exec, exec, s[42:43]
	s_and_saveexec_b64 s[42:43], s[36:37]
	s_mov_b32 s3, 0xbfb8aa3b
	v_mul_f32_e64 v10, -v10, s3
	v_mul_f32_e64 v11, -v11, s3
	v_mul_f32_e64 v12, -v12, s3
	v_mul_f32_e64 v13, -v13, s3
	v_exp_f32_e32 v10, v10
	v_exp_f32_e32 v11, v11
	v_exp_f32_e32 v12, v12
	v_exp_f32_e32 v13, v13
	v_add_f32_e32 v10, 1.0, v10
	v_add_f32_e32 v11, 1.0, v11
	v_add_f32_e32 v12, 1.0, v12
	v_add_f32_e32 v13, 1.0, v13
	v_rcp_f32_e32 v10, v10
	v_rcp_f32_e32 v12, v12
	v_rcp_f32_e32 v13, v13
	v_rcp_f32_e32 v11, v11
	v_sub_f32_e32 v21, 1.0, v47
	v_sub_f32_e32 v20, 1.0, v46
	v_sub_f32_e32 v35, 1.0, v49
	v_sub_f32_e32 v34, 1.0, v48
	v_pk_mul_f32 v[36:37], v[34:35], v[12:13]
	v_pk_mul_f32 v[34:35], v[20:21], v[10:11]
	s_or_b64 exec, exec, s[42:43]
	s_andn2_saveexec_b64 s[4:5], s[4:5]
	s_or_b64 exec, exec, s[4:5]
	v_add_u32_e32 v46, 0x4000, v76
	v_add_lshl_u32 v10, v46, v146, 1
	v_cvt_pk_bf16_f32 v20, v34, v35
	v_cvt_pk_bf16_f32 v21, v36, v37
	buffer_store_dwordx4 v[18:21], v10, s[28:31], 0 offen sc1
	v_mov_b32_e32 v10, v52
	v_mov_b32_e32 v11, v52
	v_pk_fma_f32 v[8:9], v[44:45], v[10:11], v[8:9]
	v_pk_fma_f32 v[6:7], v[42:43], v[52:53], v[6:7] neg_lo:[1,0,0] neg_hi:[1,0,0]
	v_mov_b32_e32 v10, v50
	v_mov_b32_e32 v11, v50
	v_pk_fma_f32 v[6:7], v[50:51], v[6:7], v[38:39]
	v_pk_fma_f32 v[8:9], v[10:11], v[8:9], v[40:41]
	s_and_saveexec_b64 s[4:5], s[44:45]
	s_xor_b64 s[4:5], exec, s[4:5]
	v_cmp_lt_i32_e32 vcc, 1, v172
	s_mov_b64 s[36:37], 0
	s_mov_b64 s[42:43], 0
	s_and_saveexec_b64 s[46:47], vcc
	s_xor_b64 s[46:47], exec, s[46:47]
	v_cmp_ne_u32_e32 vcc, 2, v172
	s_and_b64 s[42:43], vcc, exec
	s_andn2_saveexec_b64 s[46:47], s[46:47]
	v_cmp_ne_u32_e32 vcc, 1, v172
	s_andn2_b64 s[36:37], s[42:43], exec
	s_and_b64 s[42:43], vcc, exec
	s_or_b64 s[42:43], s[36:37], s[42:43]
	s_mov_b64 s[36:37], exec
	s_or_b64 exec, exec, s[46:47]
	v_mov_b64_e32 v[12:13], v[8:9]
	v_mov_b64_e32 v[10:11], v[6:7]
	s_and_saveexec_b64 s[46:47], s[42:43]
	s_xor_b64 s[42:43], exec, s[46:47]
	s_or_b64 exec, exec, s[42:43]
	s_and_saveexec_b64 s[42:43], s[36:37]
	s_mov_b32 s3, 0xbfb8aa3b
	v_mul_f32_e64 v6, -v6, s3
	v_mul_f32_e64 v7, -v7, s3
	v_mul_f32_e64 v8, -v8, s3
	v_mul_f32_e64 v9, -v9, s3
	v_exp_f32_e32 v6, v6
	v_exp_f32_e32 v7, v7
	v_exp_f32_e32 v8, v8
	v_exp_f32_e32 v9, v9
	v_add_f32_e32 v6, 1.0, v6
	v_add_f32_e32 v7, 1.0, v7
	v_add_f32_e32 v8, 1.0, v8
	v_add_f32_e32 v9, 1.0, v9
	v_rcp_f32_e32 v6, v6
	v_rcp_f32_e32 v8, v8
	v_rcp_f32_e32 v9, v9
	v_rcp_f32_e32 v7, v7
	v_sub_f32_e32 v11, 1.0, v31
	v_sub_f32_e32 v10, 1.0, v30
	v_sub_f32_e32 v13, 1.0, v33
	v_sub_f32_e32 v12, 1.0, v32
	v_pk_mul_f32 v[12:13], v[12:13], v[8:9]
	v_pk_mul_f32 v[10:11], v[10:11], v[6:7]
	s_or_b64 exec, exec, s[42:43]
	s_andn2_saveexec_b64 s[4:5], s[4:5]
	s_or_b64 exec, exec, s[4:5]
	v_mov_b32_e32 v8, v52
	v_mov_b32_e32 v9, v52
	v_pk_fma_f32 v[2:3], v[26:27], v[52:53], v[2:3] neg_lo:[1,0,0] neg_hi:[1,0,0]
	v_pk_fma_f32 v[4:5], v[28:29], v[8:9], v[4:5]
	v_pk_fma_f32 v[2:3], v[50:51], v[2:3], v[22:23]
	v_mov_b32_e32 v51, v50
	v_pk_fma_f32 v[4:5], v[50:51], v[4:5], v[24:25]
	v_cvt_pk_bf16_f32 v6, v10, v11
	v_cvt_pk_bf16_f32 v7, v12, v13
	s_and_saveexec_b64 s[4:5], s[44:45]
	s_xor_b64 s[4:5], exec, s[4:5]
	v_cmp_lt_i32_e32 vcc, 1, v172
	s_mov_b64 s[36:37], 0
	s_mov_b64 s[42:43], 0
	s_and_saveexec_b64 s[44:45], vcc
	s_xor_b64 s[44:45], exec, s[44:45]
	v_cmp_ne_u32_e32 vcc, 2, v172
	s_and_b64 s[42:43], vcc, exec
	s_andn2_saveexec_b64 s[44:45], s[44:45]
	v_cmp_ne_u32_e32 vcc, 1, v172
	s_andn2_b64 s[36:37], s[42:43], exec
	s_and_b64 s[42:43], vcc, exec
	s_or_b64 s[42:43], s[36:37], s[42:43]
	s_mov_b64 s[36:37], exec
	s_or_b64 exec, exec, s[44:45]
	v_mov_b64_e32 v[10:11], v[4:5]
	v_mov_b64_e32 v[8:9], v[2:3]
	s_and_saveexec_b64 s[44:45], s[42:43]
	s_xor_b64 s[42:43], exec, s[44:45]
	s_or_b64 exec, exec, s[42:43]
	s_and_saveexec_b64 s[42:43], s[36:37]
	s_mov_b32 s3, 0xbfb8aa3b
	v_mul_f32_e64 v2, -v2, s3
	v_mul_f32_e64 v3, -v3, s3
	v_mul_f32_e64 v4, -v4, s3
	v_mul_f32_e64 v5, -v5, s3
	v_exp_f32_e32 v2, v2
	v_exp_f32_e32 v3, v3
	v_exp_f32_e32 v4, v4
	v_exp_f32_e32 v5, v5
	v_add_f32_e32 v2, 1.0, v2
	v_add_f32_e32 v3, 1.0, v3
	v_add_f32_e32 v4, 1.0, v4
	v_add_f32_e32 v5, 1.0, v5
	v_rcp_f32_e32 v2, v2
	v_rcp_f32_e32 v4, v4
	v_rcp_f32_e32 v5, v5
	v_rcp_f32_e32 v3, v3
	v_sub_f32_e32 v9, 1.0, v15
	v_sub_f32_e32 v8, 1.0, v14
	v_sub_f32_e32 v11, 1.0, v17
	v_sub_f32_e32 v10, 1.0, v16
	v_pk_mul_f32 v[10:11], v[10:11], v[4:5]
	v_pk_mul_f32 v[8:9], v[8:9], v[2:3]
	s_or_b64 exec, exec, s[42:43]
	s_andn2_saveexec_b64 s[4:5], s[4:5]
	s_branch .LBB0_394

.LBB0_408_sg2:
	s_waitcnt vmcnt(0) lgkmcnt(0)
	v_xor_b32_e32 v191, 0x80000000, v73
	v_xor_b32_e32 v190, 0x80000000, v72
	v_pk_fma_f32 v[72:73], v[190:191], v[200:201], v[176:177] op_sel_hi:[1,0,1]
	v_pk_fma_f32 v[174:175], v[70:71], v[200:201], v[174:175] op_sel_hi:[1,0,1] neg_lo:[1,0,0] neg_hi:[1,0,0]
	s_movk_i32 s4, 0x3ff
	v_pk_fma_f32 v[174:175], v[192:193], v[174:175], v[66:67] op_sel_hi:[0,1,1]
	v_pk_fma_f32 v[176:177], v[192:193], v[72:73], v[68:69] op_sel_hi:[0,1,1]
	v_cmp_lt_u32_e64 s[42:43], s4, v202
	s_and_saveexec_b64 s[4:5], s[42:43]
	s_xor_b64 s[4:5], exec, s[4:5]
	v_ashrrev_i32_e32 v72, 10, v202
	v_cmp_lt_i32_e32 vcc, 1, v72
	s_mov_b64 s[36:37], 0
	s_mov_b64 s[44:45], 0
	s_and_saveexec_b64 s[54:55], vcc
	s_xor_b64 s[54:55], exec, s[54:55]
	v_cmp_ne_u32_e32 vcc, 2, v72
	s_and_b64 s[44:45], vcc, exec
	s_andn2_saveexec_b64 s[54:55], s[54:55]
	v_cmp_ne_u32_e32 vcc, 1, v72
	s_andn2_b64 s[36:37], s[44:45], exec
	s_and_b64 s[44:45], vcc, exec
	s_or_b64 s[44:45], s[36:37], s[44:45]
	s_mov_b64 s[36:37], exec
	s_or_b64 exec, exec, s[54:55]
	v_mov_b64_e32 v[180:181], v[176:177]
	v_mov_b64_e32 v[178:179], v[174:175]
	s_and_saveexec_b64 s[54:55], s[44:45]
	s_xor_b64 s[44:45], exec, s[54:55]
	s_or_b64 exec, exec, s[44:45]
	s_and_saveexec_b64 s[44:45], s[36:37]
	s_or_b64 exec, exec, s[44:45]
	s_andn2_saveexec_b64 s[4:5], s[4:5]
	s_or_b64 exec, exec, s[4:5]
	v_mov_b32_e32 v201, v200
	v_xor_b32_e32 v61, 0x80000000, v61
	v_xor_b32_e32 v60, 0x80000000, v60
	v_mov_b32_e32 v72, v200
	v_mov_b32_e32 v73, v200
	v_mov_b32_e32 v193, v192
	v_pk_fma_f32 v[72:73], v[60:61], v[72:73], v[172:173]
	v_pk_fma_f32 v[170:171], v[58:59], v[200:201], v[170:171] neg_lo:[1,0,0] neg_hi:[1,0,0]
	v_mov_b32_e32 v172, v192
	v_mov_b32_e32 v173, v192
	v_pk_fma_f32 v[170:171], v[192:193], v[170:171], v[54:55]
	v_pk_fma_f32 v[172:173], v[172:173], v[72:73], v[56:57]
	v_cvt_pk_bf16_f32 v174, v178, v179
	v_cvt_pk_bf16_f32 v175, v180, v181
	s_and_saveexec_b64 s[4:5], s[42:43]
	s_xor_b64 s[4:5], exec, s[4:5]
	v_ashrrev_i32_e32 v180, 10, v202
	v_cmp_lt_i32_e32 vcc, 1, v180
	s_mov_b64 s[36:37], 0
	s_mov_b64 s[44:45], 0
	s_and_saveexec_b64 s[54:55], vcc
	s_xor_b64 s[54:55], exec, s[54:55]
	v_cmp_ne_u32_e32 vcc, 2, v180
	s_and_b64 s[44:45], vcc, exec
	s_andn2_saveexec_b64 s[54:55], s[54:55]
	v_cmp_ne_u32_e32 vcc, 1, v180
	s_andn2_b64 s[36:37], s[44:45], exec
	s_and_b64 s[44:45], vcc, exec
	s_or_b64 s[44:45], s[36:37], s[44:45]
	s_mov_b64 s[36:37], exec
	s_or_b64 exec, exec, s[54:55]
	v_mov_b64_e32 v[178:179], v[172:173]
	v_mov_b64_e32 v[176:177], v[170:171]
	s_and_saveexec_b64 s[54:55], s[44:45]
	s_xor_b64 s[44:45], exec, s[54:55]
	s_or_b64 exec, exec, s[44:45]
	s_and_saveexec_b64 s[44:45], s[36:37]
	s_or_b64 exec, exec, s[44:45]
	s_andn2_saveexec_b64 s[4:5], s[4:5]
	s_or_b64 exec, exec, s[4:5]
	s_lshl_b32 s51, s3, 8
	v_add_lshl_u32 v181, v214, s51, 10
	s_mov_b32 s3, 0x1020000
	v_cvt_pk_bf16_f32 v176, v176, v177
	v_cvt_pk_bf16_f32 v177, v178, v179
	v_mul_lo_u32 v178, v180, s3
	v_or_b32_e32 v72, v181, v210
	v_add_lshl_u32 v72, v72, v178, 1
	buffer_store_dwordx4 v[174:177], v72, s[28:31], 0 offen sc1
	v_xor_b32_e32 v45, 0x80000000, v45
	v_xor_b32_e32 v44, 0x80000000, v44
	v_mov_b32_e32 v72, v200
	v_mov_b32_e32 v73, v200
	v_pk_fma_f32 v[72:73], v[44:45], v[72:73], v[168:169]
	v_pk_fma_f32 v[166:167], v[42:43], v[200:201], v[166:167] neg_lo:[1,0,0] neg_hi:[1,0,0]
	v_mov_b32_e32 v168, v192
	v_mov_b32_e32 v169, v192
	s_movk_i32 s3, 0x3ff
	v_pk_fma_f32 v[166:167], v[192:193], v[166:167], v[38:39]
	v_pk_fma_f32 v[168:169], v[168:169], v[72:73], v[40:41]
	v_cmp_lt_u32_e64 s[44:45], s3, v212
	s_and_saveexec_b64 s[4:5], s[44:45]
	s_xor_b64 s[4:5], exec, s[4:5]
	v_ashrrev_i32_e32 v72, 10, v212
	v_cmp_lt_i32_e32 vcc, 1, v72
	s_mov_b64 s[36:37], 0
	s_mov_b64 s[54:55], 0
	s_and_saveexec_b64 s[56:57], vcc
	s_xor_b64 s[56:57], exec, s[56:57]
	v_cmp_ne_u32_e32 vcc, 2, v72
	s_and_b64 s[54:55], vcc, exec
	s_andn2_saveexec_b64 s[56:57], s[56:57]
	v_cmp_ne_u32_e32 vcc, 1, v72
	s_andn2_b64 s[36:37], s[54:55], exec
	s_and_b64 s[54:55], vcc, exec
	s_or_b64 s[54:55], s[36:37], s[54:55]
	s_mov_b64 s[36:37], exec
	s_or_b64 exec, exec, s[56:57]
	v_mov_b64_e32 v[172:173], v[168:169]
	v_mov_b64_e32 v[170:171], v[166:167]
	s_and_saveexec_b64 s[56:57], s[54:55]
	s_xor_b64 s[54:55], exec, s[56:57]
	s_or_b64 exec, exec, s[54:55]
	s_and_saveexec_b64 s[54:55], s[36:37]
	s_or_b64 exec, exec, s[54:55]
	s_andn2_saveexec_b64 s[4:5], s[4:5]
	s_or_b64 exec, exec, s[4:5]
	v_xor_b32_e32 v29, 0x80000000, v29
	v_xor_b32_e32 v28, 0x80000000, v28
	v_mov_b32_e32 v72, v200
	v_mov_b32_e32 v73, v200
	v_pk_fma_f32 v[162:163], v[26:27], v[200:201], v[162:163] neg_lo:[1,0,0] neg_hi:[1,0,0]
	v_pk_fma_f32 v[72:73], v[28:29], v[72:73], v[164:165]
	v_pk_fma_f32 v[162:163], v[192:193], v[162:163], v[22:23]
	v_mov_b32_e32 v193, v192
	v_pk_fma_f32 v[164:165], v[192:193], v[72:73], v[24:25]
	v_cvt_pk_bf16_f32 v166, v170, v171
	v_cvt_pk_bf16_f32 v167, v172, v173
	s_and_saveexec_b64 s[4:5], s[44:45]
	s_xor_b64 s[4:5], exec, s[4:5]
	v_ashrrev_i32_e32 v172, 10, v212
	v_cmp_lt_i32_e32 vcc, 1, v172
	s_mov_b64 s[36:37], 0
	s_mov_b64 s[54:55], 0
	s_and_saveexec_b64 s[56:57], vcc
	s_xor_b64 s[56:57], exec, s[56:57]
	v_cmp_ne_u32_e32 vcc, 2, v172
	s_and_b64 s[54:55], vcc, exec
	s_andn2_saveexec_b64 s[56:57], s[56:57]
	v_cmp_ne_u32_e32 vcc, 1, v172
	s_andn2_b64 s[36:37], s[54:55], exec
	s_and_b64 s[54:55], vcc, exec
	s_or_b64 s[54:55], s[36:37], s[54:55]
	s_mov_b64 s[36:37], exec
	s_or_b64 exec, exec, s[56:57]
	v_mov_b64_e32 v[170:171], v[164:165]
	v_mov_b64_e32 v[168:169], v[162:163]
	s_and_saveexec_b64 s[56:57], s[54:55]
	s_xor_b64 s[54:55], exec, s[56:57]
	s_or_b64 exec, exec, s[54:55]
	s_and_saveexec_b64 s[54:55], s[36:37]
	s_or_b64 exec, exec, s[54:55]
	s_andn2_saveexec_b64 s[4:5], s[4:5]
	s_or_b64 exec, exec, s[4:5]
	s_mov_b32 s3, 0x1020000
	v_cvt_pk_bf16_f32 v168, v168, v169
	v_cvt_pk_bf16_f32 v169, v170, v171
	v_mul_lo_u32 v170, v172, s3
	v_or_b32_e32 v72, v181, v203
	v_add_lshl_u32 v72, v72, v170, 1
	s_and_b64 vcc, exec, s[46:47]
	buffer_store_dwordx4 v[166:169], v72, s[28:31], 0 offen sc1
	s_cbranch_vccnz .LBB0_458_sg2
	ds_read_b64 v[166:167], v211 offset:128
	s_waitcnt lgkmcnt(0)
	v_mov_b32_e32 v72, v167
	s_branch .LBB0_459_sg2

.LBB0_459_sg2:
	v_pk_fma_f32 v[160:161], v[190:191], v[166:167], v[160:161] op_sel_hi:[1,0,1]
	v_pk_fma_f32 v[158:159], v[70:71], v[166:167], v[158:159] op_sel_hi:[1,0,1] neg_lo:[1,0,0] neg_hi:[1,0,0]
	v_pk_fma_f32 v[160:161], v[72:73], v[160:161], v[68:69] op_sel_hi:[0,1,1]
	v_pk_fma_f32 v[158:159], v[72:73], v[158:159], v[66:67] op_sel_hi:[0,1,1]
	s_and_saveexec_b64 s[4:5], s[42:43]
	s_xor_b64 s[4:5], exec, s[4:5]
	v_cmp_lt_i32_e32 vcc, 1, v180
	s_mov_b64 s[36:37], 0
	s_mov_b64 s[54:55], 0
	s_and_saveexec_b64 s[56:57], vcc
	s_xor_b64 s[56:57], exec, s[56:57]
	v_cmp_ne_u32_e32 vcc, 2, v180
	s_and_b64 s[54:55], vcc, exec
	s_andn2_saveexec_b64 s[56:57], s[56:57]
	v_cmp_ne_u32_e32 vcc, 1, v180
	s_andn2_b64 s[36:37], s[54:55], exec
	s_and_b64 s[54:55], vcc, exec
	s_or_b64 s[54:55], s[36:37], s[54:55]
	s_mov_b64 s[36:37], exec
	s_or_b64 exec, exec, s[56:57]
	v_mov_b64_e32 v[164:165], v[160:161]
	v_mov_b64_e32 v[162:163], v[158:159]
	s_and_saveexec_b64 s[56:57], s[54:55]
	s_xor_b64 s[54:55], exec, s[56:57]
	s_or_b64 exec, exec, s[54:55]
	s_and_saveexec_b64 s[54:55], s[36:37]
	s_or_b64 exec, exec, s[54:55]
	s_andn2_saveexec_b64 s[4:5], s[4:5]
	s_or_b64 exec, exec, s[4:5]
	v_mov_b32_e32 v167, v166
	v_mov_b32_e32 v160, v166
	v_mov_b32_e32 v161, v166
	v_mov_b32_e32 v73, v72
	v_pk_fma_f32 v[156:157], v[60:61], v[160:161], v[156:157]
	v_pk_fma_f32 v[154:155], v[58:59], v[166:167], v[154:155] neg_lo:[1,0,0] neg_hi:[1,0,0]
	v_mov_b32_e32 v160, v72
	v_mov_b32_e32 v161, v72
	v_pk_fma_f32 v[154:155], v[72:73], v[154:155], v[54:55]
	v_pk_fma_f32 v[156:157], v[160:161], v[156:157], v[56:57]
	v_cvt_pk_bf16_f32 v158, v162, v163
	v_cvt_pk_bf16_f32 v159, v164, v165
	s_and_saveexec_b64 s[4:5], s[42:43]
	s_xor_b64 s[4:5], exec, s[4:5]
	v_cmp_lt_i32_e32 vcc, 1, v180
	s_mov_b64 s[36:37], 0
	s_mov_b64 s[54:55], 0
	s_and_saveexec_b64 s[56:57], vcc
	s_xor_b64 s[56:57], exec, s[56:57]
	v_cmp_ne_u32_e32 vcc, 2, v180
	s_and_b64 s[54:55], vcc, exec
	s_andn2_saveexec_b64 s[56:57], s[56:57]
	v_cmp_ne_u32_e32 vcc, 1, v180
	s_andn2_b64 s[36:37], s[54:55], exec
	s_and_b64 s[54:55], vcc, exec
	s_or_b64 s[54:55], s[36:37], s[54:55]
	s_mov_b64 s[36:37], exec
	s_or_b64 exec, exec, s[56:57]
	v_mov_b64_e32 v[162:163], v[156:157]
	v_mov_b64_e32 v[160:161], v[154:155]
	s_and_saveexec_b64 s[56:57], s[54:55]
	s_xor_b64 s[54:55], exec, s[56:57]
	s_or_b64 exec, exec, s[54:55]
	s_and_saveexec_b64 s[54:55], s[36:37]
	s_or_b64 exec, exec, s[54:55]
	s_andn2_saveexec_b64 s[4:5], s[4:5]
	s_or_b64 exec, exec, s[4:5]
	v_add_u32_e32 v164, 0x4000, v181
	v_or_b32_e32 v154, v164, v210
	v_add_lshl_u32 v154, v154, v178, 1
	v_cvt_pk_bf16_f32 v160, v160, v161
	v_cvt_pk_bf16_f32 v161, v162, v163
	buffer_store_dwordx4 v[158:161], v154, s[28:31], 0 offen sc1
	v_mov_b32_e32 v154, v166
	v_mov_b32_e32 v155, v166
	v_pk_fma_f32 v[152:153], v[44:45], v[154:155], v[152:153]
	v_pk_fma_f32 v[150:151], v[42:43], v[166:167], v[150:151] neg_lo:[1,0,0] neg_hi:[1,0,0]
	v_mov_b32_e32 v154, v72
	v_mov_b32_e32 v155, v72
	v_pk_fma_f32 v[150:151], v[72:73], v[150:151], v[38:39]
	v_pk_fma_f32 v[152:153], v[154:155], v[152:153], v[40:41]
	s_and_saveexec_b64 s[4:5], s[44:45]
	s_xor_b64 s[4:5], exec, s[4:5]
	v_cmp_lt_i32_e32 vcc, 1, v172
	s_mov_b64 s[36:37], 0
	s_mov_b64 s[54:55], 0
	s_and_saveexec_b64 s[56:57], vcc
	s_xor_b64 s[56:57], exec, s[56:57]
	v_cmp_ne_u32_e32 vcc, 2, v172
	s_and_b64 s[54:55], vcc, exec
	s_andn2_saveexec_b64 s[56:57], s[56:57]
	v_cmp_ne_u32_e32 vcc, 1, v172
	s_andn2_b64 s[36:37], s[54:55], exec
	s_and_b64 s[54:55], vcc, exec
	s_or_b64 s[54:55], s[36:37], s[54:55]
	s_mov_b64 s[36:37], exec
	s_or_b64 exec, exec, s[56:57]
	v_mov_b64_e32 v[156:157], v[152:153]
	v_mov_b64_e32 v[154:155], v[150:151]
	s_and_saveexec_b64 s[56:57], s[54:55]
	s_xor_b64 s[54:55], exec, s[56:57]
	s_or_b64 exec, exec, s[54:55]
	s_and_saveexec_b64 s[54:55], s[36:37]
	s_or_b64 exec, exec, s[54:55]
	s_andn2_saveexec_b64 s[4:5], s[4:5]
	s_or_b64 exec, exec, s[4:5]
	v_mov_b32_e32 v152, v166
	v_mov_b32_e32 v153, v166
	v_pk_fma_f32 v[146:147], v[26:27], v[166:167], v[146:147] neg_lo:[1,0,0] neg_hi:[1,0,0]
	v_pk_fma_f32 v[148:149], v[28:29], v[152:153], v[148:149]
	v_pk_fma_f32 v[146:147], v[72:73], v[146:147], v[22:23]
	v_mov_b32_e32 v73, v72
	v_pk_fma_f32 v[148:149], v[72:73], v[148:149], v[24:25]
	v_cvt_pk_bf16_f32 v150, v154, v155
	v_cvt_pk_bf16_f32 v151, v156, v157
	s_and_saveexec_b64 s[4:5], s[44:45]
	s_xor_b64 s[4:5], exec, s[4:5]
	v_cmp_lt_i32_e32 vcc, 1, v172
	s_mov_b64 s[36:37], 0
	s_mov_b64 s[54:55], 0
	s_and_saveexec_b64 s[56:57], vcc
	s_xor_b64 s[56:57], exec, s[56:57]
	v_cmp_ne_u32_e32 vcc, 2, v172
	s_and_b64 s[54:55], vcc, exec
	s_andn2_saveexec_b64 s[56:57], s[56:57]
	v_cmp_ne_u32_e32 vcc, 1, v172
	s_andn2_b64 s[36:37], s[54:55], exec
	s_and_b64 s[54:55], vcc, exec
	s_or_b64 s[54:55], s[36:37], s[54:55]
	s_mov_b64 s[36:37], exec
	s_or_b64 exec, exec, s[56:57]
	v_mov_b64_e32 v[154:155], v[148:149]
	v_mov_b64_e32 v[152:153], v[146:147]
	s_and_saveexec_b64 s[56:57], s[54:55]
	s_xor_b64 s[54:55], exec, s[56:57]
	s_or_b64 exec, exec, s[54:55]
	s_and_saveexec_b64 s[54:55], s[36:37]
	s_or_b64 exec, exec, s[54:55]
	s_andn2_saveexec_b64 s[4:5], s[4:5]
	s_or_b64 exec, exec, s[4:5]
	v_or_b32_e32 v72, v164, v203
	v_add_lshl_u32 v72, v72, v170, 1
	v_cvt_pk_bf16_f32 v152, v152, v153
	v_cvt_pk_bf16_f32 v153, v154, v155
	buffer_store_dwordx4 v[150:153], v72, s[28:31], 0 offen sc1
	s_and_b64 vcc, exec, s[46:47]
	s_nop 0
	v_mov_b32_e32 v153, v205
	s_nop 0
	v_lshl_add_u32 v152, v153, 3, s33
	s_cbranch_vccnz .LBB0_509_sg2
	ds_read_b64 v[150:151], v152
	s_waitcnt lgkmcnt(0)
	v_mov_b32_e32 v72, v151
	s_branch .LBB0_510_sg2

.LBB0_510_sg2:
	v_pk_fma_f32 v[144:145], v[190:191], v[150:151], v[144:145] op_sel_hi:[1,0,1]
	v_pk_fma_f32 v[142:143], v[70:71], v[150:151], v[142:143] op_sel_hi:[1,0,1] neg_lo:[1,0,0] neg_hi:[1,0,0]
	v_pk_fma_f32 v[144:145], v[72:73], v[144:145], v[68:69] op_sel_hi:[0,1,1]
	v_pk_fma_f32 v[142:143], v[72:73], v[142:143], v[66:67] op_sel_hi:[0,1,1]
	s_and_saveexec_b64 s[4:5], s[42:43]
	s_xor_b64 s[4:5], exec, s[4:5]
	v_cmp_lt_i32_e32 vcc, 1, v180
	s_mov_b64 s[36:37], 0
	s_mov_b64 s[54:55], 0
	s_and_saveexec_b64 s[56:57], vcc
	s_xor_b64 s[56:57], exec, s[56:57]
	v_cmp_ne_u32_e32 vcc, 2, v180
	s_and_b64 s[54:55], vcc, exec
	s_andn2_saveexec_b64 s[56:57], s[56:57]
	v_cmp_ne_u32_e32 vcc, 1, v180
	s_andn2_b64 s[36:37], s[54:55], exec
	s_and_b64 s[54:55], vcc, exec
	s_or_b64 s[54:55], s[36:37], s[54:55]
	s_mov_b64 s[36:37], exec
	s_or_b64 exec, exec, s[56:57]
	v_mov_b64_e32 v[148:149], v[144:145]
	v_mov_b64_e32 v[146:147], v[142:143]
	s_and_saveexec_b64 s[56:57], s[54:55]
	s_xor_b64 s[54:55], exec, s[56:57]
	s_or_b64 exec, exec, s[54:55]
	s_and_saveexec_b64 s[54:55], s[36:37]
	s_or_b64 exec, exec, s[54:55]
	s_andn2_saveexec_b64 s[4:5], s[4:5]
	s_or_b64 exec, exec, s[4:5]
	v_mov_b32_e32 v151, v150
	v_mov_b32_e32 v144, v150
	v_mov_b32_e32 v145, v150
	v_mov_b32_e32 v73, v72
	v_pk_fma_f32 v[140:141], v[60:61], v[144:145], v[140:141]
	v_pk_fma_f32 v[138:139], v[58:59], v[150:151], v[138:139] neg_lo:[1,0,0] neg_hi:[1,0,0]
	v_mov_b32_e32 v144, v72
	v_mov_b32_e32 v145, v72
	v_pk_fma_f32 v[138:139], v[72:73], v[138:139], v[54:55]
	v_pk_fma_f32 v[140:141], v[144:145], v[140:141], v[56:57]
	v_cvt_pk_bf16_f32 v142, v146, v147
	v_cvt_pk_bf16_f32 v143, v148, v149
	s_and_saveexec_b64 s[4:5], s[42:43]
	s_xor_b64 s[4:5], exec, s[4:5]
	v_cmp_lt_i32_e32 vcc, 1, v180
	s_mov_b64 s[36:37], 0
	s_mov_b64 s[54:55], 0
	s_and_saveexec_b64 s[56:57], vcc
	s_xor_b64 s[56:57], exec, s[56:57]
	v_cmp_ne_u32_e32 vcc, 2, v180
	s_and_b64 s[54:55], vcc, exec
	s_andn2_saveexec_b64 s[56:57], s[56:57]
	v_cmp_ne_u32_e32 vcc, 1, v180
	s_andn2_b64 s[36:37], s[54:55], exec
	s_and_b64 s[54:55], vcc, exec
	s_or_b64 s[54:55], s[36:37], s[54:55]
	s_mov_b64 s[36:37], exec
	s_or_b64 exec, exec, s[56:57]
	v_mov_b64_e32 v[146:147], v[140:141]
	v_mov_b64_e32 v[144:145], v[138:139]
	s_and_saveexec_b64 s[56:57], s[54:55]
	s_xor_b64 s[54:55], exec, s[56:57]
	s_or_b64 exec, exec, s[54:55]
	s_and_saveexec_b64 s[54:55], s[36:37]
	s_or_b64 exec, exec, s[54:55]
	s_andn2_saveexec_b64 s[4:5], s[4:5]
	s_or_b64 exec, exec, s[4:5]
	v_add_lshl_u32 v148, v153, s51, 10
	v_cvt_pk_bf16_f32 v144, v144, v145
	v_cvt_pk_bf16_f32 v145, v146, v147
	v_or_b32_e32 v146, v178, v210
	v_add_lshl_u32 v138, v148, v146, 1
	buffer_store_dwordx4 v[142:145], v138, s[28:31], 0 offen sc1
	v_mov_b32_e32 v138, v150
	v_mov_b32_e32 v139, v150
	v_pk_fma_f32 v[136:137], v[44:45], v[138:139], v[136:137]
	v_pk_fma_f32 v[134:135], v[42:43], v[150:151], v[134:135] neg_lo:[1,0,0] neg_hi:[1,0,0]
	v_mov_b32_e32 v138, v72
	v_mov_b32_e32 v139, v72
	v_pk_fma_f32 v[134:135], v[72:73], v[134:135], v[38:39]
	v_pk_fma_f32 v[136:137], v[138:139], v[136:137], v[40:41]
	s_and_saveexec_b64 s[4:5], s[44:45]
	s_xor_b64 s[4:5], exec, s[4:5]
	v_cmp_lt_i32_e32 vcc, 1, v172
	s_mov_b64 s[36:37], 0
	s_mov_b64 s[54:55], 0
	s_and_saveexec_b64 s[56:57], vcc
	s_xor_b64 s[56:57], exec, s[56:57]
	v_cmp_ne_u32_e32 vcc, 2, v172
	s_and_b64 s[54:55], vcc, exec
	s_andn2_saveexec_b64 s[56:57], s[56:57]
	v_cmp_ne_u32_e32 vcc, 1, v172
	s_andn2_b64 s[36:37], s[54:55], exec
	s_and_b64 s[54:55], vcc, exec
	s_or_b64 s[54:55], s[36:37], s[54:55]
	s_mov_b64 s[36:37], exec
	s_or_b64 exec, exec, s[56:57]
	v_mov_b64_e32 v[140:141], v[136:137]
	v_mov_b64_e32 v[138:139], v[134:135]
	s_and_saveexec_b64 s[56:57], s[54:55]
	s_xor_b64 s[54:55], exec, s[56:57]
	s_or_b64 exec, exec, s[54:55]
	s_and_saveexec_b64 s[54:55], s[36:37]
	s_or_b64 exec, exec, s[54:55]
	s_andn2_saveexec_b64 s[4:5], s[4:5]
	s_or_b64 exec, exec, s[4:5]
	v_mov_b32_e32 v136, v150
	v_mov_b32_e32 v137, v150
	v_pk_fma_f32 v[130:131], v[26:27], v[150:151], v[130:131] neg_lo:[1,0,0] neg_hi:[1,0,0]
	v_pk_fma_f32 v[132:133], v[28:29], v[136:137], v[132:133]
	v_pk_fma_f32 v[130:131], v[72:73], v[130:131], v[22:23]
	v_mov_b32_e32 v73, v72
	v_pk_fma_f32 v[132:133], v[72:73], v[132:133], v[24:25]
	v_cvt_pk_bf16_f32 v134, v138, v139
	v_cvt_pk_bf16_f32 v135, v140, v141
	s_and_saveexec_b64 s[4:5], s[44:45]
	s_xor_b64 s[4:5], exec, s[4:5]
	v_cmp_lt_i32_e32 vcc, 1, v172
	s_mov_b64 s[36:37], 0
	s_mov_b64 s[54:55], 0
	s_and_saveexec_b64 s[56:57], vcc
	s_xor_b64 s[56:57], exec, s[56:57]
	v_cmp_ne_u32_e32 vcc, 2, v172
	s_and_b64 s[54:55], vcc, exec
	s_andn2_saveexec_b64 s[56:57], s[56:57]
	v_cmp_ne_u32_e32 vcc, 1, v172
	s_andn2_b64 s[36:37], s[54:55], exec
	s_and_b64 s[54:55], vcc, exec
	s_or_b64 s[54:55], s[36:37], s[54:55]
	s_mov_b64 s[36:37], exec
	s_or_b64 exec, exec, s[56:57]
	v_mov_b64_e32 v[138:139], v[132:133]
	v_mov_b64_e32 v[136:137], v[130:131]
	s_and_saveexec_b64 s[56:57], s[54:55]
	s_xor_b64 s[54:55], exec, s[56:57]
	s_or_b64 exec, exec, s[54:55]
	s_and_saveexec_b64 s[54:55], s[36:37]
	s_or_b64 exec, exec, s[54:55]
	s_andn2_saveexec_b64 s[4:5], s[4:5]
	s_or_b64 exec, exec, s[4:5]
	v_cvt_pk_bf16_f32 v136, v136, v137
	v_cvt_pk_bf16_f32 v137, v138, v139
	v_or_b32_e32 v138, v170, v203
	v_add_lshl_u32 v72, v148, v138, 1
	s_and_b64 vcc, exec, s[46:47]
	buffer_store_dwordx4 v[134:137], v72, s[28:31], 0 offen sc1
	s_cbranch_vccnz .LBB0_560_sg2
	ds_read_b64 v[134:135], v152 offset:128
	s_waitcnt lgkmcnt(0)
	v_mov_b32_e32 v72, v135
	s_branch .LBB0_561_sg2

.LBB0_561_sg2:
	v_pk_fma_f32 v[128:129], v[190:191], v[134:135], v[128:129] op_sel_hi:[1,0,1]
	v_pk_fma_f32 v[126:127], v[70:71], v[134:135], v[126:127] op_sel_hi:[1,0,1] neg_lo:[1,0,0] neg_hi:[1,0,0]
	v_pk_fma_f32 v[128:129], v[72:73], v[128:129], v[68:69] op_sel_hi:[0,1,1]
	v_pk_fma_f32 v[126:127], v[72:73], v[126:127], v[66:67] op_sel_hi:[0,1,1]
	s_and_saveexec_b64 s[4:5], s[42:43]
	s_xor_b64 s[4:5], exec, s[4:5]
	v_cmp_lt_i32_e32 vcc, 1, v180
	s_mov_b64 s[36:37], 0
	s_mov_b64 s[54:55], 0
	s_and_saveexec_b64 s[56:57], vcc
	s_xor_b64 s[56:57], exec, s[56:57]
	v_cmp_ne_u32_e32 vcc, 2, v180
	s_and_b64 s[54:55], vcc, exec
	s_andn2_saveexec_b64 s[56:57], s[56:57]
	v_cmp_ne_u32_e32 vcc, 1, v180
	s_andn2_b64 s[36:37], s[54:55], exec
	s_and_b64 s[54:55], vcc, exec
	s_or_b64 s[54:55], s[36:37], s[54:55]
	s_mov_b64 s[36:37], exec
	s_or_b64 exec, exec, s[56:57]
	v_mov_b64_e32 v[132:133], v[128:129]
	v_mov_b64_e32 v[130:131], v[126:127]
	s_and_saveexec_b64 s[56:57], s[54:55]
	s_xor_b64 s[54:55], exec, s[56:57]
	s_or_b64 exec, exec, s[54:55]
	s_and_saveexec_b64 s[54:55], s[36:37]
	s_or_b64 exec, exec, s[54:55]
	s_andn2_saveexec_b64 s[4:5], s[4:5]
	s_or_b64 exec, exec, s[4:5]
	v_mov_b32_e32 v135, v134
	v_mov_b32_e32 v128, v134
	v_mov_b32_e32 v129, v134
	v_mov_b32_e32 v73, v72
	v_pk_fma_f32 v[124:125], v[60:61], v[128:129], v[124:125]
	v_pk_fma_f32 v[122:123], v[58:59], v[134:135], v[122:123] neg_lo:[1,0,0] neg_hi:[1,0,0]
	v_mov_b32_e32 v128, v72
	v_mov_b32_e32 v129, v72
	v_pk_fma_f32 v[122:123], v[72:73], v[122:123], v[54:55]
	v_pk_fma_f32 v[124:125], v[128:129], v[124:125], v[56:57]
	v_cvt_pk_bf16_f32 v126, v130, v131
	v_cvt_pk_bf16_f32 v127, v132, v133
	s_and_saveexec_b64 s[4:5], s[42:43]
	s_xor_b64 s[4:5], exec, s[4:5]
	v_cmp_lt_i32_e32 vcc, 1, v180
	s_mov_b64 s[36:37], 0
	s_mov_b64 s[54:55], 0
	s_and_saveexec_b64 s[56:57], vcc
	s_xor_b64 s[56:57], exec, s[56:57]
	v_cmp_ne_u32_e32 vcc, 2, v180
	s_and_b64 s[54:55], vcc, exec
	s_andn2_saveexec_b64 s[56:57], s[56:57]
	v_cmp_ne_u32_e32 vcc, 1, v180
	s_andn2_b64 s[36:37], s[54:55], exec
	s_and_b64 s[54:55], vcc, exec
	s_or_b64 s[54:55], s[36:37], s[54:55]
	s_mov_b64 s[36:37], exec
	s_or_b64 exec, exec, s[56:57]
	v_mov_b64_e32 v[130:131], v[124:125]
	v_mov_b64_e32 v[128:129], v[122:123]
	s_and_saveexec_b64 s[56:57], s[54:55]
	s_xor_b64 s[54:55], exec, s[56:57]
	s_or_b64 exec, exec, s[54:55]
	s_and_saveexec_b64 s[54:55], s[36:37]
	s_or_b64 exec, exec, s[54:55]
	s_andn2_saveexec_b64 s[4:5], s[4:5]
	s_or_b64 exec, exec, s[4:5]
	v_add_u32_e32 v132, 0x4000, v148
	v_add_lshl_u32 v122, v132, v146, 1
	v_cvt_pk_bf16_f32 v128, v128, v129
	v_cvt_pk_bf16_f32 v129, v130, v131
	buffer_store_dwordx4 v[126:129], v122, s[28:31], 0 offen sc1
	v_mov_b32_e32 v122, v134
	v_mov_b32_e32 v123, v134
	v_pk_fma_f32 v[120:121], v[44:45], v[122:123], v[120:121]
	v_pk_fma_f32 v[118:119], v[42:43], v[134:135], v[118:119] neg_lo:[1,0,0] neg_hi:[1,0,0]
	v_mov_b32_e32 v122, v72
	v_mov_b32_e32 v123, v72
	v_pk_fma_f32 v[118:119], v[72:73], v[118:119], v[38:39]
	v_pk_fma_f32 v[120:121], v[122:123], v[120:121], v[40:41]
	s_and_saveexec_b64 s[4:5], s[44:45]
	s_xor_b64 s[4:5], exec, s[4:5]
	v_cmp_lt_i32_e32 vcc, 1, v172
	s_mov_b64 s[36:37], 0
	s_mov_b64 s[54:55], 0
	s_and_saveexec_b64 s[56:57], vcc
	s_xor_b64 s[56:57], exec, s[56:57]
	v_cmp_ne_u32_e32 vcc, 2, v172
	s_and_b64 s[54:55], vcc, exec
	s_andn2_saveexec_b64 s[56:57], s[56:57]
	v_cmp_ne_u32_e32 vcc, 1, v172
	s_andn2_b64 s[36:37], s[54:55], exec
	s_and_b64 s[54:55], vcc, exec
	s_or_b64 s[54:55], s[36:37], s[54:55]
	s_mov_b64 s[36:37], exec
	s_or_b64 exec, exec, s[56:57]
	v_mov_b64_e32 v[124:125], v[120:121]
	v_mov_b64_e32 v[122:123], v[118:119]
	s_and_saveexec_b64 s[56:57], s[54:55]
	s_xor_b64 s[54:55], exec, s[56:57]
	s_or_b64 exec, exec, s[54:55]
	s_and_saveexec_b64 s[54:55], s[36:37]
	s_or_b64 exec, exec, s[54:55]
	s_andn2_saveexec_b64 s[4:5], s[4:5]
	s_or_b64 exec, exec, s[4:5]
	v_mov_b32_e32 v120, v134
	v_mov_b32_e32 v121, v134
	v_pk_fma_f32 v[114:115], v[26:27], v[134:135], v[114:115] neg_lo:[1,0,0] neg_hi:[1,0,0]
	v_pk_fma_f32 v[116:117], v[28:29], v[120:121], v[116:117]
	v_pk_fma_f32 v[114:115], v[72:73], v[114:115], v[22:23]
	v_mov_b32_e32 v73, v72
	v_pk_fma_f32 v[116:117], v[72:73], v[116:117], v[24:25]
	v_cvt_pk_bf16_f32 v118, v122, v123
	v_cvt_pk_bf16_f32 v119, v124, v125
	s_and_saveexec_b64 s[4:5], s[44:45]
	s_xor_b64 s[4:5], exec, s[4:5]
	v_cmp_lt_i32_e32 vcc, 1, v172
	s_mov_b64 s[36:37], 0
	s_mov_b64 s[54:55], 0
	s_and_saveexec_b64 s[56:57], vcc
	s_xor_b64 s[56:57], exec, s[56:57]
	v_cmp_ne_u32_e32 vcc, 2, v172
	s_and_b64 s[54:55], vcc, exec
	s_andn2_saveexec_b64 s[56:57], s[56:57]
	v_cmp_ne_u32_e32 vcc, 1, v172
	s_andn2_b64 s[36:37], s[54:55], exec
	s_and_b64 s[54:55], vcc, exec
	s_or_b64 s[54:55], s[36:37], s[54:55]
	s_mov_b64 s[36:37], exec
	s_or_b64 exec, exec, s[56:57]
	v_mov_b64_e32 v[122:123], v[116:117]
	v_mov_b64_e32 v[120:121], v[114:115]
	s_and_saveexec_b64 s[56:57], s[54:55]
	s_xor_b64 s[54:55], exec, s[56:57]
	s_or_b64 exec, exec, s[54:55]
	s_and_saveexec_b64 s[54:55], s[36:37]
	s_or_b64 exec, exec, s[54:55]
	s_andn2_saveexec_b64 s[4:5], s[4:5]
	s_or_b64 exec, exec, s[4:5]
	v_add_lshl_u32 v72, v132, v138, 1
	v_cvt_pk_bf16_f32 v120, v120, v121
	v_cvt_pk_bf16_f32 v121, v122, v123
	buffer_store_dwordx4 v[118:121], v72, s[28:31], 0 offen sc1
	s_and_b64 vcc, exec, s[46:47]
	s_nop 0
	v_mov_b32_e32 v121, v206
	s_nop 0
	v_lshl_add_u32 v120, v121, 3, s33
	s_cbranch_vccnz .LBB0_611_sg2
	ds_read_b64 v[118:119], v120
	s_waitcnt lgkmcnt(0)
	v_mov_b32_e32 v72, v119
	s_branch .LBB0_612_sg2

.LBB0_612_sg2:
	v_pk_fma_f32 v[112:113], v[190:191], v[118:119], v[112:113] op_sel_hi:[1,0,1]
	v_pk_fma_f32 v[110:111], v[70:71], v[118:119], v[110:111] op_sel_hi:[1,0,1] neg_lo:[1,0,0] neg_hi:[1,0,0]
	v_pk_fma_f32 v[112:113], v[72:73], v[112:113], v[68:69] op_sel_hi:[0,1,1]
	v_pk_fma_f32 v[110:111], v[72:73], v[110:111], v[66:67] op_sel_hi:[0,1,1]
	s_and_saveexec_b64 s[4:5], s[42:43]
	s_xor_b64 s[4:5], exec, s[4:5]
	v_cmp_lt_i32_e32 vcc, 1, v180
	s_mov_b64 s[36:37], 0
	s_mov_b64 s[54:55], 0
	s_and_saveexec_b64 s[56:57], vcc
	s_xor_b64 s[56:57], exec, s[56:57]
	v_cmp_ne_u32_e32 vcc, 2, v180
	s_and_b64 s[54:55], vcc, exec
	s_andn2_saveexec_b64 s[56:57], s[56:57]
	v_cmp_ne_u32_e32 vcc, 1, v180
	s_andn2_b64 s[36:37], s[54:55], exec
	s_and_b64 s[54:55], vcc, exec
	s_or_b64 s[54:55], s[36:37], s[54:55]
	s_mov_b64 s[36:37], exec
	s_or_b64 exec, exec, s[56:57]
	v_mov_b64_e32 v[116:117], v[112:113]
	v_mov_b64_e32 v[114:115], v[110:111]
	s_and_saveexec_b64 s[56:57], s[54:55]
	s_xor_b64 s[54:55], exec, s[56:57]
	s_or_b64 exec, exec, s[54:55]
	s_and_saveexec_b64 s[54:55], s[36:37]
	s_or_b64 exec, exec, s[54:55]
	s_andn2_saveexec_b64 s[4:5], s[4:5]
	s_or_b64 exec, exec, s[4:5]
	v_mov_b32_e32 v119, v118
	v_mov_b32_e32 v112, v118
	v_mov_b32_e32 v113, v118
	v_mov_b32_e32 v73, v72
	v_pk_fma_f32 v[108:109], v[60:61], v[112:113], v[108:109]
	v_pk_fma_f32 v[106:107], v[58:59], v[118:119], v[106:107] neg_lo:[1,0,0] neg_hi:[1,0,0]
	v_mov_b32_e32 v112, v72
	v_mov_b32_e32 v113, v72
	v_pk_fma_f32 v[106:107], v[72:73], v[106:107], v[54:55]
	v_pk_fma_f32 v[108:109], v[112:113], v[108:109], v[56:57]
	v_cvt_pk_bf16_f32 v110, v114, v115
	v_cvt_pk_bf16_f32 v111, v116, v117
	s_and_saveexec_b64 s[4:5], s[42:43]
	s_xor_b64 s[4:5], exec, s[4:5]
	v_cmp_lt_i32_e32 vcc, 1, v180
	s_mov_b64 s[36:37], 0
	s_mov_b64 s[54:55], 0
	s_and_saveexec_b64 s[56:57], vcc
	s_xor_b64 s[56:57], exec, s[56:57]
	v_cmp_ne_u32_e32 vcc, 2, v180
	s_and_b64 s[54:55], vcc, exec
	s_andn2_saveexec_b64 s[56:57], s[56:57]
	v_cmp_ne_u32_e32 vcc, 1, v180
	s_andn2_b64 s[36:37], s[54:55], exec
	s_and_b64 s[54:55], vcc, exec
	s_or_b64 s[54:55], s[36:37], s[54:55]
	s_mov_b64 s[36:37], exec
	s_or_b64 exec, exec, s[56:57]
	v_mov_b64_e32 v[114:115], v[108:109]
	v_mov_b64_e32 v[112:113], v[106:107]
	s_and_saveexec_b64 s[56:57], s[54:55]
	s_xor_b64 s[54:55], exec, s[56:57]
	s_or_b64 exec, exec, s[54:55]
	s_and_saveexec_b64 s[54:55], s[36:37]
	s_or_b64 exec, exec, s[54:55]
	s_andn2_saveexec_b64 s[4:5], s[4:5]
	s_or_b64 exec, exec, s[4:5]
	v_add_lshl_u32 v116, v121, s51, 10
	v_add_lshl_u32 v106, v116, v146, 1
	v_cvt_pk_bf16_f32 v112, v112, v113
	v_cvt_pk_bf16_f32 v113, v114, v115
	buffer_store_dwordx4 v[110:113], v106, s[28:31], 0 offen sc1
	v_mov_b32_e32 v106, v118
	v_mov_b32_e32 v107, v118
	v_pk_fma_f32 v[104:105], v[44:45], v[106:107], v[104:105]
	v_pk_fma_f32 v[102:103], v[42:43], v[118:119], v[102:103] neg_lo:[1,0,0] neg_hi:[1,0,0]
	v_mov_b32_e32 v106, v72
	v_mov_b32_e32 v107, v72
	v_pk_fma_f32 v[102:103], v[72:73], v[102:103], v[38:39]
	v_pk_fma_f32 v[104:105], v[106:107], v[104:105], v[40:41]
	s_and_saveexec_b64 s[4:5], s[44:45]
	s_xor_b64 s[4:5], exec, s[4:5]
	v_cmp_lt_i32_e32 vcc, 1, v172
	s_mov_b64 s[36:37], 0
	s_mov_b64 s[54:55], 0
	s_and_saveexec_b64 s[56:57], vcc
	s_xor_b64 s[56:57], exec, s[56:57]
	v_cmp_ne_u32_e32 vcc, 2, v172
	s_and_b64 s[54:55], vcc, exec
	s_andn2_saveexec_b64 s[56:57], s[56:57]
	v_cmp_ne_u32_e32 vcc, 1, v172
	s_andn2_b64 s[36:37], s[54:55], exec
	s_and_b64 s[54:55], vcc, exec
	s_or_b64 s[54:55], s[36:37], s[54:55]
	s_mov_b64 s[36:37], exec
	s_or_b64 exec, exec, s[56:57]
	v_mov_b64_e32 v[108:109], v[104:105]
	v_mov_b64_e32 v[106:107], v[102:103]
	s_and_saveexec_b64 s[56:57], s[54:55]
	s_xor_b64 s[54:55], exec, s[56:57]
	s_or_b64 exec, exec, s[54:55]
	s_and_saveexec_b64 s[54:55], s[36:37]
	s_or_b64 exec, exec, s[54:55]
	s_andn2_saveexec_b64 s[4:5], s[4:5]
	s_or_b64 exec, exec, s[4:5]
	v_mov_b32_e32 v104, v118
	v_mov_b32_e32 v105, v118
	v_pk_fma_f32 v[98:99], v[26:27], v[118:119], v[98:99] neg_lo:[1,0,0] neg_hi:[1,0,0]
	v_pk_fma_f32 v[100:101], v[28:29], v[104:105], v[100:101]
	v_pk_fma_f32 v[98:99], v[72:73], v[98:99], v[22:23]
	v_mov_b32_e32 v73, v72
	v_pk_fma_f32 v[100:101], v[72:73], v[100:101], v[24:25]
	v_cvt_pk_bf16_f32 v102, v106, v107
	v_cvt_pk_bf16_f32 v103, v108, v109
	s_and_saveexec_b64 s[4:5], s[44:45]
	s_xor_b64 s[4:5], exec, s[4:5]
	v_cmp_lt_i32_e32 vcc, 1, v172
	s_mov_b64 s[36:37], 0
	s_mov_b64 s[54:55], 0
	s_and_saveexec_b64 s[56:57], vcc
	s_xor_b64 s[56:57], exec, s[56:57]
	v_cmp_ne_u32_e32 vcc, 2, v172
	s_and_b64 s[54:55], vcc, exec
	s_andn2_saveexec_b64 s[56:57], s[56:57]
	v_cmp_ne_u32_e32 vcc, 1, v172
	s_andn2_b64 s[36:37], s[54:55], exec
	s_and_b64 s[54:55], vcc, exec
	s_or_b64 s[54:55], s[36:37], s[54:55]
	s_mov_b64 s[36:37], exec
	s_or_b64 exec, exec, s[56:57]
	v_mov_b64_e32 v[106:107], v[100:101]
	v_mov_b64_e32 v[104:105], v[98:99]
	s_and_saveexec_b64 s[56:57], s[54:55]
	s_xor_b64 s[54:55], exec, s[56:57]
	s_or_b64 exec, exec, s[54:55]
	s_and_saveexec_b64 s[54:55], s[36:37]
	s_or_b64 exec, exec, s[54:55]
	s_andn2_saveexec_b64 s[4:5], s[4:5]
	s_or_b64 exec, exec, s[4:5]
	v_add_lshl_u32 v72, v116, v138, 1
	s_and_b64 vcc, exec, s[46:47]
	v_cvt_pk_bf16_f32 v104, v104, v105
	v_cvt_pk_bf16_f32 v105, v106, v107
	buffer_store_dwordx4 v[102:105], v72, s[28:31], 0 offen sc1
	s_cbranch_vccnz .LBB0_662_sg2
	ds_read_b64 v[102:103], v120 offset:128
	s_waitcnt lgkmcnt(0)
	v_mov_b32_e32 v72, v103
	s_branch .LBB0_663_sg2

.LBB0_663_sg2:
	v_pk_fma_f32 v[96:97], v[190:191], v[102:103], v[96:97] op_sel_hi:[1,0,1]
	v_pk_fma_f32 v[94:95], v[70:71], v[102:103], v[94:95] op_sel_hi:[1,0,1] neg_lo:[1,0,0] neg_hi:[1,0,0]
	v_pk_fma_f32 v[96:97], v[72:73], v[96:97], v[68:69] op_sel_hi:[0,1,1]
	v_pk_fma_f32 v[94:95], v[72:73], v[94:95], v[66:67] op_sel_hi:[0,1,1]
	s_and_saveexec_b64 s[4:5], s[42:43]
	s_xor_b64 s[4:5], exec, s[4:5]
	v_cmp_lt_i32_e32 vcc, 1, v180
	s_mov_b64 s[36:37], 0
	s_mov_b64 s[54:55], 0
	s_and_saveexec_b64 s[56:57], vcc
	s_xor_b64 s[56:57], exec, s[56:57]
	v_cmp_ne_u32_e32 vcc, 2, v180
	s_and_b64 s[54:55], vcc, exec
	s_andn2_saveexec_b64 s[56:57], s[56:57]
	v_cmp_ne_u32_e32 vcc, 1, v180
	s_andn2_b64 s[36:37], s[54:55], exec
	s_and_b64 s[54:55], vcc, exec
	s_or_b64 s[54:55], s[36:37], s[54:55]
	s_mov_b64 s[36:37], exec
	s_or_b64 exec, exec, s[56:57]
	v_mov_b64_e32 v[100:101], v[96:97]
	v_mov_b64_e32 v[98:99], v[94:95]
	s_and_saveexec_b64 s[56:57], s[54:55]
	s_xor_b64 s[54:55], exec, s[56:57]
	s_or_b64 exec, exec, s[54:55]
	s_and_saveexec_b64 s[54:55], s[36:37]
	s_or_b64 exec, exec, s[54:55]
	s_andn2_saveexec_b64 s[4:5], s[4:5]
	s_or_b64 exec, exec, s[4:5]
	v_mov_b32_e32 v103, v102
	v_mov_b32_e32 v96, v102
	v_mov_b32_e32 v97, v102
	v_mov_b32_e32 v73, v72
	v_pk_fma_f32 v[92:93], v[60:61], v[96:97], v[92:93]
	v_pk_fma_f32 v[90:91], v[58:59], v[102:103], v[90:91] neg_lo:[1,0,0] neg_hi:[1,0,0]
	v_mov_b32_e32 v96, v72
	v_mov_b32_e32 v97, v72
	v_pk_fma_f32 v[90:91], v[72:73], v[90:91], v[54:55]
	v_pk_fma_f32 v[92:93], v[96:97], v[92:93], v[56:57]
	v_cvt_pk_bf16_f32 v94, v98, v99
	v_cvt_pk_bf16_f32 v95, v100, v101
	s_and_saveexec_b64 s[4:5], s[42:43]
	s_xor_b64 s[4:5], exec, s[4:5]
	v_cmp_lt_i32_e32 vcc, 1, v180
	s_mov_b64 s[36:37], 0
	s_mov_b64 s[54:55], 0
	s_and_saveexec_b64 s[56:57], vcc
	s_xor_b64 s[56:57], exec, s[56:57]
	v_cmp_ne_u32_e32 vcc, 2, v180
	s_and_b64 s[54:55], vcc, exec
	s_andn2_saveexec_b64 s[56:57], s[56:57]
	v_cmp_ne_u32_e32 vcc, 1, v180
	s_andn2_b64 s[36:37], s[54:55], exec
	s_and_b64 s[54:55], vcc, exec
	s_or_b64 s[54:55], s[36:37], s[54:55]
	s_mov_b64 s[36:37], exec
	s_or_b64 exec, exec, s[56:57]
	v_mov_b64_e32 v[98:99], v[92:93]
	v_mov_b64_e32 v[96:97], v[90:91]
	s_and_saveexec_b64 s[56:57], s[54:55]
	s_xor_b64 s[54:55], exec, s[56:57]
	s_or_b64 exec, exec, s[54:55]
	s_and_saveexec_b64 s[54:55], s[36:37]
	s_or_b64 exec, exec, s[54:55]
	s_andn2_saveexec_b64 s[4:5], s[4:5]
	s_or_b64 exec, exec, s[4:5]
	v_add_u32_e32 v100, 0x4000, v116
	v_add_lshl_u32 v90, v100, v146, 1
	v_cvt_pk_bf16_f32 v96, v96, v97
	v_cvt_pk_bf16_f32 v97, v98, v99
	buffer_store_dwordx4 v[94:97], v90, s[28:31], 0 offen sc1
	v_mov_b32_e32 v90, v102
	v_mov_b32_e32 v91, v102
	v_pk_fma_f32 v[88:89], v[44:45], v[90:91], v[88:89]
	v_pk_fma_f32 v[86:87], v[42:43], v[102:103], v[86:87] neg_lo:[1,0,0] neg_hi:[1,0,0]
	v_mov_b32_e32 v90, v72
	v_mov_b32_e32 v91, v72
	v_pk_fma_f32 v[86:87], v[72:73], v[86:87], v[38:39]
	v_pk_fma_f32 v[88:89], v[90:91], v[88:89], v[40:41]
	s_and_saveexec_b64 s[4:5], s[44:45]
	s_xor_b64 s[4:5], exec, s[4:5]
	v_cmp_lt_i32_e32 vcc, 1, v172
	s_mov_b64 s[36:37], 0
	s_mov_b64 s[54:55], 0
	s_and_saveexec_b64 s[56:57], vcc
	s_xor_b64 s[56:57], exec, s[56:57]
	v_cmp_ne_u32_e32 vcc, 2, v172
	s_and_b64 s[54:55], vcc, exec
	s_andn2_saveexec_b64 s[56:57], s[56:57]
	v_cmp_ne_u32_e32 vcc, 1, v172
	s_andn2_b64 s[36:37], s[54:55], exec
	s_and_b64 s[54:55], vcc, exec
	s_or_b64 s[54:55], s[36:37], s[54:55]
	s_mov_b64 s[36:37], exec
	s_or_b64 exec, exec, s[56:57]
	v_mov_b64_e32 v[92:93], v[88:89]
	v_mov_b64_e32 v[90:91], v[86:87]
	s_and_saveexec_b64 s[56:57], s[54:55]
	s_xor_b64 s[54:55], exec, s[56:57]
	s_or_b64 exec, exec, s[54:55]
	s_and_saveexec_b64 s[54:55], s[36:37]
	s_or_b64 exec, exec, s[54:55]
	s_andn2_saveexec_b64 s[4:5], s[4:5]
	s_or_b64 exec, exec, s[4:5]
	v_mov_b32_e32 v88, v102
	v_mov_b32_e32 v89, v102
	v_pk_fma_f32 v[82:83], v[26:27], v[102:103], v[82:83] neg_lo:[1,0,0] neg_hi:[1,0,0]
	v_pk_fma_f32 v[84:85], v[28:29], v[88:89], v[84:85]
	v_pk_fma_f32 v[82:83], v[72:73], v[82:83], v[22:23]
	v_mov_b32_e32 v73, v72
	v_pk_fma_f32 v[84:85], v[72:73], v[84:85], v[24:25]
	v_cvt_pk_bf16_f32 v86, v90, v91
	v_cvt_pk_bf16_f32 v87, v92, v93
	s_and_saveexec_b64 s[4:5], s[44:45]
	s_xor_b64 s[4:5], exec, s[4:5]
	v_cmp_lt_i32_e32 vcc, 1, v172
	s_mov_b64 s[36:37], 0
	s_mov_b64 s[54:55], 0
	s_and_saveexec_b64 s[56:57], vcc
	s_xor_b64 s[56:57], exec, s[56:57]
	v_cmp_ne_u32_e32 vcc, 2, v172
	s_and_b64 s[54:55], vcc, exec
	s_andn2_saveexec_b64 s[56:57], s[56:57]
	v_cmp_ne_u32_e32 vcc, 1, v172
	s_andn2_b64 s[36:37], s[54:55], exec
	s_and_b64 s[54:55], vcc, exec
	s_or_b64 s[54:55], s[36:37], s[54:55]
	s_mov_b64 s[36:37], exec
	s_or_b64 exec, exec, s[56:57]
	v_mov_b64_e32 v[90:91], v[84:85]
	v_mov_b64_e32 v[88:89], v[82:83]
	s_and_saveexec_b64 s[56:57], s[54:55]
	s_xor_b64 s[54:55], exec, s[56:57]
	s_or_b64 exec, exec, s[54:55]
	s_and_saveexec_b64 s[54:55], s[36:37]
	s_or_b64 exec, exec, s[54:55]
	s_andn2_saveexec_b64 s[4:5], s[4:5]
	s_or_b64 exec, exec, s[4:5]
	v_add_lshl_u32 v72, v100, v138, 1
	v_cvt_pk_bf16_f32 v88, v88, v89
	v_cvt_pk_bf16_f32 v89, v90, v91
	buffer_store_dwordx4 v[86:89], v72, s[28:31], 0 offen sc1
	v_mov_b32_e32 v91, v207
	s_and_b64 vcc, exec, s[46:47]
	v_lshl_add_u32 v90, v91, 3, s33
	s_cbranch_vccnz .LBB0_713_sg2
	ds_read_b64 v[88:89], v90
	s_waitcnt lgkmcnt(0)
	v_mov_b32_e32 v86, v89
	s_branch .LBB0_714_sg2

.LBB0_714_sg2:
	v_pk_fma_f32 v[72:73], v[190:191], v[88:89], v[80:81] op_sel_hi:[1,0,1]
	v_pk_fma_f32 v[78:79], v[70:71], v[88:89], v[78:79] op_sel_hi:[1,0,1] neg_lo:[1,0,0] neg_hi:[1,0,0]
	v_pk_fma_f32 v[80:81], v[86:87], v[72:73], v[68:69] op_sel_hi:[0,1,1]
	v_pk_fma_f32 v[78:79], v[86:87], v[78:79], v[66:67] op_sel_hi:[0,1,1]
	s_and_saveexec_b64 s[4:5], s[42:43]
	s_xor_b64 s[4:5], exec, s[4:5]
	v_cmp_lt_i32_e32 vcc, 1, v180
	s_mov_b64 s[36:37], 0
	s_mov_b64 s[54:55], 0
	s_and_saveexec_b64 s[56:57], vcc
	s_xor_b64 s[56:57], exec, s[56:57]
	v_cmp_ne_u32_e32 vcc, 2, v180
	s_and_b64 s[54:55], vcc, exec
	s_andn2_saveexec_b64 s[56:57], s[56:57]
	v_cmp_ne_u32_e32 vcc, 1, v180
	s_andn2_b64 s[36:37], s[54:55], exec
	s_and_b64 s[54:55], vcc, exec
	s_or_b64 s[54:55], s[36:37], s[54:55]
	s_mov_b64 s[36:37], exec
	s_or_b64 exec, exec, s[56:57]
	v_mov_b64_e32 v[84:85], v[80:81]
	v_mov_b64_e32 v[82:83], v[78:79]
	s_and_saveexec_b64 s[56:57], s[54:55]
	s_xor_b64 s[54:55], exec, s[56:57]
	s_or_b64 exec, exec, s[54:55]
	s_and_saveexec_b64 s[54:55], s[36:37]
	s_or_b64 exec, exec, s[54:55]
	s_andn2_saveexec_b64 s[4:5], s[4:5]
	s_or_b64 exec, exec, s[4:5]
	v_mov_b32_e32 v89, v88
	v_mov_b32_e32 v78, v88
	v_mov_b32_e32 v79, v88
	v_mov_b32_e32 v87, v86
	v_pk_fma_f32 v[76:77], v[60:61], v[78:79], v[76:77]
	v_pk_fma_f32 v[74:75], v[58:59], v[88:89], v[74:75] neg_lo:[1,0,0] neg_hi:[1,0,0]
	v_mov_b32_e32 v78, v86
	v_mov_b32_e32 v79, v86
	v_pk_fma_f32 v[74:75], v[86:87], v[74:75], v[54:55]
	v_pk_fma_f32 v[76:77], v[78:79], v[76:77], v[56:57]
	v_cvt_pk_bf16_f32 v72, v82, v83
	v_cvt_pk_bf16_f32 v73, v84, v85
	s_and_saveexec_b64 s[4:5], s[42:43]
	s_xor_b64 s[4:5], exec, s[4:5]
	v_cmp_lt_i32_e32 vcc, 1, v180
	s_mov_b64 s[36:37], 0
	s_mov_b64 s[54:55], 0
	s_and_saveexec_b64 s[56:57], vcc
	s_xor_b64 s[56:57], exec, s[56:57]
	v_cmp_ne_u32_e32 vcc, 2, v180
	s_and_b64 s[54:55], vcc, exec
	s_andn2_saveexec_b64 s[56:57], s[56:57]
	v_cmp_ne_u32_e32 vcc, 1, v180
	s_andn2_b64 s[36:37], s[54:55], exec
	s_and_b64 s[54:55], vcc, exec
	s_or_b64 s[54:55], s[36:37], s[54:55]
	s_mov_b64 s[36:37], exec
	s_or_b64 exec, exec, s[56:57]
	v_mov_b64_e32 v[80:81], v[76:77]
	v_mov_b64_e32 v[78:79], v[74:75]
	s_and_saveexec_b64 s[56:57], s[54:55]
	s_xor_b64 s[54:55], exec, s[56:57]
	s_or_b64 exec, exec, s[54:55]
	s_and_saveexec_b64 s[54:55], s[36:37]
	s_or_b64 exec, exec, s[54:55]
	s_andn2_saveexec_b64 s[4:5], s[4:5]
	s_or_b64 exec, exec, s[4:5]
	v_add_lshl_u32 v76, v91, s51, 10
	v_add_lshl_u32 v77, v76, v146, 1
	v_cvt_pk_bf16_f32 v74, v78, v79
	v_cvt_pk_bf16_f32 v75, v80, v81
	buffer_store_dwordx4 v[72:75], v77, s[28:31], 0 offen sc1
	v_pk_fma_f32 v[50:51], v[42:43], v[88:89], v[50:51] neg_lo:[1,0,0] neg_hi:[1,0,0]
	s_nop 0
	v_mov_b32_e32 v72, v88
	v_mov_b32_e32 v73, v88
	v_pk_fma_f32 v[52:53], v[44:45], v[72:73], v[52:53]
	v_mov_b32_e32 v72, v86
	v_mov_b32_e32 v73, v86
	v_pk_fma_f32 v[50:51], v[86:87], v[50:51], v[38:39]
	v_pk_fma_f32 v[52:53], v[72:73], v[52:53], v[40:41]
	s_and_saveexec_b64 s[4:5], s[44:45]
	s_xor_b64 s[4:5], exec, s[4:5]
	v_cmp_lt_i32_e32 vcc, 1, v172
	s_mov_b64 s[36:37], 0
	s_mov_b64 s[54:55], 0
	s_and_saveexec_b64 s[56:57], vcc
	s_xor_b64 s[56:57], exec, s[56:57]
	v_cmp_ne_u32_e32 vcc, 2, v172
	s_and_b64 s[54:55], vcc, exec
	s_andn2_saveexec_b64 s[56:57], s[56:57]
	v_cmp_ne_u32_e32 vcc, 1, v172
	s_andn2_b64 s[36:37], s[54:55], exec
	s_and_b64 s[54:55], vcc, exec
	s_or_b64 s[54:55], s[36:37], s[54:55]
	s_mov_b64 s[36:37], exec
	s_or_b64 exec, exec, s[56:57]
	v_mov_b64_e32 v[74:75], v[52:53]
	v_mov_b64_e32 v[72:73], v[50:51]
	s_and_saveexec_b64 s[56:57], s[54:55]
	s_xor_b64 s[54:55], exec, s[56:57]
	s_or_b64 exec, exec, s[54:55]
	s_and_saveexec_b64 s[54:55], s[36:37]
	s_or_b64 exec, exec, s[54:55]
	s_andn2_saveexec_b64 s[4:5], s[4:5]
	s_or_b64 exec, exec, s[4:5]
	v_mov_b32_e32 v52, v88
	v_mov_b32_e32 v53, v88
	v_pk_fma_f32 v[34:35], v[26:27], v[88:89], v[34:35] neg_lo:[1,0,0] neg_hi:[1,0,0]
	v_pk_fma_f32 v[36:37], v[28:29], v[52:53], v[36:37]
	v_pk_fma_f32 v[34:35], v[86:87], v[34:35], v[22:23]
	v_mov_b32_e32 v87, v86
	v_pk_fma_f32 v[36:37], v[86:87], v[36:37], v[24:25]
	v_cvt_pk_bf16_f32 v50, v72, v73
	v_cvt_pk_bf16_f32 v51, v74, v75
	s_and_saveexec_b64 s[4:5], s[44:45]
	s_xor_b64 s[4:5], exec, s[4:5]
	v_cmp_lt_i32_e32 vcc, 1, v172
	s_mov_b64 s[36:37], 0
	s_mov_b64 s[54:55], 0
	s_and_saveexec_b64 s[56:57], vcc
	s_xor_b64 s[56:57], exec, s[56:57]
	v_cmp_ne_u32_e32 vcc, 2, v172
	s_and_b64 s[54:55], vcc, exec
	s_andn2_saveexec_b64 s[56:57], s[56:57]
	v_cmp_ne_u32_e32 vcc, 1, v172
	s_andn2_b64 s[36:37], s[54:55], exec
	s_and_b64 s[54:55], vcc, exec
	s_or_b64 s[54:55], s[36:37], s[54:55]
	s_mov_b64 s[36:37], exec
	s_or_b64 exec, exec, s[56:57]
	v_mov_b64_e32 v[74:75], v[36:37]
	v_mov_b64_e32 v[72:73], v[34:35]
	s_and_saveexec_b64 s[56:57], s[54:55]
	s_xor_b64 s[54:55], exec, s[56:57]
	s_or_b64 exec, exec, s[54:55]
	s_and_saveexec_b64 s[54:55], s[36:37]
	s_or_b64 exec, exec, s[54:55]
	s_andn2_saveexec_b64 s[4:5], s[4:5]
	s_or_b64 exec, exec, s[4:5]
	v_add_lshl_u32 v34, v76, v138, 1
	s_and_b64 vcc, exec, s[46:47]
	v_cvt_pk_bf16_f32 v52, v72, v73
	v_cvt_pk_bf16_f32 v53, v74, v75
	buffer_store_dwordx4 v[50:53], v34, s[28:31], 0 offen sc1
	s_cbranch_vccnz .LBB0_764_sg2
	ds_read_b64 v[52:53], v90 offset:128
	s_waitcnt lgkmcnt(0)
	v_mov_b32_e32 v50, v53
	s_branch .LBB0_765_sg2

.LBB0_765_sg2:
	v_pk_fma_f32 v[20:21], v[190:191], v[52:53], v[20:21] op_sel_hi:[1,0,1]
	v_pk_fma_f32 v[18:19], v[70:71], v[52:53], v[18:19] op_sel_hi:[1,0,1] neg_lo:[1,0,0] neg_hi:[1,0,0]
	v_pk_fma_f32 v[20:21], v[50:51], v[20:21], v[68:69] op_sel_hi:[0,1,1]
	v_pk_fma_f32 v[18:19], v[50:51], v[18:19], v[66:67] op_sel_hi:[0,1,1]
	s_and_saveexec_b64 s[4:5], s[42:43]
	s_xor_b64 s[4:5], exec, s[4:5]
	v_cmp_lt_i32_e32 vcc, 1, v180
	s_mov_b64 s[36:37], 0
	s_mov_b64 s[46:47], 0
	s_and_saveexec_b64 s[54:55], vcc
	s_xor_b64 s[54:55], exec, s[54:55]
	v_cmp_ne_u32_e32 vcc, 2, v180
	s_and_b64 s[46:47], vcc, exec
	s_andn2_saveexec_b64 s[54:55], s[54:55]
	v_cmp_ne_u32_e32 vcc, 1, v180
	s_andn2_b64 s[36:37], s[46:47], exec
	s_and_b64 s[46:47], vcc, exec
	s_or_b64 s[46:47], s[36:37], s[46:47]
	s_mov_b64 s[36:37], exec
	s_or_b64 exec, exec, s[54:55]
	v_mov_b64_e32 v[36:37], v[20:21]
	v_mov_b64_e32 v[34:35], v[18:19]
	s_and_saveexec_b64 s[54:55], s[46:47]
	s_xor_b64 s[46:47], exec, s[54:55]
	s_or_b64 exec, exec, s[46:47]
	s_and_saveexec_b64 s[46:47], s[36:37]
	s_or_b64 exec, exec, s[46:47]
	s_andn2_saveexec_b64 s[4:5], s[4:5]
	s_or_b64 exec, exec, s[4:5]
	v_mov_b32_e32 v53, v52
	v_mov_b32_e32 v20, v52
	v_mov_b32_e32 v21, v52
	v_mov_b32_e32 v51, v50
	v_pk_fma_f32 v[12:13], v[60:61], v[20:21], v[12:13]
	v_pk_fma_f32 v[10:11], v[58:59], v[52:53], v[10:11] neg_lo:[1,0,0] neg_hi:[1,0,0]
	v_mov_b32_e32 v20, v50
	v_mov_b32_e32 v21, v50
	v_pk_fma_f32 v[10:11], v[50:51], v[10:11], v[54:55]
	v_pk_fma_f32 v[12:13], v[20:21], v[12:13], v[56:57]
	v_cvt_pk_bf16_f32 v18, v34, v35
	v_cvt_pk_bf16_f32 v19, v36, v37
	s_and_saveexec_b64 s[4:5], s[42:43]
	s_xor_b64 s[4:5], exec, s[4:5]
	v_cmp_lt_i32_e32 vcc, 1, v180
	s_mov_b64 s[36:37], 0
	s_mov_b64 s[42:43], 0
	s_and_saveexec_b64 s[46:47], vcc
	s_xor_b64 s[46:47], exec, s[46:47]
	v_cmp_ne_u32_e32 vcc, 2, v180
	s_and_b64 s[42:43], vcc, exec
	s_andn2_saveexec_b64 s[46:47], s[46:47]
	v_cmp_ne_u32_e32 vcc, 1, v180
	s_andn2_b64 s[36:37], s[42:43], exec
	s_and_b64 s[42:43], vcc, exec
	s_or_b64 s[42:43], s[36:37], s[42:43]
	s_mov_b64 s[36:37], exec
	s_or_b64 exec, exec, s[46:47]
	v_mov_b64_e32 v[36:37], v[12:13]
	v_mov_b64_e32 v[34:35], v[10:11]
	s_and_saveexec_b64 s[46:47], s[42:43]
	s_xor_b64 s[42:43], exec, s[46:47]
	s_or_b64 exec, exec, s[42:43]
	s_and_saveexec_b64 s[42:43], s[36:37]
	s_or_b64 exec, exec, s[42:43]
	s_andn2_saveexec_b64 s[4:5], s[4:5]
	s_or_b64 exec, exec, s[4:5]
	v_add_u32_e32 v46, 0x4000, v76
	v_add_lshl_u32 v10, v46, v146, 1
	v_cvt_pk_bf16_f32 v20, v34, v35
	v_cvt_pk_bf16_f32 v21, v36, v37
	buffer_store_dwordx4 v[18:21], v10, s[28:31], 0 offen sc1
	v_mov_b32_e32 v10, v52
	v_mov_b32_e32 v11, v52
	v_pk_fma_f32 v[8:9], v[44:45], v[10:11], v[8:9]
	v_pk_fma_f32 v[6:7], v[42:43], v[52:53], v[6:7] neg_lo:[1,0,0] neg_hi:[1,0,0]
	v_mov_b32_e32 v10, v50
	v_mov_b32_e32 v11, v50
	v_pk_fma_f32 v[6:7], v[50:51], v[6:7], v[38:39]
	v_pk_fma_f32 v[8:9], v[10:11], v[8:9], v[40:41]
	s_and_saveexec_b64 s[4:5], s[44:45]
	s_xor_b64 s[4:5], exec, s[4:5]
	v_cmp_lt_i32_e32 vcc, 1, v172
	s_mov_b64 s[36:37], 0
	s_mov_b64 s[42:43], 0
	s_and_saveexec_b64 s[46:47], vcc
	s_xor_b64 s[46:47], exec, s[46:47]
	v_cmp_ne_u32_e32 vcc, 2, v172
	s_and_b64 s[42:43], vcc, exec
	s_andn2_saveexec_b64 s[46:47], s[46:47]
	v_cmp_ne_u32_e32 vcc, 1, v172
	s_andn2_b64 s[36:37], s[42:43], exec
	s_and_b64 s[42:43], vcc, exec
	s_or_b64 s[42:43], s[36:37], s[42:43]
	s_mov_b64 s[36:37], exec
	s_or_b64 exec, exec, s[46:47]
	v_mov_b64_e32 v[12:13], v[8:9]
	v_mov_b64_e32 v[10:11], v[6:7]
	s_and_saveexec_b64 s[46:47], s[42:43]
	s_xor_b64 s[42:43], exec, s[46:47]
	s_or_b64 exec, exec, s[42:43]
	s_and_saveexec_b64 s[42:43], s[36:37]
	s_or_b64 exec, exec, s[42:43]
	s_andn2_saveexec_b64 s[4:5], s[4:5]
	s_or_b64 exec, exec, s[4:5]
	v_mov_b32_e32 v8, v52
	v_mov_b32_e32 v9, v52
	v_pk_fma_f32 v[2:3], v[26:27], v[52:53], v[2:3] neg_lo:[1,0,0] neg_hi:[1,0,0]
	v_pk_fma_f32 v[4:5], v[28:29], v[8:9], v[4:5]
	v_pk_fma_f32 v[2:3], v[50:51], v[2:3], v[22:23]
	v_mov_b32_e32 v51, v50
	v_pk_fma_f32 v[4:5], v[50:51], v[4:5], v[24:25]
	v_cvt_pk_bf16_f32 v6, v10, v11
	v_cvt_pk_bf16_f32 v7, v12, v13
	s_and_saveexec_b64 s[4:5], s[44:45]
	s_xor_b64 s[4:5], exec, s[4:5]
	v_cmp_lt_i32_e32 vcc, 1, v172
	s_mov_b64 s[36:37], 0
	s_mov_b64 s[42:43], 0
	s_and_saveexec_b64 s[44:45], vcc
	s_xor_b64 s[44:45], exec, s[44:45]
	v_cmp_ne_u32_e32 vcc, 2, v172
	s_and_b64 s[42:43], vcc, exec
	s_andn2_saveexec_b64 s[44:45], s[44:45]
	v_cmp_ne_u32_e32 vcc, 1, v172
	s_andn2_b64 s[36:37], s[42:43], exec
	s_and_b64 s[42:43], vcc, exec
	s_or_b64 s[42:43], s[36:37], s[42:43]
	s_mov_b64 s[36:37], exec
	s_or_b64 exec, exec, s[44:45]
	v_mov_b64_e32 v[10:11], v[4:5]
	v_mov_b64_e32 v[8:9], v[2:3]
	s_and_saveexec_b64 s[44:45], s[42:43]
	s_xor_b64 s[42:43], exec, s[44:45]
	s_or_b64 exec, exec, s[42:43]
	s_and_saveexec_b64 s[42:43], s[36:37]
	s_or_b64 exec, exec, s[42:43]
	s_andn2_saveexec_b64 s[4:5], s[4:5]
	s_branch .LBB0_394

.LBB0_408_sg3:
	s_waitcnt vmcnt(0) lgkmcnt(0)
	v_xor_b32_e32 v191, 0x80000000, v73
	v_xor_b32_e32 v190, 0x80000000, v72
	v_pk_fma_f32 v[72:73], v[190:191], v[200:201], v[176:177] op_sel_hi:[1,0,1]
	v_pk_fma_f32 v[174:175], v[70:71], v[200:201], v[174:175] op_sel_hi:[1,0,1] neg_lo:[1,0,0] neg_hi:[1,0,0]
	s_movk_i32 s4, 0x3ff
	v_pk_fma_f32 v[174:175], v[192:193], v[174:175], v[66:67] op_sel_hi:[0,1,1]
	v_pk_fma_f32 v[176:177], v[192:193], v[72:73], v[68:69] op_sel_hi:[0,1,1]
	v_cmp_lt_u32_e64 s[42:43], s4, v202
	s_and_saveexec_b64 s[4:5], s[42:43]
	s_xor_b64 s[4:5], exec, s[4:5]
	v_ashrrev_i32_e32 v72, 10, v202
	v_cmp_lt_i32_e32 vcc, 1, v72
	s_mov_b64 s[36:37], 0
	s_mov_b64 s[44:45], 0
	s_and_saveexec_b64 s[54:55], vcc
	s_xor_b64 s[54:55], exec, s[54:55]
	v_cmp_ne_u32_e32 vcc, 2, v72
	s_and_b64 s[44:45], vcc, exec
	s_andn2_saveexec_b64 s[54:55], s[54:55]
	v_cmp_ne_u32_e32 vcc, 1, v72
	s_andn2_b64 s[36:37], s[44:45], exec
	s_and_b64 s[44:45], vcc, exec
	s_or_b64 s[44:45], s[36:37], s[44:45]
	s_mov_b64 s[36:37], exec
	s_or_b64 exec, exec, s[54:55]
	v_mov_b64_e32 v[180:181], v[176:177]
	v_mov_b64_e32 v[178:179], v[174:175]
	s_and_saveexec_b64 s[54:55], s[44:45]
	s_xor_b64 s[44:45], exec, s[54:55]
	v_mul_f32_e32 v72, 0xbfb8aa3b, v174
	v_mul_f32_e32 v73, 0xbfb8aa3b, v175
	v_mul_f32_e32 v178, 0xbfb8aa3b, v176
	v_mul_f32_e32 v179, 0xbfb8aa3b, v177
	v_exp_f32_e32 v72, v72
	v_exp_f32_e32 v73, v73
	v_exp_f32_e32 v178, v178
	v_exp_f32_e32 v179, v179
	v_add_f32_e32 v72, 1.0, v72
	v_add_f32_e32 v73, 1.0, v73
	v_add_f32_e32 v178, 1.0, v178
	v_add_f32_e32 v179, 1.0, v179
	v_rcp_f32_e32 v72, v72
	v_rcp_f32_e32 v178, v178
	v_rcp_f32_e32 v179, v179
	v_rcp_f32_e32 v73, v73
	s_andn2_b64 s[36:37], s[36:37], exec
	v_pk_mul_f32 v[180:181], v[176:177], v[178:179]
	v_pk_mul_f32 v[178:179], v[174:175], v[72:73]
	s_or_b64 exec, exec, s[44:45]
	s_and_saveexec_b64 s[44:45], s[36:37]
	s_or_b64 exec, exec, s[44:45]
	s_andn2_saveexec_b64 s[4:5], s[4:5]
	s_or_b64 exec, exec, s[4:5]
	v_mov_b32_e32 v201, v200
	v_xor_b32_e32 v61, 0x80000000, v61
	v_xor_b32_e32 v60, 0x80000000, v60
	v_mov_b32_e32 v72, v200
	v_mov_b32_e32 v73, v200
	v_mov_b32_e32 v193, v192
	v_pk_fma_f32 v[72:73], v[60:61], v[72:73], v[172:173]
	v_pk_fma_f32 v[170:171], v[58:59], v[200:201], v[170:171] neg_lo:[1,0,0] neg_hi:[1,0,0]
	v_mov_b32_e32 v172, v192
	v_mov_b32_e32 v173, v192
	v_pk_fma_f32 v[170:171], v[192:193], v[170:171], v[54:55]
	v_pk_fma_f32 v[172:173], v[172:173], v[72:73], v[56:57]
	v_cvt_pk_bf16_f32 v174, v178, v179
	v_cvt_pk_bf16_f32 v175, v180, v181
	s_and_saveexec_b64 s[4:5], s[42:43]
	s_xor_b64 s[4:5], exec, s[4:5]
	v_ashrrev_i32_e32 v180, 10, v202
	v_cmp_lt_i32_e32 vcc, 1, v180
	s_mov_b64 s[36:37], 0
	s_mov_b64 s[44:45], 0
	s_and_saveexec_b64 s[54:55], vcc
	s_xor_b64 s[54:55], exec, s[54:55]
	v_cmp_ne_u32_e32 vcc, 2, v180
	s_and_b64 s[44:45], vcc, exec
	s_andn2_saveexec_b64 s[54:55], s[54:55]
	v_cmp_ne_u32_e32 vcc, 1, v180
	s_andn2_b64 s[36:37], s[44:45], exec
	s_and_b64 s[44:45], vcc, exec
	s_or_b64 s[44:45], s[36:37], s[44:45]
	s_mov_b64 s[36:37], exec
	s_or_b64 exec, exec, s[54:55]
	v_mov_b64_e32 v[178:179], v[172:173]
	v_mov_b64_e32 v[176:177], v[170:171]
	s_and_saveexec_b64 s[54:55], s[44:45]
	s_xor_b64 s[44:45], exec, s[54:55]
	v_mul_f32_e32 v72, 0xbfb8aa3b, v170
	v_mul_f32_e32 v73, 0xbfb8aa3b, v171
	v_mul_f32_e32 v176, 0xbfb8aa3b, v172
	v_mul_f32_e32 v177, 0xbfb8aa3b, v173
	v_exp_f32_e32 v72, v72
	v_exp_f32_e32 v73, v73
	v_exp_f32_e32 v176, v176
	v_exp_f32_e32 v177, v177
	v_add_f32_e32 v72, 1.0, v72
	v_add_f32_e32 v73, 1.0, v73
	v_add_f32_e32 v176, 1.0, v176
	v_add_f32_e32 v177, 1.0, v177
	v_rcp_f32_e32 v72, v72
	v_rcp_f32_e32 v176, v176
	v_rcp_f32_e32 v177, v177
	v_rcp_f32_e32 v73, v73
	s_andn2_b64 s[36:37], s[36:37], exec
	v_pk_mul_f32 v[178:179], v[172:173], v[176:177]
	v_pk_mul_f32 v[176:177], v[170:171], v[72:73]
	s_or_b64 exec, exec, s[44:45]
	s_and_saveexec_b64 s[44:45], s[36:37]
	s_or_b64 exec, exec, s[44:45]
	s_andn2_saveexec_b64 s[4:5], s[4:5]
	s_or_b64 exec, exec, s[4:5]
	s_lshl_b32 s51, s3, 8
	v_add_lshl_u32 v181, v214, s51, 10
	s_mov_b32 s3, 0x1020000
	v_cvt_pk_bf16_f32 v176, v176, v177
	v_cvt_pk_bf16_f32 v177, v178, v179
	v_mul_lo_u32 v178, v180, s3
	v_or_b32_e32 v72, v181, v210
	v_add_lshl_u32 v72, v72, v178, 1
	buffer_store_dwordx4 v[174:177], v72, s[28:31], 0 offen sc1
	v_xor_b32_e32 v45, 0x80000000, v45
	v_xor_b32_e32 v44, 0x80000000, v44
	v_mov_b32_e32 v72, v200
	v_mov_b32_e32 v73, v200
	v_pk_fma_f32 v[72:73], v[44:45], v[72:73], v[168:169]
	v_pk_fma_f32 v[166:167], v[42:43], v[200:201], v[166:167] neg_lo:[1,0,0] neg_hi:[1,0,0]
	v_mov_b32_e32 v168, v192
	v_mov_b32_e32 v169, v192
	s_movk_i32 s3, 0x3ff
	v_pk_fma_f32 v[166:167], v[192:193], v[166:167], v[38:39]
	v_pk_fma_f32 v[168:169], v[168:169], v[72:73], v[40:41]
	v_cmp_lt_u32_e64 s[44:45], s3, v212
	s_and_saveexec_b64 s[4:5], s[44:45]
	s_xor_b64 s[4:5], exec, s[4:5]
	v_ashrrev_i32_e32 v72, 10, v212
	v_cmp_lt_i32_e32 vcc, 1, v72
	s_mov_b64 s[36:37], 0
	s_mov_b64 s[54:55], 0
	s_and_saveexec_b64 s[56:57], vcc
	s_xor_b64 s[56:57], exec, s[56:57]
	v_cmp_ne_u32_e32 vcc, 2, v72
	s_and_b64 s[54:55], vcc, exec
	s_andn2_saveexec_b64 s[56:57], s[56:57]
	v_cmp_ne_u32_e32 vcc, 1, v72
	s_andn2_b64 s[36:37], s[54:55], exec
	s_and_b64 s[54:55], vcc, exec
	s_or_b64 s[54:55], s[36:37], s[54:55]
	s_mov_b64 s[36:37], exec
	s_or_b64 exec, exec, s[56:57]
	v_mov_b64_e32 v[172:173], v[168:169]
	v_mov_b64_e32 v[170:171], v[166:167]
	s_and_saveexec_b64 s[56:57], s[54:55]
	s_xor_b64 s[54:55], exec, s[56:57]
	v_mul_f32_e32 v72, 0xbfb8aa3b, v166
	v_mul_f32_e32 v73, 0xbfb8aa3b, v167
	v_mul_f32_e32 v170, 0xbfb8aa3b, v168
	v_mul_f32_e32 v171, 0xbfb8aa3b, v169
	v_exp_f32_e32 v72, v72
	v_exp_f32_e32 v73, v73
	v_exp_f32_e32 v170, v170
	v_exp_f32_e32 v171, v171
	v_add_f32_e32 v72, 1.0, v72
	v_add_f32_e32 v73, 1.0, v73
	v_add_f32_e32 v170, 1.0, v170
	v_add_f32_e32 v171, 1.0, v171
	v_rcp_f32_e32 v72, v72
	v_rcp_f32_e32 v170, v170
	v_rcp_f32_e32 v171, v171
	v_rcp_f32_e32 v73, v73
	s_andn2_b64 s[36:37], s[36:37], exec
	v_pk_mul_f32 v[172:173], v[168:169], v[170:171]
	v_pk_mul_f32 v[170:171], v[166:167], v[72:73]
	s_or_b64 exec, exec, s[54:55]
	s_and_saveexec_b64 s[54:55], s[36:37]
	s_or_b64 exec, exec, s[54:55]
	s_andn2_saveexec_b64 s[4:5], s[4:5]
	s_or_b64 exec, exec, s[4:5]
	v_xor_b32_e32 v29, 0x80000000, v29
	v_xor_b32_e32 v28, 0x80000000, v28
	v_mov_b32_e32 v72, v200
	v_mov_b32_e32 v73, v200
	v_pk_fma_f32 v[162:163], v[26:27], v[200:201], v[162:163] neg_lo:[1,0,0] neg_hi:[1,0,0]
	v_pk_fma_f32 v[72:73], v[28:29], v[72:73], v[164:165]
	v_pk_fma_f32 v[162:163], v[192:193], v[162:163], v[22:23]
	v_mov_b32_e32 v193, v192
	v_pk_fma_f32 v[164:165], v[192:193], v[72:73], v[24:25]
	v_cvt_pk_bf16_f32 v166, v170, v171
	v_cvt_pk_bf16_f32 v167, v172, v173
	s_and_saveexec_b64 s[4:5], s[44:45]
	s_xor_b64 s[4:5], exec, s[4:5]
	v_ashrrev_i32_e32 v172, 10, v212
	v_cmp_lt_i32_e32 vcc, 1, v172
	s_mov_b64 s[36:37], 0
	s_mov_b64 s[54:55], 0
	s_and_saveexec_b64 s[56:57], vcc
	s_xor_b64 s[56:57], exec, s[56:57]
	v_cmp_ne_u32_e32 vcc, 2, v172
	s_and_b64 s[54:55], vcc, exec
	s_andn2_saveexec_b64 s[56:57], s[56:57]
	v_cmp_ne_u32_e32 vcc, 1, v172
	s_andn2_b64 s[36:37], s[54:55], exec
	s_and_b64 s[54:55], vcc, exec
	s_or_b64 s[54:55], s[36:37], s[54:55]
	s_mov_b64 s[36:37], exec
	s_or_b64 exec, exec, s[56:57]
	v_mov_b64_e32 v[170:171], v[164:165]
	v_mov_b64_e32 v[168:169], v[162:163]
	s_and_saveexec_b64 s[56:57], s[54:55]
	s_xor_b64 s[54:55], exec, s[56:57]
	v_mul_f32_e32 v72, 0xbfb8aa3b, v162
	v_mul_f32_e32 v73, 0xbfb8aa3b, v163
	v_mul_f32_e32 v168, 0xbfb8aa3b, v164
	v_mul_f32_e32 v169, 0xbfb8aa3b, v165
	v_exp_f32_e32 v72, v72
	v_exp_f32_e32 v73, v73
	v_exp_f32_e32 v168, v168
	v_exp_f32_e32 v169, v169
	v_add_f32_e32 v72, 1.0, v72
	v_add_f32_e32 v73, 1.0, v73
	v_add_f32_e32 v168, 1.0, v168
	v_add_f32_e32 v169, 1.0, v169
	v_rcp_f32_e32 v72, v72
	v_rcp_f32_e32 v168, v168
	v_rcp_f32_e32 v169, v169
	v_rcp_f32_e32 v73, v73
	s_andn2_b64 s[36:37], s[36:37], exec
	v_pk_mul_f32 v[170:171], v[164:165], v[168:169]
	v_pk_mul_f32 v[168:169], v[162:163], v[72:73]
	s_or_b64 exec, exec, s[54:55]
	s_and_saveexec_b64 s[54:55], s[36:37]
	s_or_b64 exec, exec, s[54:55]
	s_andn2_saveexec_b64 s[4:5], s[4:5]
	s_or_b64 exec, exec, s[4:5]
	s_mov_b32 s3, 0x1020000
	v_cvt_pk_bf16_f32 v168, v168, v169
	v_cvt_pk_bf16_f32 v169, v170, v171
	v_mul_lo_u32 v170, v172, s3
	v_or_b32_e32 v72, v181, v203
	v_add_lshl_u32 v72, v72, v170, 1
	s_and_b64 vcc, exec, s[46:47]
	buffer_store_dwordx4 v[166:169], v72, s[28:31], 0 offen sc1
	s_cbranch_vccnz .LBB0_458_sg3
	ds_read_b64 v[166:167], v211 offset:128
	s_waitcnt lgkmcnt(0)
	v_mov_b32_e32 v72, v167
	s_branch .LBB0_459_sg3

.LBB0_459_sg3:
	v_pk_fma_f32 v[160:161], v[190:191], v[166:167], v[160:161] op_sel_hi:[1,0,1]
	v_pk_fma_f32 v[158:159], v[70:71], v[166:167], v[158:159] op_sel_hi:[1,0,1] neg_lo:[1,0,0] neg_hi:[1,0,0]
	v_pk_fma_f32 v[160:161], v[72:73], v[160:161], v[68:69] op_sel_hi:[0,1,1]
	v_pk_fma_f32 v[158:159], v[72:73], v[158:159], v[66:67] op_sel_hi:[0,1,1]
	s_and_saveexec_b64 s[4:5], s[42:43]
	s_xor_b64 s[4:5], exec, s[4:5]
	v_cmp_lt_i32_e32 vcc, 1, v180
	s_mov_b64 s[36:37], 0
	s_mov_b64 s[54:55], 0
	s_and_saveexec_b64 s[56:57], vcc
	s_xor_b64 s[56:57], exec, s[56:57]
	v_cmp_ne_u32_e32 vcc, 2, v180
	s_and_b64 s[54:55], vcc, exec
	s_andn2_saveexec_b64 s[56:57], s[56:57]
	v_cmp_ne_u32_e32 vcc, 1, v180
	s_andn2_b64 s[36:37], s[54:55], exec
	s_and_b64 s[54:55], vcc, exec
	s_or_b64 s[54:55], s[36:37], s[54:55]
	s_mov_b64 s[36:37], exec
	s_or_b64 exec, exec, s[56:57]
	v_mov_b64_e32 v[164:165], v[160:161]
	v_mov_b64_e32 v[162:163], v[158:159]
	s_and_saveexec_b64 s[56:57], s[54:55]
	s_xor_b64 s[54:55], exec, s[56:57]
	v_mul_f32_e32 v73, 0xbfb8aa3b, v158
	v_exp_f32_e32 v73, v73
	v_mul_f32_e32 v162, 0xbfb8aa3b, v159
	v_mul_f32_e32 v163, 0xbfb8aa3b, v160
	v_exp_f32_e32 v164, v162
	v_add_f32_e32 v73, 1.0, v73
	v_rcp_f32_e32 v162, v73
	v_exp_f32_e32 v73, v163
	v_mul_f32_e32 v163, 0xbfb8aa3b, v161
	v_exp_f32_e32 v163, v163
	v_add_f32_e32 v167, 1.0, v164
	v_add_f32_e32 v73, 1.0, v73
	v_rcp_f32_e32 v164, v73
	v_add_f32_e32 v73, 1.0, v163
	v_rcp_f32_e32 v165, v73
	v_rcp_f32_e32 v163, v167
	s_andn2_b64 s[36:37], s[36:37], exec
	v_pk_mul_f32 v[164:165], v[160:161], v[164:165]
	v_pk_mul_f32 v[162:163], v[158:159], v[162:163]
	s_or_b64 exec, exec, s[54:55]
	s_and_saveexec_b64 s[54:55], s[36:37]
	s_or_b64 exec, exec, s[54:55]
	s_andn2_saveexec_b64 s[4:5], s[4:5]
	s_or_b64 exec, exec, s[4:5]
	v_mov_b32_e32 v167, v166
	v_mov_b32_e32 v160, v166
	v_mov_b32_e32 v161, v166
	v_mov_b32_e32 v73, v72
	v_pk_fma_f32 v[156:157], v[60:61], v[160:161], v[156:157]
	v_pk_fma_f32 v[154:155], v[58:59], v[166:167], v[154:155] neg_lo:[1,0,0] neg_hi:[1,0,0]
	v_mov_b32_e32 v160, v72
	v_mov_b32_e32 v161, v72
	v_pk_fma_f32 v[154:155], v[72:73], v[154:155], v[54:55]
	v_pk_fma_f32 v[156:157], v[160:161], v[156:157], v[56:57]
	v_cvt_pk_bf16_f32 v158, v162, v163
	v_cvt_pk_bf16_f32 v159, v164, v165
	s_and_saveexec_b64 s[4:5], s[42:43]
	s_xor_b64 s[4:5], exec, s[4:5]
	v_cmp_lt_i32_e32 vcc, 1, v180
	s_mov_b64 s[36:37], 0
	s_mov_b64 s[54:55], 0
	s_and_saveexec_b64 s[56:57], vcc
	s_xor_b64 s[56:57], exec, s[56:57]
	v_cmp_ne_u32_e32 vcc, 2, v180
	s_and_b64 s[54:55], vcc, exec
	s_andn2_saveexec_b64 s[56:57], s[56:57]
	v_cmp_ne_u32_e32 vcc, 1, v180
	s_andn2_b64 s[36:37], s[54:55], exec
	s_and_b64 s[54:55], vcc, exec
	s_or_b64 s[54:55], s[36:37], s[54:55]
	s_mov_b64 s[36:37], exec
	s_or_b64 exec, exec, s[56:57]
	v_mov_b64_e32 v[162:163], v[156:157]
	v_mov_b64_e32 v[160:161], v[154:155]
	s_and_saveexec_b64 s[56:57], s[54:55]
	s_xor_b64 s[54:55], exec, s[56:57]
	v_mul_f32_e32 v160, 0xbfb8aa3b, v154
	v_mul_f32_e32 v161, 0xbfb8aa3b, v155
	v_mul_f32_e32 v162, 0xbfb8aa3b, v156
	v_mul_f32_e32 v163, 0xbfb8aa3b, v157
	v_exp_f32_e32 v160, v160
	v_exp_f32_e32 v161, v161
	v_exp_f32_e32 v162, v162
	v_exp_f32_e32 v163, v163
	v_add_f32_e32 v160, 1.0, v160
	v_add_f32_e32 v161, 1.0, v161
	v_add_f32_e32 v162, 1.0, v162
	v_add_f32_e32 v163, 1.0, v163
	v_rcp_f32_e32 v160, v160
	v_rcp_f32_e32 v162, v162
	v_rcp_f32_e32 v163, v163
	v_rcp_f32_e32 v161, v161
	s_andn2_b64 s[36:37], s[36:37], exec
	v_pk_mul_f32 v[162:163], v[156:157], v[162:163]
	v_pk_mul_f32 v[160:161], v[154:155], v[160:161]
	s_or_b64 exec, exec, s[54:55]
	s_and_saveexec_b64 s[54:55], s[36:37]
	s_or_b64 exec, exec, s[54:55]
	s_andn2_saveexec_b64 s[4:5], s[4:5]
	s_or_b64 exec, exec, s[4:5]
	v_add_u32_e32 v164, 0x4000, v181
	v_or_b32_e32 v154, v164, v210
	v_add_lshl_u32 v154, v154, v178, 1
	v_cvt_pk_bf16_f32 v160, v160, v161
	v_cvt_pk_bf16_f32 v161, v162, v163
	buffer_store_dwordx4 v[158:161], v154, s[28:31], 0 offen sc1
	v_mov_b32_e32 v154, v166
	v_mov_b32_e32 v155, v166
	v_pk_fma_f32 v[152:153], v[44:45], v[154:155], v[152:153]
	v_pk_fma_f32 v[150:151], v[42:43], v[166:167], v[150:151] neg_lo:[1,0,0] neg_hi:[1,0,0]
	v_mov_b32_e32 v154, v72
	v_mov_b32_e32 v155, v72
	v_pk_fma_f32 v[150:151], v[72:73], v[150:151], v[38:39]
	v_pk_fma_f32 v[152:153], v[154:155], v[152:153], v[40:41]
	s_and_saveexec_b64 s[4:5], s[44:45]
	s_xor_b64 s[4:5], exec, s[4:5]
	v_cmp_lt_i32_e32 vcc, 1, v172
	s_mov_b64 s[36:37], 0
	s_mov_b64 s[54:55], 0
	s_and_saveexec_b64 s[56:57], vcc
	s_xor_b64 s[56:57], exec, s[56:57]
	v_cmp_ne_u32_e32 vcc, 2, v172
	s_and_b64 s[54:55], vcc, exec
	s_andn2_saveexec_b64 s[56:57], s[56:57]
	v_cmp_ne_u32_e32 vcc, 1, v172
	s_andn2_b64 s[36:37], s[54:55], exec
	s_and_b64 s[54:55], vcc, exec
	s_or_b64 s[54:55], s[36:37], s[54:55]
	s_mov_b64 s[36:37], exec
	s_or_b64 exec, exec, s[56:57]
	v_mov_b64_e32 v[156:157], v[152:153]
	v_mov_b64_e32 v[154:155], v[150:151]
	s_and_saveexec_b64 s[56:57], s[54:55]
	s_xor_b64 s[54:55], exec, s[56:57]
	v_mul_f32_e32 v154, 0xbfb8aa3b, v150
	v_mul_f32_e32 v155, 0xbfb8aa3b, v151
	v_mul_f32_e32 v156, 0xbfb8aa3b, v152
	v_mul_f32_e32 v157, 0xbfb8aa3b, v153
	v_exp_f32_e32 v154, v154
	v_exp_f32_e32 v155, v155
	v_exp_f32_e32 v156, v156
	v_exp_f32_e32 v157, v157
	v_add_f32_e32 v154, 1.0, v154
	v_add_f32_e32 v155, 1.0, v155
	v_add_f32_e32 v156, 1.0, v156
	v_add_f32_e32 v157, 1.0, v157
	v_rcp_f32_e32 v154, v154
	v_rcp_f32_e32 v156, v156
	v_rcp_f32_e32 v157, v157
	v_rcp_f32_e32 v155, v155
	s_andn2_b64 s[36:37], s[36:37], exec
	v_pk_mul_f32 v[156:157], v[152:153], v[156:157]
	v_pk_mul_f32 v[154:155], v[150:151], v[154:155]
	s_or_b64 exec, exec, s[54:55]
	s_and_saveexec_b64 s[54:55], s[36:37]
	s_or_b64 exec, exec, s[54:55]
	s_andn2_saveexec_b64 s[4:5], s[4:5]
	s_or_b64 exec, exec, s[4:5]
	v_mov_b32_e32 v152, v166
	v_mov_b32_e32 v153, v166
	v_pk_fma_f32 v[146:147], v[26:27], v[166:167], v[146:147] neg_lo:[1,0,0] neg_hi:[1,0,0]
	v_pk_fma_f32 v[148:149], v[28:29], v[152:153], v[148:149]
	v_pk_fma_f32 v[146:147], v[72:73], v[146:147], v[22:23]
	v_mov_b32_e32 v73, v72
	v_pk_fma_f32 v[148:149], v[72:73], v[148:149], v[24:25]
	v_cvt_pk_bf16_f32 v150, v154, v155
	v_cvt_pk_bf16_f32 v151, v156, v157
	s_and_saveexec_b64 s[4:5], s[44:45]
	s_xor_b64 s[4:5], exec, s[4:5]
	v_cmp_lt_i32_e32 vcc, 1, v172
	s_mov_b64 s[36:37], 0
	s_mov_b64 s[54:55], 0
	s_and_saveexec_b64 s[56:57], vcc
	s_xor_b64 s[56:57], exec, s[56:57]
	v_cmp_ne_u32_e32 vcc, 2, v172
	s_and_b64 s[54:55], vcc, exec
	s_andn2_saveexec_b64 s[56:57], s[56:57]
	v_cmp_ne_u32_e32 vcc, 1, v172
	s_andn2_b64 s[36:37], s[54:55], exec
	s_and_b64 s[54:55], vcc, exec
	s_or_b64 s[54:55], s[36:37], s[54:55]
	s_mov_b64 s[36:37], exec
	s_or_b64 exec, exec, s[56:57]
	v_mov_b64_e32 v[154:155], v[148:149]
	v_mov_b64_e32 v[152:153], v[146:147]
	s_and_saveexec_b64 s[56:57], s[54:55]
	s_xor_b64 s[54:55], exec, s[56:57]
	v_mul_f32_e32 v72, 0xbfb8aa3b, v146
	v_mul_f32_e32 v73, 0xbfb8aa3b, v147
	v_mul_f32_e32 v152, 0xbfb8aa3b, v148
	v_mul_f32_e32 v153, 0xbfb8aa3b, v149
	v_exp_f32_e32 v72, v72
	v_exp_f32_e32 v73, v73
	v_exp_f32_e32 v152, v152
	v_exp_f32_e32 v153, v153
	v_add_f32_e32 v72, 1.0, v72
	v_add_f32_e32 v73, 1.0, v73
	v_add_f32_e32 v152, 1.0, v152
	v_add_f32_e32 v153, 1.0, v153
	v_rcp_f32_e32 v72, v72
	v_rcp_f32_e32 v152, v152
	v_rcp_f32_e32 v153, v153
	v_rcp_f32_e32 v73, v73
	s_andn2_b64 s[36:37], s[36:37], exec
	v_pk_mul_f32 v[154:155], v[148:149], v[152:153]
	v_pk_mul_f32 v[152:153], v[146:147], v[72:73]
	s_or_b64 exec, exec, s[54:55]
	s_and_saveexec_b64 s[54:55], s[36:37]
	s_or_b64 exec, exec, s[54:55]
	s_andn2_saveexec_b64 s[4:5], s[4:5]
	s_or_b64 exec, exec, s[4:5]
	v_or_b32_e32 v72, v164, v203
	v_add_lshl_u32 v72, v72, v170, 1
	v_cvt_pk_bf16_f32 v152, v152, v153
	v_cvt_pk_bf16_f32 v153, v154, v155
	buffer_store_dwordx4 v[150:153], v72, s[28:31], 0 offen sc1
	s_and_b64 vcc, exec, s[46:47]
	s_nop 0
	v_mov_b32_e32 v153, v205
	s_nop 0
	v_lshl_add_u32 v152, v153, 3, s33
	s_cbranch_vccnz .LBB0_509_sg3
	ds_read_b64 v[150:151], v152
	s_waitcnt lgkmcnt(0)
	v_mov_b32_e32 v72, v151
	s_branch .LBB0_510_sg3

.LBB0_510_sg3:
	v_pk_fma_f32 v[144:145], v[190:191], v[150:151], v[144:145] op_sel_hi:[1,0,1]
	v_pk_fma_f32 v[142:143], v[70:71], v[150:151], v[142:143] op_sel_hi:[1,0,1] neg_lo:[1,0,0] neg_hi:[1,0,0]
	v_pk_fma_f32 v[144:145], v[72:73], v[144:145], v[68:69] op_sel_hi:[0,1,1]
	v_pk_fma_f32 v[142:143], v[72:73], v[142:143], v[66:67] op_sel_hi:[0,1,1]
	s_and_saveexec_b64 s[4:5], s[42:43]
	s_xor_b64 s[4:5], exec, s[4:5]
	v_cmp_lt_i32_e32 vcc, 1, v180
	s_mov_b64 s[36:37], 0
	s_mov_b64 s[54:55], 0
	s_and_saveexec_b64 s[56:57], vcc
	s_xor_b64 s[56:57], exec, s[56:57]
	v_cmp_ne_u32_e32 vcc, 2, v180
	s_and_b64 s[54:55], vcc, exec
	s_andn2_saveexec_b64 s[56:57], s[56:57]
	v_cmp_ne_u32_e32 vcc, 1, v180
	s_andn2_b64 s[36:37], s[54:55], exec
	s_and_b64 s[54:55], vcc, exec
	s_or_b64 s[54:55], s[36:37], s[54:55]
	s_mov_b64 s[36:37], exec
	s_or_b64 exec, exec, s[56:57]
	v_mov_b64_e32 v[148:149], v[144:145]
	v_mov_b64_e32 v[146:147], v[142:143]
	s_and_saveexec_b64 s[56:57], s[54:55]
	s_xor_b64 s[54:55], exec, s[56:57]
	v_mul_f32_e32 v73, 0xbfb8aa3b, v142
	v_exp_f32_e32 v73, v73
	v_mul_f32_e32 v146, 0xbfb8aa3b, v143
	v_mul_f32_e32 v147, 0xbfb8aa3b, v144
	v_exp_f32_e32 v148, v146
	v_add_f32_e32 v73, 1.0, v73
	v_rcp_f32_e32 v146, v73
	v_exp_f32_e32 v73, v147
	v_mul_f32_e32 v147, 0xbfb8aa3b, v145
	v_exp_f32_e32 v147, v147
	v_add_f32_e32 v151, 1.0, v148
	v_add_f32_e32 v73, 1.0, v73
	v_rcp_f32_e32 v148, v73
	v_add_f32_e32 v73, 1.0, v147
	v_rcp_f32_e32 v149, v73
	v_rcp_f32_e32 v147, v151
	s_andn2_b64 s[36:37], s[36:37], exec
	v_pk_mul_f32 v[148:149], v[144:145], v[148:149]
	v_pk_mul_f32 v[146:147], v[142:143], v[146:147]
	s_or_b64 exec, exec, s[54:55]
	s_and_saveexec_b64 s[54:55], s[36:37]
	s_or_b64 exec, exec, s[54:55]
	s_andn2_saveexec_b64 s[4:5], s[4:5]
	s_or_b64 exec, exec, s[4:5]
	v_mov_b32_e32 v151, v150
	v_mov_b32_e32 v144, v150
	v_mov_b32_e32 v145, v150
	v_mov_b32_e32 v73, v72
	v_pk_fma_f32 v[140:141], v[60:61], v[144:145], v[140:141]
	v_pk_fma_f32 v[138:139], v[58:59], v[150:151], v[138:139] neg_lo:[1,0,0] neg_hi:[1,0,0]
	v_mov_b32_e32 v144, v72
	v_mov_b32_e32 v145, v72
	v_pk_fma_f32 v[138:139], v[72:73], v[138:139], v[54:55]
	v_pk_fma_f32 v[140:141], v[144:145], v[140:141], v[56:57]
	v_cvt_pk_bf16_f32 v142, v146, v147
	v_cvt_pk_bf16_f32 v143, v148, v149
	s_and_saveexec_b64 s[4:5], s[42:43]
	s_xor_b64 s[4:5], exec, s[4:5]
	v_cmp_lt_i32_e32 vcc, 1, v180
	s_mov_b64 s[36:37], 0
	s_mov_b64 s[54:55], 0
	s_and_saveexec_b64 s[56:57], vcc
	s_xor_b64 s[56:57], exec, s[56:57]
	v_cmp_ne_u32_e32 vcc, 2, v180
	s_and_b64 s[54:55], vcc, exec
	s_andn2_saveexec_b64 s[56:57], s[56:57]
	v_cmp_ne_u32_e32 vcc, 1, v180
	s_andn2_b64 s[36:37], s[54:55], exec
	s_and_b64 s[54:55], vcc, exec
	s_or_b64 s[54:55], s[36:37], s[54:55]
	s_mov_b64 s[36:37], exec
	s_or_b64 exec, exec, s[56:57]
	v_mov_b64_e32 v[146:147], v[140:141]
	v_mov_b64_e32 v[144:145], v[138:139]
	s_and_saveexec_b64 s[56:57], s[54:55]
	s_xor_b64 s[54:55], exec, s[56:57]
	v_mul_f32_e32 v144, 0xbfb8aa3b, v138
	v_mul_f32_e32 v145, 0xbfb8aa3b, v139
	v_mul_f32_e32 v146, 0xbfb8aa3b, v140
	v_mul_f32_e32 v147, 0xbfb8aa3b, v141
	v_exp_f32_e32 v144, v144
	v_exp_f32_e32 v145, v145
	v_exp_f32_e32 v146, v146
	v_exp_f32_e32 v147, v147
	v_add_f32_e32 v144, 1.0, v144
	v_add_f32_e32 v145, 1.0, v145
	v_add_f32_e32 v146, 1.0, v146
	v_add_f32_e32 v147, 1.0, v147
	v_rcp_f32_e32 v144, v144
	v_rcp_f32_e32 v146, v146
	v_rcp_f32_e32 v147, v147
	v_rcp_f32_e32 v145, v145
	s_andn2_b64 s[36:37], s[36:37], exec
	v_pk_mul_f32 v[146:147], v[140:141], v[146:147]
	v_pk_mul_f32 v[144:145], v[138:139], v[144:145]
	s_or_b64 exec, exec, s[54:55]
	s_and_saveexec_b64 s[54:55], s[36:37]
	s_or_b64 exec, exec, s[54:55]
	s_andn2_saveexec_b64 s[4:5], s[4:5]
	s_or_b64 exec, exec, s[4:5]
	v_add_lshl_u32 v148, v153, s51, 10
	v_cvt_pk_bf16_f32 v144, v144, v145
	v_cvt_pk_bf16_f32 v145, v146, v147
	v_or_b32_e32 v146, v178, v210
	v_add_lshl_u32 v138, v148, v146, 1
	buffer_store_dwordx4 v[142:145], v138, s[28:31], 0 offen sc1
	v_mov_b32_e32 v138, v150
	v_mov_b32_e32 v139, v150
	v_pk_fma_f32 v[136:137], v[44:45], v[138:139], v[136:137]
	v_pk_fma_f32 v[134:135], v[42:43], v[150:151], v[134:135] neg_lo:[1,0,0] neg_hi:[1,0,0]
	v_mov_b32_e32 v138, v72
	v_mov_b32_e32 v139, v72
	v_pk_fma_f32 v[134:135], v[72:73], v[134:135], v[38:39]
	v_pk_fma_f32 v[136:137], v[138:139], v[136:137], v[40:41]
	s_and_saveexec_b64 s[4:5], s[44:45]
	s_xor_b64 s[4:5], exec, s[4:5]
	v_cmp_lt_i32_e32 vcc, 1, v172
	s_mov_b64 s[36:37], 0
	s_mov_b64 s[54:55], 0
	s_and_saveexec_b64 s[56:57], vcc
	s_xor_b64 s[56:57], exec, s[56:57]
	v_cmp_ne_u32_e32 vcc, 2, v172
	s_and_b64 s[54:55], vcc, exec
	s_andn2_saveexec_b64 s[56:57], s[56:57]
	v_cmp_ne_u32_e32 vcc, 1, v172
	s_andn2_b64 s[36:37], s[54:55], exec
	s_and_b64 s[54:55], vcc, exec
	s_or_b64 s[54:55], s[36:37], s[54:55]
	s_mov_b64 s[36:37], exec
	s_or_b64 exec, exec, s[56:57]
	v_mov_b64_e32 v[140:141], v[136:137]
	v_mov_b64_e32 v[138:139], v[134:135]
	s_and_saveexec_b64 s[56:57], s[54:55]
	s_xor_b64 s[54:55], exec, s[56:57]
	v_mul_f32_e32 v138, 0xbfb8aa3b, v134
	v_mul_f32_e32 v139, 0xbfb8aa3b, v135
	v_mul_f32_e32 v140, 0xbfb8aa3b, v136
	v_mul_f32_e32 v141, 0xbfb8aa3b, v137
	v_exp_f32_e32 v138, v138
	v_exp_f32_e32 v139, v139
	v_exp_f32_e32 v140, v140
	v_exp_f32_e32 v141, v141
	v_add_f32_e32 v138, 1.0, v138
	v_add_f32_e32 v139, 1.0, v139
	v_add_f32_e32 v140, 1.0, v140
	v_add_f32_e32 v141, 1.0, v141
	v_rcp_f32_e32 v138, v138
	v_rcp_f32_e32 v140, v140
	v_rcp_f32_e32 v141, v141
	v_rcp_f32_e32 v139, v139
	s_andn2_b64 s[36:37], s[36:37], exec
	v_pk_mul_f32 v[140:141], v[136:137], v[140:141]
	v_pk_mul_f32 v[138:139], v[134:135], v[138:139]
	s_or_b64 exec, exec, s[54:55]
	s_and_saveexec_b64 s[54:55], s[36:37]
	s_or_b64 exec, exec, s[54:55]
	s_andn2_saveexec_b64 s[4:5], s[4:5]
	s_or_b64 exec, exec, s[4:5]
	v_mov_b32_e32 v136, v150
	v_mov_b32_e32 v137, v150
	v_pk_fma_f32 v[130:131], v[26:27], v[150:151], v[130:131] neg_lo:[1,0,0] neg_hi:[1,0,0]
	v_pk_fma_f32 v[132:133], v[28:29], v[136:137], v[132:133]
	v_pk_fma_f32 v[130:131], v[72:73], v[130:131], v[22:23]
	v_mov_b32_e32 v73, v72
	v_pk_fma_f32 v[132:133], v[72:73], v[132:133], v[24:25]
	v_cvt_pk_bf16_f32 v134, v138, v139
	v_cvt_pk_bf16_f32 v135, v140, v141
	s_and_saveexec_b64 s[4:5], s[44:45]
	s_xor_b64 s[4:5], exec, s[4:5]
	v_cmp_lt_i32_e32 vcc, 1, v172
	s_mov_b64 s[36:37], 0
	s_mov_b64 s[54:55], 0
	s_and_saveexec_b64 s[56:57], vcc
	s_xor_b64 s[56:57], exec, s[56:57]
	v_cmp_ne_u32_e32 vcc, 2, v172
	s_and_b64 s[54:55], vcc, exec
	s_andn2_saveexec_b64 s[56:57], s[56:57]
	v_cmp_ne_u32_e32 vcc, 1, v172
	s_andn2_b64 s[36:37], s[54:55], exec
	s_and_b64 s[54:55], vcc, exec
	s_or_b64 s[54:55], s[36:37], s[54:55]
	s_mov_b64 s[36:37], exec
	s_or_b64 exec, exec, s[56:57]
	v_mov_b64_e32 v[138:139], v[132:133]
	v_mov_b64_e32 v[136:137], v[130:131]
	s_and_saveexec_b64 s[56:57], s[54:55]
	s_xor_b64 s[54:55], exec, s[56:57]
	v_mul_f32_e32 v72, 0xbfb8aa3b, v130
	v_mul_f32_e32 v73, 0xbfb8aa3b, v131
	v_mul_f32_e32 v136, 0xbfb8aa3b, v132
	v_mul_f32_e32 v137, 0xbfb8aa3b, v133
	v_exp_f32_e32 v72, v72
	v_exp_f32_e32 v73, v73
	v_exp_f32_e32 v136, v136
	v_exp_f32_e32 v137, v137
	v_add_f32_e32 v72, 1.0, v72
	v_add_f32_e32 v73, 1.0, v73
	v_add_f32_e32 v136, 1.0, v136
	v_add_f32_e32 v137, 1.0, v137
	v_rcp_f32_e32 v72, v72
	v_rcp_f32_e32 v136, v136
	v_rcp_f32_e32 v137, v137
	v_rcp_f32_e32 v73, v73
	s_andn2_b64 s[36:37], s[36:37], exec
	v_pk_mul_f32 v[138:139], v[132:133], v[136:137]
	v_pk_mul_f32 v[136:137], v[130:131], v[72:73]
	s_or_b64 exec, exec, s[54:55]
	s_and_saveexec_b64 s[54:55], s[36:37]
	s_or_b64 exec, exec, s[54:55]
	s_andn2_saveexec_b64 s[4:5], s[4:5]
	s_or_b64 exec, exec, s[4:5]
	v_cvt_pk_bf16_f32 v136, v136, v137
	v_cvt_pk_bf16_f32 v137, v138, v139
	v_or_b32_e32 v138, v170, v203
	v_add_lshl_u32 v72, v148, v138, 1
	s_and_b64 vcc, exec, s[46:47]
	buffer_store_dwordx4 v[134:137], v72, s[28:31], 0 offen sc1
	s_cbranch_vccnz .LBB0_560_sg3
	ds_read_b64 v[134:135], v152 offset:128
	s_waitcnt lgkmcnt(0)
	v_mov_b32_e32 v72, v135
	s_branch .LBB0_561_sg3

.LBB0_561_sg3:
	v_pk_fma_f32 v[128:129], v[190:191], v[134:135], v[128:129] op_sel_hi:[1,0,1]
	v_pk_fma_f32 v[126:127], v[70:71], v[134:135], v[126:127] op_sel_hi:[1,0,1] neg_lo:[1,0,0] neg_hi:[1,0,0]
	v_pk_fma_f32 v[128:129], v[72:73], v[128:129], v[68:69] op_sel_hi:[0,1,1]
	v_pk_fma_f32 v[126:127], v[72:73], v[126:127], v[66:67] op_sel_hi:[0,1,1]
	s_and_saveexec_b64 s[4:5], s[42:43]
	s_xor_b64 s[4:5], exec, s[4:5]
	v_cmp_lt_i32_e32 vcc, 1, v180
	s_mov_b64 s[36:37], 0
	s_mov_b64 s[54:55], 0
	s_and_saveexec_b64 s[56:57], vcc
	s_xor_b64 s[56:57], exec, s[56:57]
	v_cmp_ne_u32_e32 vcc, 2, v180
	s_and_b64 s[54:55], vcc, exec
	s_andn2_saveexec_b64 s[56:57], s[56:57]
	v_cmp_ne_u32_e32 vcc, 1, v180
	s_andn2_b64 s[36:37], s[54:55], exec
	s_and_b64 s[54:55], vcc, exec
	s_or_b64 s[54:55], s[36:37], s[54:55]
	s_mov_b64 s[36:37], exec
	s_or_b64 exec, exec, s[56:57]
	v_mov_b64_e32 v[132:133], v[128:129]
	v_mov_b64_e32 v[130:131], v[126:127]
	s_and_saveexec_b64 s[56:57], s[54:55]
	s_xor_b64 s[54:55], exec, s[56:57]
	v_mul_f32_e32 v73, 0xbfb8aa3b, v126
	v_exp_f32_e32 v73, v73
	v_mul_f32_e32 v130, 0xbfb8aa3b, v127
	v_mul_f32_e32 v131, 0xbfb8aa3b, v128
	v_exp_f32_e32 v132, v130
	v_add_f32_e32 v73, 1.0, v73
	v_rcp_f32_e32 v130, v73
	v_exp_f32_e32 v73, v131
	v_mul_f32_e32 v131, 0xbfb8aa3b, v129
	v_exp_f32_e32 v131, v131
	v_add_f32_e32 v135, 1.0, v132
	v_add_f32_e32 v73, 1.0, v73
	v_rcp_f32_e32 v132, v73
	v_add_f32_e32 v73, 1.0, v131
	v_rcp_f32_e32 v133, v73
	v_rcp_f32_e32 v131, v135
	s_andn2_b64 s[36:37], s[36:37], exec
	v_pk_mul_f32 v[132:133], v[128:129], v[132:133]
	v_pk_mul_f32 v[130:131], v[126:127], v[130:131]
	s_or_b64 exec, exec, s[54:55]
	s_and_saveexec_b64 s[54:55], s[36:37]
	s_or_b64 exec, exec, s[54:55]
	s_andn2_saveexec_b64 s[4:5], s[4:5]
	s_or_b64 exec, exec, s[4:5]
	v_mov_b32_e32 v135, v134
	v_mov_b32_e32 v128, v134
	v_mov_b32_e32 v129, v134
	v_mov_b32_e32 v73, v72
	v_pk_fma_f32 v[124:125], v[60:61], v[128:129], v[124:125]
	v_pk_fma_f32 v[122:123], v[58:59], v[134:135], v[122:123] neg_lo:[1,0,0] neg_hi:[1,0,0]
	v_mov_b32_e32 v128, v72
	v_mov_b32_e32 v129, v72
	v_pk_fma_f32 v[122:123], v[72:73], v[122:123], v[54:55]
	v_pk_fma_f32 v[124:125], v[128:129], v[124:125], v[56:57]
	v_cvt_pk_bf16_f32 v126, v130, v131
	v_cvt_pk_bf16_f32 v127, v132, v133
	s_and_saveexec_b64 s[4:5], s[42:43]
	s_xor_b64 s[4:5], exec, s[4:5]
	v_cmp_lt_i32_e32 vcc, 1, v180
	s_mov_b64 s[36:37], 0
	s_mov_b64 s[54:55], 0
	s_and_saveexec_b64 s[56:57], vcc
	s_xor_b64 s[56:57], exec, s[56:57]
	v_cmp_ne_u32_e32 vcc, 2, v180
	s_and_b64 s[54:55], vcc, exec
	s_andn2_saveexec_b64 s[56:57], s[56:57]
	v_cmp_ne_u32_e32 vcc, 1, v180
	s_andn2_b64 s[36:37], s[54:55], exec
	s_and_b64 s[54:55], vcc, exec
	s_or_b64 s[54:55], s[36:37], s[54:55]
	s_mov_b64 s[36:37], exec
	s_or_b64 exec, exec, s[56:57]
	v_mov_b64_e32 v[130:131], v[124:125]
	v_mov_b64_e32 v[128:129], v[122:123]
	s_and_saveexec_b64 s[56:57], s[54:55]
	s_xor_b64 s[54:55], exec, s[56:57]
	v_mul_f32_e32 v128, 0xbfb8aa3b, v122
	v_mul_f32_e32 v129, 0xbfb8aa3b, v123
	v_mul_f32_e32 v130, 0xbfb8aa3b, v124
	v_mul_f32_e32 v131, 0xbfb8aa3b, v125
	v_exp_f32_e32 v128, v128
	v_exp_f32_e32 v129, v129
	v_exp_f32_e32 v130, v130
	v_exp_f32_e32 v131, v131
	v_add_f32_e32 v128, 1.0, v128
	v_add_f32_e32 v129, 1.0, v129
	v_add_f32_e32 v130, 1.0, v130
	v_add_f32_e32 v131, 1.0, v131
	v_rcp_f32_e32 v128, v128
	v_rcp_f32_e32 v130, v130
	v_rcp_f32_e32 v131, v131
	v_rcp_f32_e32 v129, v129
	s_andn2_b64 s[36:37], s[36:37], exec
	v_pk_mul_f32 v[130:131], v[124:125], v[130:131]
	v_pk_mul_f32 v[128:129], v[122:123], v[128:129]
	s_or_b64 exec, exec, s[54:55]
	s_and_saveexec_b64 s[54:55], s[36:37]
	s_or_b64 exec, exec, s[54:55]
	s_andn2_saveexec_b64 s[4:5], s[4:5]
	s_or_b64 exec, exec, s[4:5]
	v_add_u32_e32 v132, 0x4000, v148
	v_add_lshl_u32 v122, v132, v146, 1
	v_cvt_pk_bf16_f32 v128, v128, v129
	v_cvt_pk_bf16_f32 v129, v130, v131
	buffer_store_dwordx4 v[126:129], v122, s[28:31], 0 offen sc1
	v_mov_b32_e32 v122, v134
	v_mov_b32_e32 v123, v134
	v_pk_fma_f32 v[120:121], v[44:45], v[122:123], v[120:121]
	v_pk_fma_f32 v[118:119], v[42:43], v[134:135], v[118:119] neg_lo:[1,0,0] neg_hi:[1,0,0]
	v_mov_b32_e32 v122, v72
	v_mov_b32_e32 v123, v72
	v_pk_fma_f32 v[118:119], v[72:73], v[118:119], v[38:39]
	v_pk_fma_f32 v[120:121], v[122:123], v[120:121], v[40:41]
	s_and_saveexec_b64 s[4:5], s[44:45]
	s_xor_b64 s[4:5], exec, s[4:5]
	v_cmp_lt_i32_e32 vcc, 1, v172
	s_mov_b64 s[36:37], 0
	s_mov_b64 s[54:55], 0
	s_and_saveexec_b64 s[56:57], vcc
	s_xor_b64 s[56:57], exec, s[56:57]
	v_cmp_ne_u32_e32 vcc, 2, v172
	s_and_b64 s[54:55], vcc, exec
	s_andn2_saveexec_b64 s[56:57], s[56:57]
	v_cmp_ne_u32_e32 vcc, 1, v172
	s_andn2_b64 s[36:37], s[54:55], exec
	s_and_b64 s[54:55], vcc, exec
	s_or_b64 s[54:55], s[36:37], s[54:55]
	s_mov_b64 s[36:37], exec
	s_or_b64 exec, exec, s[56:57]
	v_mov_b64_e32 v[124:125], v[120:121]
	v_mov_b64_e32 v[122:123], v[118:119]
	s_and_saveexec_b64 s[56:57], s[54:55]
	s_xor_b64 s[54:55], exec, s[56:57]
	v_mul_f32_e32 v122, 0xbfb8aa3b, v118
	v_mul_f32_e32 v123, 0xbfb8aa3b, v119
	v_mul_f32_e32 v124, 0xbfb8aa3b, v120
	v_mul_f32_e32 v125, 0xbfb8aa3b, v121
	v_exp_f32_e32 v122, v122
	v_exp_f32_e32 v123, v123
	v_exp_f32_e32 v124, v124
	v_exp_f32_e32 v125, v125
	v_add_f32_e32 v122, 1.0, v122
	v_add_f32_e32 v123, 1.0, v123
	v_add_f32_e32 v124, 1.0, v124
	v_add_f32_e32 v125, 1.0, v125
	v_rcp_f32_e32 v122, v122
	v_rcp_f32_e32 v124, v124
	v_rcp_f32_e32 v125, v125
	v_rcp_f32_e32 v123, v123
	s_andn2_b64 s[36:37], s[36:37], exec
	v_pk_mul_f32 v[124:125], v[120:121], v[124:125]
	v_pk_mul_f32 v[122:123], v[118:119], v[122:123]
	s_or_b64 exec, exec, s[54:55]
	s_and_saveexec_b64 s[54:55], s[36:37]
	s_or_b64 exec, exec, s[54:55]
	s_andn2_saveexec_b64 s[4:5], s[4:5]
	s_or_b64 exec, exec, s[4:5]
	v_mov_b32_e32 v120, v134
	v_mov_b32_e32 v121, v134
	v_pk_fma_f32 v[114:115], v[26:27], v[134:135], v[114:115] neg_lo:[1,0,0] neg_hi:[1,0,0]
	v_pk_fma_f32 v[116:117], v[28:29], v[120:121], v[116:117]
	v_pk_fma_f32 v[114:115], v[72:73], v[114:115], v[22:23]
	v_mov_b32_e32 v73, v72
	v_pk_fma_f32 v[116:117], v[72:73], v[116:117], v[24:25]
	v_cvt_pk_bf16_f32 v118, v122, v123
	v_cvt_pk_bf16_f32 v119, v124, v125
	s_and_saveexec_b64 s[4:5], s[44:45]
	s_xor_b64 s[4:5], exec, s[4:5]
	v_cmp_lt_i32_e32 vcc, 1, v172
	s_mov_b64 s[36:37], 0
	s_mov_b64 s[54:55], 0
	s_and_saveexec_b64 s[56:57], vcc
	s_xor_b64 s[56:57], exec, s[56:57]
	v_cmp_ne_u32_e32 vcc, 2, v172
	s_and_b64 s[54:55], vcc, exec
	s_andn2_saveexec_b64 s[56:57], s[56:57]
	v_cmp_ne_u32_e32 vcc, 1, v172
	s_andn2_b64 s[36:37], s[54:55], exec
	s_and_b64 s[54:55], vcc, exec
	s_or_b64 s[54:55], s[36:37], s[54:55]
	s_mov_b64 s[36:37], exec
	s_or_b64 exec, exec, s[56:57]
	v_mov_b64_e32 v[122:123], v[116:117]
	v_mov_b64_e32 v[120:121], v[114:115]
	s_and_saveexec_b64 s[56:57], s[54:55]
	s_xor_b64 s[54:55], exec, s[56:57]
	v_mul_f32_e32 v72, 0xbfb8aa3b, v114
	v_mul_f32_e32 v73, 0xbfb8aa3b, v115
	v_mul_f32_e32 v120, 0xbfb8aa3b, v116
	v_mul_f32_e32 v121, 0xbfb8aa3b, v117
	v_exp_f32_e32 v72, v72
	v_exp_f32_e32 v73, v73
	v_exp_f32_e32 v120, v120
	v_exp_f32_e32 v121, v121
	v_add_f32_e32 v72, 1.0, v72
	v_add_f32_e32 v73, 1.0, v73
	v_add_f32_e32 v120, 1.0, v120
	v_add_f32_e32 v121, 1.0, v121
	v_rcp_f32_e32 v72, v72
	v_rcp_f32_e32 v120, v120
	v_rcp_f32_e32 v121, v121
	v_rcp_f32_e32 v73, v73
	s_andn2_b64 s[36:37], s[36:37], exec
	v_pk_mul_f32 v[122:123], v[116:117], v[120:121]
	v_pk_mul_f32 v[120:121], v[114:115], v[72:73]
	s_or_b64 exec, exec, s[54:55]
	s_and_saveexec_b64 s[54:55], s[36:37]
	s_or_b64 exec, exec, s[54:55]
	s_andn2_saveexec_b64 s[4:5], s[4:5]
	s_or_b64 exec, exec, s[4:5]
	v_add_lshl_u32 v72, v132, v138, 1
	v_cvt_pk_bf16_f32 v120, v120, v121
	v_cvt_pk_bf16_f32 v121, v122, v123
	buffer_store_dwordx4 v[118:121], v72, s[28:31], 0 offen sc1
	s_and_b64 vcc, exec, s[46:47]
	s_nop 0
	v_mov_b32_e32 v121, v206
	s_nop 0
	v_lshl_add_u32 v120, v121, 3, s33
	s_cbranch_vccnz .LBB0_611_sg3
	ds_read_b64 v[118:119], v120
	s_waitcnt lgkmcnt(0)
	v_mov_b32_e32 v72, v119
	s_branch .LBB0_612_sg3

.LBB0_612_sg3:
	v_pk_fma_f32 v[112:113], v[190:191], v[118:119], v[112:113] op_sel_hi:[1,0,1]
	v_pk_fma_f32 v[110:111], v[70:71], v[118:119], v[110:111] op_sel_hi:[1,0,1] neg_lo:[1,0,0] neg_hi:[1,0,0]
	v_pk_fma_f32 v[112:113], v[72:73], v[112:113], v[68:69] op_sel_hi:[0,1,1]
	v_pk_fma_f32 v[110:111], v[72:73], v[110:111], v[66:67] op_sel_hi:[0,1,1]
	s_and_saveexec_b64 s[4:5], s[42:43]
	s_xor_b64 s[4:5], exec, s[4:5]
	v_cmp_lt_i32_e32 vcc, 1, v180
	s_mov_b64 s[36:37], 0
	s_mov_b64 s[54:55], 0
	s_and_saveexec_b64 s[56:57], vcc
	s_xor_b64 s[56:57], exec, s[56:57]
	v_cmp_ne_u32_e32 vcc, 2, v180
	s_and_b64 s[54:55], vcc, exec
	s_andn2_saveexec_b64 s[56:57], s[56:57]
	v_cmp_ne_u32_e32 vcc, 1, v180
	s_andn2_b64 s[36:37], s[54:55], exec
	s_and_b64 s[54:55], vcc, exec
	s_or_b64 s[54:55], s[36:37], s[54:55]
	s_mov_b64 s[36:37], exec
	s_or_b64 exec, exec, s[56:57]
	v_mov_b64_e32 v[116:117], v[112:113]
	v_mov_b64_e32 v[114:115], v[110:111]
	s_and_saveexec_b64 s[56:57], s[54:55]
	s_xor_b64 s[54:55], exec, s[56:57]
	v_mul_f32_e32 v73, 0xbfb8aa3b, v110
	v_exp_f32_e32 v73, v73
	v_mul_f32_e32 v114, 0xbfb8aa3b, v111
	v_mul_f32_e32 v115, 0xbfb8aa3b, v112
	v_exp_f32_e32 v116, v114
	v_add_f32_e32 v73, 1.0, v73
	v_rcp_f32_e32 v114, v73
	v_exp_f32_e32 v73, v115
	v_mul_f32_e32 v115, 0xbfb8aa3b, v113
	v_exp_f32_e32 v115, v115
	v_add_f32_e32 v119, 1.0, v116
	v_add_f32_e32 v73, 1.0, v73
	v_rcp_f32_e32 v116, v73
	v_add_f32_e32 v73, 1.0, v115
	v_rcp_f32_e32 v117, v73
	v_rcp_f32_e32 v115, v119
	s_andn2_b64 s[36:37], s[36:37], exec
	v_pk_mul_f32 v[116:117], v[112:113], v[116:117]
	v_pk_mul_f32 v[114:115], v[110:111], v[114:115]
	s_or_b64 exec, exec, s[54:55]
	s_and_saveexec_b64 s[54:55], s[36:37]
	s_or_b64 exec, exec, s[54:55]
	s_andn2_saveexec_b64 s[4:5], s[4:5]
	s_or_b64 exec, exec, s[4:5]
	v_mov_b32_e32 v119, v118
	v_mov_b32_e32 v112, v118
	v_mov_b32_e32 v113, v118
	v_mov_b32_e32 v73, v72
	v_pk_fma_f32 v[108:109], v[60:61], v[112:113], v[108:109]
	v_pk_fma_f32 v[106:107], v[58:59], v[118:119], v[106:107] neg_lo:[1,0,0] neg_hi:[1,0,0]
	v_mov_b32_e32 v112, v72
	v_mov_b32_e32 v113, v72
	v_pk_fma_f32 v[106:107], v[72:73], v[106:107], v[54:55]
	v_pk_fma_f32 v[108:109], v[112:113], v[108:109], v[56:57]
	v_cvt_pk_bf16_f32 v110, v114, v115
	v_cvt_pk_bf16_f32 v111, v116, v117
	s_and_saveexec_b64 s[4:5], s[42:43]
	s_xor_b64 s[4:5], exec, s[4:5]
	v_cmp_lt_i32_e32 vcc, 1, v180
	s_mov_b64 s[36:37], 0
	s_mov_b64 s[54:55], 0
	s_and_saveexec_b64 s[56:57], vcc
	s_xor_b64 s[56:57], exec, s[56:57]
	v_cmp_ne_u32_e32 vcc, 2, v180
	s_and_b64 s[54:55], vcc, exec
	s_andn2_saveexec_b64 s[56:57], s[56:57]
	v_cmp_ne_u32_e32 vcc, 1, v180
	s_andn2_b64 s[36:37], s[54:55], exec
	s_and_b64 s[54:55], vcc, exec
	s_or_b64 s[54:55], s[36:37], s[54:55]
	s_mov_b64 s[36:37], exec
	s_or_b64 exec, exec, s[56:57]
	v_mov_b64_e32 v[114:115], v[108:109]
	v_mov_b64_e32 v[112:113], v[106:107]
	s_and_saveexec_b64 s[56:57], s[54:55]
	s_xor_b64 s[54:55], exec, s[56:57]
	v_mul_f32_e32 v112, 0xbfb8aa3b, v106
	v_mul_f32_e32 v113, 0xbfb8aa3b, v107
	v_mul_f32_e32 v114, 0xbfb8aa3b, v108
	v_mul_f32_e32 v115, 0xbfb8aa3b, v109
	v_exp_f32_e32 v112, v112
	v_exp_f32_e32 v113, v113
	v_exp_f32_e32 v114, v114
	v_exp_f32_e32 v115, v115
	v_add_f32_e32 v112, 1.0, v112
	v_add_f32_e32 v113, 1.0, v113
	v_add_f32_e32 v114, 1.0, v114
	v_add_f32_e32 v115, 1.0, v115
	v_rcp_f32_e32 v112, v112
	v_rcp_f32_e32 v114, v114
	v_rcp_f32_e32 v115, v115
	v_rcp_f32_e32 v113, v113
	s_andn2_b64 s[36:37], s[36:37], exec
	v_pk_mul_f32 v[114:115], v[108:109], v[114:115]
	v_pk_mul_f32 v[112:113], v[106:107], v[112:113]
	s_or_b64 exec, exec, s[54:55]
	s_and_saveexec_b64 s[54:55], s[36:37]
	s_or_b64 exec, exec, s[54:55]
	s_andn2_saveexec_b64 s[4:5], s[4:5]
	s_or_b64 exec, exec, s[4:5]
	v_add_lshl_u32 v116, v121, s51, 10
	v_add_lshl_u32 v106, v116, v146, 1
	v_cvt_pk_bf16_f32 v112, v112, v113
	v_cvt_pk_bf16_f32 v113, v114, v115
	buffer_store_dwordx4 v[110:113], v106, s[28:31], 0 offen sc1
	v_mov_b32_e32 v106, v118
	v_mov_b32_e32 v107, v118
	v_pk_fma_f32 v[104:105], v[44:45], v[106:107], v[104:105]
	v_pk_fma_f32 v[102:103], v[42:43], v[118:119], v[102:103] neg_lo:[1,0,0] neg_hi:[1,0,0]
	v_mov_b32_e32 v106, v72
	v_mov_b32_e32 v107, v72
	v_pk_fma_f32 v[102:103], v[72:73], v[102:103], v[38:39]
	v_pk_fma_f32 v[104:105], v[106:107], v[104:105], v[40:41]
	s_and_saveexec_b64 s[4:5], s[44:45]
	s_xor_b64 s[4:5], exec, s[4:5]
	v_cmp_lt_i32_e32 vcc, 1, v172
	s_mov_b64 s[36:37], 0
	s_mov_b64 s[54:55], 0
	s_and_saveexec_b64 s[56:57], vcc
	s_xor_b64 s[56:57], exec, s[56:57]
	v_cmp_ne_u32_e32 vcc, 2, v172
	s_and_b64 s[54:55], vcc, exec
	s_andn2_saveexec_b64 s[56:57], s[56:57]
	v_cmp_ne_u32_e32 vcc, 1, v172
	s_andn2_b64 s[36:37], s[54:55], exec
	s_and_b64 s[54:55], vcc, exec
	s_or_b64 s[54:55], s[36:37], s[54:55]
	s_mov_b64 s[36:37], exec
	s_or_b64 exec, exec, s[56:57]
	v_mov_b64_e32 v[108:109], v[104:105]
	v_mov_b64_e32 v[106:107], v[102:103]
	s_and_saveexec_b64 s[56:57], s[54:55]
	s_xor_b64 s[54:55], exec, s[56:57]
	v_mul_f32_e32 v106, 0xbfb8aa3b, v102
	v_mul_f32_e32 v107, 0xbfb8aa3b, v103
	v_mul_f32_e32 v108, 0xbfb8aa3b, v104
	v_mul_f32_e32 v109, 0xbfb8aa3b, v105
	v_exp_f32_e32 v106, v106
	v_exp_f32_e32 v107, v107
	v_exp_f32_e32 v108, v108
	v_exp_f32_e32 v109, v109
	v_add_f32_e32 v106, 1.0, v106
	v_add_f32_e32 v107, 1.0, v107
	v_add_f32_e32 v108, 1.0, v108
	v_add_f32_e32 v109, 1.0, v109
	v_rcp_f32_e32 v106, v106
	v_rcp_f32_e32 v108, v108
	v_rcp_f32_e32 v109, v109
	v_rcp_f32_e32 v107, v107
	s_andn2_b64 s[36:37], s[36:37], exec
	v_pk_mul_f32 v[108:109], v[104:105], v[108:109]
	v_pk_mul_f32 v[106:107], v[102:103], v[106:107]
	s_or_b64 exec, exec, s[54:55]
	s_and_saveexec_b64 s[54:55], s[36:37]
	s_or_b64 exec, exec, s[54:55]
	s_andn2_saveexec_b64 s[4:5], s[4:5]
	s_or_b64 exec, exec, s[4:5]
	v_mov_b32_e32 v104, v118
	v_mov_b32_e32 v105, v118
	v_pk_fma_f32 v[98:99], v[26:27], v[118:119], v[98:99] neg_lo:[1,0,0] neg_hi:[1,0,0]
	v_pk_fma_f32 v[100:101], v[28:29], v[104:105], v[100:101]
	v_pk_fma_f32 v[98:99], v[72:73], v[98:99], v[22:23]
	v_mov_b32_e32 v73, v72
	v_pk_fma_f32 v[100:101], v[72:73], v[100:101], v[24:25]
	v_cvt_pk_bf16_f32 v102, v106, v107
	v_cvt_pk_bf16_f32 v103, v108, v109
	s_and_saveexec_b64 s[4:5], s[44:45]
	s_xor_b64 s[4:5], exec, s[4:5]
	v_cmp_lt_i32_e32 vcc, 1, v172
	s_mov_b64 s[36:37], 0
	s_mov_b64 s[54:55], 0
	s_and_saveexec_b64 s[56:57], vcc
	s_xor_b64 s[56:57], exec, s[56:57]
	v_cmp_ne_u32_e32 vcc, 2, v172
	s_and_b64 s[54:55], vcc, exec
	s_andn2_saveexec_b64 s[56:57], s[56:57]
	v_cmp_ne_u32_e32 vcc, 1, v172
	s_andn2_b64 s[36:37], s[54:55], exec
	s_and_b64 s[54:55], vcc, exec
	s_or_b64 s[54:55], s[36:37], s[54:55]
	s_mov_b64 s[36:37], exec
	s_or_b64 exec, exec, s[56:57]
	v_mov_b64_e32 v[106:107], v[100:101]
	v_mov_b64_e32 v[104:105], v[98:99]
	s_and_saveexec_b64 s[56:57], s[54:55]
	s_xor_b64 s[54:55], exec, s[56:57]
	v_mul_f32_e32 v72, 0xbfb8aa3b, v98
	v_mul_f32_e32 v73, 0xbfb8aa3b, v99
	v_mul_f32_e32 v104, 0xbfb8aa3b, v100
	v_mul_f32_e32 v105, 0xbfb8aa3b, v101
	v_exp_f32_e32 v72, v72
	v_exp_f32_e32 v73, v73
	v_exp_f32_e32 v104, v104
	v_exp_f32_e32 v105, v105
	v_add_f32_e32 v72, 1.0, v72
	v_add_f32_e32 v73, 1.0, v73
	v_add_f32_e32 v104, 1.0, v104
	v_add_f32_e32 v105, 1.0, v105
	v_rcp_f32_e32 v72, v72
	v_rcp_f32_e32 v104, v104
	v_rcp_f32_e32 v105, v105
	v_rcp_f32_e32 v73, v73
	s_andn2_b64 s[36:37], s[36:37], exec
	v_pk_mul_f32 v[106:107], v[100:101], v[104:105]
	v_pk_mul_f32 v[104:105], v[98:99], v[72:73]
	s_or_b64 exec, exec, s[54:55]
	s_and_saveexec_b64 s[54:55], s[36:37]
	s_or_b64 exec, exec, s[54:55]
	s_andn2_saveexec_b64 s[4:5], s[4:5]
	s_or_b64 exec, exec, s[4:5]
	v_add_lshl_u32 v72, v116, v138, 1
	s_and_b64 vcc, exec, s[46:47]
	v_cvt_pk_bf16_f32 v104, v104, v105
	v_cvt_pk_bf16_f32 v105, v106, v107
	buffer_store_dwordx4 v[102:105], v72, s[28:31], 0 offen sc1
	s_cbranch_vccnz .LBB0_662_sg3
	ds_read_b64 v[102:103], v120 offset:128
	s_waitcnt lgkmcnt(0)
	v_mov_b32_e32 v72, v103
	s_branch .LBB0_663_sg3

.LBB0_663_sg3:
	v_pk_fma_f32 v[96:97], v[190:191], v[102:103], v[96:97] op_sel_hi:[1,0,1]
	v_pk_fma_f32 v[94:95], v[70:71], v[102:103], v[94:95] op_sel_hi:[1,0,1] neg_lo:[1,0,0] neg_hi:[1,0,0]
	v_pk_fma_f32 v[96:97], v[72:73], v[96:97], v[68:69] op_sel_hi:[0,1,1]
	v_pk_fma_f32 v[94:95], v[72:73], v[94:95], v[66:67] op_sel_hi:[0,1,1]
	s_and_saveexec_b64 s[4:5], s[42:43]
	s_xor_b64 s[4:5], exec, s[4:5]
	v_cmp_lt_i32_e32 vcc, 1, v180
	s_mov_b64 s[36:37], 0
	s_mov_b64 s[54:55], 0
	s_and_saveexec_b64 s[56:57], vcc
	s_xor_b64 s[56:57], exec, s[56:57]
	v_cmp_ne_u32_e32 vcc, 2, v180
	s_and_b64 s[54:55], vcc, exec
	s_andn2_saveexec_b64 s[56:57], s[56:57]
	v_cmp_ne_u32_e32 vcc, 1, v180
	s_andn2_b64 s[36:37], s[54:55], exec
	s_and_b64 s[54:55], vcc, exec
	s_or_b64 s[54:55], s[36:37], s[54:55]
	s_mov_b64 s[36:37], exec
	s_or_b64 exec, exec, s[56:57]
	v_mov_b64_e32 v[100:101], v[96:97]
	v_mov_b64_e32 v[98:99], v[94:95]
	s_and_saveexec_b64 s[56:57], s[54:55]
	s_xor_b64 s[54:55], exec, s[56:57]
	v_mul_f32_e32 v73, 0xbfb8aa3b, v94
	v_exp_f32_e32 v73, v73
	v_mul_f32_e32 v98, 0xbfb8aa3b, v95
	v_mul_f32_e32 v99, 0xbfb8aa3b, v96
	v_exp_f32_e32 v100, v98
	v_add_f32_e32 v73, 1.0, v73
	v_rcp_f32_e32 v98, v73
	v_exp_f32_e32 v73, v99
	v_mul_f32_e32 v99, 0xbfb8aa3b, v97
	v_exp_f32_e32 v99, v99
	v_add_f32_e32 v103, 1.0, v100
	v_add_f32_e32 v73, 1.0, v73
	v_rcp_f32_e32 v100, v73
	v_add_f32_e32 v73, 1.0, v99
	v_rcp_f32_e32 v101, v73
	v_rcp_f32_e32 v99, v103
	s_andn2_b64 s[36:37], s[36:37], exec
	v_pk_mul_f32 v[100:101], v[96:97], v[100:101]
	v_pk_mul_f32 v[98:99], v[94:95], v[98:99]
	s_or_b64 exec, exec, s[54:55]
	s_and_saveexec_b64 s[54:55], s[36:37]
	s_or_b64 exec, exec, s[54:55]
	s_andn2_saveexec_b64 s[4:5], s[4:5]
	s_or_b64 exec, exec, s[4:5]
	v_mov_b32_e32 v103, v102
	v_mov_b32_e32 v96, v102
	v_mov_b32_e32 v97, v102
	v_mov_b32_e32 v73, v72
	v_pk_fma_f32 v[92:93], v[60:61], v[96:97], v[92:93]
	v_pk_fma_f32 v[90:91], v[58:59], v[102:103], v[90:91] neg_lo:[1,0,0] neg_hi:[1,0,0]
	v_mov_b32_e32 v96, v72
	v_mov_b32_e32 v97, v72
	v_pk_fma_f32 v[90:91], v[72:73], v[90:91], v[54:55]
	v_pk_fma_f32 v[92:93], v[96:97], v[92:93], v[56:57]
	v_cvt_pk_bf16_f32 v94, v98, v99
	v_cvt_pk_bf16_f32 v95, v100, v101
	s_and_saveexec_b64 s[4:5], s[42:43]
	s_xor_b64 s[4:5], exec, s[4:5]
	v_cmp_lt_i32_e32 vcc, 1, v180
	s_mov_b64 s[36:37], 0
	s_mov_b64 s[54:55], 0
	s_and_saveexec_b64 s[56:57], vcc
	s_xor_b64 s[56:57], exec, s[56:57]
	v_cmp_ne_u32_e32 vcc, 2, v180
	s_and_b64 s[54:55], vcc, exec
	s_andn2_saveexec_b64 s[56:57], s[56:57]
	v_cmp_ne_u32_e32 vcc, 1, v180
	s_andn2_b64 s[36:37], s[54:55], exec
	s_and_b64 s[54:55], vcc, exec
	s_or_b64 s[54:55], s[36:37], s[54:55]
	s_mov_b64 s[36:37], exec
	s_or_b64 exec, exec, s[56:57]
	v_mov_b64_e32 v[98:99], v[92:93]
	v_mov_b64_e32 v[96:97], v[90:91]
	s_and_saveexec_b64 s[56:57], s[54:55]
	s_xor_b64 s[54:55], exec, s[56:57]
	v_mul_f32_e32 v96, 0xbfb8aa3b, v90
	v_mul_f32_e32 v97, 0xbfb8aa3b, v91
	v_mul_f32_e32 v98, 0xbfb8aa3b, v92
	v_mul_f32_e32 v99, 0xbfb8aa3b, v93
	v_exp_f32_e32 v96, v96
	v_exp_f32_e32 v97, v97
	v_exp_f32_e32 v98, v98
	v_exp_f32_e32 v99, v99
	v_add_f32_e32 v96, 1.0, v96
	v_add_f32_e32 v97, 1.0, v97
	v_add_f32_e32 v98, 1.0, v98
	v_add_f32_e32 v99, 1.0, v99
	v_rcp_f32_e32 v96, v96
	v_rcp_f32_e32 v98, v98
	v_rcp_f32_e32 v99, v99
	v_rcp_f32_e32 v97, v97
	s_andn2_b64 s[36:37], s[36:37], exec
	v_pk_mul_f32 v[98:99], v[92:93], v[98:99]
	v_pk_mul_f32 v[96:97], v[90:91], v[96:97]
	s_or_b64 exec, exec, s[54:55]
	s_and_saveexec_b64 s[54:55], s[36:37]
	s_or_b64 exec, exec, s[54:55]
	s_andn2_saveexec_b64 s[4:5], s[4:5]
	s_or_b64 exec, exec, s[4:5]
	v_add_u32_e32 v100, 0x4000, v116
	v_add_lshl_u32 v90, v100, v146, 1
	v_cvt_pk_bf16_f32 v96, v96, v97
	v_cvt_pk_bf16_f32 v97, v98, v99
	buffer_store_dwordx4 v[94:97], v90, s[28:31], 0 offen sc1
	v_mov_b32_e32 v90, v102
	v_mov_b32_e32 v91, v102
	v_pk_fma_f32 v[88:89], v[44:45], v[90:91], v[88:89]
	v_pk_fma_f32 v[86:87], v[42:43], v[102:103], v[86:87] neg_lo:[1,0,0] neg_hi:[1,0,0]
	v_mov_b32_e32 v90, v72
	v_mov_b32_e32 v91, v72
	v_pk_fma_f32 v[86:87], v[72:73], v[86:87], v[38:39]
	v_pk_fma_f32 v[88:89], v[90:91], v[88:89], v[40:41]
	s_and_saveexec_b64 s[4:5], s[44:45]
	s_xor_b64 s[4:5], exec, s[4:5]
	v_cmp_lt_i32_e32 vcc, 1, v172
	s_mov_b64 s[36:37], 0
	s_mov_b64 s[54:55], 0
	s_and_saveexec_b64 s[56:57], vcc
	s_xor_b64 s[56:57], exec, s[56:57]
	v_cmp_ne_u32_e32 vcc, 2, v172
	s_and_b64 s[54:55], vcc, exec
	s_andn2_saveexec_b64 s[56:57], s[56:57]
	v_cmp_ne_u32_e32 vcc, 1, v172
	s_andn2_b64 s[36:37], s[54:55], exec
	s_and_b64 s[54:55], vcc, exec
	s_or_b64 s[54:55], s[36:37], s[54:55]
	s_mov_b64 s[36:37], exec
	s_or_b64 exec, exec, s[56:57]
	v_mov_b64_e32 v[92:93], v[88:89]
	v_mov_b64_e32 v[90:91], v[86:87]
	s_and_saveexec_b64 s[56:57], s[54:55]
	s_xor_b64 s[54:55], exec, s[56:57]
	v_mul_f32_e32 v90, 0xbfb8aa3b, v86
	v_mul_f32_e32 v91, 0xbfb8aa3b, v87
	v_mul_f32_e32 v92, 0xbfb8aa3b, v88
	v_mul_f32_e32 v93, 0xbfb8aa3b, v89
	v_exp_f32_e32 v90, v90
	v_exp_f32_e32 v91, v91
	v_exp_f32_e32 v92, v92
	v_exp_f32_e32 v93, v93
	v_add_f32_e32 v90, 1.0, v90
	v_add_f32_e32 v91, 1.0, v91
	v_add_f32_e32 v92, 1.0, v92
	v_add_f32_e32 v93, 1.0, v93
	v_rcp_f32_e32 v90, v90
	v_rcp_f32_e32 v92, v92
	v_rcp_f32_e32 v93, v93
	v_rcp_f32_e32 v91, v91
	s_andn2_b64 s[36:37], s[36:37], exec
	v_pk_mul_f32 v[92:93], v[88:89], v[92:93]
	v_pk_mul_f32 v[90:91], v[86:87], v[90:91]
	s_or_b64 exec, exec, s[54:55]
	s_and_saveexec_b64 s[54:55], s[36:37]
	s_or_b64 exec, exec, s[54:55]
	s_andn2_saveexec_b64 s[4:5], s[4:5]
	s_or_b64 exec, exec, s[4:5]
	v_mov_b32_e32 v88, v102
	v_mov_b32_e32 v89, v102
	v_pk_fma_f32 v[82:83], v[26:27], v[102:103], v[82:83] neg_lo:[1,0,0] neg_hi:[1,0,0]
	v_pk_fma_f32 v[84:85], v[28:29], v[88:89], v[84:85]
	v_pk_fma_f32 v[82:83], v[72:73], v[82:83], v[22:23]
	v_mov_b32_e32 v73, v72
	v_pk_fma_f32 v[84:85], v[72:73], v[84:85], v[24:25]
	v_cvt_pk_bf16_f32 v86, v90, v91
	v_cvt_pk_bf16_f32 v87, v92, v93
	s_and_saveexec_b64 s[4:5], s[44:45]
	s_xor_b64 s[4:5], exec, s[4:5]
	v_cmp_lt_i32_e32 vcc, 1, v172
	s_mov_b64 s[36:37], 0
	s_mov_b64 s[54:55], 0
	s_and_saveexec_b64 s[56:57], vcc
	s_xor_b64 s[56:57], exec, s[56:57]
	v_cmp_ne_u32_e32 vcc, 2, v172
	s_and_b64 s[54:55], vcc, exec
	s_andn2_saveexec_b64 s[56:57], s[56:57]
	v_cmp_ne_u32_e32 vcc, 1, v172
	s_andn2_b64 s[36:37], s[54:55], exec
	s_and_b64 s[54:55], vcc, exec
	s_or_b64 s[54:55], s[36:37], s[54:55]
	s_mov_b64 s[36:37], exec
	s_or_b64 exec, exec, s[56:57]
	v_mov_b64_e32 v[90:91], v[84:85]
	v_mov_b64_e32 v[88:89], v[82:83]
	s_and_saveexec_b64 s[56:57], s[54:55]
	s_xor_b64 s[54:55], exec, s[56:57]
	v_mul_f32_e32 v72, 0xbfb8aa3b, v82
	v_mul_f32_e32 v73, 0xbfb8aa3b, v83
	v_mul_f32_e32 v88, 0xbfb8aa3b, v84
	v_mul_f32_e32 v89, 0xbfb8aa3b, v85
	v_exp_f32_e32 v72, v72
	v_exp_f32_e32 v73, v73
	v_exp_f32_e32 v88, v88
	v_exp_f32_e32 v89, v89
	v_add_f32_e32 v72, 1.0, v72
	v_add_f32_e32 v73, 1.0, v73
	v_add_f32_e32 v88, 1.0, v88
	v_add_f32_e32 v89, 1.0, v89
	v_rcp_f32_e32 v72, v72
	v_rcp_f32_e32 v88, v88
	v_rcp_f32_e32 v89, v89
	v_rcp_f32_e32 v73, v73
	s_andn2_b64 s[36:37], s[36:37], exec
	v_pk_mul_f32 v[90:91], v[84:85], v[88:89]
	v_pk_mul_f32 v[88:89], v[82:83], v[72:73]
	s_or_b64 exec, exec, s[54:55]
	s_and_saveexec_b64 s[54:55], s[36:37]
	s_or_b64 exec, exec, s[54:55]
	s_andn2_saveexec_b64 s[4:5], s[4:5]
	s_or_b64 exec, exec, s[4:5]
	v_add_lshl_u32 v72, v100, v138, 1
	v_cvt_pk_bf16_f32 v88, v88, v89
	v_cvt_pk_bf16_f32 v89, v90, v91
	buffer_store_dwordx4 v[86:89], v72, s[28:31], 0 offen sc1
	v_mov_b32_e32 v91, v207
	s_and_b64 vcc, exec, s[46:47]
	v_lshl_add_u32 v90, v91, 3, s33
	s_cbranch_vccnz .LBB0_713_sg3
	ds_read_b64 v[88:89], v90
	s_waitcnt lgkmcnt(0)
	v_mov_b32_e32 v86, v89
	s_branch .LBB0_714_sg3

.LBB0_714_sg3:
	v_pk_fma_f32 v[72:73], v[190:191], v[88:89], v[80:81] op_sel_hi:[1,0,1]
	v_pk_fma_f32 v[78:79], v[70:71], v[88:89], v[78:79] op_sel_hi:[1,0,1] neg_lo:[1,0,0] neg_hi:[1,0,0]
	v_pk_fma_f32 v[80:81], v[86:87], v[72:73], v[68:69] op_sel_hi:[0,1,1]
	v_pk_fma_f32 v[78:79], v[86:87], v[78:79], v[66:67] op_sel_hi:[0,1,1]
	s_and_saveexec_b64 s[4:5], s[42:43]
	s_xor_b64 s[4:5], exec, s[4:5]
	v_cmp_lt_i32_e32 vcc, 1, v180
	s_mov_b64 s[36:37], 0
	s_mov_b64 s[54:55], 0
	s_and_saveexec_b64 s[56:57], vcc
	s_xor_b64 s[56:57], exec, s[56:57]
	v_cmp_ne_u32_e32 vcc, 2, v180
	s_and_b64 s[54:55], vcc, exec
	s_andn2_saveexec_b64 s[56:57], s[56:57]
	v_cmp_ne_u32_e32 vcc, 1, v180
	s_andn2_b64 s[36:37], s[54:55], exec
	s_and_b64 s[54:55], vcc, exec
	s_or_b64 s[54:55], s[36:37], s[54:55]
	s_mov_b64 s[36:37], exec
	s_or_b64 exec, exec, s[56:57]
	v_mov_b64_e32 v[84:85], v[80:81]
	v_mov_b64_e32 v[82:83], v[78:79]
	s_and_saveexec_b64 s[56:57], s[54:55]
	s_xor_b64 s[54:55], exec, s[56:57]
	v_mul_f32_e32 v72, 0xbfb8aa3b, v78
	v_mul_f32_e32 v73, 0xbfb8aa3b, v79
	v_mul_f32_e32 v82, 0xbfb8aa3b, v80
	v_mul_f32_e32 v83, 0xbfb8aa3b, v81
	v_exp_f32_e32 v72, v72
	v_exp_f32_e32 v73, v73
	v_exp_f32_e32 v82, v82
	v_exp_f32_e32 v83, v83
	v_add_f32_e32 v72, 1.0, v72
	v_add_f32_e32 v73, 1.0, v73
	v_add_f32_e32 v82, 1.0, v82
	v_add_f32_e32 v83, 1.0, v83
	v_rcp_f32_e32 v72, v72
	v_rcp_f32_e32 v82, v82
	v_rcp_f32_e32 v83, v83
	v_rcp_f32_e32 v73, v73
	s_andn2_b64 s[36:37], s[36:37], exec
	v_pk_mul_f32 v[84:85], v[80:81], v[82:83]
	v_pk_mul_f32 v[82:83], v[78:79], v[72:73]
	s_or_b64 exec, exec, s[54:55]
	s_and_saveexec_b64 s[54:55], s[36:37]
	s_or_b64 exec, exec, s[54:55]
	s_andn2_saveexec_b64 s[4:5], s[4:5]
	s_or_b64 exec, exec, s[4:5]
	v_mov_b32_e32 v89, v88
	v_mov_b32_e32 v78, v88
	v_mov_b32_e32 v79, v88
	v_mov_b32_e32 v87, v86
	v_pk_fma_f32 v[76:77], v[60:61], v[78:79], v[76:77]
	v_pk_fma_f32 v[74:75], v[58:59], v[88:89], v[74:75] neg_lo:[1,0,0] neg_hi:[1,0,0]
	v_mov_b32_e32 v78, v86
	v_mov_b32_e32 v79, v86
	v_pk_fma_f32 v[74:75], v[86:87], v[74:75], v[54:55]
	v_pk_fma_f32 v[76:77], v[78:79], v[76:77], v[56:57]
	v_cvt_pk_bf16_f32 v72, v82, v83
	v_cvt_pk_bf16_f32 v73, v84, v85
	s_and_saveexec_b64 s[4:5], s[42:43]
	s_xor_b64 s[4:5], exec, s[4:5]
	v_cmp_lt_i32_e32 vcc, 1, v180
	s_mov_b64 s[36:37], 0
	s_mov_b64 s[54:55], 0
	s_and_saveexec_b64 s[56:57], vcc
	s_xor_b64 s[56:57], exec, s[56:57]
	v_cmp_ne_u32_e32 vcc, 2, v180
	s_and_b64 s[54:55], vcc, exec
	s_andn2_saveexec_b64 s[56:57], s[56:57]
	v_cmp_ne_u32_e32 vcc, 1, v180
	s_andn2_b64 s[36:37], s[54:55], exec
	s_and_b64 s[54:55], vcc, exec
	s_or_b64 s[54:55], s[36:37], s[54:55]
	s_mov_b64 s[36:37], exec
	s_or_b64 exec, exec, s[56:57]
	v_mov_b64_e32 v[80:81], v[76:77]
	v_mov_b64_e32 v[78:79], v[74:75]
	s_and_saveexec_b64 s[56:57], s[54:55]
	s_xor_b64 s[54:55], exec, s[56:57]
	v_mul_f32_e32 v78, 0xbfb8aa3b, v74
	v_mul_f32_e32 v79, 0xbfb8aa3b, v75
	v_mul_f32_e32 v80, 0xbfb8aa3b, v76
	v_mul_f32_e32 v81, 0xbfb8aa3b, v77
	v_exp_f32_e32 v78, v78
	v_exp_f32_e32 v79, v79
	v_exp_f32_e32 v80, v80
	v_exp_f32_e32 v81, v81
	v_add_f32_e32 v78, 1.0, v78
	v_add_f32_e32 v79, 1.0, v79
	v_add_f32_e32 v80, 1.0, v80
	v_add_f32_e32 v81, 1.0, v81
	v_rcp_f32_e32 v78, v78
	v_rcp_f32_e32 v80, v80
	v_rcp_f32_e32 v81, v81
	v_rcp_f32_e32 v79, v79
	s_andn2_b64 s[36:37], s[36:37], exec
	v_pk_mul_f32 v[80:81], v[76:77], v[80:81]
	v_pk_mul_f32 v[78:79], v[74:75], v[78:79]
	s_or_b64 exec, exec, s[54:55]
	s_and_saveexec_b64 s[54:55], s[36:37]
	s_or_b64 exec, exec, s[54:55]
	s_andn2_saveexec_b64 s[4:5], s[4:5]
	s_or_b64 exec, exec, s[4:5]
	v_add_lshl_u32 v76, v91, s51, 10
	v_add_lshl_u32 v77, v76, v146, 1
	v_cvt_pk_bf16_f32 v74, v78, v79
	v_cvt_pk_bf16_f32 v75, v80, v81
	buffer_store_dwordx4 v[72:75], v77, s[28:31], 0 offen sc1
	v_pk_fma_f32 v[50:51], v[42:43], v[88:89], v[50:51] neg_lo:[1,0,0] neg_hi:[1,0,0]
	s_nop 0
	v_mov_b32_e32 v72, v88
	v_mov_b32_e32 v73, v88
	v_pk_fma_f32 v[52:53], v[44:45], v[72:73], v[52:53]
	v_mov_b32_e32 v72, v86
	v_mov_b32_e32 v73, v86
	v_pk_fma_f32 v[50:51], v[86:87], v[50:51], v[38:39]
	v_pk_fma_f32 v[52:53], v[72:73], v[52:53], v[40:41]
	s_and_saveexec_b64 s[4:5], s[44:45]
	s_xor_b64 s[4:5], exec, s[4:5]
	v_cmp_lt_i32_e32 vcc, 1, v172
	s_mov_b64 s[36:37], 0
	s_mov_b64 s[54:55], 0
	s_and_saveexec_b64 s[56:57], vcc
	s_xor_b64 s[56:57], exec, s[56:57]
	v_cmp_ne_u32_e32 vcc, 2, v172
	s_and_b64 s[54:55], vcc, exec
	s_andn2_saveexec_b64 s[56:57], s[56:57]
	v_cmp_ne_u32_e32 vcc, 1, v172
	s_andn2_b64 s[36:37], s[54:55], exec
	s_and_b64 s[54:55], vcc, exec
	s_or_b64 s[54:55], s[36:37], s[54:55]
	s_mov_b64 s[36:37], exec
	s_or_b64 exec, exec, s[56:57]
	v_mov_b64_e32 v[74:75], v[52:53]
	v_mov_b64_e32 v[72:73], v[50:51]
	s_and_saveexec_b64 s[56:57], s[54:55]
	s_xor_b64 s[54:55], exec, s[56:57]
	v_mul_f32_e32 v72, 0xbfb8aa3b, v50
	v_mul_f32_e32 v73, 0xbfb8aa3b, v51
	v_mul_f32_e32 v74, 0xbfb8aa3b, v52
	v_mul_f32_e32 v75, 0xbfb8aa3b, v53
	v_exp_f32_e32 v72, v72
	v_exp_f32_e32 v73, v73
	v_exp_f32_e32 v74, v74
	v_exp_f32_e32 v75, v75
	v_add_f32_e32 v72, 1.0, v72
	v_add_f32_e32 v73, 1.0, v73
	v_add_f32_e32 v74, 1.0, v74
	v_add_f32_e32 v75, 1.0, v75
	v_rcp_f32_e32 v72, v72
	v_rcp_f32_e32 v74, v74
	v_rcp_f32_e32 v75, v75
	v_rcp_f32_e32 v73, v73
	s_andn2_b64 s[36:37], s[36:37], exec
	v_pk_mul_f32 v[74:75], v[52:53], v[74:75]
	v_pk_mul_f32 v[72:73], v[50:51], v[72:73]
	s_or_b64 exec, exec, s[54:55]
	s_and_saveexec_b64 s[54:55], s[36:37]
	s_or_b64 exec, exec, s[54:55]
	s_andn2_saveexec_b64 s[4:5], s[4:5]
	s_or_b64 exec, exec, s[4:5]
	v_mov_b32_e32 v52, v88
	v_mov_b32_e32 v53, v88
	v_pk_fma_f32 v[34:35], v[26:27], v[88:89], v[34:35] neg_lo:[1,0,0] neg_hi:[1,0,0]
	v_pk_fma_f32 v[36:37], v[28:29], v[52:53], v[36:37]
	v_pk_fma_f32 v[34:35], v[86:87], v[34:35], v[22:23]
	v_mov_b32_e32 v87, v86
	v_pk_fma_f32 v[36:37], v[86:87], v[36:37], v[24:25]
	v_cvt_pk_bf16_f32 v50, v72, v73
	v_cvt_pk_bf16_f32 v51, v74, v75
	s_and_saveexec_b64 s[4:5], s[44:45]
	s_xor_b64 s[4:5], exec, s[4:5]
	v_cmp_lt_i32_e32 vcc, 1, v172
	s_mov_b64 s[36:37], 0
	s_mov_b64 s[54:55], 0
	s_and_saveexec_b64 s[56:57], vcc
	s_xor_b64 s[56:57], exec, s[56:57]
	v_cmp_ne_u32_e32 vcc, 2, v172
	s_and_b64 s[54:55], vcc, exec
	s_andn2_saveexec_b64 s[56:57], s[56:57]
	v_cmp_ne_u32_e32 vcc, 1, v172
	s_andn2_b64 s[36:37], s[54:55], exec
	s_and_b64 s[54:55], vcc, exec
	s_or_b64 s[54:55], s[36:37], s[54:55]
	s_mov_b64 s[36:37], exec
	s_or_b64 exec, exec, s[56:57]
	v_mov_b64_e32 v[74:75], v[36:37]
	v_mov_b64_e32 v[72:73], v[34:35]
	s_and_saveexec_b64 s[56:57], s[54:55]
	s_xor_b64 s[54:55], exec, s[56:57]
	v_mul_f32_e32 v52, 0xbfb8aa3b, v34
	v_mul_f32_e32 v53, 0xbfb8aa3b, v35
	v_mul_f32_e32 v72, 0xbfb8aa3b, v36
	v_mul_f32_e32 v73, 0xbfb8aa3b, v37
	v_exp_f32_e32 v52, v52
	v_exp_f32_e32 v53, v53
	v_exp_f32_e32 v72, v72
	v_exp_f32_e32 v73, v73
	v_add_f32_e32 v52, 1.0, v52
	v_add_f32_e32 v53, 1.0, v53
	v_add_f32_e32 v72, 1.0, v72
	v_add_f32_e32 v73, 1.0, v73
	v_rcp_f32_e32 v52, v52
	v_rcp_f32_e32 v72, v72
	v_rcp_f32_e32 v73, v73
	v_rcp_f32_e32 v53, v53
	s_andn2_b64 s[36:37], s[36:37], exec
	v_pk_mul_f32 v[74:75], v[36:37], v[72:73]
	v_pk_mul_f32 v[72:73], v[34:35], v[52:53]
	s_or_b64 exec, exec, s[54:55]
	s_and_saveexec_b64 s[54:55], s[36:37]
	s_or_b64 exec, exec, s[54:55]
	s_andn2_saveexec_b64 s[4:5], s[4:5]
	s_or_b64 exec, exec, s[4:5]
	v_add_lshl_u32 v34, v76, v138, 1
	s_and_b64 vcc, exec, s[46:47]
	v_cvt_pk_bf16_f32 v52, v72, v73
	v_cvt_pk_bf16_f32 v53, v74, v75
	buffer_store_dwordx4 v[50:53], v34, s[28:31], 0 offen sc1
	s_cbranch_vccnz .LBB0_764_sg3
	ds_read_b64 v[52:53], v90 offset:128
	s_waitcnt lgkmcnt(0)
	v_mov_b32_e32 v50, v53
	s_branch .LBB0_765_sg3

.LBB0_765_sg3:
	v_pk_fma_f32 v[20:21], v[190:191], v[52:53], v[20:21] op_sel_hi:[1,0,1]
	v_pk_fma_f32 v[18:19], v[70:71], v[52:53], v[18:19] op_sel_hi:[1,0,1] neg_lo:[1,0,0] neg_hi:[1,0,0]
	v_pk_fma_f32 v[20:21], v[50:51], v[20:21], v[68:69] op_sel_hi:[0,1,1]
	v_pk_fma_f32 v[18:19], v[50:51], v[18:19], v[66:67] op_sel_hi:[0,1,1]
	s_and_saveexec_b64 s[4:5], s[42:43]
	s_xor_b64 s[4:5], exec, s[4:5]
	v_cmp_lt_i32_e32 vcc, 1, v180
	s_mov_b64 s[36:37], 0
	s_mov_b64 s[46:47], 0
	s_and_saveexec_b64 s[54:55], vcc
	s_xor_b64 s[54:55], exec, s[54:55]
	v_cmp_ne_u32_e32 vcc, 2, v180
	s_and_b64 s[46:47], vcc, exec
	s_andn2_saveexec_b64 s[54:55], s[54:55]
	v_cmp_ne_u32_e32 vcc, 1, v180
	s_andn2_b64 s[36:37], s[46:47], exec
	s_and_b64 s[46:47], vcc, exec
	s_or_b64 s[46:47], s[36:37], s[46:47]
	s_mov_b64 s[36:37], exec
	s_or_b64 exec, exec, s[54:55]
	v_mov_b64_e32 v[36:37], v[20:21]
	v_mov_b64_e32 v[34:35], v[18:19]
	s_and_saveexec_b64 s[54:55], s[46:47]
	s_xor_b64 s[46:47], exec, s[54:55]
	v_mul_f32_e32 v34, 0xbfb8aa3b, v18
	v_mul_f32_e32 v35, 0xbfb8aa3b, v19
	v_mul_f32_e32 v36, 0xbfb8aa3b, v20
	v_mul_f32_e32 v37, 0xbfb8aa3b, v21
	v_exp_f32_e32 v34, v34
	v_exp_f32_e32 v35, v35
	v_exp_f32_e32 v36, v36
	v_exp_f32_e32 v37, v37
	v_add_f32_e32 v34, 1.0, v34
	v_add_f32_e32 v35, 1.0, v35
	v_add_f32_e32 v36, 1.0, v36
	v_add_f32_e32 v37, 1.0, v37
	v_rcp_f32_e32 v34, v34
	v_rcp_f32_e32 v36, v36
	v_rcp_f32_e32 v37, v37
	v_rcp_f32_e32 v35, v35
	s_andn2_b64 s[36:37], s[36:37], exec
	v_pk_mul_f32 v[36:37], v[20:21], v[36:37]
	v_pk_mul_f32 v[34:35], v[18:19], v[34:35]
	s_or_b64 exec, exec, s[46:47]
	s_and_saveexec_b64 s[46:47], s[36:37]
	s_or_b64 exec, exec, s[46:47]
	s_andn2_saveexec_b64 s[4:5], s[4:5]
	s_or_b64 exec, exec, s[4:5]
	v_mov_b32_e32 v53, v52
	v_mov_b32_e32 v20, v52
	v_mov_b32_e32 v21, v52
	v_mov_b32_e32 v51, v50
	v_pk_fma_f32 v[12:13], v[60:61], v[20:21], v[12:13]
	v_pk_fma_f32 v[10:11], v[58:59], v[52:53], v[10:11] neg_lo:[1,0,0] neg_hi:[1,0,0]
	v_mov_b32_e32 v20, v50
	v_mov_b32_e32 v21, v50
	v_pk_fma_f32 v[10:11], v[50:51], v[10:11], v[54:55]
	v_pk_fma_f32 v[12:13], v[20:21], v[12:13], v[56:57]
	v_cvt_pk_bf16_f32 v18, v34, v35
	v_cvt_pk_bf16_f32 v19, v36, v37
	s_and_saveexec_b64 s[4:5], s[42:43]
	s_xor_b64 s[4:5], exec, s[4:5]
	v_cmp_lt_i32_e32 vcc, 1, v180
	s_mov_b64 s[36:37], 0
	s_mov_b64 s[42:43], 0
	s_and_saveexec_b64 s[46:47], vcc
	s_xor_b64 s[46:47], exec, s[46:47]
	v_cmp_ne_u32_e32 vcc, 2, v180
	s_and_b64 s[42:43], vcc, exec
	s_andn2_saveexec_b64 s[46:47], s[46:47]
	v_cmp_ne_u32_e32 vcc, 1, v180
	s_andn2_b64 s[36:37], s[42:43], exec
	s_and_b64 s[42:43], vcc, exec
	s_or_b64 s[42:43], s[36:37], s[42:43]
	s_mov_b64 s[36:37], exec
	s_or_b64 exec, exec, s[46:47]
	v_mov_b64_e32 v[36:37], v[12:13]
	v_mov_b64_e32 v[34:35], v[10:11]
	s_and_saveexec_b64 s[46:47], s[42:43]
	s_xor_b64 s[42:43], exec, s[46:47]
	v_mul_f32_e32 v20, 0xbfb8aa3b, v10
	v_mul_f32_e32 v21, 0xbfb8aa3b, v11
	v_mul_f32_e32 v34, 0xbfb8aa3b, v12
	v_mul_f32_e32 v35, 0xbfb8aa3b, v13
	v_exp_f32_e32 v20, v20
	v_exp_f32_e32 v21, v21
	v_exp_f32_e32 v34, v34
	v_exp_f32_e32 v35, v35
	v_add_f32_e32 v20, 1.0, v20
	v_add_f32_e32 v21, 1.0, v21
	v_add_f32_e32 v34, 1.0, v34
	v_add_f32_e32 v35, 1.0, v35
	v_rcp_f32_e32 v20, v20
	v_rcp_f32_e32 v34, v34
	v_rcp_f32_e32 v35, v35
	v_rcp_f32_e32 v21, v21
	s_andn2_b64 s[36:37], s[36:37], exec
	v_pk_mul_f32 v[36:37], v[12:13], v[34:35]
	v_pk_mul_f32 v[34:35], v[10:11], v[20:21]
	s_or_b64 exec, exec, s[42:43]
	s_and_saveexec_b64 s[42:43], s[36:37]
	s_or_b64 exec, exec, s[42:43]
	s_andn2_saveexec_b64 s[4:5], s[4:5]
	s_or_b64 exec, exec, s[4:5]
	v_add_u32_e32 v46, 0x4000, v76
	v_add_lshl_u32 v10, v46, v146, 1
	v_cvt_pk_bf16_f32 v20, v34, v35
	v_cvt_pk_bf16_f32 v21, v36, v37
	buffer_store_dwordx4 v[18:21], v10, s[28:31], 0 offen sc1
	v_mov_b32_e32 v10, v52
	v_mov_b32_e32 v11, v52
	v_pk_fma_f32 v[8:9], v[44:45], v[10:11], v[8:9]
	v_pk_fma_f32 v[6:7], v[42:43], v[52:53], v[6:7] neg_lo:[1,0,0] neg_hi:[1,0,0]
	v_mov_b32_e32 v10, v50
	v_mov_b32_e32 v11, v50
	v_pk_fma_f32 v[6:7], v[50:51], v[6:7], v[38:39]
	v_pk_fma_f32 v[8:9], v[10:11], v[8:9], v[40:41]
	s_and_saveexec_b64 s[4:5], s[44:45]
	s_xor_b64 s[4:5], exec, s[4:5]
	v_cmp_lt_i32_e32 vcc, 1, v172
	s_mov_b64 s[36:37], 0
	s_mov_b64 s[42:43], 0
	s_and_saveexec_b64 s[46:47], vcc
	s_xor_b64 s[46:47], exec, s[46:47]
	v_cmp_ne_u32_e32 vcc, 2, v172
	s_and_b64 s[42:43], vcc, exec
	s_andn2_saveexec_b64 s[46:47], s[46:47]
	v_cmp_ne_u32_e32 vcc, 1, v172
	s_andn2_b64 s[36:37], s[42:43], exec
	s_and_b64 s[42:43], vcc, exec
	s_or_b64 s[42:43], s[36:37], s[42:43]
	s_mov_b64 s[36:37], exec
	s_or_b64 exec, exec, s[46:47]
	v_mov_b64_e32 v[12:13], v[8:9]
	v_mov_b64_e32 v[10:11], v[6:7]
	s_and_saveexec_b64 s[46:47], s[42:43]
	s_xor_b64 s[42:43], exec, s[46:47]
	v_mul_f32_e32 v10, 0xbfb8aa3b, v6
	v_mul_f32_e32 v11, 0xbfb8aa3b, v7
	v_mul_f32_e32 v12, 0xbfb8aa3b, v8
	v_mul_f32_e32 v13, 0xbfb8aa3b, v9
	v_exp_f32_e32 v10, v10
	v_exp_f32_e32 v11, v11
	v_exp_f32_e32 v12, v12
	v_exp_f32_e32 v13, v13
	v_add_f32_e32 v10, 1.0, v10
	v_add_f32_e32 v11, 1.0, v11
	v_add_f32_e32 v12, 1.0, v12
	v_add_f32_e32 v13, 1.0, v13
	v_rcp_f32_e32 v10, v10
	v_rcp_f32_e32 v12, v12
	v_rcp_f32_e32 v13, v13
	v_rcp_f32_e32 v11, v11
	s_andn2_b64 s[36:37], s[36:37], exec
	v_pk_mul_f32 v[12:13], v[8:9], v[12:13]
	v_pk_mul_f32 v[10:11], v[6:7], v[10:11]
	s_or_b64 exec, exec, s[42:43]
	s_and_saveexec_b64 s[42:43], s[36:37]
	s_or_b64 exec, exec, s[42:43]
	s_andn2_saveexec_b64 s[4:5], s[4:5]
	s_or_b64 exec, exec, s[4:5]
	v_mov_b32_e32 v8, v52
	v_mov_b32_e32 v9, v52
	v_pk_fma_f32 v[2:3], v[26:27], v[52:53], v[2:3] neg_lo:[1,0,0] neg_hi:[1,0,0]
	v_pk_fma_f32 v[4:5], v[28:29], v[8:9], v[4:5]
	v_pk_fma_f32 v[2:3], v[50:51], v[2:3], v[22:23]
	v_mov_b32_e32 v51, v50
	v_pk_fma_f32 v[4:5], v[50:51], v[4:5], v[24:25]
	v_cvt_pk_bf16_f32 v6, v10, v11
	v_cvt_pk_bf16_f32 v7, v12, v13
	s_and_saveexec_b64 s[4:5], s[44:45]
	s_xor_b64 s[4:5], exec, s[4:5]
	v_cmp_lt_i32_e32 vcc, 1, v172
	s_mov_b64 s[36:37], 0
	s_mov_b64 s[42:43], 0
	s_and_saveexec_b64 s[44:45], vcc
	s_xor_b64 s[44:45], exec, s[44:45]
	v_cmp_ne_u32_e32 vcc, 2, v172
	s_and_b64 s[42:43], vcc, exec
	s_andn2_saveexec_b64 s[44:45], s[44:45]
	v_cmp_ne_u32_e32 vcc, 1, v172
	s_andn2_b64 s[36:37], s[42:43], exec
	s_and_b64 s[42:43], vcc, exec
	s_or_b64 s[42:43], s[36:37], s[42:43]
	s_mov_b64 s[36:37], exec
	s_or_b64 exec, exec, s[44:45]
	v_mov_b64_e32 v[10:11], v[4:5]
	v_mov_b64_e32 v[8:9], v[2:3]
	s_and_saveexec_b64 s[44:45], s[42:43]
	s_xor_b64 s[42:43], exec, s[44:45]
	v_mul_f32_e32 v8, 0xbfb8aa3b, v2
	v_mul_f32_e32 v9, 0xbfb8aa3b, v3
	v_mul_f32_e32 v10, 0xbfb8aa3b, v4
	v_mul_f32_e32 v11, 0xbfb8aa3b, v5
	v_exp_f32_e32 v8, v8
	v_exp_f32_e32 v9, v9
	v_exp_f32_e32 v10, v10
	v_exp_f32_e32 v11, v11
	v_add_f32_e32 v8, 1.0, v8
	v_add_f32_e32 v9, 1.0, v9
	v_add_f32_e32 v10, 1.0, v10
	v_add_f32_e32 v11, 1.0, v11
	v_rcp_f32_e32 v8, v8
	v_rcp_f32_e32 v10, v10
	v_rcp_f32_e32 v11, v11
	v_rcp_f32_e32 v9, v9
	s_andn2_b64 s[36:37], s[36:37], exec
	v_pk_mul_f32 v[10:11], v[4:5], v[10:11]
	v_pk_mul_f32 v[8:9], v[2:3], v[8:9]
	s_or_b64 exec, exec, s[42:43]
	s_and_saveexec_b64 s[42:43], s[36:37]
	s_or_b64 exec, exec, s[42:43]
	s_andn2_saveexec_b64 s[4:5], s[4:5]
	s_branch .LBB0_394
